# packed f32 VALU ops split into scalar ops in all mixer phases (GLA, attention, RG-LRU)
# baseline (speedup 1.0000x reference)
.LBB0_464:
	ds_read_b128 v[94:97], v149 offset:6144
	ds_read_b128 v[98:101], v149 offset:6160
	s_waitcnt vmcnt(5)
	v_lshlrev_b32_e32 v102, 16, v22
	v_and_b32_e32 v103, 0xffff0000, v22
	s_add_i32 s46, s47, s46
	s_waitcnt lgkmcnt(1)
	v_mul_f32_e32 v94, 0xbfb8aa3b, v94
	v_mul_f32_e32 v95, 0xbfb8aa3b, v95
	v_exp_f32_e32 v94, v94
	v_exp_f32_e32 v95, v95
	v_mul_f32_e32 v22, 0xbfb8aa3b, v96
	v_exp_f32_e32 v96, v22
	v_mul_f32_e32 v22, 0xbfb8aa3b, v97
	v_exp_f32_e32 v97, v22
	v_mul_f32_e64 v94, v94, v102
	v_mul_f32_e64 v95, v95, v103
	s_add_i32 s83, s83, 1
	v_cvt_pk_bf16_f32 v22, v94, v95
	v_lshlrev_b32_e32 v94, 16, v23
	v_and_b32_e32 v95, 0xffff0000, v23
	s_waitcnt lgkmcnt(0)
	v_mul_f32_e32 v23, 0xbfb8aa3b, v98
	v_mul_f32_e64 v94, v96, v94
	v_mul_f32_e64 v95, v97, v95
	v_exp_f32_e32 v96, v23
	v_mul_f32_e32 v23, 0xbfb8aa3b, v99
	v_exp_f32_e32 v97, v23
	v_cvt_pk_bf16_f32 v23, v94, v95
	v_lshlrev_b32_e32 v94, 16, v24
	v_and_b32_e32 v95, 0xffff0000, v24
	v_mul_f32_e32 v24, 0xbfb8aa3b, v100
	v_mul_f32_e64 v94, v96, v94
	v_mul_f32_e64 v95, v97, v95
	v_exp_f32_e32 v96, v24
	v_mul_f32_e32 v24, 0xbfb8aa3b, v101
	v_exp_f32_e32 v97, v24
	v_cvt_pk_bf16_f32 v24, v94, v95
	v_lshlrev_b32_e32 v94, 16, v25
	v_and_b32_e32 v95, 0xffff0000, v25
	v_mul_f32_e64 v94, v96, v94
	v_mul_f32_e64 v95, v97, v95
	s_waitcnt vmcnt(4)
	v_lshlrev_b32_e32 v98, 16, v6
	v_cvt_pk_bf16_f32 v25, v94, v95
	ds_write_b128 v150, v[22:25] offset:56320
	ds_read_b128 v[22:25], v151 offset:6144
	ds_read_b128 v[94:97], v151 offset:6160
	v_and_b32_e32 v99, 0xffff0000, v6
	s_mul_i32 s53, s46, 0x1800
	s_mul_hi_i32 s52, s46, 0x1800
	s_waitcnt lgkmcnt(1)
	v_mul_f32_e32 v22, 0xbfb8aa3b, v22
	v_mul_f32_e32 v23, 0xbfb8aa3b, v23
	v_exp_f32_e32 v22, v22
	v_exp_f32_e32 v23, v23
	v_mul_f32_e32 v6, 0xbfb8aa3b, v24
	v_exp_f32_e32 v24, v6
	v_mul_f32_e32 v6, 0xbfb8aa3b, v25
	v_exp_f32_e32 v25, v6
	v_mul_f32_e64 v22, v22, v98
	v_mul_f32_e64 v23, v23, v99
	s_add_u32 s50, s80, s53
	v_cvt_pk_bf16_f32 v6, v22, v23
	v_lshlrev_b32_e32 v22, 16, v7
	v_and_b32_e32 v23, 0xffff0000, v7
	s_waitcnt lgkmcnt(0)
	v_mul_f32_e32 v7, 0xbfb8aa3b, v94
	v_mul_f32_e64 v22, v24, v22
	v_mul_f32_e64 v23, v25, v23
	v_exp_f32_e32 v24, v7
	v_mul_f32_e32 v7, 0xbfb8aa3b, v95
	v_exp_f32_e32 v25, v7
	v_cvt_pk_bf16_f32 v7, v22, v23
	v_lshlrev_b32_e32 v22, 16, v8
	v_and_b32_e32 v23, 0xffff0000, v8
	v_mul_f32_e32 v8, 0xbfb8aa3b, v96
	v_mul_f32_e64 v22, v24, v22
	v_mul_f32_e64 v23, v25, v23
	v_exp_f32_e32 v24, v8
	v_mul_f32_e32 v8, 0xbfb8aa3b, v97
	v_exp_f32_e32 v25, v8
	v_cvt_pk_bf16_f32 v8, v22, v23
	v_lshlrev_b32_e32 v22, 16, v9
	v_and_b32_e32 v23, 0xffff0000, v9
	v_mul_f32_e64 v22, v24, v22
	v_mul_f32_e64 v23, v25, v23
	s_addc_u32 s51, s81, s52
	v_cvt_pk_bf16_f32 v9, v22, v23
	ds_write_b128 v152, v[6:9] offset:56320
	s_waitcnt vmcnt(3)
	ds_write_b128 v153, v[2:5]
	s_waitcnt vmcnt(2)
	ds_write_b128 v155, v[10:13]
	s_waitcnt vmcnt(1)
	ds_write_b128 v153, v[14:17] offset:16896
	s_waitcnt vmcnt(0)
	ds_write_b128 v156, v[18:21]
	v_lshl_add_u64 v[2:3], s[50:51], 0, v[112:113]
	s_add_u32 s50, s38, s53
	s_addc_u32 s51, s39, s52
	s_add_u32 s50, s50, s76
	s_addc_u32 s51, s51, 0
	s_add_u32 s50, s50, 0xad20800
	global_load_dwordx4 v[22:25], v[2:3], off offset:1024
	v_add_co_u32_e32 v2, vcc, s63, v2
	s_addc_u32 s51, s51, 0
	s_nop 0
	v_addc_co_u32_e32 v3, vcc, 0, v3, vcc
	v_lshl_add_u64 v[18:19], s[50:51], 0, v[114:115]
	v_add_co_u32_e32 v10, vcc, s64, v18
	global_load_dwordx4 v[6:9], v[2:3], off offset:1024
	s_nop 0
	v_addc_co_u32_e32 v11, vcc, 0, v19, vcc
	v_add_co_u32_e32 v14, vcc, s63, v18
	global_load_dwordx4 v[2:5], v[18:19], off
	s_nop 0
	v_addc_co_u32_e32 v15, vcc, 0, v19, vcc
	v_add_co_u32_e32 v18, vcc, s65, v18
	global_load_dwordx4 v[10:13], v[10:11], off
	s_nop 0
	v_addc_co_u32_e32 v19, vcc, 0, v19, vcc
	global_load_dwordx4 v[14:17], v[14:15], off
	v_lshl_add_u32 v167, s87, 9, v128
	global_load_dwordx4 v[18:21], v[18:19], off
	s_waitcnt lgkmcnt(0)
	s_barrier
	ds_read_b64_tr_b16 v[96:97], v158 offset:57408
	ds_read_b64_tr_b16 v[94:95], v158 offset:56320
	ds_read_b64_tr_b16 v[108:109], v157 offset:2112
	ds_read_b64_tr_b16 v[106:107], v157
	ds_read_b64_tr_b16 v[102:103], v157 offset:32
	ds_read_b64_tr_b16 v[104:105], v157 offset:2144
	s_waitcnt lgkmcnt(2)
	v_mfma_f32_16x16x32_bf16 v[70:73], v[94:97], v[106:109], v[70:73]
	ds_read_b64_tr_b16 v[168:169], v158 offset:65024
	ds_read_b64_tr_b16 v[170:171], v159 offset:57408
	ds_read_b64_tr_b16 v[98:99], v157 offset:16896
	s_cmp_eq_u32 s43, s83
	s_waitcnt lgkmcnt(3)
	v_mfma_f32_16x16x32_bf16 v[74:77], v[94:97], v[102:105], v[74:77]
	ds_read_b64_tr_b16 v[100:101], v157 offset:19008
	ds_read_b64_tr_b16 v[94:95], v157 offset:16928
	ds_read_b64_tr_b16 v[96:97], v157 offset:19040
	ds_read_b64_tr_b16 v[172:173], v158 offset:56352
	ds_read_b64_tr_b16 v[174:175], v158 offset:57440
	s_waitcnt lgkmcnt(4)
	v_mfma_f32_16x16x32_bf16 v[70:73], v[168:171], v[98:101], v[70:73]
	s_waitcnt lgkmcnt(2)
	v_mfma_f32_16x16x32_bf16 v[74:77], v[168:171], v[94:97], v[74:77]
	ds_read_b64_tr_b16 v[170:171], v159 offset:57440
	ds_read_b64_tr_b16 v[168:169], v158 offset:65056
	s_waitcnt lgkmcnt(2)
	v_mfma_f32_16x16x32_bf16 v[58:61], v[172:175], v[106:109], v[58:61]
	v_mfma_f32_16x16x32_bf16 v[82:85], v[172:175], v[102:105], v[82:85]
	s_waitcnt lgkmcnt(0)
	v_mfma_f32_16x16x32_bf16 v[58:61], v[168:171], v[98:101], v[58:61]
	v_mfma_f32_16x16x32_bf16 v[82:85], v[168:171], v[94:97], v[82:85]
	ds_read_b64_tr_b16 v[168:169], v158 offset:56384
	ds_read_b64_tr_b16 v[170:171], v158 offset:57472
	s_waitcnt lgkmcnt(0)
	v_mfma_f32_16x16x32_bf16 v[66:69], v[168:171], v[106:109], v[66:69]
	v_mfma_f32_16x16x32_bf16 v[78:81], v[168:171], v[102:105], v[78:81]
	ds_read_b64_tr_b16 v[168:169], v158 offset:65088
	ds_read_b64_tr_b16 v[170:171], v159 offset:57472
	s_waitcnt lgkmcnt(0)
	v_mfma_f32_16x16x32_bf16 v[66:69], v[168:171], v[98:101], v[66:69]
	v_mfma_f32_16x16x32_bf16 v[78:81], v[168:171], v[94:97], v[78:81]
	ds_read_b64_tr_b16 v[168:169], v158 offset:56416
	ds_read_b64_tr_b16 v[170:171], v158 offset:57504
	s_waitcnt lgkmcnt(0)
	v_mfma_f32_16x16x32_bf16 v[62:65], v[168:171], v[106:109], v[62:65]
	v_mfma_f32_16x16x32_bf16 v[86:89], v[168:171], v[102:105], v[86:89]
	ds_read_b64_tr_b16 v[168:169], v158 offset:65120
	ds_read_b64_tr_b16 v[170:171], v159 offset:57504
	s_waitcnt lgkmcnt(0)
	v_mfma_f32_16x16x32_bf16 v[62:65], v[168:171], v[98:101], v[62:65]
	v_mfma_f32_16x16x32_bf16 v[86:89], v[168:171], v[94:97], v[86:89]
	ds_read_b64_tr_b16 v[168:169], v158 offset:56448
	ds_read_b64_tr_b16 v[170:171], v158 offset:57536
	s_waitcnt lgkmcnt(0)
	v_mfma_f32_16x16x32_bf16 v[38:41], v[168:171], v[106:109], v[38:41]
	v_mfma_f32_16x16x32_bf16 v[50:53], v[168:171], v[102:105], v[50:53]
	ds_read_b64_tr_b16 v[168:169], v158 offset:65152
	ds_read_b64_tr_b16 v[170:171], v159 offset:57536
	s_waitcnt lgkmcnt(0)
	v_mfma_f32_16x16x32_bf16 v[38:41], v[168:171], v[98:101], v[38:41]
	v_mfma_f32_16x16x32_bf16 v[50:53], v[168:171], v[94:97], v[50:53]
	ds_read_b64_tr_b16 v[168:169], v158 offset:56480
	ds_read_b64_tr_b16 v[170:171], v158 offset:57568
	s_waitcnt lgkmcnt(0)
	v_mfma_f32_16x16x32_bf16 v[30:33], v[168:171], v[106:109], v[30:33]
	v_mfma_f32_16x16x32_bf16 v[54:57], v[168:171], v[102:105], v[54:57]
	ds_read_b64_tr_b16 v[168:169], v158 offset:65184
	ds_read_b64_tr_b16 v[170:171], v159 offset:57568
	s_waitcnt lgkmcnt(0)
	v_mfma_f32_16x16x32_bf16 v[30:33], v[168:171], v[98:101], v[30:33]
	v_mfma_f32_16x16x32_bf16 v[54:57], v[168:171], v[94:97], v[54:57]
	ds_read_b64_tr_b16 v[168:169], v158 offset:56512
	ds_read_b64_tr_b16 v[170:171], v158 offset:57600
	s_waitcnt lgkmcnt(0)
	v_mfma_f32_16x16x32_bf16 v[42:45], v[168:171], v[106:109], v[42:45]
	v_mfma_f32_16x16x32_bf16 v[46:49], v[168:171], v[102:105], v[46:49]
	ds_read_b64_tr_b16 v[168:169], v158 offset:65216
	ds_read_b64_tr_b16 v[170:171], v159 offset:57600
	s_waitcnt lgkmcnt(0)
	v_mfma_f32_16x16x32_bf16 v[42:45], v[168:171], v[98:101], v[42:45]
	v_mfma_f32_16x16x32_bf16 v[46:49], v[168:171], v[94:97], v[46:49]
	ds_read_b64_tr_b16 v[168:169], v158 offset:56544
	ds_read_b64_tr_b16 v[170:171], v158 offset:57632
	s_waitcnt lgkmcnt(0)
	v_mfma_f32_16x16x32_bf16 v[34:37], v[168:171], v[106:109], v[34:37]
	ds_read_b64_tr_b16 v[106:107], v158 offset:65248
	ds_read_b64_tr_b16 v[108:109], v159 offset:57632
	v_mfma_f32_16x16x32_bf16 v[102:105], v[168:171], v[102:105], v[26:29]
	ds_read_b128 v[168:171], v167 offset:4096
	s_waitcnt lgkmcnt(1)
	v_mfma_f32_16x16x32_bf16 v[26:29], v[106:109], v[98:101], v[34:37]
	s_waitcnt lgkmcnt(0)
	s_nop 1
	v_mul_f32_e32 v34, 0x3fb8aa3b, v168
	v_exp_f32_e32 v98, v34
	v_mul_f32_e32 v34, 0x3fb8aa3b, v169
	v_exp_f32_e32 v99, v34
	v_mul_f32_e32 v34, 0x3fb8aa3b, v170
	v_exp_f32_e32 v100, v34
	v_mul_f32_e32 v34, 0x3fb8aa3b, v171
	v_exp_f32_e32 v101, v34
	ds_read_b128 v[34:37], v167 offset:4160
	v_mfma_f32_16x16x32_bf16 v[94:97], v[106:109], v[94:97], v[102:105]
	v_mul_f32_e64 v70, v70, v98
	v_mul_f32_e64 v71, v71, v99
	v_mul_f32_e64 v74, v74, v98
	v_mul_f32_e64 v75, v75, v99
	v_mul_f32_e64 v72, v72, v100
	v_mul_f32_e64 v73, v73, v101
	s_waitcnt lgkmcnt(0)
	v_mul_f32_e32 v34, 0x3fb8aa3b, v34
	v_exp_f32_e32 v102, v34
	v_mul_f32_e32 v34, 0x3fb8aa3b, v35
	v_exp_f32_e32 v103, v34
	v_mul_f32_e32 v34, 0x3fb8aa3b, v36
	v_exp_f32_e32 v104, v34
	v_mul_f32_e32 v34, 0x3fb8aa3b, v37
	v_exp_f32_e32 v105, v34
	ds_read_b128 v[34:37], v167 offset:4224
	v_mul_f32_e64 v76, v76, v100
	v_mul_f32_e64 v77, v77, v101
	v_mul_f32_e64 v58, v58, v102
	v_mul_f32_e64 v59, v59, v103
	v_mul_f32_e64 v82, v82, v102
	v_mul_f32_e64 v83, v83, v103
	v_mul_f32_e64 v60, v60, v104
	v_mul_f32_e64 v61, v61, v105
	s_waitcnt lgkmcnt(0)
	v_mul_f32_e32 v34, 0x3fb8aa3b, v34
	v_exp_f32_e32 v98, v34
	v_mul_f32_e32 v34, 0x3fb8aa3b, v35
	v_exp_f32_e32 v99, v34
	v_mul_f32_e32 v34, 0x3fb8aa3b, v36
	v_exp_f32_e32 v100, v34
	v_mul_f32_e32 v34, 0x3fb8aa3b, v37
	v_exp_f32_e32 v101, v34
	ds_read_b128 v[34:37], v167 offset:4288
	v_mul_f32_e64 v84, v84, v104
	v_mul_f32_e64 v85, v85, v105
	v_mul_f32_e64 v66, v66, v98
	v_mul_f32_e64 v67, v67, v99
	v_mul_f32_e64 v78, v78, v98
	v_mul_f32_e64 v79, v79, v99
	v_mul_f32_e64 v68, v68, v100
	v_mul_f32_e64 v69, v69, v101
	s_waitcnt lgkmcnt(0)
	v_mul_f32_e32 v34, 0x3fb8aa3b, v34
	v_exp_f32_e32 v102, v34
	v_mul_f32_e32 v34, 0x3fb8aa3b, v35
	v_exp_f32_e32 v103, v34
	v_mul_f32_e32 v34, 0x3fb8aa3b, v36
	v_exp_f32_e32 v104, v34
	v_mul_f32_e32 v34, 0x3fb8aa3b, v37
	v_exp_f32_e32 v105, v34
	ds_read_b128 v[34:37], v167 offset:4352
	v_mul_f32_e64 v80, v80, v100
	v_mul_f32_e64 v81, v81, v101
	v_mul_f32_e64 v62, v62, v102
	v_mul_f32_e64 v63, v63, v103
	v_mul_f32_e64 v86, v86, v102
	v_mul_f32_e64 v87, v87, v103
	v_mul_f32_e64 v64, v64, v104
	v_mul_f32_e64 v65, v65, v105
	s_waitcnt lgkmcnt(0)
	v_mul_f32_e32 v34, 0x3fb8aa3b, v34
	v_exp_f32_e32 v98, v34
	v_mul_f32_e32 v34, 0x3fb8aa3b, v35
	v_exp_f32_e32 v99, v34
	v_mul_f32_e32 v34, 0x3fb8aa3b, v36
	v_exp_f32_e32 v100, v34
	v_mul_f32_e32 v34, 0x3fb8aa3b, v37
	v_exp_f32_e32 v101, v34
	ds_read_b128 v[34:37], v167 offset:4416
	v_mul_f32_e64 v88, v88, v104
	v_mul_f32_e64 v89, v89, v105
	v_mul_f32_e64 v38, v38, v98
	v_mul_f32_e64 v39, v39, v99
	v_mul_f32_e64 v50, v50, v98
	v_mul_f32_e64 v51, v51, v99
	v_mul_f32_e64 v40, v40, v100
	v_mul_f32_e64 v41, v41, v101
	s_waitcnt lgkmcnt(0)
	v_mul_f32_e32 v34, 0x3fb8aa3b, v34
	v_exp_f32_e32 v102, v34
	v_mul_f32_e32 v34, 0x3fb8aa3b, v35
	v_exp_f32_e32 v103, v34
	v_mul_f32_e32 v34, 0x3fb8aa3b, v36
	v_exp_f32_e32 v104, v34
	v_mul_f32_e32 v34, 0x3fb8aa3b, v37
	v_exp_f32_e32 v105, v34
	ds_read_b128 v[34:37], v167 offset:4480
	v_mul_f32_e64 v52, v52, v100
	v_mul_f32_e64 v53, v53, v101
	v_mul_f32_e64 v30, v30, v102
	v_mul_f32_e64 v31, v31, v103
	v_mul_f32_e64 v54, v54, v102
	v_mul_f32_e64 v55, v55, v103
	v_mul_f32_e64 v32, v32, v104
	v_mul_f32_e64 v33, v33, v105
	s_waitcnt lgkmcnt(0)
	v_mul_f32_e32 v34, 0x3fb8aa3b, v34
	v_exp_f32_e32 v98, v34
	v_mul_f32_e32 v34, 0x3fb8aa3b, v35
	v_exp_f32_e32 v99, v34
	v_mul_f32_e32 v34, 0x3fb8aa3b, v36
	v_exp_f32_e32 v100, v34
	v_mul_f32_e32 v34, 0x3fb8aa3b, v37
	v_exp_f32_e32 v101, v34
	ds_read_b128 v[34:37], v167 offset:4544
	v_mul_f32_e64 v56, v56, v104
	v_mul_f32_e64 v57, v57, v105
	v_mul_f32_e64 v42, v42, v98
	v_mul_f32_e64 v43, v43, v99
	v_mul_f32_e64 v44, v44, v100
	v_mul_f32_e64 v45, v45, v101
	v_mul_f32_e64 v48, v48, v100
	v_mul_f32_e64 v49, v49, v101
	s_waitcnt lgkmcnt(0)
	v_mul_f32_e32 v34, 0x3fb8aa3b, v34
	v_exp_f32_e32 v102, v34
	v_mul_f32_e32 v34, 0x3fb8aa3b, v35
	v_mul_f32_e32 v35, 0x3fb8aa3b, v36
	v_exp_f32_e32 v104, v35
	v_mul_f32_e32 v35, 0x3fb8aa3b, v37
	v_exp_f32_e32 v105, v35
	v_exp_f32_e32 v103, v34
	v_mul_f32_e64 v46, v46, v98
	v_mul_f32_e64 v47, v47, v99
	v_mul_f32_e64 v36, v28, v104
	v_mul_f32_e64 v37, v29, v105
	v_mul_f32_e64 v34, v26, v102
	v_mul_f32_e64 v35, v27, v103
	v_mul_f32_e64 v28, v96, v104
	v_mul_f32_e64 v29, v97, v105
	v_mul_f32_e64 v26, v94, v102
	v_mul_f32_e64 v27, v95, v103
	s_cbranch_scc1 .LBB0_480

.LBB0_490:
	s_or_b64 exec, exec, s[30:31]
	ds_read_b128 v[90:93], v149 offset:6144
	ds_read_b128 v[94:97], v149 offset:6160
	s_waitcnt vmcnt(5)
	v_lshlrev_b32_e32 v98, 16, v22
	v_and_b32_e32 v99, 0xffff0000, v22
	s_waitcnt lgkmcnt(1)
	v_mul_f32_e32 v90, 0xbfb8aa3b, v90
	v_mul_f32_e32 v91, 0xbfb8aa3b, v91
	v_exp_f32_e32 v90, v90
	v_exp_f32_e32 v91, v91
	v_mul_f32_e32 v22, 0xbfb8aa3b, v92
	v_exp_f32_e32 v92, v22
	v_mul_f32_e32 v22, 0xbfb8aa3b, v93
	v_exp_f32_e32 v93, v22
	v_mul_f32_e64 v90, v90, v98
	v_mul_f32_e64 v91, v91, v99
	s_nop 0
	v_cvt_pk_bf16_f32 v22, v90, v91
	v_lshlrev_b32_e32 v90, 16, v23
	v_and_b32_e32 v91, 0xffff0000, v23
	s_waitcnt lgkmcnt(0)
	v_mul_f32_e32 v23, 0xbfb8aa3b, v94
	v_mul_f32_e64 v90, v92, v90
	v_mul_f32_e64 v91, v93, v91
	v_exp_f32_e32 v92, v23
	v_mul_f32_e32 v23, 0xbfb8aa3b, v95
	v_exp_f32_e32 v93, v23
	v_cvt_pk_bf16_f32 v23, v90, v91
	v_lshlrev_b32_e32 v90, 16, v24
	v_and_b32_e32 v91, 0xffff0000, v24
	v_mul_f32_e32 v24, 0xbfb8aa3b, v96
	v_mul_f32_e64 v90, v92, v90
	v_mul_f32_e64 v91, v93, v91
	v_exp_f32_e32 v92, v24
	v_mul_f32_e32 v24, 0xbfb8aa3b, v97
	v_exp_f32_e32 v93, v24
	v_cvt_pk_bf16_f32 v24, v90, v91
	v_lshlrev_b32_e32 v90, 16, v25
	v_and_b32_e32 v91, 0xffff0000, v25
	v_mul_f32_e64 v90, v92, v90
	v_mul_f32_e64 v91, v93, v91
	s_waitcnt vmcnt(4)
	v_lshlrev_b32_e32 v94, 16, v6
	v_cvt_pk_bf16_f32 v25, v90, v91
	ds_write_b128 v150, v[22:25] offset:56320
	ds_read_b128 v[22:25], v151 offset:6144
	ds_read_b128 v[90:93], v151 offset:6160
	v_and_b32_e32 v95, 0xffff0000, v6
	s_waitcnt lgkmcnt(1)
	v_mul_f32_e32 v22, 0xbfb8aa3b, v22
	v_mul_f32_e32 v23, 0xbfb8aa3b, v23
	v_exp_f32_e32 v22, v22
	v_exp_f32_e32 v23, v23
	v_mul_f32_e32 v6, 0xbfb8aa3b, v24
	v_exp_f32_e32 v24, v6
	v_mul_f32_e32 v6, 0xbfb8aa3b, v25
	v_exp_f32_e32 v25, v6
	v_mul_f32_e64 v22, v22, v94
	v_mul_f32_e64 v23, v23, v95
	s_nop 0
	v_cvt_pk_bf16_f32 v6, v22, v23
	v_lshlrev_b32_e32 v22, 16, v7
	v_and_b32_e32 v23, 0xffff0000, v7
	s_waitcnt lgkmcnt(0)
	v_mul_f32_e32 v7, 0xbfb8aa3b, v90
	v_mul_f32_e64 v22, v24, v22
	v_mul_f32_e64 v23, v25, v23
	v_exp_f32_e32 v24, v7
	v_mul_f32_e32 v7, 0xbfb8aa3b, v91
	v_exp_f32_e32 v25, v7
	v_cvt_pk_bf16_f32 v7, v22, v23
	v_lshlrev_b32_e32 v22, 16, v8
	v_and_b32_e32 v23, 0xffff0000, v8
	v_mul_f32_e32 v8, 0xbfb8aa3b, v92
	v_mul_f32_e64 v22, v24, v22
	v_mul_f32_e64 v23, v25, v23
	v_exp_f32_e32 v24, v8
	v_mul_f32_e32 v8, 0xbfb8aa3b, v93
	v_exp_f32_e32 v25, v8
	v_cvt_pk_bf16_f32 v8, v22, v23
	v_lshlrev_b32_e32 v22, 16, v9
	v_and_b32_e32 v23, 0xffff0000, v9
	v_mul_f32_e64 v22, v24, v22
	v_mul_f32_e64 v23, v25, v23
	s_nop 0
	v_cvt_pk_bf16_f32 v9, v22, v23
	ds_write_b128 v152, v[6:9] offset:56320
	s_waitcnt vmcnt(3)
	ds_write_b128 v153, v[2:5]
	s_waitcnt vmcnt(2)
	ds_write_b128 v155, v[10:13]
	s_waitcnt vmcnt(1)
	ds_write_b128 v153, v[14:17] offset:16896
	s_waitcnt vmcnt(0)
	ds_write_b128 v156, v[18:21]
	s_waitcnt lgkmcnt(0)
	s_barrier
	ds_read_b64_tr_b16 v[4:5], v158 offset:57408
	ds_read_b64_tr_b16 v[2:3], v158 offset:56320
	ds_read_b64_tr_b16 v[8:9], v157 offset:2112
	ds_read_b64_tr_b16 v[6:7], v157
	ds_read_b64_tr_b16 v[12:13], v157 offset:2144
	ds_read_b64_tr_b16 v[10:11], v157 offset:32
	ds_read_b64_tr_b16 v[14:15], v158 offset:56352
	ds_read_b64_tr_b16 v[18:19], v158 offset:56384
	ds_read_b64_tr_b16 v[22:23], v158 offset:56416
	ds_read_b64_tr_b16 v[16:17], v158 offset:57440
	ds_read_b64_tr_b16 v[20:21], v158 offset:57472
	ds_read_b64_tr_b16 v[24:25], v158 offset:57504
	ds_read_b64_tr_b16 v[90:91], v158 offset:65024
	ds_read_b64_tr_b16 v[92:93], v159 offset:57408
	ds_read_b64_tr_b16 v[94:95], v157 offset:16896
	ds_read_b64_tr_b16 v[96:97], v157 offset:19008
	ds_read_b64_tr_b16 v[100:101], v157 offset:19040
	ds_read_b64_tr_b16 v[98:99], v157 offset:16928
	s_waitcnt lgkmcnt(8)
	v_mfma_f32_16x16x32_bf16 v[58:61], v[14:17], v[6:9], v[58:61]
	v_mfma_f32_16x16x32_bf16 v[14:17], v[14:17], v[10:13], v[82:85]
	v_mfma_f32_16x16x32_bf16 v[70:73], v[2:5], v[6:9], v[70:73]
	v_mfma_f32_16x16x32_bf16 v[2:5], v[2:5], v[10:13], v[74:77]
	s_nop 2
	ds_read_b64_tr_b16 v[74:75], v158 offset:65056
	ds_read_b64_tr_b16 v[102:103], v158 offset:65088
	ds_read_b64_tr_b16 v[106:107], v158 offset:65120
	ds_read_b64_tr_b16 v[76:77], v159 offset:57440
	ds_read_b64_tr_b16 v[104:105], v159 offset:57472
	ds_read_b64_tr_b16 v[108:109], v159 offset:57504
	s_waitcnt lgkmcnt(2)
	v_mfma_f32_16x16x32_bf16 v[58:61], v[74:77], v[94:97], v[58:61]
	v_mfma_f32_16x16x32_bf16 v[14:17], v[74:77], v[98:101], v[14:17]
	ds_read_b64_tr_b16 v[74:75], v158 offset:56448
	ds_read_b64_tr_b16 v[76:77], v158 offset:57536
	v_mfma_f32_16x16x32_bf16 v[66:69], v[18:21], v[6:9], v[66:69]
	v_mfma_f32_16x16x32_bf16 v[18:21], v[18:21], v[10:13], v[78:81]
	v_mfma_f32_16x16x32_bf16 v[62:65], v[22:25], v[6:9], v[62:65]
	v_mfma_f32_16x16x32_bf16 v[22:25], v[22:25], v[10:13], v[86:89]
	s_nop 0
	ds_read_b64_tr_b16 v[78:79], v158 offset:56480
	ds_read_b64_tr_b16 v[82:83], v158 offset:56512
	ds_read_b64_tr_b16 v[86:87], v158 offset:56544
	ds_read_b64_tr_b16 v[80:81], v158 offset:57568
	ds_read_b64_tr_b16 v[84:85], v158 offset:57600
	ds_read_b64_tr_b16 v[88:89], v158 offset:57632
	s_waitcnt lgkmcnt(1)
	v_mfma_f32_16x16x32_bf16 v[42:45], v[82:85], v[6:9], v[42:45]
	v_mfma_f32_16x16x32_bf16 v[46:49], v[82:85], v[10:13], v[46:49]
	v_add_u32_e32 v82, s43, v128
	s_ashr_i32 s43, s42, 31
	s_lshl_b64 s[30:31], s[42:43], 17
	v_mfma_f32_16x16x32_bf16 v[70:73], v[90:93], v[94:97], v[70:73]
	v_mfma_f32_16x16x32_bf16 v[2:5], v[90:93], v[98:101], v[2:5]
	ds_read_b64_tr_b16 v[90:91], v158 offset:65152
	ds_read_b64_tr_b16 v[92:93], v159 offset:57536
	v_mfma_f32_16x16x32_bf16 v[66:69], v[102:105], v[94:97], v[66:69]
	v_mfma_f32_16x16x32_bf16 v[18:21], v[102:105], v[98:101], v[18:21]
	v_mfma_f32_16x16x32_bf16 v[62:65], v[106:109], v[94:97], v[62:65]
	v_mfma_f32_16x16x32_bf16 v[22:25], v[106:109], v[98:101], v[22:25]
	v_mfma_f32_16x16x32_bf16 v[38:41], v[74:77], v[6:9], v[38:41]
	v_mfma_f32_16x16x32_bf16 v[50:53], v[74:77], v[10:13], v[50:53]
	ds_read_b64_tr_b16 v[74:75], v158 offset:65184
	ds_read_b64_tr_b16 v[102:103], v158 offset:65216
	ds_read_b64_tr_b16 v[106:107], v158 offset:65248
	ds_read_b64_tr_b16 v[76:77], v159 offset:57568
	ds_read_b64_tr_b16 v[104:105], v159 offset:57600
	ds_read_b64_tr_b16 v[108:109], v159 offset:57632
	v_mfma_f32_16x16x32_bf16 v[54:57], v[78:81], v[10:13], v[54:57]
	s_waitcnt lgkmcnt(8)
	v_mfma_f32_16x16x32_bf16 v[10:13], v[86:89], v[10:13], v[26:29]
	s_nop 2
	ds_read_b128 v[26:29], v82 offset:4096
	v_mfma_f32_16x16x32_bf16 v[30:33], v[78:81], v[6:9], v[30:33]
	v_mfma_f32_16x16x32_bf16 v[6:9], v[86:89], v[6:9], v[34:37]
	s_nop 2
	ds_read_b128 v[34:37], v82 offset:4160
	s_waitcnt lgkmcnt(1)
	v_mul_f32_e32 v26, 0x3fb8aa3b, v26
	v_mfma_f32_16x16x32_bf16 v[30:33], v[74:77], v[94:97], v[30:33]
	s_waitcnt lgkmcnt(0)
	v_mul_f32_e32 v34, 0x3fb8aa3b, v34
	v_mfma_f32_16x16x32_bf16 v[54:57], v[74:77], v[98:101], v[54:57]
	v_exp_f32_e32 v74, v26
	v_mul_f32_e32 v26, 0x3fb8aa3b, v27
	v_mul_f32_e32 v27, 0x3fb8aa3b, v28
	v_exp_f32_e32 v76, v27
	v_mul_f32_e32 v27, 0x3fb8aa3b, v29
	v_exp_f32_e32 v77, v27
	v_exp_f32_e32 v75, v26
	v_mfma_f32_16x16x32_bf16 v[38:41], v[90:93], v[94:97], v[38:41]
	v_mul_f32_e64 v28, v72, v76
	v_mul_f32_e64 v29, v73, v77
	v_mul_f32_e64 v4, v4, v76
	v_mul_f32_e64 v5, v5, v77
	v_exp_f32_e32 v76, v34
	v_mul_f32_e32 v34, 0x3fb8aa3b, v35
	v_mul_f32_e32 v35, 0x3fb8aa3b, v36
	v_exp_f32_e32 v78, v35
	v_mul_f32_e32 v35, 0x3fb8aa3b, v37
	v_exp_f32_e32 v79, v35
	v_exp_f32_e32 v77, v34
	ds_read_b128 v[34:37], v82 offset:4224
	v_mul_f32_e64 v26, v70, v74
	v_mul_f32_e64 v27, v71, v75
	ds_read_b128 v[70:73], v82 offset:4288
	v_mul_f32_e64 v2, v2, v74
	v_mul_f32_e64 v3, v3, v75
	v_mul_f32_e64 v60, v60, v78
	v_mul_f32_e64 v61, v61, v79
	s_waitcnt lgkmcnt(1)
	v_mul_f32_e32 v34, 0x3fb8aa3b, v34
	v_exp_f32_e32 v74, v34
	v_mul_f32_e32 v34, 0x3fb8aa3b, v35
	v_mul_f32_e32 v35, 0x3fb8aa3b, v36
	v_exp_f32_e32 v75, v34
	v_exp_f32_e32 v80, v35
	v_mul_f32_e32 v35, 0x3fb8aa3b, v37
	v_exp_f32_e32 v81, v35
	v_mul_f32_e64 v34, v66, v74
	v_mul_f32_e64 v35, v67, v75
	s_waitcnt lgkmcnt(0)
	v_mul_f32_e32 v66, 0x3fb8aa3b, v70
	v_mul_f32_e32 v67, 0x3fb8aa3b, v72
	v_mul_f32_e64 v58, v58, v76
	v_mul_f32_e64 v59, v59, v77
	v_mul_f32_e64 v16, v16, v78
	v_mul_f32_e64 v17, v17, v79
	v_mul_f32_e64 v14, v14, v76
	v_mul_f32_e64 v15, v15, v77
	v_exp_f32_e32 v76, v66
	v_mul_f32_e32 v66, 0x3fb8aa3b, v71
	v_exp_f32_e32 v78, v67
	v_mul_f32_e32 v67, 0x3fb8aa3b, v73
	v_mul_f32_e64 v36, v68, v80
	v_mul_f32_e64 v37, v69, v81
	v_exp_f32_e32 v79, v67
	v_exp_f32_e32 v77, v66
	ds_read_b128 v[66:69], v82 offset:4352
	ds_read_b128 v[70:73], v82 offset:4416
	v_mul_f32_e64 v18, v18, v74
	v_mul_f32_e64 v19, v19, v75
	v_mfma_f32_16x16x32_bf16 v[50:53], v[90:93], v[98:101], v[50:53]
	v_mul_f32_e64 v64, v64, v78
	v_mul_f32_e64 v65, v65, v79
	s_waitcnt lgkmcnt(1)
	v_mul_f32_e32 v66, 0x3fb8aa3b, v66
	v_exp_f32_e32 v74, v66
	v_mul_f32_e32 v75, 0x3fb8aa3b, v67
	v_mul_f32_e32 v66, 0x3fb8aa3b, v68
	v_mul_f32_e32 v67, 0x3fb8aa3b, v69
	v_exp_f32_e32 v66, v66
	v_exp_f32_e32 v67, v67
	v_mul_f32_e64 v62, v62, v76
	v_mul_f32_e64 v63, v63, v77
	v_mul_f32_e64 v24, v24, v78
	v_mul_f32_e64 v25, v25, v79
	v_mul_f32_e64 v22, v22, v76
	v_mul_f32_e64 v23, v23, v77
	v_mul_f32_e64 v40, v40, v66
	v_mul_f32_e64 v41, v41, v67
	v_mul_f32_e64 v52, v52, v66
	v_mul_f32_e64 v53, v53, v67
	s_waitcnt lgkmcnt(0)
	v_mul_f32_e32 v66, 0x3fb8aa3b, v70
	v_mul_f32_e32 v67, 0x3fb8aa3b, v72
	v_exp_f32_e32 v76, v66
	v_mul_f32_e32 v66, 0x3fb8aa3b, v71
	v_exp_f32_e32 v78, v67
	v_mul_f32_e32 v67, 0x3fb8aa3b, v73
	v_exp_f32_e32 v79, v67
	v_exp_f32_e32 v77, v66
	ds_read_b128 v[66:69], v82 offset:4480
	ds_read_b128 v[70:73], v82 offset:4544
	v_mfma_f32_16x16x32_bf16 v[42:45], v[102:105], v[94:97], v[42:45]
	v_mul_f32_e64 v20, v20, v80
	v_mul_f32_e64 v21, v21, v81
	v_exp_f32_e32 v75, v75
	s_waitcnt lgkmcnt(1)
	v_mul_f32_e32 v66, 0x3fb8aa3b, v66
	v_mul_f32_e32 v67, 0x3fb8aa3b, v67
	v_mfma_f32_16x16x32_bf16 v[46:49], v[102:105], v[98:101], v[46:49]
	v_exp_f32_e32 v66, v66
	v_exp_f32_e32 v67, v67
	v_mul_f32_e64 v38, v38, v74
	v_mul_f32_e64 v39, v39, v75
	v_mul_f32_e64 v50, v50, v74
	v_mul_f32_e64 v51, v51, v75
	v_mul_f32_e32 v68, 0x3fb8aa3b, v68
	v_mul_f32_e64 v42, v42, v66
	v_mul_f32_e64 v43, v43, v67
	s_nop 1
	v_mul_f32_e64 v46, v46, v66
	v_mul_f32_e64 v47, v47, v67
	v_lshl_add_u64 v[66:67], v[120:121], 0, s[30:31]
	s_movk_i32 s30, 0x2000
	global_store_dwordx4 v[66:67], v[26:29], off
	v_mul_f32_e32 v69, 0x3fb8aa3b, v69
	v_mul_f32_e64 v32, v32, v78
	v_mul_f32_e64 v33, v33, v79
	v_add_co_u32_e32 v26, vcc, s30, v66
	s_movk_i32 s30, 0x4000
	s_nop 0
	v_addc_co_u32_e32 v27, vcc, 0, v67, vcc
	global_store_dwordx4 v[26:27], v[2:5], off
	v_mul_f32_e64 v30, v30, v76
	v_mul_f32_e64 v31, v31, v77
	v_exp_f32_e32 v68, v68
	v_add_co_u32_e32 v2, vcc, s30, v66
	s_movk_i32 s30, 0x6000
	s_nop 0
	v_addc_co_u32_e32 v3, vcc, 0, v67, vcc
	global_store_dwordx4 v[2:3], v[58:61], off
	v_add_co_u32_e32 v2, vcc, s30, v66
	v_exp_f32_e32 v69, v69
	s_nop 0
	v_addc_co_u32_e32 v3, vcc, 0, v67, vcc
	global_store_dwordx4 v[2:3], v[14:17], off
	v_add_co_u32_e32 v2, vcc, s62, v66
	v_mul_f32_e64 v56, v56, v78
	v_mul_f32_e64 v57, v57, v79
	s_nop 0
	v_addc_co_u32_e32 v3, vcc, 0, v67, vcc
	global_store_dwordx4 v[2:3], v[34:37], off
	v_add_co_u32_e32 v2, vcc, s69, v66
	v_mul_f32_e64 v54, v54, v76
	v_mul_f32_e64 v55, v55, v77
	s_nop 0
	v_addc_co_u32_e32 v3, vcc, 0, v67, vcc
	global_store_dwordx4 v[2:3], v[18:21], off
	v_add_co_u32_e32 v2, vcc, s70, v66
	s_waitcnt lgkmcnt(0)
	v_mul_f32_e32 v70, 0x3fb8aa3b, v70
	v_addc_co_u32_e32 v3, vcc, 0, v67, vcc
	global_store_dwordx4 v[2:3], v[62:65], off
	v_add_co_u32_e32 v2, vcc, s71, v66
	v_mul_f32_e32 v71, 0x3fb8aa3b, v71
	s_nop 0
	v_addc_co_u32_e32 v3, vcc, 0, v67, vcc
	global_store_dwordx4 v[2:3], v[22:25], off
	v_add_co_u32_e32 v2, vcc, s72, v66
	v_mul_f32_e32 v72, 0x3fb8aa3b, v72
	s_nop 0
	v_addc_co_u32_e32 v3, vcc, 0, v67, vcc
	global_store_dwordx4 v[2:3], v[38:41], off
	v_add_co_u32_e32 v2, vcc, s66, v66
	v_mul_f32_e32 v73, 0x3fb8aa3b, v73
	s_nop 0
	v_addc_co_u32_e32 v3, vcc, 0, v67, vcc
	global_store_dwordx4 v[2:3], v[50:53], off
	v_add_co_u32_e32 v2, vcc, s73, v66
	v_mfma_f32_16x16x32_bf16 v[6:9], v[106:109], v[94:97], v[6:9]
	s_nop 0
	v_addc_co_u32_e32 v3, vcc, 0, v67, vcc
	global_store_dwordx4 v[2:3], v[30:33], off
	v_add_co_u32_e32 v2, vcc, s74, v66
	v_mul_f32_e64 v44, v44, v68
	v_mul_f32_e64 v45, v45, v69
	s_nop 0
	v_addc_co_u32_e32 v3, vcc, 0, v67, vcc
	global_store_dwordx4 v[2:3], v[54:57], off
	v_add_co_u32_e32 v2, vcc, s64, v66
	v_exp_f32_e32 v70, v70
	v_exp_f32_e32 v72, v72
	v_exp_f32_e32 v73, v73
	v_exp_f32_e32 v71, v71
	v_addc_co_u32_e32 v3, vcc, 0, v67, vcc
	global_store_dwordx4 v[2:3], v[42:45], off
	v_add_co_u32_e32 v2, vcc, s75, v66
	v_mfma_f32_16x16x32_bf16 v[10:13], v[106:109], v[98:101], v[10:13]
	v_mul_f32_e64 v48, v48, v68
	v_mul_f32_e64 v49, v49, v69
	v_addc_co_u32_e32 v3, vcc, 0, v67, vcc
	global_store_dwordx4 v[2:3], v[46:49], off
	v_add_co_u32_e32 v2, vcc, 0x1c000, v66
	v_mul_f32_e64 v8, v8, v72
	v_mul_f32_e64 v9, v9, v73
	v_mul_f32_e64 v6, v6, v70
	v_mul_f32_e64 v7, v7, v71
	v_addc_co_u32_e32 v3, vcc, 0, v67, vcc
	global_store_dwordx4 v[2:3], v[6:9], off
	v_add_co_u32_e32 v2, vcc, 0x1e000, v66
	v_mul_f32_e64 v12, v12, v72
	v_mul_f32_e64 v13, v13, v73
	v_mul_f32_e64 v10, v10, v70
	v_mul_f32_e64 v11, v11, v71
	v_addc_co_u32_e32 v3, vcc, 0, v67, vcc
	global_store_dwordx4 v[2:3], v[10:13], off
	s_and_saveexec_b64 s[30:31], s[4:5]
	s_cbranch_execz .LBB0_450
	v_mul_f32_e32 v1, 0x3fb8aa3b, v1
	v_exp_f32_e32 v1, v1
	s_lshl_b64 s[46:47], s[42:43], 9
	v_lshl_add_u64 v[2:3], v[118:119], 0, s[46:47]
	global_store_dword v[2:3], v1, off
	s_branch .LBB0_450

.LBB0_501:
	ds_read_b128 v[160:163], v149 offset:6144
	ds_read_b128 v[164:167], v149 offset:6160
	s_waitcnt vmcnt(6)
	v_lshlrev_b32_e32 v108, 16, v98
	v_and_b32_e32 v109, 0xffff0000, v98
	v_cvt_pk_bf16_f32 v180, v34, v35
	s_waitcnt lgkmcnt(1)
	v_mul_f32_e32 v1, 0xbfb8aa3b, v160
	v_mul_f32_e32 v107, 0xbfb8aa3b, v161
	v_exp_f32_e32 v168, v1
	v_exp_f32_e32 v169, v107
	v_mul_f32_e32 v1, 0xbfb8aa3b, v162
	v_exp_f32_e32 v170, v1
	v_mul_f32_e32 v1, 0xbfb8aa3b, v163
	v_exp_f32_e32 v171, v1
	s_waitcnt lgkmcnt(0)
	v_mul_f32_e32 v1, 0xbfb8aa3b, v164
	v_mul_f32_e64 v108, v168, v108
	v_mul_f32_e64 v109, v169, v109
	v_exp_f32_e32 v168, v1
	v_mul_f32_e32 v1, 0xbfb8aa3b, v165
	v_exp_f32_e32 v169, v1
	v_cvt_pk_bf16_f32 v98, v108, v109
	v_lshlrev_b32_e32 v108, 16, v99
	v_and_b32_e32 v109, 0xffff0000, v99
	v_mul_f32_e64 v108, v170, v108
	v_mul_f32_e64 v109, v171, v109
	v_mul_f32_e32 v1, 0xbfb8aa3b, v166
	v_cvt_pk_bf16_f32 v99, v108, v109
	v_lshlrev_b32_e32 v108, 16, v100
	v_and_b32_e32 v109, 0xffff0000, v100
	v_mul_f32_e64 v108, v168, v108
	v_mul_f32_e64 v109, v169, v109
	v_exp_f32_e32 v168, v1
	v_mul_f32_e32 v1, 0xbfb8aa3b, v167
	v_exp_f32_e32 v169, v1
	v_cvt_pk_bf16_f32 v100, v108, v109
	v_lshlrev_b32_e32 v108, 16, v101
	v_and_b32_e32 v109, 0xffff0000, v101
	v_mul_f32_e64 v108, v168, v108
	v_mul_f32_e64 v109, v169, v109
	v_mul_f32_e32 v1, 0x3fb8aa3b, v160
	v_cvt_pk_bf16_f32 v101, v108, v109
	v_exp_f32_e32 v108, v1
	v_mul_f32_e32 v1, 0x3fb8aa3b, v161
	v_exp_f32_e32 v109, v1
	ds_write_b128 v135, v[98:101] offset:56320
	v_lshlrev_b32_e32 v98, 16, v94
	v_and_b32_e32 v99, 0xffff0000, v94
	v_mul_f32_e64 v100, v108, s40
	v_mul_f32_e64 v101, v109, s40
	v_mul_f32_e32 v1, 0x3fb8aa3b, v162
	v_mul_f32_e64 v98, v100, v98
	v_mul_f32_e64 v99, v101, v99
	v_exp_f32_e32 v100, v1
	v_mul_f32_e32 v1, 0x3fb8aa3b, v163
	v_exp_f32_e32 v101, v1
	v_cvt_pk_bf16_f32 v94, v98, v99
	v_lshlrev_b32_e32 v98, 16, v95
	v_and_b32_e32 v99, 0xffff0000, v95
	v_mul_f32_e64 v100, v100, s40
	v_mul_f32_e64 v101, v101, s40
	v_mul_f32_e32 v1, 0x3fb8aa3b, v164
	v_mul_f32_e64 v98, v100, v98
	v_mul_f32_e64 v99, v101, v99
	v_exp_f32_e32 v100, v1
	v_mul_f32_e32 v1, 0x3fb8aa3b, v165
	v_exp_f32_e32 v101, v1
	v_cvt_pk_bf16_f32 v95, v98, v99
	v_lshlrev_b32_e32 v98, 16, v96
	v_and_b32_e32 v99, 0xffff0000, v96
	v_mul_f32_e64 v100, v100, s40
	v_mul_f32_e64 v101, v101, s40
	v_mul_f32_e32 v1, 0x3fb8aa3b, v166
	v_mul_f32_e64 v98, v100, v98
	v_mul_f32_e64 v99, v101, v99
	v_exp_f32_e32 v100, v1
	v_mul_f32_e32 v1, 0x3fb8aa3b, v167
	v_exp_f32_e32 v101, v1
	v_cvt_pk_bf16_f32 v96, v98, v99
	v_lshlrev_b32_e32 v98, 16, v97
	v_and_b32_e32 v99, 0xffff0000, v97
	v_mul_f32_e64 v100, v100, s40
	v_mul_f32_e64 v101, v101, s40
	s_waitcnt vmcnt(4)
	v_lshlrev_b32_e32 v160, 16, v90
	v_mul_f32_e64 v98, v100, v98
	v_mul_f32_e64 v99, v101, v99
	v_and_b32_e32 v161, 0xffff0000, v90
	v_cvt_pk_bf16_f32 v97, v98, v99
	ds_write_b128 v135, v[94:97] offset:38912
	ds_read_b128 v[94:97], v151 offset:6144
	ds_read_b128 v[98:101], v151 offset:6160
	v_cvt_pk_bf16_f32 v181, v36, v37
	v_cvt_pk_bf16_f32 v182, v30, v31
	v_cvt_pk_bf16_f32 v183, v32, v33
	s_waitcnt lgkmcnt(1)
	v_mul_f32_e32 v1, 0xbfb8aa3b, v94
	v_exp_f32_e32 v108, v1
	v_mul_f32_e32 v1, 0xbfb8aa3b, v95
	v_exp_f32_e32 v109, v1
	v_mul_f32_e32 v1, 0xbfb8aa3b, v96
	v_add_u32_e32 v107, 0xa800, v147
	s_add_u32 s46, s46, 0x60000
	v_mul_f32_e64 v108, v108, v160
	v_mul_f32_e64 v109, v109, v161
	v_exp_f32_e32 v160, v1
	v_mul_f32_e32 v1, 0xbfb8aa3b, v97
	v_exp_f32_e32 v161, v1
	v_cvt_pk_bf16_f32 v90, v108, v109
	v_lshlrev_b32_e32 v108, 16, v91
	v_and_b32_e32 v109, 0xffff0000, v91
	s_waitcnt lgkmcnt(0)
	v_mul_f32_e32 v1, 0xbfb8aa3b, v98
	v_mul_f32_e64 v108, v160, v108
	v_mul_f32_e64 v109, v161, v109
	v_exp_f32_e32 v160, v1
	v_mul_f32_e32 v1, 0xbfb8aa3b, v99
	v_exp_f32_e32 v161, v1
	v_cvt_pk_bf16_f32 v91, v108, v109
	v_lshlrev_b32_e32 v108, 16, v92
	v_and_b32_e32 v109, 0xffff0000, v92
	v_mul_f32_e32 v1, 0xbfb8aa3b, v100
	v_mul_f32_e64 v108, v160, v108
	v_mul_f32_e64 v109, v161, v109
	v_exp_f32_e32 v160, v1
	v_mul_f32_e32 v1, 0xbfb8aa3b, v101
	v_exp_f32_e32 v161, v1
	v_mul_f32_e32 v1, 0x3fb8aa3b, v94
	v_exp_f32_e32 v94, v1
	v_mul_f32_e32 v1, 0x3fb8aa3b, v95
	v_exp_f32_e32 v95, v1
	v_cvt_pk_bf16_f32 v92, v108, v109
	v_lshlrev_b32_e32 v108, 16, v93
	v_and_b32_e32 v109, 0xffff0000, v93
	v_mul_f32_e64 v108, v160, v108
	v_mul_f32_e64 v109, v161, v109
	v_mul_f32_e32 v1, 0x3fb8aa3b, v96
	v_cvt_pk_bf16_f32 v93, v108, v109
	ds_write_b128 v136, v[90:93] offset:56320
	v_lshlrev_b32_e32 v90, 16, v86
	v_and_b32_e32 v91, 0xffff0000, v86
	v_mul_f32_e64 v92, v94, s40
	v_mul_f32_e64 v93, v95, s40
	v_add_u32_e32 v108, 0xb800, v147
	v_mul_f32_e64 v90, v92, v90
	v_mul_f32_e64 v91, v93, v91
	v_exp_f32_e32 v92, v1
	v_mul_f32_e32 v1, 0x3fb8aa3b, v97
	v_exp_f32_e32 v93, v1
	v_cvt_pk_bf16_f32 v86, v90, v91
	v_lshlrev_b32_e32 v90, 16, v87
	v_and_b32_e32 v91, 0xffff0000, v87
	v_mul_f32_e64 v92, v92, s40
	v_mul_f32_e64 v93, v93, s40
	v_mul_f32_e32 v1, 0x3fb8aa3b, v98
	v_mul_f32_e64 v90, v92, v90
	v_mul_f32_e64 v91, v93, v91
	v_exp_f32_e32 v92, v1
	v_mul_f32_e32 v1, 0x3fb8aa3b, v99
	v_exp_f32_e32 v93, v1
	v_cvt_pk_bf16_f32 v87, v90, v91
	v_lshlrev_b32_e32 v90, 16, v88
	v_and_b32_e32 v91, 0xffff0000, v88
	v_mul_f32_e64 v92, v92, s40
	v_mul_f32_e64 v93, v93, s40
	v_mul_f32_e32 v1, 0x3fb8aa3b, v100
	v_mul_f32_e64 v90, v92, v90
	v_mul_f32_e64 v91, v93, v91
	v_exp_f32_e32 v92, v1
	v_mul_f32_e32 v1, 0x3fb8aa3b, v101
	v_exp_f32_e32 v93, v1
	v_cvt_pk_bf16_f32 v88, v90, v91
	v_lshlrev_b32_e32 v90, 16, v89
	v_and_b32_e32 v91, 0xffff0000, v89
	v_mul_f32_e64 v92, v92, s40
	v_mul_f32_e64 v93, v93, s40
	v_add_u32_e32 v109, 0xc800, v147
	v_mul_f32_e64 v90, v92, v90
	v_mul_f32_e64 v91, v93, v91
	s_addc_u32 s47, s47, 0
	v_cvt_pk_bf16_f32 v89, v90, v91
	ds_write_b128 v136, v[86:89] offset:38912
	s_waitcnt vmcnt(3)
	ds_write_b128 v153, v[70:73]
	s_waitcnt vmcnt(2)
	ds_write_b128 v155, v[74:77]
	s_waitcnt vmcnt(1)
	ds_write_b128 v153, v[78:81] offset:16896
	s_waitcnt vmcnt(0)
	ds_write_b128 v156, v[82:85]
	s_waitcnt lgkmcnt(0)
	s_barrier
	ds_read_b128 v[70:73], v142 offset:56320
	ds_read_b128 v[74:77], v142 offset:56384
	ds_read_b128 v[78:81], v134 offset:38912
	ds_read_b128 v[82:85], v134 offset:38976
	ds_read_b128 v[86:89], v142 offset:56448
	s_waitcnt lgkmcnt(2)
	v_mfma_f32_16x16x32_bf16 v[70:73], v[70:73], v[78:81], 0
	s_add_i32 s30, s30, 64
	s_waitcnt lgkmcnt(1)
	v_mfma_f32_16x16x32_bf16 v[70:73], v[74:77], v[82:85], v[70:73]
	ds_read_b128 v[74:77], v142 offset:56512
	ds_read_b128 v[90:93], v134 offset:39040
	ds_read_b128 v[94:97], v134 offset:39104
	s_waitcnt lgkmcnt(1)
	v_mfma_f32_16x16x32_bf16 v[70:73], v[86:89], v[90:93], v[70:73]
	s_waitcnt lgkmcnt(0)
	v_mfma_f32_16x16x32_bf16 v[70:73], v[74:77], v[94:97], v[70:73]
	v_mov_b32_e32 v74, s59
	s_nop 6
	v_cndmask_b32_e64 v1, v70, v74, s[14:15]
	v_cndmask_b32_e64 v1, v1, v70, s[16:17]
	v_cndmask_b32_e64 v70, 0, v71, s[16:17]
	v_cndmask_b32_e64 v71, v72, 0, s[18:19]
	v_cndmask_b32_e64 v72, v73, 0, s[20:21]
	v_cvt_pk_bf16_f32 v70, v1, v70
	v_cvt_pk_bf16_f32 v71, v71, v72
	ds_write_b64 v143, v[70:71]
	ds_read_b128 v[70:73], v144 offset:56320
	ds_read_b128 v[74:77], v144 offset:56384
	s_waitcnt lgkmcnt(1)
	v_mfma_f32_16x16x32_bf16 v[70:73], v[70:73], v[78:81], 0
	ds_read_b128 v[78:81], v144 offset:56448
	s_waitcnt lgkmcnt(1)
	v_mfma_f32_16x16x32_bf16 v[70:73], v[74:77], v[82:85], v[70:73]
	ds_read_b128 v[74:77], v144 offset:56512
	s_waitcnt lgkmcnt(1)
	v_mfma_f32_16x16x32_bf16 v[70:73], v[78:81], v[90:93], v[70:73]
	s_waitcnt lgkmcnt(0)
	v_mfma_f32_16x16x32_bf16 v[70:73], v[74:77], v[94:97], v[70:73]
	v_mov_b32_e32 v74, s59
	s_nop 6
	v_cndmask_b32_e64 v1, v70, v74, s[22:23]
	v_cndmask_b32_e64 v1, v1, v70, s[24:25]
	v_cndmask_b32_e64 v70, 0, v71, s[24:25]
	v_cndmask_b32_e64 v71, v72, 0, s[26:27]
	v_cndmask_b32_e64 v72, v73, 0, s[28:29]
	v_cvt_pk_bf16_f32 v70, v1, v70
	v_cvt_pk_bf16_f32 v71, v71, v72
	ds_write_b64 v145, v[70:71]
	s_waitcnt lgkmcnt(0)
	s_barrier
	ds_read_b64_tr_b16 v[76:77], v157 offset:2112
	ds_read_b64_tr_b16 v[74:75], v157
	ds_read_b64_tr_b16 v[80:81], v157 offset:2144
	ds_read_b64_tr_b16 v[78:79], v157 offset:32
	ds_read_b128 v[70:73], v146
	ds_read_b128 v[86:89], v146 offset:64
	s_waitcnt lgkmcnt(1)
	v_mfma_f32_16x16x32_bf16 v[90:93], v[74:77], v[70:73], 0
	ds_read_b64_tr_b16 v[82:83], v157 offset:16896
	ds_read_b64_tr_b16 v[84:85], v157 offset:19008
	v_add_u32_e32 v1, 0x9800, v147
	v_mfma_f32_16x16x32_bf16 v[94:97], v[78:81], v[70:73], 0
	ds_read_b64_tr_b16 v[72:73], v157 offset:19040
	ds_read_b64_tr_b16 v[70:71], v157 offset:16928
	s_waitcnt lgkmcnt(2)
	v_mfma_f32_16x16x32_bf16 v[90:93], v[82:85], v[86:89], v[90:93]
	s_waitcnt lgkmcnt(0)
	v_mfma_f32_16x16x32_bf16 v[86:89], v[70:73], v[86:89], v[94:97]
	s_nop 2
	ds_read_b128 v[94:97], v146 offset:2304
	ds_read_b128 v[98:101], v146 offset:2368
	s_waitcnt lgkmcnt(1)
	v_mfma_f32_16x16x32_bf16 v[160:163], v[74:77], v[94:97], 0
	v_mfma_f32_16x16x32_bf16 v[94:97], v[78:81], v[94:97], 0
	s_waitcnt lgkmcnt(0)
	v_mfma_f32_16x16x32_bf16 v[160:163], v[82:85], v[98:101], v[160:163]
	v_mfma_f32_16x16x32_bf16 v[94:97], v[70:73], v[98:101], v[94:97]
	ds_read_b128 v[98:101], v146 offset:4608
	ds_read_b128 v[164:167], v146 offset:4672
	s_waitcnt lgkmcnt(1)
	v_mfma_f32_16x16x32_bf16 v[168:171], v[74:77], v[98:101], 0
	v_mfma_f32_16x16x32_bf16 v[98:101], v[78:81], v[98:101], 0
	s_waitcnt lgkmcnt(0)
	v_mfma_f32_16x16x32_bf16 v[168:171], v[82:85], v[164:167], v[168:171]
	v_mfma_f32_16x16x32_bf16 v[98:101], v[70:73], v[164:167], v[98:101]
	ds_read_b128 v[164:167], v146 offset:6912
	ds_read_b128 v[172:175], v146 offset:6976
	ds_read2_b64 v[184:187], v1 offset1:4
	ds_read2_b64 v[188:191], v1 offset0:8 offset1:12
	s_waitcnt lgkmcnt(3)
	v_mfma_f32_16x16x32_bf16 v[176:179], v[74:77], v[164:167], 0
	v_mfma_f32_16x16x32_bf16 v[164:167], v[78:81], v[164:167], 0
	s_waitcnt lgkmcnt(2)
	v_mfma_f32_16x16x32_bf16 v[176:179], v[82:85], v[172:175], v[176:179]
	v_mfma_f32_16x16x32_bf16 v[164:167], v[70:73], v[172:175], v[164:167]
	v_cvt_pk_bf16_f32 v172, v14, v15
	v_cvt_pk_bf16_f32 v173, v16, v17
	v_cvt_pk_bf16_f32 v174, v58, v59
	v_cvt_pk_bf16_f32 v175, v60, v61
	s_waitcnt lgkmcnt(1)
	v_mfma_f32_16x16x32_bf16 v[90:93], v[180:183], v[184:187], v[90:93]
	v_mfma_f32_16x16x32_bf16 v[86:89], v[172:175], v[184:187], v[86:89]
	ds_read2_b64 v[184:187], v107 offset0:32 offset1:36
	s_waitcnt lgkmcnt(0)
	v_mfma_f32_16x16x32_bf16 v[160:163], v[180:183], v[184:187], v[160:163]
	v_mfma_f32_16x16x32_bf16 v[94:97], v[172:175], v[184:187], v[94:97]
	ds_read2_b64 v[184:187], v108 offset0:64 offset1:68
	s_waitcnt lgkmcnt(0)
	v_mfma_f32_16x16x32_bf16 v[168:171], v[180:183], v[184:187], v[168:171]
	v_mfma_f32_16x16x32_bf16 v[98:101], v[172:175], v[184:187], v[98:101]
	ds_read2_b64 v[184:187], v109 offset0:96 offset1:100
	s_waitcnt lgkmcnt(0)
	v_mfma_f32_16x16x32_bf16 v[176:179], v[180:183], v[184:187], v[176:179]
	v_cvt_pk_bf16_f32 v180, v54, v55
	v_cvt_pk_bf16_f32 v181, v56, v57
	v_cvt_pk_bf16_f32 v182, v62, v63
	v_cvt_pk_bf16_f32 v183, v64, v65
	v_mfma_f32_16x16x32_bf16 v[164:167], v[172:175], v[184:187], v[164:167]
	v_cvt_pk_bf16_f32 v172, v46, v47
	v_cvt_pk_bf16_f32 v173, v48, v49
	v_cvt_pk_bf16_f32 v174, v66, v67
	v_cvt_pk_bf16_f32 v175, v68, v69
	ds_read2_b64 v[184:187], v107 offset0:40 offset1:44
	s_waitcnt lgkmcnt(0)
	v_mfma_f32_16x16x32_bf16 v[160:163], v[180:183], v[184:187], v[160:163]
	v_mfma_f32_16x16x32_bf16 v[94:97], v[172:175], v[184:187], v[94:97]
	ds_read2_b64 v[184:187], v108 offset0:72 offset1:76
	s_waitcnt lgkmcnt(0)
	v_mfma_f32_16x16x32_bf16 v[168:171], v[180:183], v[184:187], v[168:171]
	v_mfma_f32_16x16x32_bf16 v[98:101], v[172:175], v[184:187], v[98:101]
	ds_read2_b64 v[184:187], v109 offset0:104 offset1:108
	v_mfma_f32_16x16x32_bf16 v[90:93], v[180:183], v[188:191], v[90:93]
	v_mfma_f32_16x16x32_bf16 v[86:89], v[172:175], v[188:191], v[86:89]
	ds_read2_b64 v[188:191], v1 offset0:16 offset1:20
	s_waitcnt lgkmcnt(1)
	v_mfma_f32_16x16x32_bf16 v[176:179], v[180:183], v[184:187], v[176:179]
	v_cvt_pk_bf16_f32 v180, v22, v23
	v_cvt_pk_bf16_f32 v181, v24, v25
	v_cvt_pk_bf16_f32 v182, v18, v19
	v_cvt_pk_bf16_f32 v183, v20, v21
	v_mfma_f32_16x16x32_bf16 v[164:167], v[172:175], v[184:187], v[164:167]
	v_cvt_pk_bf16_f32 v172, v10, v11
	v_cvt_pk_bf16_f32 v173, v12, v13
	v_cvt_pk_bf16_f32 v174, v50, v51
	v_cvt_pk_bf16_f32 v175, v52, v53
	ds_read2_b64 v[184:187], v107 offset0:48 offset1:52
	s_waitcnt lgkmcnt(0)
	v_mfma_f32_16x16x32_bf16 v[160:163], v[180:183], v[184:187], v[160:163]
	v_mfma_f32_16x16x32_bf16 v[94:97], v[172:175], v[184:187], v[94:97]
	ds_read2_b64 v[184:187], v108 offset0:80 offset1:84
	s_waitcnt lgkmcnt(0)
	v_mfma_f32_16x16x32_bf16 v[168:171], v[180:183], v[184:187], v[168:171]
	v_mfma_f32_16x16x32_bf16 v[98:101], v[172:175], v[184:187], v[98:101]
	ds_read2_b64 v[184:187], v109 offset0:112 offset1:116
	v_mfma_f32_16x16x32_bf16 v[90:93], v[180:183], v[188:191], v[90:93]
	v_mfma_f32_16x16x32_bf16 v[86:89], v[172:175], v[188:191], v[86:89]
	ds_read2_b64 v[188:191], v1 offset0:24 offset1:28
	v_lshl_add_u32 v1, s79, 9, v128
	s_waitcnt lgkmcnt(1)
	v_mfma_f32_16x16x32_bf16 v[176:179], v[180:183], v[184:187], v[176:179]
	v_cvt_pk_bf16_f32 v180, v38, v39
	v_cvt_pk_bf16_f32 v181, v40, v41
	v_cvt_pk_bf16_f32 v182, v26, v27
	v_cvt_pk_bf16_f32 v183, v28, v29
	v_mfma_f32_16x16x32_bf16 v[164:167], v[172:175], v[184:187], v[164:167]
	v_cvt_pk_bf16_f32 v172, v42, v43
	v_cvt_pk_bf16_f32 v173, v44, v45
	v_cvt_pk_bf16_f32 v174, v6, v7
	v_cvt_pk_bf16_f32 v175, v8, v9
	ds_read2_b64 v[184:187], v107 offset0:56 offset1:60
	s_waitcnt lgkmcnt(0)
	v_mfma_f32_16x16x32_bf16 v[160:163], v[180:183], v[184:187], v[160:163]
	v_mfma_f32_16x16x32_bf16 v[94:97], v[172:175], v[184:187], v[94:97]
	ds_read2_b64 v[184:187], v108 offset0:88 offset1:92
	s_waitcnt lgkmcnt(0)
	v_mfma_f32_16x16x32_bf16 v[168:171], v[180:183], v[184:187], v[168:171]
	v_mfma_f32_16x16x32_bf16 v[98:101], v[172:175], v[184:187], v[98:101]
	ds_read2_b64 v[184:187], v109 offset0:120 offset1:124
	v_mfma_f32_16x16x32_bf16 v[90:93], v[180:183], v[188:191], v[90:93]
	s_waitcnt lgkmcnt(0)
	v_mfma_f32_16x16x32_bf16 v[176:179], v[180:183], v[184:187], v[176:179]
	ds_read_b64_tr_b16 v[182:183], v158 offset:57408
	ds_read_b64_tr_b16 v[180:181], v158 offset:56320
	s_nop 3
	v_cvt_pk_bf16_f32 v90, v90, v91
	v_cvt_pk_bf16_f32 v91, v92, v93
	v_mfma_f32_16x16x32_bf16 v[86:89], v[172:175], v[188:191], v[86:89]
	v_lshl_add_u64 v[92:93], s[44:45], 0, v[116:117]
	s_add_u32 s44, s44, 0x20000
	s_addc_u32 s45, s45, 0
	v_mfma_f32_16x16x32_bf16 v[164:167], v[172:175], v[184:187], v[164:167]
	ds_read_b64_tr_b16 v[172:173], v158 offset:56352
	ds_read_b64_tr_b16 v[184:185], v158 offset:56384
	ds_read_b64_tr_b16 v[188:189], v158 offset:56416
	ds_read_b64_tr_b16 v[174:175], v158 offset:57440
	ds_read_b64_tr_b16 v[186:187], v158 offset:57472
	ds_read_b64_tr_b16 v[190:191], v158 offset:57504
	ds_read_b64_tr_b16 v[192:193], v158 offset:65024
	ds_read_b64_tr_b16 v[194:195], v159 offset:57408
	v_cvt_pk_bf16_f32 v86, v86, v87
	s_waitcnt lgkmcnt(4)
	v_mfma_f32_16x16x32_bf16 v[30:33], v[172:175], v[74:77], v[30:33]
	v_cvt_pk_bf16_f32 v87, v88, v89
	v_add_co_u32_e32 v88, vcc, s62, v92
	v_mfma_f32_16x16x32_bf16 v[58:61], v[172:175], v[78:81], v[58:61]
	s_nop 0
	v_addc_co_u32_e32 v89, vcc, 0, v93, vcc
	s_add_i32 s78, s78, 1
	v_mfma_f32_16x16x32_bf16 v[34:37], v[180:183], v[74:77], v[34:37]
	s_cmp_lg_u32 s46, 0x180000
	v_mfma_f32_16x16x32_bf16 v[14:17], v[180:183], v[78:81], v[14:17]
	ds_read_b64_tr_b16 v[180:181], v158 offset:65056
	ds_read_b64_tr_b16 v[196:197], v158 offset:65088
	ds_read_b64_tr_b16 v[200:201], v158 offset:65120
	ds_read_b64_tr_b16 v[182:183], v159 offset:57440
	ds_read_b64_tr_b16 v[198:199], v159 offset:57472
	ds_read_b64_tr_b16 v[202:203], v159 offset:57504
	ds_read_b64_tr_b16 v[172:173], v158 offset:56448
	ds_read_b64_tr_b16 v[174:175], v158 offset:57536
	s_waitcnt lgkmcnt(4)
	v_mfma_f32_16x16x32_bf16 v[30:33], v[180:183], v[82:85], v[30:33]
	v_mfma_f32_16x16x32_bf16 v[58:61], v[180:183], v[70:73], v[58:61]
	v_mfma_f32_16x16x32_bf16 v[54:57], v[184:187], v[74:77], v[54:57]
	v_mfma_f32_16x16x32_bf16 v[46:49], v[184:187], v[78:81], v[46:49]
	v_mfma_f32_16x16x32_bf16 v[62:65], v[188:191], v[74:77], v[62:65]
	v_mfma_f32_16x16x32_bf16 v[66:69], v[188:191], v[78:81], v[66:69]
	ds_read_b64_tr_b16 v[180:181], v158 offset:56480
	ds_read_b64_tr_b16 v[184:185], v158 offset:56512
	ds_read_b64_tr_b16 v[188:189], v158 offset:56544
	ds_read_b64_tr_b16 v[182:183], v158 offset:57568
	ds_read_b64_tr_b16 v[186:187], v158 offset:57600
	ds_read_b64_tr_b16 v[190:191], v158 offset:57632
	v_mfma_f32_16x16x32_bf16 v[34:37], v[192:195], v[82:85], v[34:37]
	v_mfma_f32_16x16x32_bf16 v[14:17], v[192:195], v[70:73], v[14:17]
	ds_read_b64_tr_b16 v[192:193], v158 offset:65152
	ds_read_b64_tr_b16 v[194:195], v159 offset:57536
	s_waitcnt lgkmcnt(11)
	v_mfma_f32_16x16x32_bf16 v[54:57], v[196:199], v[82:85], v[54:57]
	v_mfma_f32_16x16x32_bf16 v[46:49], v[196:199], v[70:73], v[46:49]
	s_waitcnt lgkmcnt(10)
	v_mfma_f32_16x16x32_bf16 v[62:65], v[200:203], v[82:85], v[62:65]
	v_mfma_f32_16x16x32_bf16 v[66:69], v[200:203], v[70:73], v[66:69]
	s_waitcnt lgkmcnt(8)
	v_mfma_f32_16x16x32_bf16 v[22:25], v[172:175], v[74:77], v[22:25]
	v_mfma_f32_16x16x32_bf16 v[10:13], v[172:175], v[78:81], v[10:13]
	ds_read_b64_tr_b16 v[172:173], v158 offset:65184
	ds_read_b64_tr_b16 v[196:197], v158 offset:65216
	ds_read_b64_tr_b16 v[200:201], v158 offset:65248
	ds_read_b64_tr_b16 v[174:175], v159 offset:57568
	ds_read_b64_tr_b16 v[198:199], v159 offset:57600
	ds_read_b64_tr_b16 v[202:203], v159 offset:57632
	global_store_dwordx2 v[92:93], v[86:87], off offset:32
	v_cvt_pk_bf16_f32 v86, v160, v161
	s_waitcnt lgkmcnt(10)
	v_mfma_f32_16x16x32_bf16 v[18:21], v[180:183], v[74:77], v[18:21]
	v_cvt_pk_bf16_f32 v87, v162, v163
	global_store_dwordx2 v[88:89], v[86:87], off
	v_cvt_pk_bf16_f32 v86, v94, v95
	v_mfma_f32_16x16x32_bf16 v[50:53], v[180:183], v[78:81], v[50:53]
	v_cvt_pk_bf16_f32 v87, v96, v97
	global_store_dwordx2 v[88:89], v[86:87], off offset:32
	v_add_co_u32_e32 v88, vcc, s72, v92
	s_waitcnt lgkmcnt(9)
	v_mfma_f32_16x16x32_bf16 v[38:41], v[184:187], v[74:77], v[38:41]
	v_cvt_pk_bf16_f32 v86, v168, v169
	v_cvt_pk_bf16_f32 v87, v170, v171
	v_addc_co_u32_e32 v89, vcc, 0, v93, vcc
	v_mfma_f32_16x16x32_bf16 v[42:45], v[184:187], v[78:81], v[42:45]
	global_store_dwordx2 v[88:89], v[86:87], off
	v_cvt_pk_bf16_f32 v86, v98, v99
	v_cvt_pk_bf16_f32 v87, v100, v101
	s_waitcnt lgkmcnt(8)
	v_mfma_f32_16x16x32_bf16 v[26:29], v[188:191], v[74:77], v[26:29]
	ds_read_b128 v[74:77], v1 offset:4096
	global_store_dwordx2 v[88:89], v[86:87], off offset:32
	v_add_co_u32_e32 v88, vcc, s64, v92
	v_mfma_f32_16x16x32_bf16 v[6:9], v[188:191], v[78:81], v[6:9]
	ds_read_b128 v[78:81], v1 offset:4160
	s_waitcnt lgkmcnt(1)
	v_mul_f32_e32 v74, 0x3fb8aa3b, v74
	v_mul_f32_e32 v75, 0x3fb8aa3b, v75
	v_mfma_f32_16x16x32_bf16 v[10:13], v[192:195], v[70:73], v[10:13]
	v_mul_f32_e32 v76, 0x3fb8aa3b, v76
	v_mul_f32_e32 v77, 0x3fb8aa3b, v77
	v_exp_f32_e32 v74, v74
	v_mfma_f32_16x16x32_bf16 v[50:53], v[172:175], v[70:73], v[50:53]
	v_exp_f32_e32 v76, v76
	v_exp_f32_e32 v77, v77
	v_exp_f32_e32 v75, v75
	v_mfma_f32_16x16x32_bf16 v[42:45], v[196:199], v[70:73], v[42:45]
	v_cvt_pk_bf16_f32 v86, v176, v177
	v_mul_f32_e64 v36, v36, v76
	v_mul_f32_e64 v37, v37, v77
	v_mul_f32_e64 v34, v34, v74
	v_mul_f32_e64 v35, v35, v75
	v_mfma_f32_16x16x32_bf16 v[6:9], v[200:203], v[70:73], v[6:9]
	s_waitcnt lgkmcnt(0)
	v_mul_f32_e32 v70, 0x3fb8aa3b, v78
	v_mul_f32_e32 v71, 0x3fb8aa3b, v80
	v_exp_f32_e32 v78, v70
	v_mul_f32_e32 v70, 0x3fb8aa3b, v79
	v_exp_f32_e32 v80, v71
	v_mul_f32_e32 v71, 0x3fb8aa3b, v81
	v_exp_f32_e32 v81, v71
	v_exp_f32_e32 v79, v70
	ds_read_b128 v[70:73], v1 offset:4224
	v_mul_f32_e64 v16, v16, v76
	v_mul_f32_e64 v17, v17, v77
	v_mul_f32_e64 v14, v14, v74
	v_mul_f32_e64 v15, v15, v75
	ds_read_b128 v[74:77], v1 offset:4288
	v_mfma_f32_16x16x32_bf16 v[22:25], v[192:195], v[82:85], v[22:25]
	s_waitcnt lgkmcnt(1)
	v_mul_f32_e32 v70, 0x3fb8aa3b, v70
	v_mul_f32_e64 v32, v32, v80
	v_mul_f32_e64 v33, v33, v81
	v_mul_f32_e64 v30, v30, v78
	v_mul_f32_e64 v31, v31, v79
	v_mfma_f32_16x16x32_bf16 v[18:21], v[172:175], v[82:85], v[18:21]
	v_mul_f32_e64 v60, v60, v80
	v_mul_f32_e64 v61, v61, v81
	v_mul_f32_e64 v58, v58, v78
	v_mul_f32_e64 v59, v59, v79
	v_cvt_pk_bf16_f32 v87, v178, v179
	v_mfma_f32_16x16x32_bf16 v[38:41], v[196:199], v[82:85], v[38:41]
	v_addc_co_u32_e32 v89, vcc, 0, v93, vcc
	global_store_dwordx2 v[88:89], v[86:87], off
	v_mfma_f32_16x16x32_bf16 v[26:29], v[200:203], v[82:85], v[26:29]
	v_exp_f32_e32 v82, v70
	v_mul_f32_e32 v83, 0x3fb8aa3b, v71
	v_mul_f32_e32 v70, 0x3fb8aa3b, v72
	v_mul_f32_e32 v71, 0x3fb8aa3b, v73
	v_exp_f32_e32 v70, v70
	v_exp_f32_e32 v71, v71
	v_exp_f32_e32 v83, v83
	v_cvt_pk_bf16_f32 v86, v164, v165
	v_cvt_pk_bf16_f32 v87, v166, v167
	v_mul_f32_e64 v56, v56, v70
	v_mul_f32_e64 v57, v57, v71
	v_mul_f32_e64 v48, v48, v70
	v_mul_f32_e64 v49, v49, v71
	s_waitcnt lgkmcnt(0)
	v_mul_f32_e32 v70, 0x3fb8aa3b, v74
	v_mul_f32_e32 v71, 0x3fb8aa3b, v76
	v_exp_f32_e32 v78, v70
	v_mul_f32_e32 v70, 0x3fb8aa3b, v75
	v_exp_f32_e32 v80, v71
	v_mul_f32_e32 v71, 0x3fb8aa3b, v77
	v_exp_f32_e32 v81, v71
	v_exp_f32_e32 v79, v70
	ds_read_b128 v[70:73], v1 offset:4352
	ds_read_b128 v[74:77], v1 offset:4416
	v_mul_f32_e64 v54, v54, v82
	v_mul_f32_e64 v55, v55, v83
	v_mul_f32_e64 v46, v46, v82
	v_mul_f32_e64 v47, v47, v83
	v_mul_f32_e64 v64, v64, v80
	v_mul_f32_e64 v65, v65, v81
	s_waitcnt lgkmcnt(1)
	v_mul_f32_e32 v70, 0x3fb8aa3b, v70
	v_exp_f32_e32 v82, v70
	v_mul_f32_e32 v83, 0x3fb8aa3b, v71
	v_mul_f32_e32 v70, 0x3fb8aa3b, v72
	v_mul_f32_e32 v71, 0x3fb8aa3b, v73
	v_exp_f32_e32 v70, v70
	v_exp_f32_e32 v71, v71
	v_mul_f32_e64 v62, v62, v78
	v_mul_f32_e64 v63, v63, v79
	v_mul_f32_e64 v68, v68, v80
	v_mul_f32_e64 v69, v69, v81
	v_mul_f32_e64 v66, v66, v78
	v_mul_f32_e64 v67, v67, v79
	v_mul_f32_e64 v24, v24, v70
	v_mul_f32_e64 v25, v25, v71
	v_mul_f32_e64 v12, v12, v70
	v_mul_f32_e64 v13, v13, v71
	s_waitcnt lgkmcnt(0)
	v_mul_f32_e32 v70, 0x3fb8aa3b, v74
	v_mul_f32_e32 v71, 0x3fb8aa3b, v76
	v_exp_f32_e32 v78, v70
	v_mul_f32_e32 v70, 0x3fb8aa3b, v75
	v_exp_f32_e32 v80, v71
	v_mul_f32_e32 v71, 0x3fb8aa3b, v77
	v_exp_f32_e32 v81, v71
	v_exp_f32_e32 v79, v70
	ds_read_b128 v[70:73], v1 offset:4480
	ds_read_b128 v[74:77], v1 offset:4544
	v_exp_f32_e32 v83, v83
	v_mul_f32_e64 v20, v20, v80
	v_mul_f32_e64 v21, v21, v81
	v_mul_f32_e64 v18, v18, v78
	v_mul_f32_e64 v19, v19, v79
	s_waitcnt lgkmcnt(1)
	v_mul_f32_e32 v1, 0x3fb8aa3b, v70
	v_exp_f32_e32 v70, v1
	v_mul_f32_e32 v1, 0x3fb8aa3b, v71
	v_mul_f32_e32 v71, 0x3fb8aa3b, v72
	v_exp_f32_e32 v72, v71
	v_mul_f32_e32 v71, 0x3fb8aa3b, v73
	v_exp_f32_e32 v73, v71
	v_exp_f32_e32 v71, v1
	s_waitcnt lgkmcnt(0)
	v_mul_f32_e32 v1, 0x3fb8aa3b, v74
	v_exp_f32_e32 v74, v1
	v_mul_f32_e32 v1, 0x3fb8aa3b, v75
	v_mul_f32_e32 v75, 0x3fb8aa3b, v76
	v_exp_f32_e32 v76, v75
	v_mul_f32_e32 v75, 0x3fb8aa3b, v77
	v_exp_f32_e32 v77, v75
	v_exp_f32_e32 v75, v1
	v_mul_f32_e64 v22, v22, v82
	v_mul_f32_e64 v23, v23, v83
	v_mul_f32_e64 v10, v10, v82
	v_mul_f32_e64 v11, v11, v83
	v_mul_f32_e64 v52, v52, v80
	v_mul_f32_e64 v53, v53, v81
	v_mul_f32_e64 v50, v50, v78
	v_mul_f32_e64 v51, v51, v79
	v_mul_f32_e64 v40, v40, v72
	v_mul_f32_e64 v41, v41, v73
	v_mul_f32_e64 v38, v38, v70
	v_mul_f32_e64 v39, v39, v71
	v_mul_f32_e64 v44, v44, v72
	v_mul_f32_e64 v45, v45, v73
	v_mul_f32_e64 v42, v42, v70
	v_mul_f32_e64 v43, v43, v71
	v_mul_f32_e64 v28, v28, v76
	v_mul_f32_e64 v29, v29, v77
	v_mul_f32_e64 v26, v26, v74
	v_mul_f32_e64 v27, v27, v75
	v_mul_f32_e64 v8, v8, v76
	v_mul_f32_e64 v9, v9, v77
	v_mul_f32_e64 v6, v6, v74
	v_mul_f32_e64 v7, v7, v75
	global_store_dwordx2 v[92:93], v[90:91], off
	global_store_dwordx2 v[88:89], v[86:87], off offset:32
	s_cbranch_scc0 .LBB0_451

.LBB0_569:
	v_ashrrev_i32_e32 v3, 9, v2
	v_and_b32_e32 v4, -16, v3
	v_ashrrev_i32_e32 v5, 31, v4
	v_and_b32_e32 v0, 0x1fff, v2
	v_lshlrev_b64 v[6:7], 17, v[4:5]
	v_lshlrev_b32_e32 v0, 4, v0
	v_lshl_add_u64 v[6:7], s[6:7], 0, v[6:7]
	v_lshrrev_b32_e32 v10, 4, v2
	v_lshlrev_b64 v[4:5], 9, v[4:5]
	v_lshl_add_u64 v[20:21], v[6:7], 0, v[0:1]
	v_lshl_add_u64 v[8:9], s[8:9], 0, v[4:5]
	v_and_b32_e32 v0, 0x1c0, v10
	v_add_co_u32_e32 v22, vcc, 0x20000, v20
	v_lshl_add_u64 v[8:9], v[8:9], 0, v[0:1]
	v_and_b32_e32 v0, 48, v2
	v_addc_co_u32_e32 v23, vcc, 0, v21, vcc
	global_load_dwordx4 v[4:7], v[20:21], off
	v_lshl_add_u64 v[24:25], v[8:9], 0, v[0:1]
	global_load_dwordx4 v[8:11], v[22:23], off
	global_load_dwordx4 v[12:15], v[24:25], off offset:512
	v_add_co_u32_e32 v26, vcc, s12, v20
	v_add_u32_e32 v2, s13, v2
	s_nop 0
	v_addc_co_u32_e32 v27, vcc, 0, v21, vcc
	global_load_dwordx4 v[16:19], v[26:27], off
	s_waitcnt vmcnt(0)
	v_fma_f32 v6, v6, v14, v10
	v_fma_f32 v7, v7, v15, v11
	v_fma_f32 v4, v4, v12, v8
	v_fma_f32 v5, v5, v13, v9
	global_store_dwordx4 v[22:23], v[4:7], off
	global_load_dwordx4 v[8:11], v[24:25], off offset:1024
	v_add_co_u32_e32 v22, vcc, 0x60000, v20
	s_nop 1
	v_addc_co_u32_e32 v23, vcc, 0, v21, vcc
	global_load_dwordx4 v[12:15], v[22:23], off
	s_waitcnt vmcnt(1)
	v_fma_f32 v6, v6, v10, v18
	v_fma_f32 v7, v7, v11, v19
	v_fma_f32 v4, v4, v8, v16
	v_fma_f32 v5, v5, v9, v17
	global_store_dwordx4 v[26:27], v[4:7], off
	global_load_dwordx4 v[8:11], v[24:25], off offset:1536
	v_add_co_u32_e32 v26, vcc, 0x80000, v20
	s_nop 1
	v_addc_co_u32_e32 v27, vcc, 0, v21, vcc
	global_load_dwordx4 v[16:19], v[26:27], off
	s_waitcnt vmcnt(1)
	v_fma_f32 v6, v6, v10, v14
	v_fma_f32 v7, v7, v11, v15
	v_fma_f32 v4, v4, v8, v12
	v_fma_f32 v5, v5, v9, v13
	global_store_dwordx4 v[22:23], v[4:7], off
	global_load_dwordx4 v[8:11], v[24:25], off offset:2048
	v_add_co_u32_e32 v22, vcc, 0xa0000, v20
	s_nop 1
	v_addc_co_u32_e32 v23, vcc, 0, v21, vcc
	global_load_dwordx4 v[12:15], v[22:23], off
	s_waitcnt vmcnt(1)
	v_fma_f32 v6, v6, v10, v18
	v_fma_f32 v7, v7, v11, v19
	v_fma_f32 v4, v4, v8, v16
	v_fma_f32 v5, v5, v9, v17
	global_store_dwordx4 v[26:27], v[4:7], off
	global_load_dwordx4 v[8:11], v[24:25], off offset:2560
	v_add_co_u32_e32 v26, vcc, 0xc0000, v20
	s_nop 1
	v_addc_co_u32_e32 v27, vcc, 0, v21, vcc
	global_load_dwordx4 v[16:19], v[26:27], off
	s_waitcnt vmcnt(1)
	v_fma_f32 v6, v6, v10, v14
	v_fma_f32 v7, v7, v11, v15
	v_fma_f32 v4, v4, v8, v12
	v_fma_f32 v5, v5, v9, v13
	global_store_dwordx4 v[22:23], v[4:7], off
	global_load_dwordx4 v[8:11], v[24:25], off offset:3072
	v_add_co_u32_e32 v22, vcc, 0xe0000, v20
	s_nop 1
	v_addc_co_u32_e32 v23, vcc, 0, v21, vcc
	global_load_dwordx4 v[12:15], v[22:23], off
	s_waitcnt vmcnt(1)
	v_fma_f32 v6, v6, v10, v18
	v_fma_f32 v7, v7, v11, v19
	v_fma_f32 v4, v4, v8, v16
	v_fma_f32 v5, v5, v9, v17
	global_store_dwordx4 v[26:27], v[4:7], off
	global_load_dwordx4 v[8:11], v[24:25], off offset:3584
	v_add_co_u32_e32 v24, vcc, s14, v24
	s_waitcnt vmcnt(0)
	v_fma_f32 v6, v6, v10, v14
	v_fma_f32 v7, v7, v11, v15
	v_addc_co_u32_e32 v25, vcc, 0, v25, vcc
	v_add_co_u32_e32 v26, vcc, 0x100000, v20
	v_fma_f32 v4, v4, v8, v12
	v_fma_f32 v5, v5, v9, v13
	s_nop 0
	v_addc_co_u32_e32 v27, vcc, 0, v21, vcc
	global_store_dwordx4 v[22:23], v[4:7], off
	global_load_dwordx4 v[16:19], v[26:27], off
	global_load_dwordx4 v[8:11], v[24:25], off
	v_add_co_u32_e32 v22, vcc, 0x120000, v20
	s_nop 1
	v_addc_co_u32_e32 v23, vcc, 0, v21, vcc
	global_load_dwordx4 v[12:15], v[22:23], off
	s_waitcnt vmcnt(1)
	v_fma_f32 v6, v6, v10, v18
	v_fma_f32 v7, v7, v11, v19
	v_fma_f32 v4, v4, v8, v16
	v_fma_f32 v5, v5, v9, v17
	global_store_dwordx4 v[26:27], v[4:7], off
	global_load_dwordx4 v[8:11], v[24:25], off offset:512
	v_add_co_u32_e32 v26, vcc, 0x140000, v20
	s_nop 1
	v_addc_co_u32_e32 v27, vcc, 0, v21, vcc
	global_load_dwordx4 v[16:19], v[26:27], off
	s_waitcnt vmcnt(1)
	v_fma_f32 v6, v6, v10, v14
	v_fma_f32 v7, v7, v11, v15
	v_fma_f32 v4, v4, v8, v12
	v_fma_f32 v5, v5, v9, v13
	global_store_dwordx4 v[22:23], v[4:7], off
	global_load_dwordx4 v[8:11], v[24:25], off offset:1024
	v_add_co_u32_e32 v22, vcc, 0x160000, v20
	s_nop 1
	v_addc_co_u32_e32 v23, vcc, 0, v21, vcc
	global_load_dwordx4 v[12:15], v[22:23], off
	s_waitcnt vmcnt(1)
	v_fma_f32 v6, v6, v10, v18
	v_fma_f32 v7, v7, v11, v19
	v_fma_f32 v4, v4, v8, v16
	v_fma_f32 v5, v5, v9, v17
	global_store_dwordx4 v[26:27], v[4:7], off
	global_load_dwordx4 v[8:11], v[24:25], off offset:1536
	v_add_co_u32_e32 v26, vcc, 0x180000, v20
	s_nop 1
	v_addc_co_u32_e32 v27, vcc, 0, v21, vcc
	global_load_dwordx4 v[16:19], v[26:27], off
	s_waitcnt vmcnt(1)
	v_fma_f32 v6, v6, v10, v14
	v_fma_f32 v7, v7, v11, v15
	v_fma_f32 v4, v4, v8, v12
	v_fma_f32 v5, v5, v9, v13
	global_store_dwordx4 v[22:23], v[4:7], off
	global_load_dwordx4 v[8:11], v[24:25], off offset:2048
	v_add_co_u32_e32 v22, vcc, 0x1a0000, v20
	s_nop 1
	v_addc_co_u32_e32 v23, vcc, 0, v21, vcc
	global_load_dwordx4 v[12:15], v[22:23], off
	s_waitcnt vmcnt(1)
	v_fma_f32 v6, v6, v10, v18
	v_fma_f32 v7, v7, v11, v19
	v_fma_f32 v4, v4, v8, v16
	v_fma_f32 v5, v5, v9, v17
	global_store_dwordx4 v[26:27], v[4:7], off
	global_load_dwordx4 v[8:11], v[24:25], off offset:2560
	v_add_co_u32_e32 v26, vcc, 0x1c0000, v20
	s_nop 1
	v_addc_co_u32_e32 v27, vcc, 0, v21, vcc
	global_load_dwordx4 v[16:19], v[26:27], off
	v_add_co_u32_e32 v20, vcc, 0x1e0000, v20
	s_waitcnt vmcnt(1)
	v_fma_f32 v6, v6, v10, v14
	v_fma_f32 v7, v7, v11, v15
	v_fma_f32 v4, v4, v8, v12
	v_fma_f32 v5, v5, v9, v13
	global_store_dwordx4 v[22:23], v[4:7], off
	global_load_dwordx4 v[8:11], v[24:25], off offset:3072
	v_addc_co_u32_e32 v21, vcc, 0, v21, vcc
	global_load_dwordx4 v[12:15], v[20:21], off
	v_cmp_lt_i32_e32 vcc, s15, v2
	s_or_b64 s[10:11], vcc, s[10:11]
	s_waitcnt vmcnt(1)
	v_fma_f32 v6, v6, v10, v18
	v_fma_f32 v7, v7, v11, v19
	v_fma_f32 v4, v4, v8, v16
	v_fma_f32 v5, v5, v9, v17
	global_store_dwordx4 v[26:27], v[4:7], off
	global_load_dwordx4 v[8:11], v[24:25], off offset:3584
	s_waitcnt vmcnt(0)
	v_fma_f32 v6, v6, v10, v14
	v_fma_f32 v7, v7, v11, v15
	v_fma_f32 v4, v4, v8, v12
	v_fma_f32 v5, v5, v9, v13
	global_store_dwordx4 v[20:21], v[4:7], off
	s_andn2_b64 exec, exec, s[10:11]
	s_cbranch_execnz .LBB0_569

.LBB0_579:
	s_or_b64 exec, exec, s[0:1]
	s_waitcnt lgkmcnt(0)
	s_barrier
	ds_read_b128 v[132:135], v180
	ds_read_b128 v[138:141], v180 offset:16
	s_add_i32 s58, s58, 1
	s_add_u32 s38, s38, 0xfffa0000
	s_addc_u32 s39, s39, -1
	s_waitcnt lgkmcnt(1)
	v_mov_b32_e32 v78, v133
	v_mov_b32_e32 v79, v134
	v_mov_b32_e32 v133, v135
	s_waitcnt vmcnt(9)
	v_lshlrev_b32_e32 v134, 16, v162
	v_and_b32_e32 v135, 0xffff0000, v162
	v_add_f32_e64 v78, v78, v132
	v_add_f32_e64 v79, v79, v133
	s_waitcnt lgkmcnt(0)
	v_mov_b32_e32 v132, v140
	v_mov_b32_e32 v133, v138
	v_mov_b32_e32 v138, v141
	v_mul_f32_e32 v140, 0xbfb8aa3b, v134
	v_mul_f32_e32 v141, 0xbfb8aa3b, v135
	v_exp_f32_e32 v140, v140
	v_exp_f32_e32 v141, v141
	v_add_f32_e64 v144, v132, v138
	v_add_f32_e64 v145, v133, v139
	v_lshlrev_b32_e32 v138, 16, v163
	v_and_b32_e32 v139, 0xffff0000, v163
	v_add_f32_e32 v132, 1.0, v140
	v_add_f32_e32 v133, 1.0, v141
	v_mul_f32_e32 v140, 0xbfb8aa3b, v138
	v_mul_f32_e32 v141, 0xbfb8aa3b, v139
	v_rcp_f32_e32 v132, v132
	v_rcp_f32_e32 v133, v133
	v_exp_f32_e32 v140, v140
	v_exp_f32_e32 v141, v141
	s_waitcnt vmcnt(8)
	v_lshlrev_b32_e32 v162, 16, v152
	v_mul_f32_e64 v146, v132, v134
	v_mul_f32_e64 v147, v133, v135
	v_add_f32_e32 v132, 1.0, v140
	v_add_f32_e32 v133, 1.0, v141
	v_and_b32_e32 v163, 0xffff0000, v152
	v_mul_f32_e32 v134, 0xbfb8aa3b, v162
	v_rcp_f32_e32 v132, v132
	v_rcp_f32_e32 v133, v133
	v_exp_f32_e32 v134, v134
	v_mul_f32_e32 v135, 0xbfb8aa3b, v163
	v_exp_f32_e32 v135, v135
	v_mul_f32_e64 v200, v132, v138
	v_mul_f32_e64 v201, v133, v139
	v_add_f32_e32 v132, 1.0, v134
	v_rcp_f32_e32 v202, v132
	v_add_f32_e32 v132, 1.0, v135
	v_lshlrev_b32_e32 v152, 16, v153
	v_and_b32_e32 v153, 0xffff0000, v153
	v_rcp_f32_e32 v203, v132
	v_mul_f32_e32 v132, 0xbfb8aa3b, v152
	v_mul_f32_e32 v133, 0xbfb8aa3b, v153
	v_exp_f32_e32 v132, v132
	v_exp_f32_e32 v138, v133
	s_sub_i32 s30, s30, 64
	v_add_f32_e32 v139, 1.0, v132
	ds_read_b128 v[132:135], v180 offset:512
	v_add_f32_e32 v138, 1.0, v138
	v_rcp_f32_e32 v204, v139
	v_rcp_f32_e32 v205, v138
	ds_read_b128 v[138:141], v180 offset:528
	s_waitcnt lgkmcnt(1)
	v_mov_b32_e32 v206, v133
	v_mov_b32_e32 v207, v134
	v_mov_b32_e32 v133, v135
	v_add_f32_e64 v132, v206, v132
	v_add_f32_e64 v133, v207, v133
	s_waitcnt lgkmcnt(0)
	v_mov_b32_e32 v134, v140
	v_mov_b32_e32 v135, v138
	v_mov_b32_e32 v138, v141
	v_add_f32_e64 v134, v134, v138
	v_add_f32_e64 v135, v135, v139
	v_mov_b32_e32 v138, v132
	v_mov_b32_e32 v139, v78
	v_mov_b32_e32 v78, v133
	v_add_f32_e64 v78, v138, v78
	v_add_f32_e64 v79, v139, v79
	v_mov_b32_e32 v132, v135
	v_mov_b32_e32 v133, v145
	v_add_f32_e64 v78, v78, v132
	v_add_f32_e64 v79, v79, v133
	v_mov_b32_e32 v135, v144
	v_add_f32_e64 v132, v134, v78
	v_add_f32_e64 v133, v135, v79
	v_mov_b64_e32 v[78:79], s[42:43]
	v_fma_f32 v132, v132, s40, v78
	v_fma_f32 v133, v133, s40, v78
	v_mul_f32_e64 v138, v202, v162
	v_mul_f32_e64 v139, v203, v163
	v_mul_f32_e32 v134, 0x4b800000, v133
	v_cmp_gt_f32_e64 s[0:1], s57, v133
	v_mul_f32_e64 v140, v204, v152
	v_mul_f32_e64 v141, v205, v153
	v_lshl_add_u64 v[152:153], s[34:35], 0, v[116:117]
	v_cndmask_b32_e64 v133, v133, v134, s[0:1]
	v_rsq_f32_e32 v133, v133
	v_lshl_add_u64 v[134:135], s[34:35], 0, v[106:107]
	v_mul_f32_e32 v144, 0x45800000, v133
	v_cndmask_b32_e64 v144, v133, v144, s[0:1]
	v_mul_f32_e64 v148, v148, v144
	v_mul_f32_e64 v149, v149, v144
	v_mul_f32_e32 v133, 0x4b800000, v132
	s_waitcnt vmcnt(1)
	v_mul_f32_e64 v148, v72, v148
	v_mul_f32_e64 v149, v73, v149
	v_cmp_gt_f32_e64 s[0:1], s57, v132
	v_mul_f32_e64 v146, v146, v148
	v_mul_f32_e64 v147, v147, v149
	v_mul_f32_e64 v148, v150, v144
	v_mul_f32_e64 v149, v151, v144
	v_cvt_pk_bf16_f32 v146, v146, v147
	v_mul_f32_e64 v148, v74, v148
	v_mul_f32_e64 v149, v75, v149
	v_cndmask_b32_e64 v132, v132, v133, s[0:1]
	v_mul_f32_e64 v148, v200, v148
	v_mul_f32_e64 v149, v201, v149
	v_rsq_f32_e32 v133, v132
	v_cvt_pk_bf16_f32 v147, v148, v149
	global_store_dwordx2 v[134:135], v[146:147], off
	v_mul_f32_e64 v146, v156, v144
	v_mul_f32_e64 v147, v157, v144
	v_mul_f32_e64 v145, v159, v144
	v_mul_f32_e64 v144, v158, v144
	s_waitcnt vmcnt(1)
	v_mul_f32_e64 v146, v68, v146
	v_mul_f32_e64 v147, v69, v147
	v_mul_f32_e64 v144, v70, v144
	v_mul_f32_e64 v145, v71, v145
	v_mul_f32_e64 v138, v138, v146
	v_mul_f32_e64 v139, v139, v147
	v_mul_f32_e64 v140, v140, v144
	v_mul_f32_e64 v141, v141, v145
	v_cvt_pk_bf16_f32 v138, v138, v139
	v_cvt_pk_bf16_f32 v139, v140, v141
	v_lshlrev_b32_e32 v132, 16, v142
	global_store_dwordx2 v[134:135], v[138:139], off offset:32
	v_mul_f32_e32 v134, 0xbfb8aa3b, v132
	v_exp_f32_e32 v135, v134
	v_mul_f32_e32 v134, 0x45800000, v133
	v_cndmask_b32_e64 v134, v133, v134, s[0:1]
	v_and_b32_e32 v133, 0xffff0000, v142
	v_mul_f32_e32 v138, 0xbfb8aa3b, v133
	v_exp_f32_e32 v139, v138
	v_add_f32_e32 v135, 1.0, v135
	v_rcp_f32_e32 v138, v135
	v_mul_f32_e64 v140, v160, v134
	v_mul_f32_e64 v141, v161, v134
	v_add_f32_e32 v135, 1.0, v139
	v_lshlrev_b32_e32 v142, 16, v143
	v_rcp_f32_e32 v139, v135
	v_and_b32_e32 v143, 0xffff0000, v143
	v_mul_f32_e32 v135, 0xbfb8aa3b, v142
	v_exp_f32_e32 v135, v135
	v_mul_f32_e32 v144, 0xbfb8aa3b, v143
	v_exp_f32_e32 v144, v144
	v_mul_f32_e64 v132, v138, v132
	v_mul_f32_e64 v133, v139, v133
	v_add_f32_e32 v135, 1.0, v135
	v_rcp_f32_e32 v138, v135
	v_add_f32_e32 v135, 1.0, v144
	v_rcp_f32_e32 v139, v135
	v_mul_f32_e64 v98, v98, v134
	v_mul_f32_e64 v99, v99, v134
	v_mul_f32_e64 v140, v72, v140
	v_mul_f32_e64 v141, v73, v141
	v_mul_f32_e64 v98, v74, v98
	v_mul_f32_e64 v99, v75, v99
	v_mul_f32_e64 v138, v138, v142
	v_mul_f32_e64 v139, v139, v143
	v_mul_f32_e64 v132, v132, v140
	v_mul_f32_e64 v133, v133, v141
	v_mul_f32_e64 v98, v138, v98
	v_mul_f32_e64 v99, v139, v99
	v_cvt_pk_bf16_f32 v132, v132, v133
	v_cvt_pk_bf16_f32 v133, v98, v99
	v_lshlrev_b32_e32 v98, 16, v136
	v_mul_f32_e32 v99, 0xbfb8aa3b, v98
	v_exp_f32_e32 v135, v99
	v_lshl_add_u64 v[138:139], s[34:35], 0, v[110:111]
	v_and_b32_e32 v99, 0xffff0000, v136
	global_store_dwordx2 v[138:139], v[132:133], off
	v_mul_f32_e32 v133, 0xbfb8aa3b, v99
	v_exp_f32_e32 v133, v133
	v_lshlrev_b32_e32 v136, 16, v137
	v_and_b32_e32 v137, 0xffff0000, v137
	v_add_f32_e32 v132, 1.0, v135
	v_mul_f32_e64 v96, v96, v134
	v_mul_f32_e64 v97, v97, v134
	v_add_f32_e32 v133, 1.0, v133
	v_mul_f32_e32 v135, 0xbfb8aa3b, v136
	v_mul_f32_e32 v138, 0xbfb8aa3b, v137
	v_rcp_f32_e32 v132, v132
	v_rcp_f32_e32 v133, v133
	v_exp_f32_e32 v135, v135
	v_exp_f32_e32 v138, v138
	v_mul_f32_e64 v96, v68, v96
	v_mul_f32_e64 v97, v69, v97
	v_mul_f32_e64 v98, v132, v98
	v_mul_f32_e64 v99, v133, v99
	v_add_f32_e32 v132, 1.0, v135
	v_add_f32_e32 v133, 1.0, v138
	v_rcp_f32_e32 v132, v132
	v_rcp_f32_e32 v133, v133
	v_mul_f32_e64 v94, v94, v134
	v_mul_f32_e64 v95, v95, v134
	v_mul_f32_e64 v96, v98, v96
	v_mul_f32_e64 v97, v99, v97
	v_mul_f32_e64 v94, v70, v94
	v_mul_f32_e64 v95, v71, v95
	v_mul_f32_e64 v98, v132, v136
	v_mul_f32_e64 v99, v133, v137
	v_cvt_pk_bf16_f32 v132, v96, v97
	v_mul_f32_e64 v98, v98, v94
	v_mul_f32_e64 v99, v99, v95
	ds_read_b128 v[94:97], v180 offset:1024
	v_cvt_pk_bf16_f32 v133, v98, v99
	v_lshl_add_u64 v[98:99], s[34:35], 0, v[112:113]
	global_store_dwordx2 v[98:99], v[132:133], off
	ds_read_b128 v[132:135], v180 offset:1040
	s_waitcnt lgkmcnt(1)
	v_mov_b32_e32 v98, v95
	v_mov_b32_e32 v99, v96
	v_mov_b32_e32 v95, v97
	v_lshlrev_b32_e32 v96, 16, v130
	v_add_f32_e64 v98, v98, v94
	v_add_f32_e64 v99, v99, v95
	v_and_b32_e32 v97, 0xffff0000, v130
	v_mul_f32_e32 v95, 0xbfb8aa3b, v96
	v_exp_f32_e32 v130, v95
	v_mul_f32_e32 v95, 0xbfb8aa3b, v97
	s_waitcnt lgkmcnt(0)
	v_mov_b32_e32 v94, v134
	v_exp_f32_e32 v134, v95
	v_lshlrev_b32_e32 v136, 16, v131
	v_and_b32_e32 v137, 0xffff0000, v131
	v_mul_f32_e32 v131, 0xbfb8aa3b, v136
	v_mov_b32_e32 v95, v132
	v_add_f32_e32 v132, 1.0, v134
	v_exp_f32_e32 v134, v131
	v_mul_f32_e32 v131, 0xbfb8aa3b, v137
	v_exp_f32_e32 v139, v131
	v_rcp_f32_e32 v131, v132
	v_add_f32_e32 v132, 1.0, v134
	v_rcp_f32_e32 v138, v132
	v_add_f32_e32 v132, 1.0, v139
	v_rcp_f32_e32 v139, v132
	v_mov_b32_e32 v132, v135
	v_add_f32_e64 v132, v94, v132
	v_add_f32_e64 v133, v95, v133
	v_lshlrev_b32_e32 v144, 16, v129
	v_mul_f32_e64 v136, v138, v136
	v_mul_f32_e64 v137, v139, v137
	v_lshlrev_b32_e32 v138, 16, v128
	v_and_b32_e32 v139, 0xffff0000, v128
	v_mul_f32_e32 v94, 0xbfb8aa3b, v138
	v_exp_f32_e32 v94, v94
	v_mul_f32_e32 v95, 0xbfb8aa3b, v139
	v_exp_f32_e32 v95, v95
	v_and_b32_e32 v145, 0xffff0000, v129
	v_add_f32_e32 v94, 1.0, v94
	v_rcp_f32_e32 v142, v94
	v_add_f32_e32 v94, 1.0, v95
	v_add_f32_e32 v130, 1.0, v130
	v_rcp_f32_e32 v143, v94
	v_mul_f32_e32 v94, 0xbfb8aa3b, v144
	v_mul_f32_e32 v95, 0xbfb8aa3b, v145
	v_rcp_f32_e32 v130, v130
	v_exp_f32_e32 v94, v94
	v_exp_f32_e32 v128, v95
	v_lshl_add_u64 v[140:141], s[34:35], 0, v[114:115]
	v_mul_f32_e64 v134, v130, v96
	v_mul_f32_e64 v135, v131, v97
	v_add_f32_e32 v129, 1.0, v94
	ds_read_b128 v[94:97], v180 offset:1536
	v_add_f32_e32 v128, 1.0, v128
	v_rcp_f32_e32 v146, v129
	v_rcp_f32_e32 v147, v128
	ds_read_b128 v[128:131], v180 offset:1552
	s_waitcnt lgkmcnt(1)
	v_mov_b32_e32 v148, v95
	v_mov_b32_e32 v149, v96
	v_mov_b32_e32 v95, v97
	v_add_f32_e64 v94, v148, v94
	v_add_f32_e64 v95, v149, v95
	s_waitcnt lgkmcnt(0)
	v_mov_b32_e32 v96, v130
	v_mov_b32_e32 v97, v128
	v_mov_b32_e32 v128, v131
	v_add_f32_e64 v96, v96, v128
	v_add_f32_e64 v97, v97, v129
	v_mov_b32_e32 v128, v94
	v_mov_b32_e32 v129, v98
	v_mov_b32_e32 v98, v95
	v_add_f32_e64 v94, v128, v98
	v_add_f32_e64 v95, v129, v99
	v_mov_b32_e32 v98, v97
	v_mov_b32_e32 v99, v133
	v_add_f32_e64 v94, v94, v98
	v_add_f32_e64 v95, v95, v99
	v_mov_b32_e32 v97, v132
	v_add_f32_e64 v94, v96, v94
	v_add_f32_e64 v95, v97, v95
	v_mul_f32_e64 v98, v146, v144
	v_mul_f32_e64 v99, v147, v145
	v_fma_f32 v79, v95, s40, v78
	v_fma_f32 v78, v94, s40, v78
	s_nop 0
	v_mul_f32_e32 v94, 0x4b800000, v79
	v_cmp_gt_f32_e64 s[0:1], s57, v79
	s_nop 1
	v_cndmask_b32_e64 v79, v79, v94, s[0:1]
	v_rsq_f32_e32 v79, v79
	v_mul_f32_e64 v94, v142, v138
	v_mul_f32_e64 v95, v143, v139
	v_mul_f32_e32 v96, 0x45800000, v79
	v_cndmask_b32_e64 v96, v79, v96, s[0:1]
	v_mul_f32_e64 v88, v88, v96
	v_mul_f32_e64 v89, v89, v96
	v_mul_f32_e64 v92, v92, v96
	v_mul_f32_e64 v93, v93, v96
	v_mul_f32_e64 v88, v72, v88
	v_mul_f32_e64 v89, v73, v89
	v_mul_f32_e64 v92, v74, v92
	v_mul_f32_e64 v93, v75, v93
	v_mul_f32_e64 v88, v134, v88
	v_mul_f32_e64 v89, v135, v89
	v_mul_f32_e64 v92, v136, v92
	v_mul_f32_e64 v93, v137, v93
	v_cvt_pk_bf16_f32 v88, v88, v89
	v_cvt_pk_bf16_f32 v89, v92, v93
	global_store_dwordx2 v[140:141], v[88:89], off
	v_mul_f32_e64 v88, v90, v96
	v_mul_f32_e64 v89, v91, v96
	v_mul_f32_e32 v79, 0x4b800000, v78
	v_cmp_gt_f32_e64 s[0:1], s57, v78
	v_mul_f32_e64 v88, v68, v88
	v_mul_f32_e64 v89, v69, v89
	v_mul_f32_e64 v86, v86, v96
	v_mul_f32_e64 v87, v87, v96
	v_cndmask_b32_e64 v78, v78, v79, s[0:1]
	v_mul_f32_e64 v200, v94, v88
	v_mul_f32_e64 v201, v95, v89
	v_mul_f32_e64 v202, v70, v86
	v_mul_f32_e64 v203, v71, v87
	ds_read_b64_tr_b16 v[88:89], v196 offset:57408
	ds_read_b64_tr_b16 v[86:87], v196 offset:56320
	ds_read_b64_tr_b16 v[92:93], v198 offset:2112
	ds_read_b64_tr_b16 v[90:91], v198
	ds_read_b64_tr_b16 v[96:97], v198 offset:2144
	ds_read_b64_tr_b16 v[94:95], v198 offset:32
	ds_read_b64_tr_b16 v[128:129], v196 offset:56352
	ds_read_b64_tr_b16 v[132:133], v196 offset:56384
	ds_read_b64_tr_b16 v[136:137], v196 offset:56416
	ds_read_b64_tr_b16 v[130:131], v196 offset:57440
	ds_read_b64_tr_b16 v[134:135], v196 offset:57472
	ds_read_b64_tr_b16 v[138:139], v196 offset:57504
	v_rsq_f32_e32 v78, v78
	ds_read_b64_tr_b16 v[140:141], v196 offset:65024
	ds_read_b64_tr_b16 v[142:143], v197 offset:57408
	ds_read_b64_tr_b16 v[144:145], v198 offset:16896
	ds_read_b64_tr_b16 v[146:147], v198 offset:19008
	ds_read_b64_tr_b16 v[150:151], v198 offset:19040
	ds_read_b64_tr_b16 v[148:149], v198 offset:16928
	v_mul_f32_e64 v98, v98, v202
	v_mul_f32_e64 v99, v99, v203
	s_waitcnt lgkmcnt(8)
	v_mfma_f32_16x16x32_bf16 v[12:15], v[128:131], v[90:93], v[12:15]
	v_cvt_pk_bf16_f32 v200, v200, v201
	v_cvt_pk_bf16_f32 v201, v98, v99
	v_mul_f32_e32 v79, 0x45800000, v78
	v_mfma_f32_16x16x32_bf16 v[36:39], v[128:131], v[94:97], v[36:39]
	v_lshlrev_b32_e32 v98, 16, v126
	v_cndmask_b32_e64 v78, v78, v79, s[0:1]
	v_and_b32_e32 v99, 0xffff0000, v126
	v_mfma_f32_16x16x32_bf16 v[8:11], v[86:89], v[90:93], v[8:11]
	v_mul_f32_e32 v79, 0xbfb8aa3b, v98
	v_exp_f32_e32 v79, v79
	v_mul_f32_e32 v126, 0xbfb8aa3b, v99
	v_mfma_f32_16x16x32_bf16 v[4:7], v[86:89], v[94:97], v[4:7]
	ds_read_b64_tr_b16 v[86:87], v196 offset:65056
	ds_read_b64_tr_b16 v[156:157], v196 offset:65088
	ds_read_b64_tr_b16 v[160:161], v196 offset:65120
	ds_read_b64_tr_b16 v[88:89], v197 offset:57440
	ds_read_b64_tr_b16 v[158:159], v197 offset:57472
	ds_read_b64_tr_b16 v[162:163], v197 offset:57504
	v_add_f32_e32 v79, 1.0, v79
	global_store_dwordx2 v[152:153], v[200:201], off
	s_waitcnt lgkmcnt(2)
	v_mfma_f32_16x16x32_bf16 v[12:15], v[86:89], v[144:147], v[12:15]
	v_mfma_f32_16x16x32_bf16 v[36:39], v[86:89], v[148:151], v[36:39]
	v_exp_f32_e32 v87, v126
	v_rcp_f32_e32 v86, v79
	v_add_f32_e32 v79, 1.0, v87
	v_rcp_f32_e32 v87, v79
	v_mul_f32_e64 v84, v84, v78
	v_mul_f32_e64 v85, v85, v78
	v_mfma_f32_16x16x32_bf16 v[24:27], v[132:135], v[90:93], v[24:27]
	v_mul_f32_e64 v72, v72, v84
	v_mul_f32_e64 v73, v73, v85
	v_mul_f32_e64 v84, v86, v98
	v_mul_f32_e64 v85, v87, v99
	v_lshlrev_b32_e32 v86, 16, v127
	v_mul_f32_e32 v79, 0xbfb8aa3b, v86
	v_exp_f32_e32 v79, v79
	v_mul_f32_e64 v98, v84, v72
	v_mul_f32_e64 v99, v85, v73
	v_and_b32_e32 v87, 0xffff0000, v127
	v_mfma_f32_16x16x32_bf16 v[32:35], v[132:135], v[94:97], v[32:35]
	v_add_f32_e32 v72, 1.0, v79
	v_rcp_f32_e32 v84, v72
	v_mul_f32_e32 v72, 0xbfb8aa3b, v87
	v_exp_f32_e32 v79, v72
	v_mfma_f32_16x16x32_bf16 v[40:43], v[136:139], v[90:93], v[40:43]
	v_cvt_pk_bf16_f32 v98, v98, v99
	v_mul_f32_e64 v72, v82, v78
	v_mul_f32_e64 v73, v83, v78
	s_nop 0
	v_mul_f32_e64 v134, v74, v72
	v_mul_f32_e64 v135, v75, v73
	v_add_f32_e32 v72, 1.0, v79
	v_rcp_f32_e32 v85, v72
	ds_read_b64_tr_b16 v[72:73], v196 offset:56448
	ds_read_b64_tr_b16 v[74:75], v196 offset:57536
	v_mfma_f32_16x16x32_bf16 v[64:67], v[136:139], v[94:97], v[64:67]
	v_mul_f32_e64 v136, v84, v86
	v_mul_f32_e64 v137, v85, v87
	ds_read_b64_tr_b16 v[82:83], v196 offset:56480
	ds_read_b64_tr_b16 v[86:87], v196 offset:56512
	ds_read_b64_tr_b16 v[126:127], v196 offset:56544
	ds_read_b64_tr_b16 v[84:85], v196 offset:57568
	ds_read_b64_tr_b16 v[88:89], v196 offset:57600
	ds_read_b64_tr_b16 v[128:129], v196 offset:57632
	v_mfma_f32_16x16x32_bf16 v[8:11], v[140:143], v[144:147], v[8:11]
	ds_read_b64_tr_b16 v[130:131], v196 offset:65152
	ds_read_b64_tr_b16 v[132:133], v197 offset:57536
	v_mfma_f32_16x16x32_bf16 v[4:7], v[140:143], v[148:151], v[4:7]
	v_mul_f32_e64 v142, v136, v134
	v_mul_f32_e64 v143, v137, v135
	v_cvt_pk_bf16_f32 v99, v142, v143
	v_lshl_add_u64 v[142:143], s[34:35], 0, v[118:119]
	s_waitcnt lgkmcnt(8)
	v_mfma_f32_16x16x32_bf16 v[16:19], v[72:75], v[90:93], v[16:19]
	v_mfma_f32_16x16x32_bf16 v[20:23], v[72:75], v[94:97], v[20:23]
	ds_read_b64_tr_b16 v[72:73], v196 offset:65184
	ds_read_b64_tr_b16 v[134:135], v196 offset:65216
	ds_read_b64_tr_b16 v[138:139], v196 offset:65248
	ds_read_b64_tr_b16 v[74:75], v197 offset:57568
	ds_read_b64_tr_b16 v[136:137], v197 offset:57600
	ds_read_b64_tr_b16 v[140:141], v197 offset:57632
	global_store_dwordx2 v[142:143], v[98:99], off
	v_lshlrev_b32_e32 v98, 16, v124
	v_and_b32_e32 v99, 0xffff0000, v124
	v_mul_f32_e32 v79, 0xbfb8aa3b, v98
	v_exp_f32_e32 v79, v79
	v_mul_f32_e32 v124, 0xbfb8aa3b, v99
	s_waitcnt lgkmcnt(10)
	v_mfma_f32_16x16x32_bf16 v[28:31], v[82:85], v[90:93], v[28:31]
	v_add_f32_e32 v79, 1.0, v79
	v_mfma_f32_16x16x32_bf16 v[48:51], v[82:85], v[94:97], v[48:51]
	v_exp_f32_e32 v83, v124
	v_rcp_f32_e32 v82, v79
	v_add_f32_e32 v79, 1.0, v83
	v_rcp_f32_e32 v83, v79
	v_mul_f32_e64 v80, v80, v78
	v_mul_f32_e64 v81, v81, v78
	s_waitcnt lgkmcnt(2)
	v_mfma_f32_16x16x32_bf16 v[28:31], v[72:75], v[144:147], v[28:31]
	v_mul_f32_e64 v68, v68, v80
	v_mul_f32_e64 v69, v69, v81
	v_mul_f32_e64 v76, v76, v78
	v_mul_f32_e64 v77, v77, v78
	v_lshl_add_u64 v[78:79], s[34:35], 0, v[120:121]
	v_mfma_f32_16x16x32_bf16 v[48:51], v[72:75], v[148:151], v[48:51]
	v_mul_f32_e64 v72, v82, v98
	v_mul_f32_e64 v73, v83, v99
	v_mul_f32_e64 v70, v70, v76
	v_mul_f32_e64 v71, v71, v77
	v_mul_f32_e64 v68, v72, v68
	v_mul_f32_e64 v69, v73, v69
	v_lshlrev_b32_e32 v72, 16, v125
	v_and_b32_e32 v73, 0xffff0000, v125
	v_mul_f32_e32 v74, 0xbfb8aa3b, v72
	v_mul_f32_e32 v75, 0xbfb8aa3b, v73
	v_exp_f32_e32 v74, v74
	v_exp_f32_e32 v75, v75
	v_lshl_add_u32 v82, s59, 9, v176
	v_cvt_pk_bf16_f32 v76, v68, v69
	v_add_f32_e32 v74, 1.0, v74
	v_add_f32_e32 v75, 1.0, v75
	v_rcp_f32_e32 v74, v74
	v_rcp_f32_e32 v75, v75
	v_mfma_f32_16x16x32_bf16 v[24:27], v[156:159], v[144:147], v[24:27]
	s_add_u32 s34, s34, 0xfffe0000
	s_addc_u32 s35, s35, -1
	v_mul_f32_e64 v72, v74, v72
	v_mul_f32_e64 v73, v75, v73
	v_mfma_f32_16x16x32_bf16 v[32:35], v[156:159], v[148:151], v[32:35]
	v_mul_f32_e64 v72, v72, v70
	v_mul_f32_e64 v73, v73, v71
	ds_read_b128 v[68:71], v82 offset:4096
	v_cvt_pk_bf16_f32 v77, v72, v73
	ds_read_b128 v[72:75], v82 offset:4160
	global_store_dwordx2 v[78:79], v[76:77], off
	v_mfma_f32_16x16x32_bf16 v[16:19], v[130:133], v[144:147], v[16:19]
	s_waitcnt lgkmcnt(1)
	v_mul_f32_e32 v68, 0x3fb8aa3b, v68
	v_exp_f32_e32 v80, v68
	v_mul_f32_e32 v81, 0x3fb8aa3b, v69
	v_mul_f32_e32 v68, 0x3fb8aa3b, v70
	v_mul_f32_e32 v69, 0x3fb8aa3b, v71
	v_exp_f32_e32 v68, v68
	v_exp_f32_e32 v69, v69
	v_exp_f32_e32 v81, v81
	v_mfma_f32_16x16x32_bf16 v[20:23], v[130:133], v[148:151], v[20:23]
	s_add_u32 s36, s36, 0xfffe0000
	v_mul_f32_e64 v10, v10, v68
	v_mul_f32_e64 v11, v11, v69
	v_mul_f32_e64 v6, v6, v68
	v_mul_f32_e64 v7, v7, v69
	s_waitcnt lgkmcnt(0)
	v_mul_f32_e32 v68, 0x3fb8aa3b, v72
	v_mul_f32_e32 v69, 0x3fb8aa3b, v74
	v_exp_f32_e32 v76, v68
	v_mul_f32_e32 v68, 0x3fb8aa3b, v73
	v_exp_f32_e32 v78, v69
	v_mul_f32_e32 v69, 0x3fb8aa3b, v75
	v_exp_f32_e32 v79, v69
	v_exp_f32_e32 v77, v68
	ds_read_b128 v[68:71], v82 offset:4224
	ds_read_b128 v[72:75], v82 offset:4288
	v_mul_f32_e64 v8, v8, v80
	v_mul_f32_e64 v9, v9, v81
	v_mul_f32_e64 v4, v4, v80
	v_mul_f32_e64 v5, v5, v81
	v_mul_f32_e64 v14, v14, v78
	v_mul_f32_e64 v15, v15, v79
	s_waitcnt lgkmcnt(1)
	v_mul_f32_e32 v68, 0x3fb8aa3b, v68
	v_exp_f32_e32 v80, v68
	v_mul_f32_e32 v81, 0x3fb8aa3b, v69
	v_mul_f32_e32 v68, 0x3fb8aa3b, v70
	v_mul_f32_e32 v69, 0x3fb8aa3b, v71
	v_exp_f32_e32 v68, v68
	v_exp_f32_e32 v69, v69
	v_mul_f32_e64 v12, v12, v76
	v_mul_f32_e64 v13, v13, v77
	v_mul_f32_e64 v38, v38, v78
	v_mul_f32_e64 v39, v39, v79
	v_mul_f32_e64 v36, v36, v76
	v_mul_f32_e64 v37, v37, v77
	v_mul_f32_e64 v26, v26, v68
	v_mul_f32_e64 v27, v27, v69
	v_mul_f32_e64 v34, v34, v68
	v_mul_f32_e64 v35, v35, v69
	s_waitcnt lgkmcnt(0)
	v_mul_f32_e32 v68, 0x3fb8aa3b, v72
	v_mul_f32_e32 v69, 0x3fb8aa3b, v74
	v_exp_f32_e32 v76, v68
	v_mul_f32_e32 v68, 0x3fb8aa3b, v73
	v_exp_f32_e32 v78, v69
	v_mul_f32_e32 v69, 0x3fb8aa3b, v75
	v_exp_f32_e32 v79, v69
	v_exp_f32_e32 v77, v68
	ds_read_b128 v[68:71], v82 offset:4352
	ds_read_b128 v[72:75], v82 offset:4416
	v_exp_f32_e32 v81, v81
	v_mfma_f32_16x16x32_bf16 v[40:43], v[160:163], v[144:147], v[40:43]
	s_addc_u32 s37, s37, -1
	s_waitcnt lgkmcnt(1)
	v_mul_f32_e32 v68, 0x3fb8aa3b, v68
	v_mul_f32_e64 v24, v24, v80
	v_mul_f32_e64 v25, v25, v81
	v_mul_f32_e64 v32, v32, v80
	v_mul_f32_e64 v33, v33, v81
	v_exp_f32_e32 v80, v68
	v_mul_f32_e32 v81, 0x3fb8aa3b, v69
	v_mul_f32_e32 v68, 0x3fb8aa3b, v70
	v_mul_f32_e32 v69, 0x3fb8aa3b, v71
	v_exp_f32_e32 v68, v68
	v_exp_f32_e32 v69, v69
	v_mfma_f32_16x16x32_bf16 v[64:67], v[160:163], v[148:151], v[64:67]
	v_mul_f32_e64 v42, v42, v78
	v_mul_f32_e64 v43, v43, v79
	v_mul_f32_e64 v40, v40, v76
	v_mul_f32_e64 v41, v41, v77
	v_mul_f32_e64 v18, v18, v68
	v_mul_f32_e64 v19, v19, v69
	v_mul_f32_e64 v22, v22, v68
	v_mul_f32_e64 v23, v23, v69
	s_waitcnt lgkmcnt(0)
	v_mul_f32_e32 v68, 0x3fb8aa3b, v72
	v_mul_f32_e32 v69, 0x3fb8aa3b, v74
	v_mul_f32_e64 v66, v66, v78
	v_mul_f32_e64 v67, v67, v79
	v_mul_f32_e64 v64, v64, v76
	v_mul_f32_e64 v65, v65, v77
	v_exp_f32_e32 v76, v68
	v_mul_f32_e32 v68, 0x3fb8aa3b, v73
	v_exp_f32_e32 v78, v69
	v_mul_f32_e32 v69, 0x3fb8aa3b, v75
	v_exp_f32_e32 v79, v69
	v_exp_f32_e32 v77, v68
	ds_read_b128 v[68:71], v82 offset:4480
	ds_read_b128 v[72:75], v82 offset:4544
	v_mfma_f32_16x16x32_bf16 v[44:47], v[86:89], v[90:93], v[44:47]
	v_exp_f32_e32 v81, v81
	v_mul_f32_e64 v30, v30, v78
	v_mul_f32_e64 v31, v31, v79
	s_waitcnt lgkmcnt(1)
	v_mul_f32_e32 v68, 0x3fb8aa3b, v68
	v_mfma_f32_16x16x32_bf16 v[56:59], v[86:89], v[94:97], v[56:59]
	v_mul_f32_e32 v69, 0x3fb8aa3b, v69
	v_mul_f32_e32 v70, 0x3fb8aa3b, v70
	v_mul_f32_e32 v71, 0x3fb8aa3b, v71
	v_mfma_f32_16x16x32_bf16 v[52:55], v[126:129], v[90:93], v[52:55]
	s_waitcnt lgkmcnt(0)
	v_mul_f32_e32 v72, 0x3fb8aa3b, v72
	v_mul_f32_e32 v73, 0x3fb8aa3b, v73
	v_mul_f32_e32 v74, 0x3fb8aa3b, v74
	v_mfma_f32_16x16x32_bf16 v[60:63], v[126:129], v[94:97], v[60:63]
	v_mul_f32_e32 v75, 0x3fb8aa3b, v75
	v_exp_f32_e32 v68, v68
	v_exp_f32_e32 v70, v70
	v_mfma_f32_16x16x32_bf16 v[44:47], v[134:137], v[144:147], v[44:47]
	v_exp_f32_e32 v71, v71
	v_exp_f32_e32 v69, v69
	v_exp_f32_e32 v72, v72
	v_mfma_f32_16x16x32_bf16 v[56:59], v[134:137], v[148:151], v[56:59]
	v_exp_f32_e32 v74, v74
	v_exp_f32_e32 v75, v75
	v_exp_f32_e32 v73, v73
	v_mfma_f32_16x16x32_bf16 v[52:55], v[138:141], v[144:147], v[52:55]
	v_mul_f32_e64 v16, v16, v80
	v_mul_f32_e64 v17, v17, v81
	v_mul_f32_e64 v20, v20, v80
	v_mul_f32_e64 v21, v21, v81
	v_mul_f32_e64 v28, v28, v76
	v_mul_f32_e64 v29, v29, v77
	v_mfma_f32_16x16x32_bf16 v[60:63], v[138:141], v[148:151], v[60:63]
	v_mul_f32_e64 v50, v50, v78
	v_mul_f32_e64 v51, v51, v79
	v_mul_f32_e64 v48, v48, v76
	v_mul_f32_e64 v49, v49, v77
	v_mul_f32_e64 v46, v46, v70
	v_mul_f32_e64 v47, v47, v71
	v_mul_f32_e64 v44, v44, v68
	v_mul_f32_e64 v45, v45, v69
	v_mul_f32_e64 v58, v58, v70
	v_mul_f32_e64 v59, v59, v71
	v_mul_f32_e64 v56, v56, v68
	v_mul_f32_e64 v57, v57, v69
	v_mul_f32_e64 v54, v54, v74
	v_mul_f32_e64 v55, v55, v75
	v_mul_f32_e64 v52, v52, v72
	v_mul_f32_e64 v53, v53, v73
	v_mul_f32_e64 v62, v62, v74
	v_mul_f32_e64 v63, v63, v75
	s_cmp_eq_u32 s58, 4
	v_mul_f32_e64 v60, v60, v72
	v_mul_f32_e64 v61, v61, v73
	s_cbranch_scc1 .LBB0_597

.LBB0_589:
	ds_read_b128 v[124:127], v185 offset:6144
	ds_read_b128 v[128:131], v185 offset:6160
	s_waitcnt vmcnt(6)
	v_lshlrev_b32_e32 v132, 16, v96
	s_waitcnt lgkmcnt(1)
	v_mul_f32_e32 v133, 0xbfb8aa3b, v124
	v_mul_f32_e32 v135, 0xbfb8aa3b, v125
	v_exp_f32_e32 v134, v133
	v_exp_f32_e32 v135, v135
	v_and_b32_e32 v133, 0xffff0000, v96
	v_mul_f32_e32 v96, 0xbfb8aa3b, v126
	v_exp_f32_e32 v136, v96
	v_mul_f32_e64 v132, v134, v132
	v_mul_f32_e64 v133, v135, v133
	v_mul_f32_e32 v96, 0xbfb8aa3b, v127
	v_exp_f32_e32 v137, v96
	v_cvt_pk_bf16_f32 v96, v132, v133
	v_lshlrev_b32_e32 v132, 16, v97
	v_and_b32_e32 v133, 0xffff0000, v97
	s_waitcnt lgkmcnt(0)
	v_mul_f32_e32 v97, 0xbfb8aa3b, v128
	v_exp_f32_e32 v134, v97
	v_mul_f32_e32 v97, 0xbfb8aa3b, v129
	v_exp_f32_e32 v135, v97
	v_mul_f32_e64 v132, v136, v132
	v_mul_f32_e64 v133, v137, v133
	v_mul_f32_e32 v124, 0x3fb8aa3b, v124
	v_cvt_pk_bf16_f32 v97, v132, v133
	v_lshlrev_b32_e32 v132, 16, v98
	v_and_b32_e32 v133, 0xffff0000, v98
	v_mul_f32_e32 v98, 0xbfb8aa3b, v130
	v_mul_f32_e64 v132, v134, v132
	v_mul_f32_e64 v133, v135, v133
	v_exp_f32_e32 v134, v98
	v_mul_f32_e32 v98, 0xbfb8aa3b, v131
	v_exp_f32_e32 v135, v98
	v_mul_f32_e32 v125, 0x3fb8aa3b, v125
	v_exp_f32_e32 v124, v124
	v_exp_f32_e32 v125, v125
	v_cvt_pk_bf16_f32 v98, v132, v133
	v_lshlrev_b32_e32 v132, 16, v99
	v_and_b32_e32 v133, 0xffff0000, v99
	v_mul_f32_e64 v132, v134, v132
	v_mul_f32_e64 v133, v135, v133
	s_nop 0
	v_cvt_pk_bf16_f32 v99, v132, v133
	ds_write_b128 v182, v[96:99] offset:56320
	v_lshlrev_b32_e32 v96, 16, v92
	v_and_b32_e32 v97, 0xffff0000, v92
	v_mul_f32_e64 v98, v124, s28
	v_mul_f32_e64 v99, v125, s28
	v_mul_f32_e32 v92, 0x3fb8aa3b, v126
	v_mul_f32_e64 v96, v98, v96
	v_mul_f32_e64 v97, v99, v97
	v_exp_f32_e32 v98, v92
	v_mul_f32_e32 v92, 0x3fb8aa3b, v127
	v_exp_f32_e32 v99, v92
	v_cvt_pk_bf16_f32 v92, v96, v97
	v_lshlrev_b32_e32 v96, 16, v93
	v_and_b32_e32 v97, 0xffff0000, v93
	v_mul_f32_e64 v98, v98, s28
	v_mul_f32_e64 v99, v99, s28
	v_mul_f32_e32 v93, 0x3fb8aa3b, v128
	v_mul_f32_e64 v96, v98, v96
	v_mul_f32_e64 v97, v99, v97
	v_exp_f32_e32 v98, v93
	v_mul_f32_e32 v93, 0x3fb8aa3b, v129
	v_exp_f32_e32 v99, v93
	v_cvt_pk_bf16_f32 v93, v96, v97
	v_lshlrev_b32_e32 v96, 16, v94
	v_and_b32_e32 v97, 0xffff0000, v94
	v_mul_f32_e64 v98, v98, s28
	v_mul_f32_e64 v99, v99, s28
	v_mul_f32_e32 v94, 0x3fb8aa3b, v130
	v_mul_f32_e64 v96, v98, v96
	v_mul_f32_e64 v97, v99, v97
	v_exp_f32_e32 v98, v94
	v_mul_f32_e32 v94, 0x3fb8aa3b, v131
	v_exp_f32_e32 v99, v94
	v_cvt_pk_bf16_f32 v94, v96, v97
	v_lshlrev_b32_e32 v96, 16, v95
	v_and_b32_e32 v97, 0xffff0000, v95
	v_mul_f32_e64 v98, v98, s28
	v_mul_f32_e64 v99, v99, s28
	s_waitcnt vmcnt(4)
	v_lshlrev_b32_e32 v126, 16, v88
	v_mul_f32_e64 v96, v98, v96
	v_mul_f32_e64 v97, v99, v97
	v_and_b32_e32 v127, 0xffff0000, v88
	v_cvt_pk_bf16_f32 v95, v96, v97
	ds_write_b128 v182, v[92:95] offset:38912
	ds_read_b128 v[92:95], v186 offset:6144
	ds_read_b128 v[96:99], v186 offset:6160
	s_waitcnt lgkmcnt(1)
	v_mul_f32_e32 v124, 0xbfb8aa3b, v92
	v_mul_f32_e32 v125, 0xbfb8aa3b, v93
	v_exp_f32_e32 v124, v124
	v_exp_f32_e32 v125, v125
	v_mul_f32_e32 v88, 0xbfb8aa3b, v94
	v_mul_f32_e32 v92, 0x3fb8aa3b, v92
	v_mul_f32_e32 v93, 0x3fb8aa3b, v93
	v_mul_f32_e64 v124, v124, v126
	v_mul_f32_e64 v125, v125, v127
	v_exp_f32_e32 v126, v88
	v_mul_f32_e32 v88, 0xbfb8aa3b, v95
	v_exp_f32_e32 v127, v88
	v_cvt_pk_bf16_f32 v88, v124, v125
	v_lshlrev_b32_e32 v124, 16, v89
	v_and_b32_e32 v125, 0xffff0000, v89
	s_waitcnt lgkmcnt(0)
	v_mul_f32_e32 v89, 0xbfb8aa3b, v96
	v_mul_f32_e64 v124, v126, v124
	v_mul_f32_e64 v125, v127, v125
	v_exp_f32_e32 v126, v89
	v_mul_f32_e32 v89, 0xbfb8aa3b, v97
	v_exp_f32_e32 v127, v89
	v_cvt_pk_bf16_f32 v89, v124, v125
	v_lshlrev_b32_e32 v124, 16, v90
	v_and_b32_e32 v125, 0xffff0000, v90
	v_mul_f32_e32 v90, 0xbfb8aa3b, v98
	v_mul_f32_e64 v124, v126, v124
	v_mul_f32_e64 v125, v127, v125
	v_exp_f32_e32 v126, v90
	v_mul_f32_e32 v90, 0xbfb8aa3b, v99
	v_exp_f32_e32 v127, v90
	v_exp_f32_e32 v92, v92
	v_exp_f32_e32 v93, v93
	v_cvt_pk_bf16_f32 v90, v124, v125
	v_lshlrev_b32_e32 v124, 16, v91
	v_and_b32_e32 v125, 0xffff0000, v91
	v_mul_f32_e64 v124, v126, v124
	v_mul_f32_e64 v125, v127, v125
	s_nop 0
	v_cvt_pk_bf16_f32 v91, v124, v125
	ds_write_b128 v183, v[88:91] offset:56320
	v_lshlrev_b32_e32 v88, 16, v84
	v_and_b32_e32 v89, 0xffff0000, v84
	v_mul_f32_e64 v90, v92, s28
	v_mul_f32_e64 v91, v93, s28
	v_mul_f32_e32 v84, 0x3fb8aa3b, v94
	v_mul_f32_e64 v88, v90, v88
	v_mul_f32_e64 v89, v91, v89
	v_exp_f32_e32 v90, v84
	v_mul_f32_e32 v84, 0x3fb8aa3b, v95
	v_exp_f32_e32 v91, v84
	v_cvt_pk_bf16_f32 v84, v88, v89
	v_lshlrev_b32_e32 v88, 16, v85
	v_and_b32_e32 v89, 0xffff0000, v85
	v_mul_f32_e64 v90, v90, s28
	v_mul_f32_e64 v91, v91, s28
	v_mul_f32_e32 v85, 0x3fb8aa3b, v96
	v_mul_f32_e64 v88, v90, v88
	v_mul_f32_e64 v89, v91, v89
	v_exp_f32_e32 v90, v85
	v_mul_f32_e32 v85, 0x3fb8aa3b, v97
	v_exp_f32_e32 v91, v85
	v_cvt_pk_bf16_f32 v85, v88, v89
	v_lshlrev_b32_e32 v88, 16, v86
	v_and_b32_e32 v89, 0xffff0000, v86
	v_mul_f32_e64 v90, v90, s28
	v_mul_f32_e64 v91, v91, s28
	v_mul_f32_e32 v86, 0x3fb8aa3b, v98
	v_mul_f32_e64 v88, v90, v88
	v_mul_f32_e64 v89, v91, v89
	v_exp_f32_e32 v90, v86
	v_mul_f32_e32 v86, 0x3fb8aa3b, v99
	v_exp_f32_e32 v91, v86
	v_cvt_pk_bf16_f32 v86, v88, v89
	v_lshlrev_b32_e32 v88, 16, v87
	v_and_b32_e32 v89, 0xffff0000, v87
	v_mul_f32_e64 v90, v90, s28
	v_mul_f32_e64 v91, v91, s28
	s_nop 0
	v_mul_f32_e64 v88, v90, v88
	v_mul_f32_e64 v89, v91, v89
	s_nop 0
	v_cvt_pk_bf16_f32 v87, v88, v89
	ds_write_b128 v183, v[84:87] offset:38912
	s_waitcnt vmcnt(3)
	ds_write_b128 v187, v[68:71]
	s_waitcnt vmcnt(2)
	ds_write_b128 v188, v[72:75]
	s_waitcnt vmcnt(1)
	ds_write_b128 v187, v[76:79] offset:16896
	s_waitcnt vmcnt(0)
	ds_write_b128 v189, v[80:83]
	v_lshl_add_u64 v[68:69], s[36:37], 0, v[106:107]
	v_lshl_add_u64 v[70:71], s[36:37], 0, v[110:111]
	v_lshl_add_u64 v[72:73], s[36:37], 0, v[112:113]
	global_load_dwordx2 v[78:79], v[68:69], off
	global_load_dwordx2 v[76:77], v[68:69], off offset:32
	global_load_dwordx2 v[146:147], v[70:71], off
	global_load_dwordx2 v[144:145], v[72:73], off
	v_lshl_add_u64 v[68:69], s[36:37], 0, v[114:115]
	v_lshl_add_u64 v[70:71], s[36:37], 0, v[116:117]
	v_lshl_add_u64 v[72:73], s[36:37], 0, v[118:119]
	v_lshl_add_u64 v[74:75], s[36:37], 0, v[120:121]
	global_load_dwordx2 v[140:141], v[68:69], off
	global_load_dwordx2 v[138:139], v[70:71], off
	global_load_dwordx2 v[134:135], v[72:73], off
	global_load_dwordx2 v[132:133], v[74:75], off
	s_waitcnt lgkmcnt(0)
	s_barrier
	ds_read_b128 v[68:71], v190 offset:56320
	ds_read_b128 v[72:75], v190 offset:56384
	ds_read_b128 v[80:83], v177 offset:38912
	ds_read_b128 v[84:87], v177 offset:38976
	s_waitcnt lgkmcnt(1)
	v_mfma_f32_16x16x32_bf16 v[68:71], v[68:71], v[80:83], 0
	ds_read_b128 v[88:91], v190 offset:56448
	ds_read_b128 v[92:95], v190 offset:56512
	v_add_u32_e32 v199, 0x9800, v195
	v_add_u32_e32 v232, 0xa800, v195
	s_waitcnt lgkmcnt(2)
	v_mfma_f32_16x16x32_bf16 v[68:71], v[72:75], v[84:87], v[68:71]
	ds_read_b128 v[72:75], v177 offset:39040
	ds_read_b128 v[96:99], v177 offset:39104
	v_add_u32_e32 v236, 0xb800, v195
	v_add_u32_e32 v237, 0xc800, v195
	s_waitcnt lgkmcnt(1)
	v_mfma_f32_16x16x32_bf16 v[68:71], v[88:91], v[72:75], v[68:71]
	v_mov_b32_e32 v88, s29
	v_cvt_pk_bf16_f32 v204, v32, v33
	v_cvt_pk_bf16_f32 v205, v34, v35
	s_waitcnt lgkmcnt(0)
	v_mfma_f32_16x16x32_bf16 v[68:71], v[92:95], v[96:99], v[68:71]
	v_cvt_pk_bf16_f32 v206, v64, v65
	v_cvt_pk_bf16_f32 v207, v66, v67
	s_add_u32 s0, s60, s46
	s_addc_u32 s1, s61, 0
	s_add_u32 s0, s0, 0x16e41000
	s_nop 2
	v_cndmask_b32_e64 v68, v68, v88, s[10:11]
	v_cndmask_b32_e64 v69, v69, 0, s[12:13]
	v_cndmask_b32_e64 v70, v70, 0, s[14:15]
	v_cndmask_b32_e64 v71, v71, 0, s[16:17]
	v_cvt_pk_bf16_f32 v68, v68, v69
	v_cvt_pk_bf16_f32 v69, v70, v71
	ds_write_b64 v191, v[68:69]
	ds_read_b128 v[68:71], v192 offset:56320
	ds_read_b128 v[88:91], v192 offset:56384
	s_waitcnt lgkmcnt(1)
	v_mfma_f32_16x16x32_bf16 v[68:71], v[68:71], v[80:83], 0
	ds_read_b128 v[80:83], v192 offset:56448
	s_addc_u32 s1, s1, 0
	v_cvt_pk_bf16_f32 v208, v16, v17
	s_waitcnt lgkmcnt(1)
	v_mfma_f32_16x16x32_bf16 v[68:71], v[88:91], v[84:87], v[68:71]
	ds_read_b128 v[84:87], v192 offset:56512
	v_cvt_pk_bf16_f32 v209, v18, v19
	v_cvt_pk_bf16_f32 v210, v28, v29
	s_waitcnt lgkmcnt(1)
	v_mfma_f32_16x16x32_bf16 v[68:71], v[80:83], v[72:75], v[68:71]
	v_mov_b32_e32 v72, s29
	v_cvt_pk_bf16_f32 v211, v30, v31
	v_cvt_pk_bf16_f32 v224, v44, v45
	s_waitcnt lgkmcnt(0)
	v_mfma_f32_16x16x32_bf16 v[68:71], v[84:87], v[96:99], v[68:71]
	v_cvt_pk_bf16_f32 v225, v46, v47
	v_cvt_pk_bf16_f32 v226, v52, v53
	v_cvt_pk_bf16_f32 v227, v54, v55
	v_cvt_pk_bf16_f32 v228, v56, v57
	v_cvt_pk_bf16_f32 v229, v58, v59
	s_nop 2
	v_cndmask_b32_e64 v68, v68, v72, s[18:19]
	v_cndmask_b32_e64 v69, v69, 0, s[20:21]
	v_cndmask_b32_e64 v70, v70, 0, s[22:23]
	v_cndmask_b32_e64 v71, v71, 0, s[24:25]
	v_cvt_pk_bf16_f32 v68, v68, v69
	v_cvt_pk_bf16_f32 v69, v70, v71
	ds_write_b64 v193, v[68:69]
	s_waitcnt lgkmcnt(0)
	s_barrier
	ds_read_b64_tr_b16 v[70:71], v198 offset:2112
	ds_read_b64_tr_b16 v[68:69], v198
	ds_read_b64_tr_b16 v[74:75], v198 offset:2144
	ds_read_b64_tr_b16 v[72:73], v198 offset:32
	ds_read_b128 v[80:83], v194
	ds_read_b128 v[84:87], v194 offset:64
	ds_read_b128 v[92:95], v194 offset:2304
	ds_read_b128 v[96:99], v194 offset:2368
	ds_read_b128 v[128:131], v194 offset:4608
	ds_read_b64_tr_b16 v[148:149], v198 offset:16896
	ds_read_b64_tr_b16 v[150:151], v198 offset:19008
	ds_read_b128 v[156:159], v194 offset:4672
	ds_read_b64_tr_b16 v[202:203], v198 offset:19040
	ds_read_b64_tr_b16 v[200:201], v198 offset:16928
	s_waitcnt lgkmcnt(9)
	v_mfma_f32_16x16x32_bf16 v[88:91], v[68:71], v[80:83], 0
	v_cvt_pk_bf16_f32 v230, v60, v61
	v_cvt_pk_bf16_f32 v231, v62, v63
	v_mfma_f32_16x16x32_bf16 v[80:83], v[72:75], v[80:83], 0
	s_waitcnt lgkmcnt(7)
	v_mfma_f32_16x16x32_bf16 v[124:127], v[68:71], v[92:95], 0
	v_mfma_f32_16x16x32_bf16 v[92:95], v[72:75], v[92:95], 0
	s_waitcnt lgkmcnt(5)
	v_mfma_f32_16x16x32_bf16 v[160:163], v[68:71], v[128:131], 0
	s_waitcnt lgkmcnt(3)
	v_mfma_f32_16x16x32_bf16 v[88:91], v[148:151], v[84:87], v[88:91]
	s_waitcnt lgkmcnt(0)
	v_mfma_f32_16x16x32_bf16 v[80:83], v[200:203], v[84:87], v[80:83]
	v_mfma_f32_16x16x32_bf16 v[84:87], v[148:151], v[96:99], v[124:127]
	v_mfma_f32_16x16x32_bf16 v[92:95], v[200:203], v[96:99], v[92:95]
	v_mfma_f32_16x16x32_bf16 v[96:99], v[72:75], v[128:131], 0
	v_mfma_f32_16x16x32_bf16 v[124:127], v[148:151], v[156:159], v[160:163]
	v_mfma_f32_16x16x32_bf16 v[96:99], v[200:203], v[156:159], v[96:99]
	ds_read_b128 v[128:131], v194 offset:6912
	ds_read_b128 v[156:159], v194 offset:6976
	ds_read2_b64 v[160:163], v236 offset0:64 offset1:68
	s_waitcnt lgkmcnt(2)
	v_mfma_f32_16x16x32_bf16 v[68:71], v[68:71], v[128:131], 0
	v_mfma_f32_16x16x32_bf16 v[72:75], v[72:75], v[128:131], 0
	v_cvt_pk_bf16_f32 v128, v8, v9
	v_cvt_pk_bf16_f32 v129, v10, v11
	v_cvt_pk_bf16_f32 v130, v12, v13
	s_waitcnt lgkmcnt(1)
	v_mfma_f32_16x16x32_bf16 v[68:71], v[148:151], v[156:159], v[68:71]
	v_cvt_pk_bf16_f32 v131, v14, v15
	ds_read2_b64 v[148:151], v199 offset1:4
	v_mfma_f32_16x16x32_bf16 v[72:75], v[200:203], v[156:159], v[72:75]
	v_cvt_pk_bf16_f32 v156, v4, v5
	v_cvt_pk_bf16_f32 v157, v6, v7
	v_cvt_pk_bf16_f32 v158, v36, v37
	v_cvt_pk_bf16_f32 v159, v38, v39
	s_waitcnt lgkmcnt(0)
	v_mfma_f32_16x16x32_bf16 v[88:91], v[128:131], v[148:151], v[88:91]
	v_cvt_pk_bf16_f32 v200, v24, v25
	v_cvt_pk_bf16_f32 v201, v26, v27
	v_cvt_pk_bf16_f32 v202, v40, v41
	v_mfma_f32_16x16x32_bf16 v[80:83], v[156:159], v[148:151], v[80:83]
	ds_read2_b64 v[148:151], v232 offset0:32 offset1:36
	v_cvt_pk_bf16_f32 v203, v42, v43
	s_waitcnt lgkmcnt(0)
	v_mfma_f32_16x16x32_bf16 v[84:87], v[128:131], v[148:151], v[84:87]
	v_mfma_f32_16x16x32_bf16 v[92:95], v[156:159], v[148:151], v[92:95]
	ds_read2_b64 v[148:151], v237 offset0:96 offset1:100
	v_mfma_f32_16x16x32_bf16 v[124:127], v[128:131], v[160:163], v[124:127]
	v_mfma_f32_16x16x32_bf16 v[96:99], v[156:159], v[160:163], v[96:99]
	s_waitcnt lgkmcnt(0)
	v_mfma_f32_16x16x32_bf16 v[68:71], v[128:131], v[148:151], v[68:71]
	ds_read2_b64 v[128:131], v199 offset0:8 offset1:12
	ds_read2_b64 v[160:163], v232 offset0:40 offset1:44
	v_mfma_f32_16x16x32_bf16 v[148:151], v[156:159], v[148:151], v[72:75]
	s_nop 2
	ds_read2_b64 v[72:75], v236 offset0:72 offset1:76
	ds_read2_b64 v[156:159], v237 offset0:104 offset1:108
	ds_read2_b64 v[212:215], v199 offset0:16 offset1:20
	s_waitcnt lgkmcnt(4)
	v_mfma_f32_16x16x32_bf16 v[88:91], v[200:203], v[128:131], v[88:91]
	v_mfma_f32_16x16x32_bf16 v[80:83], v[204:207], v[128:131], v[80:83]
	v_lshl_add_u64 v[128:129], s[0:1], 0, v[108:109]
	v_add_co_u32_e64 v130, s[0:1], s47, v128
	s_waitcnt lgkmcnt(2)
	v_mfma_f32_16x16x32_bf16 v[216:219], v[200:203], v[72:75], v[124:127]
	v_addc_co_u32_e64 v131, s[0:1], 0, v129, s[0:1]
	v_mfma_f32_16x16x32_bf16 v[96:99], v[204:207], v[72:75], v[96:99]
	v_add_co_u32_e64 v72, s[0:1], s52, v128
	s_nop 1
	v_addc_co_u32_e64 v73, s[0:1], 0, v129, s[0:1]
	v_mfma_f32_16x16x32_bf16 v[84:87], v[200:203], v[160:163], v[84:87]
	s_waitcnt lgkmcnt(1)
	v_mfma_f32_16x16x32_bf16 v[200:203], v[200:203], v[156:159], v[68:71]
	s_nop 2
	v_add_co_u32_e64 v68, s[0:1], s53, v128
	v_mfma_f32_16x16x32_bf16 v[92:95], v[204:207], v[160:163], v[92:95]
	s_nop 0
	v_addc_co_u32_e64 v69, s[0:1], 0, v129, s[0:1]
	global_load_dwordx2 v[162:163], v[128:129], off
	global_load_dwordx2 v[152:153], v[128:129], off offset:32
	global_load_dwordx2 v[142:143], v[130:131], off
	global_load_dwordx2 v[136:137], v[130:131], off offset:32
	s_nop 0
	global_load_dwordx2 v[130:131], v[72:73], off
	global_load_dwordx2 v[128:129], v[72:73], off offset:32
	global_load_dwordx2 v[126:127], v[68:69], off
	global_load_dwordx2 v[124:125], v[68:69], off offset:32
	s_nop 0
	global_load_dwordx4 v[72:75], v[122:123], off
	global_load_dwordx4 v[68:71], v[122:123], off offset:64
	v_mfma_f32_16x16x32_bf16 v[156:159], v[204:207], v[156:159], v[148:151]
	v_cvt_pk_bf16_f32 v204, v20, v21
	v_cvt_pk_bf16_f32 v205, v22, v23
	v_cvt_pk_bf16_f32 v206, v48, v49
	v_cvt_pk_bf16_f32 v207, v50, v51
	s_waitcnt lgkmcnt(0)
	v_mfma_f32_16x16x32_bf16 v[88:91], v[208:211], v[212:215], v[88:91]
	ds_read2_b64 v[148:151], v232 offset0:48 offset1:52
	v_mfma_f32_16x16x32_bf16 v[80:83], v[204:207], v[212:215], v[80:83]
	ds_read2_b64 v[212:215], v236 offset0:80 offset1:84
	ds_read2_b64 v[220:223], v237 offset0:112 offset1:116
	s_waitcnt lgkmcnt(1)
	v_mfma_f32_16x16x32_bf16 v[216:219], v[208:211], v[212:215], v[216:219]
	v_mfma_f32_16x16x32_bf16 v[212:215], v[204:207], v[212:215], v[96:99]
	s_nop 2
	ds_read2_b64 v[96:99], v199 offset0:24 offset1:28
	ds_read2_b64 v[232:235], v232 offset0:56 offset1:60
	s_waitcnt lgkmcnt(1)
	v_mfma_f32_16x16x32_bf16 v[88:91], v[224:227], v[96:99], v[88:91]
	v_mfma_f32_16x16x32_bf16 v[84:87], v[208:211], v[148:151], v[84:87]
	v_mfma_f32_16x16x32_bf16 v[92:95], v[204:207], v[148:151], v[92:95]
	s_waitcnt vmcnt(17)
	v_lshlrev_b32_e32 v148, 16, v78
	v_and_b32_e32 v149, 0xffff0000, v78
	v_lshlrev_b32_e32 v78, 16, v79
	v_and_b32_e32 v79, 0xffff0000, v79
	s_nop 0
	v_add_f32_e64 v150, v90, v78
	v_add_f32_e64 v151, v91, v79
	v_mfma_f32_16x16x32_bf16 v[78:81], v[228:231], v[96:99], v[80:83]
	v_add_f32_e64 v148, v88, v148
	v_add_f32_e64 v149, v89, v149
	s_waitcnt vmcnt(16)
	v_lshlrev_b32_e32 v88, 16, v76
	v_mul_f32_e64 v160, v148, v148
	v_mul_f32_e64 v161, v149, v149
	v_and_b32_e32 v89, 0xffff0000, v76
	v_lshlrev_b32_e32 v76, 16, v77
	v_and_b32_e32 v77, 0xffff0000, v77
	v_mfma_f32_16x16x32_bf16 v[204:207], v[204:207], v[220:223], v[156:159]
	v_mul_f32_e64 v82, v150, v150
	v_mul_f32_e64 v83, v151, v151
	s_nop 0
	v_add_f32_e64 v158, v80, v76
	v_add_f32_e64 v159, v81, v77
	v_add_f32_e32 v80, v160, v161
	v_add_f32_e64 v156, v78, v88
	v_add_f32_e64 v157, v79, v89
	v_add_f32_e32 v80, v82, v80
	v_mul_f32_e64 v76, v156, v156
	v_mul_f32_e64 v77, v157, v157
	v_add_f32_e32 v80, v83, v80
	v_add_f32_e32 v76, v76, v80
	v_mul_f32_e64 v78, v158, v158
	v_mul_f32_e64 v79, v159, v159
	v_add_f32_e32 v76, v77, v76
	v_add_f32_e32 v76, v78, v76
	v_add_f32_e32 v76, v79, v76
	ds_bpermute_b32 v77, v178, v76
	v_mfma_f32_16x16x32_bf16 v[200:203], v[208:211], v[220:223], v[200:203]
	ds_read2_b64 v[208:211], v236 offset0:88 offset1:92
	ds_read2_b64 v[236:239], v237 offset0:120 offset1:124
	s_waitcnt lgkmcnt(2)
	v_add_f32_e32 v160, v76, v77
	ds_bpermute_b32 v161, v179, v160
	v_mfma_f32_16x16x32_bf16 v[96:99], v[224:227], v[232:235], v[84:87]
	v_mfma_f32_16x16x32_bf16 v[92:95], v[228:231], v[232:235], v[92:95]
	s_waitcnt lgkmcnt(2)
	v_mfma_f32_16x16x32_bf16 v[88:91], v[224:227], v[208:211], v[216:219]
	v_mfma_f32_16x16x32_bf16 v[84:87], v[228:231], v[208:211], v[212:215]
	s_waitcnt lgkmcnt(1)
	v_mfma_f32_16x16x32_bf16 v[80:83], v[224:227], v[236:239], v[200:203]
	v_mfma_f32_16x16x32_bf16 v[76:79], v[228:231], v[236:239], v[204:207]
	s_and_saveexec_b64 s[0:1], s[6:7]
	s_cbranch_execz .LBB0_591
	s_waitcnt lgkmcnt(0)
	v_add_f32_e32 v160, v160, v161
	ds_write_b32 v181, v160
.LBB0_591:
	s_or_b64 exec, exec, s[0:1]
	s_waitcnt vmcnt(15)
	v_lshlrev_b32_e32 v160, 16, v146
	s_waitcnt lgkmcnt(0)
	v_and_b32_e32 v161, 0xffff0000, v146
	v_add_f32_e64 v160, v96, v160
	v_add_f32_e64 v161, v97, v161
	v_lshlrev_b32_e32 v96, 16, v147
	v_and_b32_e32 v97, 0xffff0000, v147
	v_add_f32_e64 v98, v98, v96
	v_add_f32_e64 v99, v99, v97
	v_mul_f32_e64 v146, v160, v160
	v_mul_f32_e64 v147, v161, v161
	v_mul_f32_e64 v200, v98, v98
	v_mul_f32_e64 v201, v99, v99
	s_waitcnt vmcnt(14)
	v_lshlrev_b32_e32 v96, 16, v144
	v_and_b32_e32 v97, 0xffff0000, v144
	v_add_f32_e32 v146, v146, v147
	v_add_f32_e64 v96, v92, v96
	v_add_f32_e64 v97, v93, v97
	v_lshlrev_b32_e32 v92, 16, v145
	v_and_b32_e32 v93, 0xffff0000, v145
	v_add_f32_e32 v146, v200, v146
	v_add_f32_e64 v94, v94, v92
	v_add_f32_e64 v95, v95, v93
	v_mul_f32_e64 v92, v96, v96
	v_mul_f32_e64 v93, v97, v97
	v_add_f32_e32 v146, v201, v146
	v_add_f32_e32 v92, v92, v146
	v_mul_f32_e64 v144, v94, v94
	v_mul_f32_e64 v145, v95, v95
	v_add_f32_e32 v92, v93, v92
	v_add_f32_e32 v92, v144, v92
	v_add_f32_e32 v92, v145, v92
	ds_bpermute_b32 v93, v178, v92
	s_waitcnt lgkmcnt(0)
	v_add_f32_e32 v92, v92, v93
	ds_bpermute_b32 v93, v179, v92
	s_and_saveexec_b64 s[0:1], s[6:7]
	s_cbranch_execz .LBB0_593
	s_waitcnt lgkmcnt(0)
	v_add_f32_e32 v92, v92, v93
	ds_write_b32 v181, v92 offset:512
.LBB0_593:
	s_or_b64 exec, exec, s[0:1]
	s_waitcnt vmcnt(13)
	v_lshlrev_b32_e32 v92, 16, v140
	s_waitcnt lgkmcnt(0)
	v_and_b32_e32 v93, 0xffff0000, v140
	v_add_f32_e64 v88, v88, v92
	v_add_f32_e64 v89, v89, v93
	v_lshlrev_b32_e32 v92, 16, v141
	v_and_b32_e32 v93, 0xffff0000, v141
	v_add_f32_e64 v92, v90, v92
	v_add_f32_e64 v93, v91, v93
	v_mul_f32_e64 v140, v88, v88
	v_mul_f32_e64 v141, v89, v89
	v_mul_f32_e64 v144, v92, v92
	v_mul_f32_e64 v145, v93, v93
	s_waitcnt vmcnt(12)
	v_lshlrev_b32_e32 v90, 16, v138
	v_and_b32_e32 v91, 0xffff0000, v138
	v_add_f32_e32 v140, v140, v141
	v_add_f32_e64 v90, v84, v90
	v_add_f32_e64 v91, v85, v91
	v_lshlrev_b32_e32 v84, 16, v139
	v_and_b32_e32 v85, 0xffff0000, v139
	v_add_f32_e32 v140, v144, v140
	v_add_f32_e64 v86, v86, v84
	v_add_f32_e64 v87, v87, v85
	v_mul_f32_e64 v84, v90, v90
	v_mul_f32_e64 v85, v91, v91
	v_add_f32_e32 v140, v145, v140
	v_add_f32_e32 v84, v84, v140
	v_mul_f32_e64 v138, v86, v86
	v_mul_f32_e64 v139, v87, v87
	v_add_f32_e32 v84, v85, v84
	v_add_f32_e32 v84, v138, v84
	v_add_f32_e32 v84, v139, v84
	ds_bpermute_b32 v85, v178, v84
	s_waitcnt lgkmcnt(0)
	v_add_f32_e32 v84, v84, v85
	ds_bpermute_b32 v85, v179, v84
	s_and_saveexec_b64 s[0:1], s[6:7]
	s_cbranch_execz .LBB0_595
	s_waitcnt lgkmcnt(0)
	v_add_f32_e32 v84, v84, v85
	ds_write_b32 v181, v84 offset:1024
.LBB0_595:
	s_or_b64 exec, exec, s[0:1]
	s_waitcnt vmcnt(11)
	v_lshlrev_b32_e32 v84, 16, v134
	s_waitcnt lgkmcnt(0)
	v_and_b32_e32 v85, 0xffff0000, v134
	v_add_f32_e64 v84, v80, v84
	v_add_f32_e64 v85, v81, v85
	v_lshlrev_b32_e32 v80, 16, v135
	v_and_b32_e32 v81, 0xffff0000, v135
	v_add_f32_e64 v82, v82, v80
	v_add_f32_e64 v83, v83, v81
	v_mul_f32_e64 v134, v84, v84
	v_mul_f32_e64 v135, v85, v85
	v_mul_f32_e64 v138, v82, v82
	v_mul_f32_e64 v139, v83, v83
	s_waitcnt vmcnt(10)
	v_lshlrev_b32_e32 v80, 16, v132
	v_and_b32_e32 v81, 0xffff0000, v132
	v_add_f32_e32 v134, v134, v135
	v_add_f32_e64 v80, v76, v80
	v_add_f32_e64 v81, v77, v81
	v_lshlrev_b32_e32 v76, 16, v133
	v_and_b32_e32 v77, 0xffff0000, v133
	v_add_f32_e32 v134, v138, v134
	v_add_f32_e64 v76, v78, v76
	v_add_f32_e64 v77, v79, v77
	v_mul_f32_e64 v78, v80, v80
	v_mul_f32_e64 v79, v81, v81
	v_add_f32_e32 v134, v139, v134
	v_add_f32_e32 v78, v78, v134
	v_mul_f32_e64 v132, v76, v76
	v_mul_f32_e64 v133, v77, v77
	v_add_f32_e32 v78, v79, v78
	v_add_f32_e32 v78, v132, v78
	v_add_f32_e32 v78, v133, v78
	ds_bpermute_b32 v79, v178, v78
	s_waitcnt lgkmcnt(0)
	v_add_f32_e32 v78, v78, v79
	ds_bpermute_b32 v79, v179, v78
	s_and_saveexec_b64 s[0:1], s[6:7]
	s_cbranch_execz .LBB0_579
	s_waitcnt lgkmcnt(0)
	v_add_f32_e32 v78, v78, v79
	ds_write_b32 v181, v78 offset:1536
	s_branch .LBB0_579

.LBB0_663:
	ds_read_b128 v[134:137], v201 offset:6144
	ds_read_b128 v[138:141], v201 offset:6160
	s_waitcnt vmcnt(6)
	v_lshlrev_b32_e32 v144, 16, v98
	v_and_b32_e32 v145, 0xffff0000, v98
	v_add_u32_e32 v215, 0x9800, v212
	s_waitcnt lgkmcnt(1)
	v_mul_f32_e32 v109, 0xbfb8aa3b, v134
	v_exp_f32_e32 v142, v109
	v_mul_f32_e32 v109, 0xbfb8aa3b, v135
	v_exp_f32_e32 v143, v109
	v_mul_f32_e32 v109, 0xbfb8aa3b, v136
	v_cvt_pk_bf16_f32 v156, v10, v11
	v_cvt_pk_bf16_f32 v157, v12, v13
	v_mul_f32_e64 v142, v142, v144
	v_mul_f32_e64 v143, v143, v145
	v_lshlrev_b32_e32 v144, 16, v99
	v_cvt_pk_bf16_f32 v98, v142, v143
	v_exp_f32_e32 v142, v109
	v_mul_f32_e32 v109, 0xbfb8aa3b, v137
	v_exp_f32_e32 v143, v109
	v_and_b32_e32 v145, 0xffff0000, v99
	s_waitcnt lgkmcnt(0)
	v_mul_f32_e32 v109, 0xbfb8aa3b, v138
	v_cvt_pk_bf16_f32 v158, v26, v27
	v_mul_f32_e64 v142, v142, v144
	v_mul_f32_e64 v143, v143, v145
	v_lshlrev_b32_e32 v144, 16, v100
	v_cvt_pk_bf16_f32 v99, v142, v143
	v_exp_f32_e32 v142, v109
	v_mul_f32_e32 v109, 0xbfb8aa3b, v139
	v_exp_f32_e32 v143, v109
	v_and_b32_e32 v145, 0xffff0000, v100
	v_mul_f32_e32 v109, 0xbfb8aa3b, v140
	v_cvt_pk_bf16_f32 v159, v28, v29
	v_mul_f32_e64 v142, v142, v144
	v_mul_f32_e64 v143, v143, v145
	v_lshlrev_b32_e32 v144, 16, v101
	v_cvt_pk_bf16_f32 v100, v142, v143
	v_exp_f32_e32 v142, v109
	v_mul_f32_e32 v109, 0xbfb8aa3b, v141
	v_exp_f32_e32 v143, v109
	v_and_b32_e32 v145, 0xffff0000, v101
	v_add_u32_e32 v216, 0xa800, v212
	v_add_u32_e32 v217, 0xb800, v212
	v_mul_f32_e64 v142, v142, v144
	v_mul_f32_e64 v143, v143, v145
	v_add_u32_e32 v218, 0xc800, v212
	v_cvt_pk_bf16_f32 v101, v142, v143
	ds_write_b128 v181, v[98:101] offset:56320
	v_mul_f32_e32 v98, 0x3fb8aa3b, v134
	v_mul_f32_e32 v99, 0x3fb8aa3b, v135
	v_exp_f32_e32 v98, v98
	v_exp_f32_e32 v99, v99
	v_lshlrev_b32_e32 v100, 16, v94
	v_and_b32_e32 v101, 0xffff0000, v94
	s_mov_b32 s62, 0x8000
	v_mul_f32_e64 v98, v98, s50
	v_mul_f32_e64 v99, v99, s50
	s_add_u32 s76, s76, 0x60000
	v_mul_f32_e64 v98, v98, v100
	v_mul_f32_e64 v99, v99, v101
	v_lshlrev_b32_e32 v100, 16, v95
	v_cvt_pk_bf16_f32 v94, v98, v99
	v_mul_f32_e32 v98, 0x3fb8aa3b, v136
	v_mul_f32_e32 v99, 0x3fb8aa3b, v137
	v_exp_f32_e32 v98, v98
	v_exp_f32_e32 v99, v99
	v_and_b32_e32 v101, 0xffff0000, v95
	s_waitcnt vmcnt(4)
	v_lshlrev_b32_e32 v136, 16, v90
	v_and_b32_e32 v137, 0xffff0000, v90
	v_mul_f32_e64 v98, v98, s50
	v_mul_f32_e64 v99, v99, s50
	s_addc_u32 s77, s77, 0
	v_mul_f32_e64 v98, v98, v100
	v_mul_f32_e64 v99, v99, v101
	v_lshlrev_b32_e32 v100, 16, v96
	v_cvt_pk_bf16_f32 v95, v98, v99
	v_mul_f32_e32 v98, 0x3fb8aa3b, v138
	v_mul_f32_e32 v99, 0x3fb8aa3b, v139
	v_exp_f32_e32 v98, v98
	v_exp_f32_e32 v99, v99
	v_and_b32_e32 v101, 0xffff0000, v96
	s_add_i32 s64, s64, 64
	v_mul_f32_e64 v98, v98, s50
	v_mul_f32_e64 v99, v99, s50
	s_nop 0
	v_mul_f32_e64 v98, v98, v100
	v_mul_f32_e64 v99, v99, v101
	v_lshlrev_b32_e32 v100, 16, v97
	v_cvt_pk_bf16_f32 v96, v98, v99
	v_mul_f32_e32 v98, 0x3fb8aa3b, v140
	v_mul_f32_e32 v99, 0x3fb8aa3b, v141
	v_exp_f32_e32 v98, v98
	v_exp_f32_e32 v99, v99
	v_and_b32_e32 v101, 0xffff0000, v97
	v_mul_f32_e64 v98, v98, s50
	v_mul_f32_e64 v99, v99, s50
	s_nop 0
	v_mul_f32_e64 v98, v98, v100
	v_mul_f32_e64 v99, v99, v101
	s_nop 0
	v_cvt_pk_bf16_f32 v97, v98, v99
	ds_write_b128 v181, v[94:97] offset:38912
	ds_read_b128 v[94:97], v202 offset:6144
	ds_read_b128 v[98:101], v202 offset:6160
	s_waitcnt lgkmcnt(1)
	v_mul_f32_e32 v109, 0xbfb8aa3b, v94
	v_exp_f32_e32 v134, v109
	v_mul_f32_e32 v109, 0xbfb8aa3b, v95
	v_exp_f32_e32 v135, v109
	v_mul_f32_e32 v109, 0xbfb8aa3b, v96
	v_mul_f32_e64 v134, v134, v136
	v_mul_f32_e64 v135, v135, v137
	s_nop 0
	v_cvt_pk_bf16_f32 v90, v134, v135
	v_exp_f32_e32 v134, v109
	v_mul_f32_e32 v109, 0xbfb8aa3b, v97
	v_exp_f32_e32 v135, v109
	v_lshlrev_b32_e32 v136, 16, v91
	v_and_b32_e32 v137, 0xffff0000, v91
	s_waitcnt lgkmcnt(0)
	v_mul_f32_e32 v109, 0xbfb8aa3b, v98
	v_mul_f32_e64 v134, v134, v136
	v_mul_f32_e64 v135, v135, v137
	v_lshlrev_b32_e32 v136, 16, v92
	v_cvt_pk_bf16_f32 v91, v134, v135
	v_exp_f32_e32 v134, v109
	v_mul_f32_e32 v109, 0xbfb8aa3b, v99
	v_exp_f32_e32 v135, v109
	v_and_b32_e32 v137, 0xffff0000, v92
	v_mul_f32_e32 v109, 0xbfb8aa3b, v100
	v_mul_f32_e64 v134, v134, v136
	v_mul_f32_e64 v135, v135, v137
	s_nop 0
	v_cvt_pk_bf16_f32 v92, v134, v135
	v_exp_f32_e32 v134, v109
	v_mul_f32_e32 v109, 0xbfb8aa3b, v101
	v_exp_f32_e32 v135, v109
	v_lshlrev_b32_e32 v136, 16, v93
	v_and_b32_e32 v137, 0xffff0000, v93
	v_mul_f32_e64 v134, v134, v136
	v_mul_f32_e64 v135, v135, v137
	s_nop 0
	v_cvt_pk_bf16_f32 v93, v134, v135
	ds_write_b128 v182, v[90:93] offset:56320
	v_mul_f32_e32 v90, 0x3fb8aa3b, v94
	v_mul_f32_e32 v91, 0x3fb8aa3b, v95
	v_exp_f32_e32 v90, v90
	v_exp_f32_e32 v91, v91
	v_lshlrev_b32_e32 v92, 16, v70
	v_and_b32_e32 v93, 0xffff0000, v70
	v_mul_f32_e64 v90, v90, s50
	v_mul_f32_e64 v91, v91, s50
	s_nop 0
	v_mul_f32_e64 v90, v90, v92
	v_mul_f32_e64 v91, v91, v93
	v_lshlrev_b32_e32 v92, 16, v71
	v_cvt_pk_bf16_f32 v70, v90, v91
	v_mul_f32_e32 v90, 0x3fb8aa3b, v96
	v_mul_f32_e32 v91, 0x3fb8aa3b, v97
	v_exp_f32_e32 v90, v90
	v_exp_f32_e32 v91, v91
	v_and_b32_e32 v93, 0xffff0000, v71
	v_mul_f32_e64 v90, v90, s50
	v_mul_f32_e64 v91, v91, s50
	s_nop 0
	v_mul_f32_e64 v90, v90, v92
	v_mul_f32_e64 v91, v91, v93
	v_lshlrev_b32_e32 v92, 16, v72
	v_cvt_pk_bf16_f32 v71, v90, v91
	v_mul_f32_e32 v90, 0x3fb8aa3b, v98
	v_mul_f32_e32 v91, 0x3fb8aa3b, v99
	v_exp_f32_e32 v90, v90
	v_exp_f32_e32 v91, v91
	v_and_b32_e32 v93, 0xffff0000, v72
	v_mul_f32_e64 v90, v90, s50
	v_mul_f32_e64 v91, v91, s50
	s_nop 0
	v_mul_f32_e64 v90, v90, v92
	v_mul_f32_e64 v91, v91, v93
	v_lshlrev_b32_e32 v92, 16, v73
	v_cvt_pk_bf16_f32 v72, v90, v91
	v_mul_f32_e32 v90, 0x3fb8aa3b, v100
	v_mul_f32_e32 v91, 0x3fb8aa3b, v101
	v_exp_f32_e32 v90, v90
	v_exp_f32_e32 v91, v91
	v_and_b32_e32 v93, 0xffff0000, v73
	v_mul_f32_e64 v90, v90, s50
	v_mul_f32_e64 v91, v91, s50
	s_nop 0
	v_mul_f32_e64 v90, v90, v92
	v_mul_f32_e64 v91, v91, v93
	s_nop 0
	v_cvt_pk_bf16_f32 v73, v90, v91
	ds_write_b128 v182, v[70:73] offset:38912
	s_waitcnt vmcnt(3)
	ds_write_b128 v203, v[74:77]
	s_waitcnt vmcnt(2)
	ds_write_b128 v204, v[78:81]
	s_waitcnt vmcnt(1)
	ds_write_b128 v203, v[82:85] offset:16896
	s_waitcnt vmcnt(0)
	ds_write_b128 v205, v[86:89]
	s_waitcnt lgkmcnt(0)
	s_barrier
	ds_read_b128 v[70:73], v206 offset:56320
	ds_read_b128 v[74:77], v180 offset:38912
	ds_read_b128 v[78:81], v206 offset:56384
	ds_read_b128 v[82:85], v180 offset:38976
	s_waitcnt lgkmcnt(2)
	v_mfma_f32_16x16x32_bf16 v[70:73], v[70:73], v[74:77], 0
	s_waitcnt lgkmcnt(0)
	v_mfma_f32_16x16x32_bf16 v[70:73], v[78:81], v[82:85], v[70:73]
	ds_read_b128 v[78:81], v206 offset:56448
	ds_read_b128 v[86:89], v180 offset:39040
	s_waitcnt lgkmcnt(0)
	v_mfma_f32_16x16x32_bf16 v[70:73], v[78:81], v[86:89], v[70:73]
	ds_read_b128 v[78:81], v206 offset:56512
	ds_read_b128 v[90:93], v180 offset:39104
	s_waitcnt lgkmcnt(0)
	v_mfma_f32_16x16x32_bf16 v[70:73], v[78:81], v[90:93], v[70:73]
	v_mov_b32_e32 v78, s49
	s_nop 6
	v_cndmask_b32_e64 v78, v70, v78, s[12:13]
	v_cndmask_b32_e64 v70, v78, v70, s[14:15]
	v_cndmask_b32_e64 v71, 0, v71, s[14:15]
	v_cndmask_b32_e64 v72, v72, 0, s[16:17]
	v_cndmask_b32_e64 v73, v73, 0, s[18:19]
	v_cvt_pk_bf16_f32 v70, v70, v71
	v_cvt_pk_bf16_f32 v71, v72, v73
	ds_write_b64 v207, v[70:71]
	ds_read_b128 v[70:73], v208 offset:56320
	s_waitcnt lgkmcnt(0)
	v_mfma_f32_16x16x32_bf16 v[70:73], v[70:73], v[74:77], 0
	ds_read_b128 v[74:77], v208 offset:56384
	s_waitcnt lgkmcnt(0)
	v_mfma_f32_16x16x32_bf16 v[70:73], v[74:77], v[82:85], v[70:73]
	ds_read_b128 v[74:77], v208 offset:56448
	s_waitcnt lgkmcnt(0)
	v_mfma_f32_16x16x32_bf16 v[70:73], v[74:77], v[86:89], v[70:73]
	ds_read_b128 v[74:77], v208 offset:56512
	s_waitcnt lgkmcnt(0)
	v_mfma_f32_16x16x32_bf16 v[70:73], v[74:77], v[90:93], v[70:73]
	v_mov_b32_e32 v74, s49
	s_nop 6
	v_cndmask_b32_e64 v74, v70, v74, s[20:21]
	v_cndmask_b32_e64 v70, v74, v70, s[22:23]
	v_cndmask_b32_e64 v71, 0, v71, s[22:23]
	v_cndmask_b32_e64 v72, v72, 0, s[24:25]
	v_cndmask_b32_e64 v73, v73, 0, s[26:27]
	v_cvt_pk_bf16_f32 v70, v70, v71
	v_cvt_pk_bf16_f32 v71, v72, v73
	ds_write_b64 v209, v[70:71]
	s_waitcnt lgkmcnt(0)
	s_barrier
	ds_read_b64_tr_b16 v[80:81], v210 offset:2112
	ds_read_b64_tr_b16 v[78:79], v210
	ds_read_b64_tr_b16 v[82:83], v210 offset:32
	ds_read_b64_tr_b16 v[70:71], v210 offset:16896
	ds_read_b64_tr_b16 v[72:73], v210 offset:19008
	ds_read_b64_tr_b16 v[84:85], v210 offset:2144
	ds_read_b64_tr_b16 v[74:75], v210 offset:16928
	ds_read_b64_tr_b16 v[76:77], v210 offset:19040
	ds_read_b128 v[86:89], v211
	ds_read_b128 v[94:97], v211 offset:64
	ds_read_b128 v[134:137], v211 offset:2368
	s_waitcnt lgkmcnt(2)
	v_mfma_f32_16x16x32_bf16 v[90:93], v[78:81], v[86:89], 0
	ds_read_b128 v[142:145], v211 offset:4672
	ds_read_b128 v[150:153], v211 offset:6976
	ds_read2_b64 v[160:163], v215 offset1:4
	v_mfma_f32_16x16x32_bf16 v[86:89], v[82:85], v[86:89], 0
	s_waitcnt lgkmcnt(4)
	v_mfma_f32_16x16x32_bf16 v[90:93], v[70:73], v[94:97], v[90:93]
	v_mfma_f32_16x16x32_bf16 v[86:89], v[74:77], v[94:97], v[86:89]
	ds_read_b128 v[94:97], v211 offset:2304
	s_waitcnt lgkmcnt(0)
	v_mfma_f32_16x16x32_bf16 v[98:101], v[78:81], v[94:97], 0
	v_mfma_f32_16x16x32_bf16 v[94:97], v[82:85], v[94:97], 0
	v_mfma_f32_16x16x32_bf16 v[98:101], v[70:73], v[134:137], v[98:101]
	v_mfma_f32_16x16x32_bf16 v[94:97], v[74:77], v[134:137], v[94:97]
	ds_read_b128 v[134:137], v211 offset:4608
	s_waitcnt lgkmcnt(0)
	v_mfma_f32_16x16x32_bf16 v[138:141], v[78:81], v[134:137], 0
	v_mfma_f32_16x16x32_bf16 v[134:137], v[82:85], v[134:137], 0
	v_mfma_f32_16x16x32_bf16 v[138:141], v[70:73], v[142:145], v[138:141]
	v_mfma_f32_16x16x32_bf16 v[134:137], v[74:77], v[142:145], v[134:137]
	ds_read_b128 v[142:145], v211 offset:6912
	s_waitcnt lgkmcnt(0)
	v_mfma_f32_16x16x32_bf16 v[146:149], v[78:81], v[142:145], 0
	v_mfma_f32_16x16x32_bf16 v[142:145], v[82:85], v[142:145], 0
	v_mfma_f32_16x16x32_bf16 v[146:149], v[70:73], v[150:153], v[146:149]
	v_mfma_f32_16x16x32_bf16 v[142:145], v[74:77], v[150:153], v[142:145]
	v_cvt_pk_bf16_f32 v150, v6, v7
	v_cvt_pk_bf16_f32 v151, v8, v9
	v_cvt_pk_bf16_f32 v152, v22, v23
	v_cvt_pk_bf16_f32 v153, v24, v25
	v_mfma_f32_16x16x32_bf16 v[86:89], v[156:159], v[160:163], v[86:89]
	s_nop 0
	v_mfma_f32_16x16x32_bf16 v[90:93], v[150:153], v[160:163], v[90:93]
	ds_read2_b64 v[160:163], v216 offset0:32 offset1:36
	s_waitcnt lgkmcnt(0)
	v_mfma_f32_16x16x32_bf16 v[98:101], v[150:153], v[160:163], v[98:101]
	v_mfma_f32_16x16x32_bf16 v[94:97], v[156:159], v[160:163], v[94:97]
	ds_read2_b64 v[160:163], v217 offset0:64 offset1:68
	s_waitcnt lgkmcnt(0)
	v_mfma_f32_16x16x32_bf16 v[138:141], v[150:153], v[160:163], v[138:141]
	v_mfma_f32_16x16x32_bf16 v[134:137], v[156:159], v[160:163], v[134:137]
	ds_read2_b64 v[160:163], v218 offset0:96 offset1:100
	s_waitcnt lgkmcnt(0)
	v_mfma_f32_16x16x32_bf16 v[146:149], v[150:153], v[160:163], v[146:149]
	v_cvt_pk_bf16_f32 v150, v14, v15
	v_cvt_pk_bf16_f32 v151, v16, v17
	v_cvt_pk_bf16_f32 v152, v38, v39
	v_mfma_f32_16x16x32_bf16 v[142:145], v[156:159], v[160:163], v[142:145]
	v_cvt_pk_bf16_f32 v153, v40, v41
	v_cvt_pk_bf16_f32 v156, v18, v19
	v_cvt_pk_bf16_f32 v157, v20, v21
	v_cvt_pk_bf16_f32 v158, v42, v43
	v_cvt_pk_bf16_f32 v159, v44, v45
	ds_read2_b64 v[160:163], v215 offset0:8 offset1:12
	s_waitcnt lgkmcnt(0)
	v_mfma_f32_16x16x32_bf16 v[90:93], v[150:153], v[160:163], v[90:93]
	v_mfma_f32_16x16x32_bf16 v[86:89], v[156:159], v[160:163], v[86:89]
	ds_read2_b64 v[160:163], v216 offset0:40 offset1:44
	s_waitcnt lgkmcnt(0)
	v_mfma_f32_16x16x32_bf16 v[98:101], v[150:153], v[160:163], v[98:101]
	v_mfma_f32_16x16x32_bf16 v[94:97], v[156:159], v[160:163], v[94:97]
	ds_read2_b64 v[160:163], v217 offset0:72 offset1:76
	s_waitcnt lgkmcnt(0)
	v_mfma_f32_16x16x32_bf16 v[138:141], v[150:153], v[160:163], v[138:141]
	v_mfma_f32_16x16x32_bf16 v[134:137], v[156:159], v[160:163], v[134:137]
	ds_read2_b64 v[160:163], v218 offset0:104 offset1:108
	s_waitcnt lgkmcnt(0)
	v_mfma_f32_16x16x32_bf16 v[146:149], v[150:153], v[160:163], v[146:149]
	v_cvt_pk_bf16_f32 v150, v30, v31
	v_cvt_pk_bf16_f32 v151, v32, v33
	v_cvt_pk_bf16_f32 v152, v46, v47
	v_mfma_f32_16x16x32_bf16 v[142:145], v[156:159], v[160:163], v[142:145]
	v_cvt_pk_bf16_f32 v153, v48, v49
	v_cvt_pk_bf16_f32 v156, v34, v35
	v_cvt_pk_bf16_f32 v157, v36, v37
	v_cvt_pk_bf16_f32 v158, v54, v55
	v_cvt_pk_bf16_f32 v159, v56, v57
	ds_read2_b64 v[160:163], v215 offset0:16 offset1:20
	s_waitcnt lgkmcnt(0)
	v_mfma_f32_16x16x32_bf16 v[90:93], v[150:153], v[160:163], v[90:93]
	v_mfma_f32_16x16x32_bf16 v[86:89], v[156:159], v[160:163], v[86:89]
	ds_read2_b64 v[160:163], v216 offset0:48 offset1:52
	s_waitcnt lgkmcnt(0)
	v_mfma_f32_16x16x32_bf16 v[98:101], v[150:153], v[160:163], v[98:101]
	v_mfma_f32_16x16x32_bf16 v[94:97], v[156:159], v[160:163], v[94:97]
	ds_read2_b64 v[160:163], v217 offset0:80 offset1:84
	s_waitcnt lgkmcnt(0)
	v_mfma_f32_16x16x32_bf16 v[138:141], v[150:153], v[160:163], v[138:141]
	v_mfma_f32_16x16x32_bf16 v[134:137], v[156:159], v[160:163], v[134:137]
	ds_read2_b64 v[160:163], v218 offset0:112 offset1:116
	s_waitcnt lgkmcnt(0)
	v_mfma_f32_16x16x32_bf16 v[146:149], v[150:153], v[160:163], v[146:149]
	v_cvt_pk_bf16_f32 v150, v50, v51
	v_cvt_pk_bf16_f32 v151, v52, v53
	v_cvt_pk_bf16_f32 v152, v62, v63
	v_mfma_f32_16x16x32_bf16 v[142:145], v[156:159], v[160:163], v[142:145]
	v_cvt_pk_bf16_f32 v153, v64, v65
	v_cvt_pk_bf16_f32 v156, v58, v59
	v_cvt_pk_bf16_f32 v157, v60, v61
	v_cvt_pk_bf16_f32 v158, v66, v67
	v_cvt_pk_bf16_f32 v159, v68, v69
	ds_read2_b64 v[160:163], v215 offset0:24 offset1:28
	s_waitcnt lgkmcnt(0)
	v_mfma_f32_16x16x32_bf16 v[90:93], v[150:153], v[160:163], v[90:93]
	v_mfma_f32_16x16x32_bf16 v[86:89], v[156:159], v[160:163], v[86:89]
	ds_read2_b64 v[160:163], v216 offset0:56 offset1:60
	s_nop 5
	v_cvt_pk_bf16_f32 v90, v90, v91
	v_cvt_pk_bf16_f32 v91, v92, v93
	s_waitcnt lgkmcnt(0)
	v_mfma_f32_16x16x32_bf16 v[98:101], v[150:153], v[160:163], v[98:101]
	v_lshl_add_u64 v[92:93], s[74:75], 0, v[116:117]
	v_cvt_pk_bf16_f32 v86, v86, v87
	v_cvt_pk_bf16_f32 v87, v88, v89
	v_mfma_f32_16x16x32_bf16 v[94:97], v[156:159], v[160:163], v[94:97]
	ds_read2_b64 v[160:163], v217 offset0:88 offset1:92
	v_add_co_u32_e32 v88, vcc, s62, v92
	s_waitcnt lgkmcnt(0)
	v_mfma_f32_16x16x32_bf16 v[138:141], v[150:153], v[160:163], v[138:141]
	global_store_dwordx2 v[92:93], v[86:87], off offset:32
	v_cvt_pk_bf16_f32 v86, v98, v99
	v_cvt_pk_bf16_f32 v87, v100, v101
	v_mfma_f32_16x16x32_bf16 v[134:137], v[156:159], v[160:163], v[134:137]
	ds_read2_b64 v[160:163], v218 offset0:120 offset1:124
	v_addc_co_u32_e32 v89, vcc, 0, v93, vcc
	global_store_dwordx2 v[88:89], v[86:87], off
	v_cvt_pk_bf16_f32 v86, v94, v95
	v_cvt_pk_bf16_f32 v87, v96, v97
	s_mov_b32 s62, 0x10000
	s_waitcnt lgkmcnt(0)
	v_mfma_f32_16x16x32_bf16 v[146:149], v[150:153], v[160:163], v[146:149]
	global_store_dwordx2 v[88:89], v[86:87], off offset:32
	v_add_co_u32_e32 v88, vcc, s62, v92
	v_mfma_f32_16x16x32_bf16 v[142:145], v[156:159], v[160:163], v[142:145]
	v_cvt_pk_bf16_f32 v86, v138, v139
	v_cvt_pk_bf16_f32 v87, v140, v141
	v_addc_co_u32_e32 v89, vcc, 0, v93, vcc
	global_store_dwordx2 v[88:89], v[86:87], off
	v_cvt_pk_bf16_f32 v86, v134, v135
	v_cvt_pk_bf16_f32 v87, v136, v137
	global_store_dwordx2 v[88:89], v[86:87], off offset:32
	v_add_co_u32_e32 v88, vcc, s81, v92
	v_cvt_pk_bf16_f32 v86, v146, v147
	v_cvt_pk_bf16_f32 v87, v148, v149
	v_addc_co_u32_e32 v89, vcc, 0, v93, vcc
	global_store_dwordx2 v[88:89], v[86:87], off
	v_cvt_pk_bf16_f32 v86, v142, v143
	v_cvt_pk_bf16_f32 v87, v144, v145
	global_store_dwordx2 v[92:93], v[90:91], off
	global_store_dwordx2 v[88:89], v[86:87], off offset:32
	ds_read_b64_tr_b16 v[88:89], v213 offset:57408
	ds_read_b64_tr_b16 v[86:87], v213 offset:56320
	ds_read_b64_tr_b16 v[90:91], v213 offset:56352
	s_waitcnt lgkmcnt(1)
	v_mfma_f32_16x16x32_bf16 v[6:9], v[86:89], v[78:81], v[6:9]
	s_add_u32 s74, s74, 0x20000
	s_addc_u32 s75, s75, 0
	s_add_i32 s92, s92, 1
	v_mfma_f32_16x16x32_bf16 v[10:13], v[86:89], v[82:85], v[10:13]
	ds_read_b64_tr_b16 v[86:87], v213 offset:65024
	ds_read_b64_tr_b16 v[88:89], v214 offset:57408
	ds_read_b64_tr_b16 v[94:95], v214 offset:57440
	ds_read_b64_tr_b16 v[92:93], v213 offset:57440
	s_cmp_lg_u32 s76, 0x300000
	s_waitcnt lgkmcnt(2)
	v_mfma_f32_16x16x32_bf16 v[6:9], v[86:89], v[70:73], v[6:9]
	v_mfma_f32_16x16x32_bf16 v[10:13], v[86:89], v[74:77], v[10:13]
	s_waitcnt lgkmcnt(0)
	v_mfma_f32_16x16x32_bf16 v[22:25], v[90:93], v[78:81], v[22:25]
	v_mfma_f32_16x16x32_bf16 v[26:29], v[90:93], v[82:85], v[26:29]
	ds_read_b64_tr_b16 v[92:93], v213 offset:65056
	ds_read_b64_tr_b16 v[86:87], v213 offset:56384
	ds_read_b64_tr_b16 v[88:89], v213 offset:57472
	s_waitcnt lgkmcnt(0)
	v_mfma_f32_16x16x32_bf16 v[14:17], v[86:89], v[78:81], v[14:17]
	v_mfma_f32_16x16x32_bf16 v[18:21], v[86:89], v[82:85], v[18:21]
	ds_read_b64_tr_b16 v[86:87], v213 offset:65088
	ds_read_b64_tr_b16 v[88:89], v214 offset:57472
	s_waitcnt lgkmcnt(0)
	v_mfma_f32_16x16x32_bf16 v[14:17], v[86:89], v[70:73], v[14:17]
	v_mfma_f32_16x16x32_bf16 v[18:21], v[86:89], v[74:77], v[18:21]
	ds_read_b64_tr_b16 v[86:87], v213 offset:56416
	ds_read_b64_tr_b16 v[88:89], v213 offset:57504
	s_waitcnt lgkmcnt(0)
	v_mfma_f32_16x16x32_bf16 v[38:41], v[86:89], v[78:81], v[38:41]
	v_mfma_f32_16x16x32_bf16 v[42:45], v[86:89], v[82:85], v[42:45]
	ds_read_b64_tr_b16 v[86:87], v213 offset:65120
	ds_read_b64_tr_b16 v[88:89], v214 offset:57504
	s_waitcnt lgkmcnt(0)
	v_mfma_f32_16x16x32_bf16 v[38:41], v[86:89], v[70:73], v[38:41]
	v_mfma_f32_16x16x32_bf16 v[42:45], v[86:89], v[74:77], v[42:45]
	ds_read_b64_tr_b16 v[86:87], v213 offset:56448
	ds_read_b64_tr_b16 v[88:89], v213 offset:57536
	s_waitcnt lgkmcnt(0)
	v_mfma_f32_16x16x32_bf16 v[30:33], v[86:89], v[78:81], v[30:33]
	v_mfma_f32_16x16x32_bf16 v[34:37], v[86:89], v[82:85], v[34:37]
	ds_read_b64_tr_b16 v[86:87], v213 offset:65152
	ds_read_b64_tr_b16 v[88:89], v214 offset:57536
	s_waitcnt lgkmcnt(0)
	v_mfma_f32_16x16x32_bf16 v[30:33], v[86:89], v[70:73], v[30:33]
	v_mfma_f32_16x16x32_bf16 v[34:37], v[86:89], v[74:77], v[34:37]
	ds_read_b64_tr_b16 v[86:87], v213 offset:56480
	ds_read_b64_tr_b16 v[88:89], v213 offset:57568
	s_waitcnt lgkmcnt(0)
	v_mfma_f32_16x16x32_bf16 v[46:49], v[86:89], v[78:81], v[46:49]
	v_mfma_f32_16x16x32_bf16 v[54:57], v[86:89], v[82:85], v[54:57]
	ds_read_b64_tr_b16 v[86:87], v213 offset:65184
	ds_read_b64_tr_b16 v[88:89], v214 offset:57568
	s_waitcnt lgkmcnt(0)
	v_mfma_f32_16x16x32_bf16 v[46:49], v[86:89], v[70:73], v[46:49]
	v_mfma_f32_16x16x32_bf16 v[54:57], v[86:89], v[74:77], v[54:57]
	ds_read_b64_tr_b16 v[86:87], v213 offset:56512
	ds_read_b64_tr_b16 v[88:89], v213 offset:57600
	s_waitcnt lgkmcnt(0)
	v_mfma_f32_16x16x32_bf16 v[50:53], v[86:89], v[78:81], v[50:53]
	v_mfma_f32_16x16x32_bf16 v[58:61], v[86:89], v[82:85], v[58:61]
	ds_read_b64_tr_b16 v[86:87], v213 offset:65216
	ds_read_b64_tr_b16 v[88:89], v214 offset:57600
	s_waitcnt lgkmcnt(0)
	v_mfma_f32_16x16x32_bf16 v[50:53], v[86:89], v[70:73], v[50:53]
	v_mfma_f32_16x16x32_bf16 v[58:61], v[86:89], v[74:77], v[58:61]
	ds_read_b64_tr_b16 v[86:87], v213 offset:56544
	ds_read_b64_tr_b16 v[88:89], v213 offset:57632
	s_waitcnt lgkmcnt(0)
	v_mfma_f32_16x16x32_bf16 v[62:65], v[86:89], v[78:81], v[62:65]
	ds_read_b64_tr_b16 v[78:79], v213 offset:65248
	ds_read_b64_tr_b16 v[80:81], v214 offset:57632
	v_mfma_f32_16x16x32_bf16 v[66:69], v[86:89], v[82:85], v[66:69]
	v_mfma_f32_16x16x32_bf16 v[22:25], v[92:95], v[70:73], v[22:25]
	s_waitcnt lgkmcnt(0)
	v_mfma_f32_16x16x32_bf16 v[62:65], v[78:81], v[70:73], v[62:65]
	v_lshl_add_u32 v70, s93, 9, v179
	v_mfma_f32_16x16x32_bf16 v[26:29], v[92:95], v[74:77], v[26:29]
	v_mfma_f32_16x16x32_bf16 v[66:69], v[78:81], v[74:77], v[66:69]
	ds_read_b128 v[72:75], v70 offset:4096
	s_waitcnt lgkmcnt(0)
	v_mul_f32_e32 v71, 0x3fb8aa3b, v72
	v_exp_f32_e32 v72, v71
	v_mul_f32_e32 v71, 0x3fb8aa3b, v73
	v_exp_f32_e32 v73, v71
	v_mul_f32_e32 v71, 0x3fb8aa3b, v74
	v_exp_f32_e32 v74, v71
	v_mul_f32_e32 v71, 0x3fb8aa3b, v75
	v_exp_f32_e32 v75, v71
	v_mul_f32_e64 v6, v6, v72
	v_mul_f32_e64 v7, v7, v73
	v_mul_f32_e64 v10, v10, v72
	v_mul_f32_e64 v11, v11, v73
	v_mul_f32_e64 v8, v8, v74
	v_mul_f32_e64 v9, v9, v75
	v_mul_f32_e64 v12, v12, v74
	v_mul_f32_e64 v13, v13, v75
	ds_read_b128 v[72:75], v70 offset:4160
	s_waitcnt lgkmcnt(0)
	v_mul_f32_e32 v71, 0x3fb8aa3b, v72
	v_exp_f32_e32 v72, v71
	v_mul_f32_e32 v71, 0x3fb8aa3b, v73
	v_exp_f32_e32 v73, v71
	v_mul_f32_e32 v71, 0x3fb8aa3b, v74
	v_exp_f32_e32 v74, v71
	v_mul_f32_e32 v71, 0x3fb8aa3b, v75
	v_exp_f32_e32 v75, v71
	v_mul_f32_e64 v22, v22, v72
	v_mul_f32_e64 v23, v23, v73
	v_mul_f32_e64 v26, v26, v72
	v_mul_f32_e64 v27, v27, v73
	v_mul_f32_e64 v24, v24, v74
	v_mul_f32_e64 v25, v25, v75
	v_mul_f32_e64 v28, v28, v74
	v_mul_f32_e64 v29, v29, v75
	ds_read_b128 v[72:75], v70 offset:4224
	s_waitcnt lgkmcnt(0)
	v_mul_f32_e32 v71, 0x3fb8aa3b, v72
	v_exp_f32_e32 v72, v71
	v_mul_f32_e32 v71, 0x3fb8aa3b, v73
	v_exp_f32_e32 v73, v71
	v_mul_f32_e32 v71, 0x3fb8aa3b, v74
	v_exp_f32_e32 v74, v71
	v_mul_f32_e32 v71, 0x3fb8aa3b, v75
	v_exp_f32_e32 v75, v71
	v_mul_f32_e64 v14, v14, v72
	v_mul_f32_e64 v15, v15, v73
	v_mul_f32_e64 v18, v18, v72
	v_mul_f32_e64 v19, v19, v73
	v_mul_f32_e64 v16, v16, v74
	v_mul_f32_e64 v17, v17, v75
	v_mul_f32_e64 v20, v20, v74
	v_mul_f32_e64 v21, v21, v75
	ds_read_b128 v[72:75], v70 offset:4288
	s_waitcnt lgkmcnt(0)
	v_mul_f32_e32 v71, 0x3fb8aa3b, v72
	v_exp_f32_e32 v72, v71
	v_mul_f32_e32 v71, 0x3fb8aa3b, v73
	v_exp_f32_e32 v73, v71
	v_mul_f32_e32 v71, 0x3fb8aa3b, v74
	v_exp_f32_e32 v74, v71
	v_mul_f32_e32 v71, 0x3fb8aa3b, v75
	v_exp_f32_e32 v75, v71
	v_mul_f32_e64 v38, v38, v72
	v_mul_f32_e64 v39, v39, v73
	v_mul_f32_e64 v42, v42, v72
	v_mul_f32_e64 v43, v43, v73
	v_mul_f32_e64 v40, v40, v74
	v_mul_f32_e64 v41, v41, v75
	v_mul_f32_e64 v44, v44, v74
	v_mul_f32_e64 v45, v45, v75
	ds_read_b128 v[72:75], v70 offset:4352
	s_waitcnt lgkmcnt(0)
	v_mul_f32_e32 v71, 0x3fb8aa3b, v72
	v_exp_f32_e32 v72, v71
	v_mul_f32_e32 v71, 0x3fb8aa3b, v73
	v_exp_f32_e32 v73, v71
	v_mul_f32_e32 v71, 0x3fb8aa3b, v74
	v_exp_f32_e32 v74, v71
	v_mul_f32_e32 v71, 0x3fb8aa3b, v75
	v_exp_f32_e32 v75, v71
	v_mul_f32_e64 v30, v30, v72
	v_mul_f32_e64 v31, v31, v73
	v_mul_f32_e64 v34, v34, v72
	v_mul_f32_e64 v35, v35, v73
	v_mul_f32_e64 v32, v32, v74
	v_mul_f32_e64 v33, v33, v75
	v_mul_f32_e64 v36, v36, v74
	v_mul_f32_e64 v37, v37, v75
	ds_read_b128 v[72:75], v70 offset:4416
	s_waitcnt lgkmcnt(0)
	v_mul_f32_e32 v71, 0x3fb8aa3b, v72
	v_exp_f32_e32 v72, v71
	v_mul_f32_e32 v71, 0x3fb8aa3b, v73
	v_exp_f32_e32 v73, v71
	v_mul_f32_e32 v71, 0x3fb8aa3b, v74
	v_exp_f32_e32 v74, v71
	v_mul_f32_e32 v71, 0x3fb8aa3b, v75
	v_exp_f32_e32 v75, v71
	v_mul_f32_e64 v46, v46, v72
	v_mul_f32_e64 v47, v47, v73
	v_mul_f32_e64 v54, v54, v72
	v_mul_f32_e64 v55, v55, v73
	v_mul_f32_e64 v48, v48, v74
	v_mul_f32_e64 v49, v49, v75
	v_mul_f32_e64 v56, v56, v74
	v_mul_f32_e64 v57, v57, v75
	ds_read_b128 v[72:75], v70 offset:4480
	s_waitcnt lgkmcnt(0)
	v_mul_f32_e32 v71, 0x3fb8aa3b, v72
	v_exp_f32_e32 v72, v71
	v_mul_f32_e32 v71, 0x3fb8aa3b, v73
	v_exp_f32_e32 v73, v71
	v_mul_f32_e32 v71, 0x3fb8aa3b, v74
	v_exp_f32_e32 v74, v71
	v_mul_f32_e32 v71, 0x3fb8aa3b, v75
	v_exp_f32_e32 v75, v71
	v_mul_f32_e64 v50, v50, v72
	v_mul_f32_e64 v51, v51, v73
	v_mul_f32_e64 v58, v58, v72
	v_mul_f32_e64 v59, v59, v73
	ds_read_b128 v[70:73], v70 offset:4544
	v_mul_f32_e64 v52, v52, v74
	v_mul_f32_e64 v53, v53, v75
	v_mul_f32_e64 v60, v60, v74
	v_mul_f32_e64 v61, v61, v75
	s_waitcnt lgkmcnt(0)
	v_mul_f32_e32 v70, 0x3fb8aa3b, v70
	v_mul_f32_e32 v71, 0x3fb8aa3b, v71
	v_mul_f32_e32 v72, 0x3fb8aa3b, v72
	v_mul_f32_e32 v73, 0x3fb8aa3b, v73
	v_exp_f32_e32 v70, v70
	v_exp_f32_e32 v71, v71
	v_exp_f32_e32 v72, v72
	v_exp_f32_e32 v73, v73
	v_mul_f32_e64 v62, v62, v70
	v_mul_f32_e64 v63, v63, v71
	v_mul_f32_e64 v66, v66, v70
	v_mul_f32_e64 v67, v67, v71
	v_mul_f32_e64 v64, v64, v72
	v_mul_f32_e64 v65, v65, v73
	v_mul_f32_e64 v68, v68, v72
	v_mul_f32_e64 v69, v69, v73
	s_cbranch_scc0 .LBB0_672

.LBB0_679:
	s_or_b64 exec, exec, s[62:63]
	s_waitcnt lgkmcnt(0)
	s_barrier
	ds_read_b128 v[136:139], v184
	ds_read_b128 v[142:145], v184 offset:16
	s_waitcnt vmcnt(8)
	v_lshlrev_b32_e32 v156, 16, v166
	v_and_b32_e32 v157, 0xffff0000, v166
	v_lshlrev_b32_e32 v166, 16, v167
	s_waitcnt lgkmcnt(1)
	v_mov_b32_e32 v81, v138
	v_lshlrev_b32_e32 v138, 16, v168
	v_mov_b32_e32 v80, v137
	v_mov_b32_e32 v137, v139
	v_and_b32_e32 v139, 0xffff0000, v168
	v_mul_f32_e32 v0, 0xbfb8aa3b, v138
	v_add_f32_e64 v80, v80, v136
	v_add_f32_e64 v81, v81, v137
	s_waitcnt lgkmcnt(0)
	v_mov_b32_e32 v136, v144
	v_exp_f32_e32 v0, v0
	v_mul_f32_e32 v144, 0xbfb8aa3b, v139
	v_exp_f32_e32 v144, v144
	v_mov_b32_e32 v137, v142
	v_mov_b32_e32 v142, v145
	v_add_f32_e32 v0, 1.0, v0
	v_add_f32_e64 v146, v136, v142
	v_add_f32_e64 v147, v137, v143
	v_rcp_f32_e32 v136, v0
	v_add_f32_e32 v0, 1.0, v144
	v_lshlrev_b32_e32 v142, 16, v169
	v_rcp_f32_e32 v137, v0
	v_and_b32_e32 v143, 0xffff0000, v169
	v_mul_f32_e32 v0, 0xbfb8aa3b, v142
	v_exp_f32_e32 v0, v0
	v_mul_f32_e32 v144, 0xbfb8aa3b, v143
	v_exp_f32_e32 v144, v144
	v_mul_f32_e64 v148, v136, v138
	v_mul_f32_e64 v149, v137, v139
	v_add_f32_e32 v0, 1.0, v0
	v_rcp_f32_e32 v136, v0
	v_add_f32_e32 v0, 1.0, v144
	v_rcp_f32_e32 v137, v0
	v_mul_f32_e32 v0, 0xbfb8aa3b, v156
	v_exp_f32_e32 v0, v0
	v_mul_f32_e32 v138, 0xbfb8aa3b, v157
	v_exp_f32_e32 v138, v138
	v_and_b32_e32 v167, 0xffff0000, v167
	v_add_f32_e32 v0, 1.0, v0
	v_rcp_f32_e32 v224, v0
	v_add_f32_e32 v0, 1.0, v138
	v_rcp_f32_e32 v225, v0
	v_mul_f32_e32 v0, 0xbfb8aa3b, v166
	v_mul_f32_e64 v168, v136, v142
	v_mul_f32_e64 v169, v137, v143
	v_exp_f32_e32 v0, v0
	v_mul_f32_e32 v136, 0xbfb8aa3b, v167
	v_exp_f32_e32 v142, v136
	ds_read_b128 v[136:139], v184 offset:512
	v_add_f32_e32 v0, 1.0, v0
	v_rcp_f32_e32 v226, v0
	v_add_f32_e32 v0, 1.0, v142
	ds_read_b128 v[142:145], v184 offset:528
	s_waitcnt lgkmcnt(1)
	v_mov_b32_e32 v228, v137
	v_mov_b32_e32 v229, v138
	v_mov_b32_e32 v137, v139
	v_add_f32_e64 v136, v228, v136
	v_add_f32_e64 v137, v229, v137
	s_waitcnt lgkmcnt(0)
	v_mov_b32_e32 v138, v144
	v_mov_b32_e32 v139, v142
	v_mov_b32_e32 v142, v145
	v_add_f32_e64 v138, v138, v142
	v_add_f32_e64 v139, v139, v143
	v_mov_b32_e32 v142, v136
	v_mov_b32_e32 v143, v80
	v_mov_b32_e32 v80, v137
	v_add_f32_e64 v80, v142, v80
	v_add_f32_e64 v81, v143, v81
	v_mov_b32_e32 v136, v139
	v_mov_b32_e32 v137, v147
	v_add_f32_e64 v80, v80, v136
	v_add_f32_e64 v81, v81, v137
	v_mov_b32_e32 v139, v146
	s_mov_b32 s62, 0x358637bd
	v_add_f32_e64 v136, v138, v80
	v_add_f32_e64 v137, v139, v81
	v_mov_b64_e32 v[80:81], s[62:63]
	v_fma_f32 v136, v136, s52, v80
	v_fma_f32 v137, v137, s52, v80
	v_rcp_f32_e32 v227, v0
	v_mul_f32_e32 v0, 0x4b800000, v137
	v_cmp_gt_f32_e32 vcc, s1, v137
	v_mul_f32_e64 v142, v224, v156
	v_mul_f32_e64 v143, v225, v157
	v_mul_f32_e64 v144, v226, v166
	v_mul_f32_e64 v145, v227, v167
	v_cndmask_b32_e32 v0, v137, v0, vcc
	v_rsq_f32_e32 v0, v0
	v_lshl_add_u64 v[138:139], s[56:57], 0, v[116:117]
	s_waitcnt vmcnt(4)
	v_lshlrev_b32_e32 v146, 16, v159
	v_and_b32_e32 v147, 0xffff0000, v159
	v_mul_f32_e32 v137, 0x45800000, v0
	v_cndmask_b32_e32 v0, v0, v137, vcc
	v_mul_f32_e64 v106, v106, v0
	v_mul_f32_e64 v107, v107, v0
	v_mul_f32_e64 v108, v108, v0
	v_mul_f32_e64 v109, v109, v0
	v_mul_f32_e64 v102, v102, v0
	v_mul_f32_e64 v103, v103, v0
	v_mul_f32_e64 v104, v104, v0
	v_mul_f32_e64 v105, v105, v0
	v_mul_f32_e32 v0, 0x4b800000, v136
	v_cmp_gt_f32_e32 vcc, s1, v136
	s_waitcnt vmcnt(0)
	v_mul_f32_e64 v102, v70, v102
	v_mul_f32_e64 v103, v71, v103
	v_mul_f32_e64 v104, v72, v104
	v_mul_f32_e64 v105, v73, v105
	v_cndmask_b32_e32 v0, v136, v0, vcc
	v_mul_f32_e64 v102, v142, v102
	v_mul_f32_e64 v103, v143, v103
	v_mul_f32_e64 v104, v144, v104
	v_mul_f32_e64 v105, v145, v105
	v_rsq_f32_e32 v0, v0
	v_cvt_pk_bf16_f32 v102, v102, v103
	v_cvt_pk_bf16_f32 v103, v104, v105
	global_store_dwordx2 v[138:139], v[102:103], off offset:32
	v_lshlrev_b32_e32 v102, 16, v164
	v_mul_f32_e32 v103, 0xbfb8aa3b, v102
	v_exp_f32_e32 v104, v103
	v_mul_f32_e32 v103, 0x45800000, v0
	v_cndmask_b32_e32 v0, v0, v103, vcc
	v_and_b32_e32 v103, 0xffff0000, v164
	v_mul_f32_e32 v105, 0xbfb8aa3b, v103
	v_exp_f32_e32 v105, v105
	v_mul_f32_e64 v106, v74, v106
	v_mul_f32_e64 v107, v75, v107
	v_mul_f32_e64 v108, v76, v108
	v_mul_f32_e64 v109, v77, v109
	v_mul_f32_e64 v106, v148, v106
	v_mul_f32_e64 v107, v149, v107
	v_mul_f32_e64 v108, v168, v108
	v_mul_f32_e64 v109, v169, v109
	v_cvt_pk_bf16_f32 v106, v106, v107
	v_cvt_pk_bf16_f32 v107, v108, v109
	v_lshlrev_b32_e32 v108, 16, v165
	v_and_b32_e32 v109, 0xffff0000, v165
	v_add_f32_e32 v104, 1.0, v104
	v_add_f32_e32 v105, 1.0, v105
	v_mul_f32_e32 v136, 0xbfb8aa3b, v108
	v_mul_f32_e32 v137, 0xbfb8aa3b, v109
	v_rcp_f32_e32 v104, v104
	v_rcp_f32_e32 v105, v105
	v_exp_f32_e32 v136, v136
	v_exp_f32_e32 v137, v137
	global_store_dwordx2 v[138:139], v[106:107], off
	v_mul_f32_e64 v102, v104, v102
	v_mul_f32_e64 v103, v105, v103
	v_add_f32_e32 v104, 1.0, v136
	v_add_f32_e32 v105, 1.0, v137
	v_rcp_f32_e32 v104, v104
	v_rcp_f32_e32 v105, v105
	v_mul_f32_e64 v106, v152, v0
	v_mul_f32_e64 v107, v153, v0
	v_mul_f32_e64 v100, v100, v0
	v_mul_f32_e64 v101, v101, v0
	v_mul_f32_e64 v106, v74, v106
	v_mul_f32_e64 v107, v75, v107
	v_mul_f32_e64 v100, v76, v100
	v_mul_f32_e64 v101, v77, v101
	v_mul_f32_e64 v104, v104, v108
	v_mul_f32_e64 v105, v105, v109
	v_mul_f32_e64 v102, v102, v106
	v_mul_f32_e64 v103, v103, v107
	v_mul_f32_e64 v100, v104, v100
	v_mul_f32_e64 v101, v105, v101
	v_cvt_pk_bf16_f32 v102, v102, v103
	v_cvt_pk_bf16_f32 v103, v100, v101
	v_lshlrev_b32_e32 v100, 16, v162
	v_mul_f32_e32 v101, 0xbfb8aa3b, v100
	v_exp_f32_e32 v106, v101
	v_lshl_add_u64 v[104:105], s[56:57], 0, v[120:121]
	v_and_b32_e32 v101, 0xffff0000, v162
	global_store_dwordx2 v[104:105], v[102:103], off
	v_mul_f32_e32 v103, 0xbfb8aa3b, v101
	v_exp_f32_e32 v103, v103
	v_lshlrev_b32_e32 v104, 16, v163
	v_and_b32_e32 v105, 0xffff0000, v163
	v_add_f32_e32 v102, 1.0, v106
	v_add_f32_e32 v103, 1.0, v103
	v_mul_f32_e32 v106, 0xbfb8aa3b, v104
	v_mul_f32_e32 v107, 0xbfb8aa3b, v105
	v_rcp_f32_e32 v102, v102
	v_rcp_f32_e32 v103, v103
	v_exp_f32_e32 v106, v106
	v_exp_f32_e32 v107, v107
	v_mul_f32_e64 v98, v98, v0
	v_mul_f32_e64 v99, v99, v0
	v_mul_f32_e64 v100, v102, v100
	v_mul_f32_e64 v101, v103, v101
	v_add_f32_e32 v102, 1.0, v106
	v_add_f32_e32 v103, 1.0, v107
	v_rcp_f32_e32 v102, v102
	v_rcp_f32_e32 v103, v103
	v_mul_f32_e64 v98, v70, v98
	v_mul_f32_e64 v99, v71, v99
	v_mul_f32_e64 v96, v96, v0
	v_mul_f32_e64 v97, v97, v0
	v_mul_f32_e64 v98, v100, v98
	v_mul_f32_e64 v99, v101, v99
	v_mul_f32_e64 v96, v72, v96
	v_mul_f32_e64 v97, v73, v97
	v_mul_f32_e64 v100, v102, v104
	v_mul_f32_e64 v101, v103, v105
	v_cvt_pk_bf16_f32 v102, v98, v99
	v_mul_f32_e64 v100, v100, v96
	v_mul_f32_e64 v101, v101, v97
	ds_read_b128 v[96:99], v184 offset:1024
	v_cvt_pk_bf16_f32 v103, v100, v101
	v_lshl_add_u64 v[100:101], s[56:57], 0, v[122:123]
	global_store_dwordx2 v[100:101], v[102:103], off
	ds_read_b128 v[100:103], v184 offset:1040
	s_waitcnt lgkmcnt(1)
	v_mov_b32_e32 v105, v98
	v_lshlrev_b32_e32 v98, 16, v160
	v_mov_b32_e32 v104, v97
	v_mov_b32_e32 v97, v99
	v_and_b32_e32 v99, 0xffff0000, v160
	v_mul_f32_e32 v0, 0xbfb8aa3b, v98
	v_add_f32_e64 v104, v104, v96
	v_add_f32_e64 v105, v105, v97
	v_exp_f32_e32 v0, v0
	v_mul_f32_e32 v97, 0xbfb8aa3b, v99
	s_waitcnt lgkmcnt(0)
	v_mov_b32_e32 v96, v102
	v_exp_f32_e32 v102, v97
	v_lshlrev_b32_e32 v108, 16, v161
	v_mov_b32_e32 v97, v100
	v_add_f32_e32 v0, 1.0, v0
	v_and_b32_e32 v109, 0xffff0000, v161
	v_mul_f32_e32 v100, 0xbfb8aa3b, v108
	v_rcp_f32_e32 v106, v0
	v_add_f32_e32 v0, 1.0, v102
	v_exp_f32_e32 v100, v100
	v_mul_f32_e32 v102, 0xbfb8aa3b, v109
	v_exp_f32_e32 v102, v102
	v_rcp_f32_e32 v107, v0
	v_add_f32_e32 v0, 1.0, v100
	v_rcp_f32_e32 v136, v0
	v_add_f32_e32 v0, 1.0, v102
	v_rcp_f32_e32 v137, v0
	v_mov_b32_e32 v100, v103
	v_add_f32_e64 v138, v96, v100
	v_add_f32_e64 v139, v97, v101
	v_mul_f32_e64 v106, v106, v98
	v_mul_f32_e64 v107, v107, v99
	v_mul_f32_e64 v108, v136, v108
	v_mul_f32_e64 v109, v137, v109
	v_lshlrev_b32_e32 v136, 16, v158
	v_and_b32_e32 v137, 0xffff0000, v158
	v_mul_f32_e32 v0, 0xbfb8aa3b, v136
	v_exp_f32_e32 v0, v0
	v_mul_f32_e32 v96, 0xbfb8aa3b, v137
	v_exp_f32_e32 v96, v96
	v_lshl_add_u64 v[142:143], s[56:57], 0, v[124:125]
	v_add_f32_e32 v0, 1.0, v0
	v_rcp_f32_e32 v144, v0
	v_add_f32_e32 v0, 1.0, v96
	v_rcp_f32_e32 v145, v0
	v_mul_f32_e32 v0, 0xbfb8aa3b, v146
	v_exp_f32_e32 v0, v0
	v_mul_f32_e32 v96, 0xbfb8aa3b, v147
	v_exp_f32_e32 v100, v96
	ds_read_b128 v[96:99], v184 offset:1536
	v_add_f32_e32 v0, 1.0, v0
	v_rcp_f32_e32 v148, v0
	v_add_f32_e32 v0, 1.0, v100
	ds_read_b128 v[100:103], v184 offset:1552
	s_waitcnt lgkmcnt(1)
	v_mov_b32_e32 v152, v97
	v_mov_b32_e32 v153, v98
	v_mov_b32_e32 v97, v99
	v_add_f32_e64 v96, v152, v96
	v_add_f32_e64 v97, v153, v97
	s_waitcnt lgkmcnt(0)
	v_mov_b32_e32 v98, v102
	v_mov_b32_e32 v99, v100
	v_mov_b32_e32 v100, v103
	v_add_f32_e64 v98, v98, v100
	v_add_f32_e64 v99, v99, v101
	v_mov_b32_e32 v100, v96
	v_mov_b32_e32 v101, v104
	v_mov_b32_e32 v104, v97
	v_add_f32_e64 v96, v100, v104
	v_add_f32_e64 v97, v101, v105
	v_mov_b32_e32 v100, v99
	v_mov_b32_e32 v101, v139
	v_add_f32_e64 v96, v96, v100
	v_add_f32_e64 v97, v97, v101
	v_mov_b32_e32 v99, v138
	v_add_f32_e64 v96, v98, v96
	v_add_f32_e64 v97, v99, v97
	v_rcp_f32_e32 v149, v0
	v_fma_f32 v81, v97, s52, v80
	v_fma_f32 v80, v96, s52, v80
	v_mul_f32_e64 v96, v144, v136
	v_mul_f32_e64 v97, v145, v137
	v_mul_f32_e32 v0, 0x4b800000, v81
	v_cmp_gt_f32_e32 vcc, s1, v81
	v_mul_f32_e64 v152, v148, v146
	v_mul_f32_e64 v153, v149, v147
	v_lshl_add_u64 v[168:169], s[56:57], 0, v[126:127]
	v_cndmask_b32_e32 v0, v81, v0, vcc
	v_rsq_f32_e32 v0, v0
	s_add_i32 s75, s75, 1
	s_add_u32 s60, s60, 0xfffa0000
	s_addc_u32 s61, s61, -1
	v_mul_f32_e32 v81, 0x45800000, v0
	v_cndmask_b32_e32 v0, v0, v81, vcc
	v_mul_f32_e64 v90, v90, v0
	v_mul_f32_e64 v91, v91, v0
	v_mul_f32_e64 v94, v94, v0
	v_mul_f32_e64 v95, v95, v0
	v_mul_f32_e64 v90, v74, v90
	v_mul_f32_e64 v91, v75, v91
	v_mul_f32_e64 v94, v76, v94
	v_mul_f32_e64 v95, v77, v95
	v_mul_f32_e64 v90, v106, v90
	v_mul_f32_e64 v91, v107, v91
	v_mul_f32_e64 v94, v108, v94
	v_mul_f32_e64 v95, v109, v95
	v_cvt_pk_bf16_f32 v90, v90, v91
	v_cvt_pk_bf16_f32 v91, v94, v95
	global_store_dwordx2 v[142:143], v[90:91], off
	v_mul_f32_e64 v90, v92, v0
	v_mul_f32_e64 v91, v93, v0
	v_mul_f32_e64 v88, v88, v0
	v_mul_f32_e64 v89, v89, v0
	v_mul_f32_e32 v0, 0x4b800000, v80
	v_cmp_gt_f32_e32 vcc, s1, v80
	v_mul_f32_e64 v90, v70, v90
	v_mul_f32_e64 v91, v71, v91
	v_mul_f32_e64 v224, v72, v88
	v_mul_f32_e64 v225, v73, v89
	v_cndmask_b32_e32 v0, v80, v0, vcc
	v_mul_f32_e64 v108, v96, v90
	v_mul_f32_e64 v109, v97, v91
	ds_read_b64_tr_b16 v[90:91], v213 offset:57408
	ds_read_b64_tr_b16 v[88:89], v213 offset:56320
	ds_read_b64_tr_b16 v[94:95], v210 offset:2112
	ds_read_b64_tr_b16 v[92:93], v210
	ds_read_b64_tr_b16 v[98:99], v210 offset:2144
	ds_read_b64_tr_b16 v[96:97], v210 offset:32
	ds_read_b64_tr_b16 v[100:101], v213 offset:56352
	ds_read_b64_tr_b16 v[104:105], v213 offset:56384
	ds_read_b64_tr_b16 v[136:137], v213 offset:56416
	ds_read_b64_tr_b16 v[102:103], v213 offset:57440
	ds_read_b64_tr_b16 v[106:107], v213 offset:57472
	ds_read_b64_tr_b16 v[138:139], v213 offset:57504
	v_rsq_f32_e32 v0, v0
	ds_read_b64_tr_b16 v[142:143], v213 offset:65024
	ds_read_b64_tr_b16 v[144:145], v214 offset:57408
	ds_read_b64_tr_b16 v[146:147], v210 offset:16896
	ds_read_b64_tr_b16 v[148:149], v210 offset:19008
	ds_read_b64_tr_b16 v[158:159], v210 offset:19040
	ds_read_b64_tr_b16 v[156:157], v210 offset:16928
	s_waitcnt lgkmcnt(8)
	v_mfma_f32_16x16x32_bf16 v[10:13], v[100:103], v[92:95], v[10:13]
	v_and_b32_e32 v81, 0xffff0000, v150
	v_mul_f32_e32 v80, 0x45800000, v0
	v_cndmask_b32_e32 v0, v0, v80, vcc
	v_mfma_f32_16x16x32_bf16 v[18:21], v[100:103], v[96:99], v[18:21]
	v_lshlrev_b32_e32 v80, 16, v150
	v_mul_f32_e32 v100, 0xbfb8aa3b, v80
	v_mul_f32_e32 v101, 0xbfb8aa3b, v81
	v_mfma_f32_16x16x32_bf16 v[30:33], v[88:91], v[92:95], v[30:33]
	v_exp_f32_e32 v100, v100
	v_mul_f32_e64 v86, v86, v0
	v_mul_f32_e64 v87, v87, v0
	v_mul_f32_e64 v152, v152, v224
	v_mul_f32_e64 v153, v153, v225
	v_mfma_f32_16x16x32_bf16 v[6:9], v[88:91], v[96:99], v[6:9]
	ds_read_b64_tr_b16 v[88:89], v213 offset:65056
	ds_read_b64_tr_b16 v[160:161], v213 offset:65088
	ds_read_b64_tr_b16 v[164:165], v213 offset:65120
	ds_read_b64_tr_b16 v[90:91], v214 offset:57440
	ds_read_b64_tr_b16 v[162:163], v214 offset:57472
	ds_read_b64_tr_b16 v[166:167], v214 offset:57504
	v_mul_f32_e64 v74, v74, v86
	v_mul_f32_e64 v75, v75, v87
	v_lshlrev_b32_e32 v86, 16, v151
	s_waitcnt lgkmcnt(2)
	v_mfma_f32_16x16x32_bf16 v[10:13], v[88:91], v[146:149], v[10:13]
	v_mul_f32_e32 v87, 0xbfb8aa3b, v86
	v_cvt_pk_bf16_f32 v108, v108, v109
	v_cvt_pk_bf16_f32 v109, v152, v153
	v_mfma_f32_16x16x32_bf16 v[18:21], v[88:91], v[156:159], v[18:21]
	v_exp_f32_e32 v89, v101
	v_add_f32_e32 v88, 1.0, v100
	v_rcp_f32_e32 v88, v88
	global_store_dwordx2 v[168:169], v[108:109], off
	v_add_f32_e32 v89, 1.0, v89
	v_rcp_f32_e32 v89, v89
	v_mfma_f32_16x16x32_bf16 v[14:17], v[104:107], v[92:95], v[14:17]
	v_mul_f32_e64 v82, v82, v0
	v_mul_f32_e64 v83, v83, v0
	v_mul_f32_e64 v78, v78, v0
	v_mul_f32_e64 v79, v79, v0
	v_mul_f32_e64 v80, v88, v80
	v_mul_f32_e64 v81, v89, v81
	v_exp_f32_e32 v88, v87
	v_mul_f32_e64 v80, v80, v74
	v_mul_f32_e64 v81, v81, v75
	v_and_b32_e32 v87, 0xffff0000, v151
	v_mfma_f32_16x16x32_bf16 v[26:29], v[104:107], v[96:99], v[26:29]
	v_add_f32_e32 v74, 1.0, v88
	v_rcp_f32_e32 v88, v74
	v_mul_f32_e32 v74, 0xbfb8aa3b, v87
	v_exp_f32_e32 v89, v74
	v_mul_f32_e64 v74, v84, v0
	v_mul_f32_e64 v75, v85, v0
	v_mfma_f32_16x16x32_bf16 v[38:41], v[136:139], v[92:95], v[38:41]
	v_mul_f32_e64 v108, v76, v74
	v_mul_f32_e64 v109, v77, v75
	v_add_f32_e32 v74, 1.0, v89
	v_rcp_f32_e32 v89, v74
	ds_read_b64_tr_b16 v[74:75], v213 offset:56448
	ds_read_b64_tr_b16 v[76:77], v213 offset:57536
	v_mfma_f32_16x16x32_bf16 v[50:53], v[136:139], v[96:99], v[50:53]
	v_cvt_pk_bf16_f32 v80, v80, v81
	v_mul_f32_e64 v136, v88, v86
	v_mul_f32_e64 v137, v89, v87
	ds_read_b64_tr_b16 v[84:85], v213 offset:56480
	ds_read_b64_tr_b16 v[88:89], v213 offset:56512
	ds_read_b64_tr_b16 v[100:101], v213 offset:56544
	ds_read_b64_tr_b16 v[86:87], v213 offset:57568
	ds_read_b64_tr_b16 v[90:91], v213 offset:57600
	ds_read_b64_tr_b16 v[102:103], v213 offset:57632
	ds_read_b64_tr_b16 v[104:105], v213 offset:65152
	ds_read_b64_tr_b16 v[106:107], v214 offset:57536
	s_waitcnt lgkmcnt(8)
	v_mfma_f32_16x16x32_bf16 v[22:25], v[74:77], v[92:95], v[22:25]
	v_mul_f32_e64 v108, v136, v108
	v_mul_f32_e64 v109, v137, v109
	v_mul_f32_e64 v70, v70, v82
	v_mul_f32_e64 v71, v71, v83
	v_cvt_pk_bf16_f32 v81, v108, v109
	v_mfma_f32_16x16x32_bf16 v[34:37], v[74:77], v[96:99], v[34:37]
	v_lshl_add_u64 v[108:109], s[56:57], 0, v[128:129]
	v_mul_f32_e64 v72, v72, v78
	v_mul_f32_e64 v73, v73, v79
	v_lshl_add_u32 v0, s67, 9, v179
	v_mfma_f32_16x16x32_bf16 v[30:33], v[142:145], v[146:149], v[30:33]
	s_sub_i32 s54, s54, 64
	v_mfma_f32_16x16x32_bf16 v[6:9], v[142:145], v[156:159], v[6:9]
	ds_read_b64_tr_b16 v[74:75], v213 offset:65184
	ds_read_b64_tr_b16 v[136:137], v213 offset:65216
	ds_read_b64_tr_b16 v[142:143], v213 offset:65248
	ds_read_b64_tr_b16 v[76:77], v214 offset:57568
	ds_read_b64_tr_b16 v[138:139], v214 offset:57600
	ds_read_b64_tr_b16 v[144:145], v214 offset:57632
	global_store_dwordx2 v[108:109], v[80:81], off
	v_lshlrev_b32_e32 v80, 16, v140
	v_and_b32_e32 v81, 0xffff0000, v140
	s_waitcnt lgkmcnt(6)
	v_mfma_f32_16x16x32_bf16 v[22:25], v[104:107], v[146:149], v[22:25]
	v_mfma_f32_16x16x32_bf16 v[34:37], v[104:107], v[156:159], v[34:37]
	v_mul_f32_e32 v104, 0xbfb8aa3b, v80
	v_mul_f32_e32 v105, 0xbfb8aa3b, v81
	v_exp_f32_e32 v104, v104
	v_mfma_f32_16x16x32_bf16 v[42:45], v[84:87], v[92:95], v[42:45]
	v_mfma_f32_16x16x32_bf16 v[54:57], v[84:87], v[96:99], v[54:57]
	v_exp_f32_e32 v85, v105
	v_add_f32_e32 v84, 1.0, v104
	v_rcp_f32_e32 v84, v84
	s_waitcnt lgkmcnt(2)
	v_mfma_f32_16x16x32_bf16 v[42:45], v[74:77], v[146:149], v[42:45]
	v_add_f32_e32 v85, 1.0, v85
	v_rcp_f32_e32 v85, v85
	v_mfma_f32_16x16x32_bf16 v[54:57], v[74:77], v[156:159], v[54:57]
	v_mul_f32_e64 v74, v84, v80
	v_mul_f32_e64 v75, v85, v81
	v_mul_f32_e64 v70, v74, v70
	v_mul_f32_e64 v71, v75, v71
	v_lshlrev_b32_e32 v74, 16, v141
	v_and_b32_e32 v75, 0xffff0000, v141
	v_mul_f32_e32 v76, 0xbfb8aa3b, v74
	v_mul_f32_e32 v77, 0xbfb8aa3b, v75
	v_exp_f32_e32 v76, v76
	v_exp_f32_e32 v77, v77
	v_cvt_pk_bf16_f32 v78, v70, v71
	v_lshl_add_u64 v[80:81], s[56:57], 0, v[130:131]
	v_add_f32_e32 v76, 1.0, v76
	v_add_f32_e32 v77, 1.0, v77
	v_rcp_f32_e32 v76, v76
	v_rcp_f32_e32 v77, v77
	v_mfma_f32_16x16x32_bf16 v[14:17], v[160:163], v[146:149], v[14:17]
	s_add_u32 s56, s56, 0xfffe0000
	s_addc_u32 s57, s57, -1
	v_mul_f32_e64 v74, v76, v74
	v_mul_f32_e64 v75, v77, v75
	v_mfma_f32_16x16x32_bf16 v[26:29], v[160:163], v[156:159], v[26:29]
	v_mul_f32_e64 v74, v74, v72
	v_mul_f32_e64 v75, v75, v73
	ds_read_b128 v[70:73], v0 offset:4096
	v_cvt_pk_bf16_f32 v79, v74, v75
	ds_read_b128 v[74:77], v0 offset:4160
	global_store_dwordx2 v[80:81], v[78:79], off
	v_mfma_f32_16x16x32_bf16 v[38:41], v[164:167], v[146:149], v[38:41]
	s_waitcnt lgkmcnt(1)
	v_mul_f32_e32 v70, 0x3fb8aa3b, v70
	v_exp_f32_e32 v82, v70
	v_mul_f32_e32 v83, 0x3fb8aa3b, v71
	v_mul_f32_e32 v70, 0x3fb8aa3b, v72
	v_mul_f32_e32 v71, 0x3fb8aa3b, v73
	v_exp_f32_e32 v70, v70
	v_exp_f32_e32 v71, v71
	v_exp_f32_e32 v83, v83
	v_mfma_f32_16x16x32_bf16 v[50:53], v[164:167], v[156:159], v[50:53]
	s_add_u32 s58, s58, 0xfffe0000
	v_mul_f32_e64 v32, v32, v70
	v_mul_f32_e64 v33, v33, v71
	v_mul_f32_e64 v8, v8, v70
	v_mul_f32_e64 v9, v9, v71
	s_waitcnt lgkmcnt(0)
	v_mul_f32_e32 v70, 0x3fb8aa3b, v74
	v_mul_f32_e32 v71, 0x3fb8aa3b, v76
	v_exp_f32_e32 v78, v70
	v_mul_f32_e32 v70, 0x3fb8aa3b, v75
	v_exp_f32_e32 v80, v71
	v_mul_f32_e32 v71, 0x3fb8aa3b, v77
	v_exp_f32_e32 v81, v71
	v_exp_f32_e32 v79, v70
	ds_read_b128 v[70:73], v0 offset:4224
	ds_read_b128 v[74:77], v0 offset:4288
	v_mul_f32_e64 v30, v30, v82
	v_mul_f32_e64 v31, v31, v83
	v_mul_f32_e64 v6, v6, v82
	v_mul_f32_e64 v7, v7, v83
	v_mul_f32_e64 v12, v12, v80
	v_mul_f32_e64 v13, v13, v81
	s_waitcnt lgkmcnt(1)
	v_mul_f32_e32 v70, 0x3fb8aa3b, v70
	v_exp_f32_e32 v82, v70
	v_mul_f32_e32 v83, 0x3fb8aa3b, v71
	v_mul_f32_e32 v70, 0x3fb8aa3b, v72
	v_mul_f32_e32 v71, 0x3fb8aa3b, v73
	v_exp_f32_e32 v70, v70
	v_exp_f32_e32 v71, v71
	v_mul_f32_e64 v10, v10, v78
	v_mul_f32_e64 v11, v11, v79
	v_mul_f32_e64 v20, v20, v80
	v_mul_f32_e64 v21, v21, v81
	v_mul_f32_e64 v18, v18, v78
	v_mul_f32_e64 v19, v19, v79
	v_mul_f32_e64 v16, v16, v70
	v_mul_f32_e64 v17, v17, v71
	v_mul_f32_e64 v28, v28, v70
	v_mul_f32_e64 v29, v29, v71
	s_waitcnt lgkmcnt(0)
	v_mul_f32_e32 v70, 0x3fb8aa3b, v74
	v_mul_f32_e32 v71, 0x3fb8aa3b, v76
	v_exp_f32_e32 v78, v70
	v_mul_f32_e32 v70, 0x3fb8aa3b, v75
	v_exp_f32_e32 v80, v71
	v_mul_f32_e32 v71, 0x3fb8aa3b, v77
	v_exp_f32_e32 v81, v71
	v_exp_f32_e32 v79, v70
	ds_read_b128 v[70:73], v0 offset:4352
	ds_read_b128 v[74:77], v0 offset:4416
	v_exp_f32_e32 v83, v83
	v_mul_f32_e64 v40, v40, v80
	v_mul_f32_e64 v41, v41, v81
	v_mul_f32_e64 v38, v38, v78
	v_mul_f32_e64 v39, v39, v79
	s_waitcnt lgkmcnt(1)
	v_mul_f32_e32 v70, 0x3fb8aa3b, v70
	v_mul_f32_e64 v14, v14, v82
	v_mul_f32_e64 v15, v15, v83
	v_mul_f32_e64 v26, v26, v82
	v_mul_f32_e64 v27, v27, v83
	v_exp_f32_e32 v82, v70
	v_mul_f32_e32 v83, 0x3fb8aa3b, v71
	v_mul_f32_e32 v70, 0x3fb8aa3b, v72
	v_mul_f32_e32 v71, 0x3fb8aa3b, v73
	v_exp_f32_e32 v70, v70
	v_exp_f32_e32 v71, v71
	v_mul_f32_e64 v52, v52, v80
	v_mul_f32_e64 v53, v53, v81
	v_mul_f32_e64 v50, v50, v78
	v_mul_f32_e64 v51, v51, v79
	v_mfma_f32_16x16x32_bf16 v[46:49], v[88:91], v[92:95], v[46:49]
	v_mul_f32_e64 v24, v24, v70
	v_mul_f32_e64 v25, v25, v71
	v_mul_f32_e64 v36, v36, v70
	v_mul_f32_e64 v37, v37, v71
	s_waitcnt lgkmcnt(0)
	v_mul_f32_e32 v70, 0x3fb8aa3b, v74
	v_mul_f32_e32 v71, 0x3fb8aa3b, v76
	v_exp_f32_e32 v78, v70
	v_mul_f32_e32 v70, 0x3fb8aa3b, v75
	v_exp_f32_e32 v80, v71
	v_mul_f32_e32 v71, 0x3fb8aa3b, v77
	v_exp_f32_e32 v81, v71
	v_exp_f32_e32 v79, v70
	ds_read_b128 v[70:73], v0 offset:4480
	ds_read_b128 v[74:77], v0 offset:4544
	v_mfma_f32_16x16x32_bf16 v[62:65], v[88:91], v[96:99], v[62:65]
	v_exp_f32_e32 v83, v83
	s_addc_u32 s59, s59, -1
	s_waitcnt lgkmcnt(1)
	v_mul_f32_e32 v0, 0x3fb8aa3b, v70
	v_exp_f32_e32 v70, v0
	v_mul_f32_e32 v0, 0x3fb8aa3b, v71
	v_mul_f32_e32 v71, 0x3fb8aa3b, v72
	v_mfma_f32_16x16x32_bf16 v[58:61], v[100:103], v[92:95], v[58:61]
	v_exp_f32_e32 v72, v71
	v_mul_f32_e32 v71, 0x3fb8aa3b, v73
	v_exp_f32_e32 v73, v71
	v_mfma_f32_16x16x32_bf16 v[66:69], v[100:103], v[96:99], v[66:69]
	v_exp_f32_e32 v71, v0
	s_waitcnt lgkmcnt(0)
	v_mul_f32_e32 v0, 0x3fb8aa3b, v74
	v_exp_f32_e32 v74, v0
	v_mul_f32_e32 v0, 0x3fb8aa3b, v75
	v_mul_f32_e32 v75, 0x3fb8aa3b, v76
	v_exp_f32_e32 v76, v75
	v_mul_f32_e32 v75, 0x3fb8aa3b, v77
	v_mfma_f32_16x16x32_bf16 v[46:49], v[136:139], v[146:149], v[46:49]
	v_exp_f32_e32 v77, v75
	v_exp_f32_e32 v75, v0
	v_mul_f32_e64 v22, v22, v82
	v_mul_f32_e64 v23, v23, v83
	v_mfma_f32_16x16x32_bf16 v[62:65], v[136:139], v[156:159], v[62:65]
	v_mul_f32_e64 v34, v34, v82
	v_mul_f32_e64 v35, v35, v83
	v_mul_f32_e64 v44, v44, v80
	v_mul_f32_e64 v45, v45, v81
	v_mul_f32_e64 v42, v42, v78
	v_mul_f32_e64 v43, v43, v79
	v_mfma_f32_16x16x32_bf16 v[58:61], v[142:145], v[146:149], v[58:61]
	v_mul_f32_e64 v56, v56, v80
	v_mul_f32_e64 v57, v57, v81
	v_mul_f32_e64 v54, v54, v78
	v_mul_f32_e64 v55, v55, v79
	v_mul_f32_e64 v48, v48, v72
	v_mul_f32_e64 v49, v49, v73
	v_mfma_f32_16x16x32_bf16 v[66:69], v[142:145], v[156:159], v[66:69]
	v_mul_f32_e64 v46, v46, v70
	v_mul_f32_e64 v47, v47, v71
	v_mul_f32_e64 v64, v64, v72
	v_mul_f32_e64 v65, v65, v73
	v_mul_f32_e64 v62, v62, v70
	v_mul_f32_e64 v63, v63, v71
	v_mul_f32_e64 v60, v60, v76
	v_mul_f32_e64 v61, v61, v77
	v_mul_f32_e64 v58, v58, v74
	v_mul_f32_e64 v59, v59, v75
	s_nop 1
	v_mul_f32_e64 v68, v68, v76
	v_mul_f32_e64 v69, v69, v77
	s_cmp_lg_u32 s75, 8
	v_mul_f32_e64 v66, v66, v74
	v_mul_f32_e64 v67, v67, v75
	s_cbranch_scc0 .LBB0_654

.LBB0_689:
	ds_read_b128 v[102:105], v201 offset:6144
	ds_read_b128 v[106:109], v201 offset:6160
	s_waitcnt vmcnt(6)
	v_lshlrev_b32_e32 v138, 16, v98
	v_and_b32_e32 v139, 0xffff0000, v98
	s_waitcnt lgkmcnt(1)
	v_mul_f32_e32 v0, 0xbfb8aa3b, v102
	v_exp_f32_e32 v136, v0
	v_mul_f32_e32 v0, 0xbfb8aa3b, v103
	v_exp_f32_e32 v137, v0
	v_mul_f32_e32 v0, 0xbfb8aa3b, v104
	v_mul_f32_e64 v136, v136, v138
	v_mul_f32_e64 v137, v137, v139
	s_nop 0
	v_cvt_pk_bf16_f32 v98, v136, v137
	v_exp_f32_e32 v136, v0
	v_mul_f32_e32 v0, 0xbfb8aa3b, v105
	v_exp_f32_e32 v137, v0
	v_lshlrev_b32_e32 v138, 16, v99
	v_and_b32_e32 v139, 0xffff0000, v99
	s_waitcnt lgkmcnt(0)
	v_mul_f32_e32 v0, 0xbfb8aa3b, v106
	v_mul_f32_e64 v136, v136, v138
	v_mul_f32_e64 v137, v137, v139
	v_lshlrev_b32_e32 v138, 16, v100
	v_cvt_pk_bf16_f32 v99, v136, v137
	v_exp_f32_e32 v136, v0
	v_mul_f32_e32 v0, 0xbfb8aa3b, v107
	v_exp_f32_e32 v137, v0
	v_and_b32_e32 v139, 0xffff0000, v100
	v_mul_f32_e32 v0, 0xbfb8aa3b, v108
	v_mul_f32_e64 v136, v136, v138
	v_mul_f32_e64 v137, v137, v139
	s_nop 0
	v_cvt_pk_bf16_f32 v100, v136, v137
	v_exp_f32_e32 v136, v0
	v_mul_f32_e32 v0, 0xbfb8aa3b, v109
	v_exp_f32_e32 v137, v0
	v_lshlrev_b32_e32 v138, 16, v101
	v_and_b32_e32 v139, 0xffff0000, v101
	v_mul_f32_e32 v0, 0x3fb8aa3b, v102
	v_mul_f32_e64 v136, v136, v138
	v_mul_f32_e64 v137, v137, v139
	s_nop 0
	v_cvt_pk_bf16_f32 v101, v136, v137
	ds_write_b128 v181, v[98:101] offset:56320
	v_exp_f32_e32 v98, v0
	v_mul_f32_e32 v0, 0x3fb8aa3b, v103
	v_exp_f32_e32 v99, v0
	v_lshlrev_b32_e32 v100, 16, v94
	v_and_b32_e32 v101, 0xffff0000, v94
	v_mul_f32_e32 v0, 0x3fb8aa3b, v104
	v_mul_f32_e64 v98, v98, s50
	v_mul_f32_e64 v99, v99, s50
	s_waitcnt vmcnt(4)
	v_lshlrev_b32_e32 v104, 16, v90
	v_mul_f32_e64 v98, v98, v100
	v_mul_f32_e64 v99, v99, v101
	v_lshlrev_b32_e32 v100, 16, v95
	v_cvt_pk_bf16_f32 v94, v98, v99
	v_exp_f32_e32 v98, v0
	v_mul_f32_e32 v0, 0x3fb8aa3b, v105
	v_exp_f32_e32 v99, v0
	v_and_b32_e32 v101, 0xffff0000, v95
	v_mul_f32_e32 v0, 0x3fb8aa3b, v106
	v_and_b32_e32 v105, 0xffff0000, v90
	v_mul_f32_e64 v98, v98, s50
	v_mul_f32_e64 v99, v99, s50
	s_nop 0
	v_mul_f32_e64 v98, v98, v100
	v_mul_f32_e64 v99, v99, v101
	v_lshlrev_b32_e32 v100, 16, v96
	v_cvt_pk_bf16_f32 v95, v98, v99
	v_exp_f32_e32 v98, v0
	v_mul_f32_e32 v0, 0x3fb8aa3b, v107
	v_exp_f32_e32 v99, v0
	v_and_b32_e32 v101, 0xffff0000, v96
	v_mul_f32_e32 v0, 0x3fb8aa3b, v108
	v_mul_f32_e64 v98, v98, s50
	v_mul_f32_e64 v99, v99, s50
	s_nop 0
	v_mul_f32_e64 v98, v98, v100
	v_mul_f32_e64 v99, v99, v101
	v_lshlrev_b32_e32 v100, 16, v97
	v_cvt_pk_bf16_f32 v96, v98, v99
	v_exp_f32_e32 v98, v0
	v_mul_f32_e32 v0, 0x3fb8aa3b, v109
	v_exp_f32_e32 v99, v0
	v_and_b32_e32 v101, 0xffff0000, v97
	v_mul_f32_e64 v98, v98, s50
	v_mul_f32_e64 v99, v99, s50
	s_nop 0
	v_mul_f32_e64 v98, v98, v100
	v_mul_f32_e64 v99, v99, v101
	s_nop 0
	v_cvt_pk_bf16_f32 v97, v98, v99
	ds_write_b128 v181, v[94:97] offset:38912
	ds_read_b128 v[94:97], v202 offset:6144
	ds_read_b128 v[98:101], v202 offset:6160
	s_waitcnt lgkmcnt(1)
	v_mul_f32_e32 v0, 0xbfb8aa3b, v94
	v_exp_f32_e32 v102, v0
	v_mul_f32_e32 v0, 0xbfb8aa3b, v95
	v_exp_f32_e32 v103, v0
	v_mul_f32_e32 v0, 0xbfb8aa3b, v96
	v_mul_f32_e64 v102, v102, v104
	v_mul_f32_e64 v103, v103, v105
	s_nop 0
	v_cvt_pk_bf16_f32 v90, v102, v103
	v_exp_f32_e32 v102, v0
	v_mul_f32_e32 v0, 0xbfb8aa3b, v97
	v_exp_f32_e32 v103, v0
	v_lshlrev_b32_e32 v104, 16, v91
	v_and_b32_e32 v105, 0xffff0000, v91
	s_waitcnt lgkmcnt(0)
	v_mul_f32_e32 v0, 0xbfb8aa3b, v98
	v_mul_f32_e64 v102, v102, v104
	v_mul_f32_e64 v103, v103, v105
	v_lshlrev_b32_e32 v104, 16, v92
	v_cvt_pk_bf16_f32 v91, v102, v103
	v_exp_f32_e32 v102, v0
	v_mul_f32_e32 v0, 0xbfb8aa3b, v99
	v_exp_f32_e32 v103, v0
	v_and_b32_e32 v105, 0xffff0000, v92
	v_mul_f32_e32 v0, 0xbfb8aa3b, v100
	v_mul_f32_e64 v102, v102, v104
	v_mul_f32_e64 v103, v103, v105
	s_nop 0
	v_cvt_pk_bf16_f32 v92, v102, v103
	v_exp_f32_e32 v102, v0
	v_mul_f32_e32 v0, 0xbfb8aa3b, v101
	v_exp_f32_e32 v103, v0
	v_lshlrev_b32_e32 v104, 16, v93
	v_and_b32_e32 v105, 0xffff0000, v93
	v_mul_f32_e32 v0, 0x3fb8aa3b, v94
	v_mul_f32_e64 v102, v102, v104
	v_mul_f32_e64 v103, v103, v105
	s_nop 0
	v_cvt_pk_bf16_f32 v93, v102, v103
	ds_write_b128 v182, v[90:93] offset:56320
	v_exp_f32_e32 v90, v0
	v_mul_f32_e32 v0, 0x3fb8aa3b, v95
	v_exp_f32_e32 v91, v0
	v_lshlrev_b32_e32 v92, 16, v70
	v_and_b32_e32 v93, 0xffff0000, v70
	v_mul_f32_e32 v0, 0x3fb8aa3b, v96
	v_mul_f32_e64 v90, v90, s50
	v_mul_f32_e64 v91, v91, s50
	s_nop 0
	v_mul_f32_e64 v90, v90, v92
	v_mul_f32_e64 v91, v91, v93
	v_lshlrev_b32_e32 v92, 16, v71
	v_cvt_pk_bf16_f32 v70, v90, v91
	v_exp_f32_e32 v90, v0
	v_mul_f32_e32 v0, 0x3fb8aa3b, v97
	v_exp_f32_e32 v91, v0
	v_and_b32_e32 v93, 0xffff0000, v71
	v_mul_f32_e32 v0, 0x3fb8aa3b, v98
	v_mul_f32_e64 v90, v90, s50
	v_mul_f32_e64 v91, v91, s50
	s_nop 0
	v_mul_f32_e64 v90, v90, v92
	v_mul_f32_e64 v91, v91, v93
	v_lshlrev_b32_e32 v92, 16, v72
	v_cvt_pk_bf16_f32 v71, v90, v91
	v_exp_f32_e32 v90, v0
	v_mul_f32_e32 v0, 0x3fb8aa3b, v99
	v_exp_f32_e32 v91, v0
	v_and_b32_e32 v93, 0xffff0000, v72
	v_mul_f32_e32 v0, 0x3fb8aa3b, v100
	v_mul_f32_e64 v90, v90, s50
	v_mul_f32_e64 v91, v91, s50
	s_nop 0
	v_mul_f32_e64 v90, v90, v92
	v_mul_f32_e64 v91, v91, v93
	v_lshlrev_b32_e32 v92, 16, v73
	v_cvt_pk_bf16_f32 v72, v90, v91
	v_exp_f32_e32 v90, v0
	v_mul_f32_e32 v0, 0x3fb8aa3b, v101
	v_exp_f32_e32 v91, v0
	v_and_b32_e32 v93, 0xffff0000, v73
	v_mul_f32_e64 v90, v90, s50
	v_mul_f32_e64 v91, v91, s50
	s_nop 0
	v_mul_f32_e64 v90, v90, v92
	v_mul_f32_e64 v91, v91, v93
	s_nop 0
	v_cvt_pk_bf16_f32 v73, v90, v91
	ds_write_b128 v182, v[70:73] offset:38912
	s_waitcnt vmcnt(3)
	ds_write_b128 v203, v[74:77]
	s_waitcnt vmcnt(2)
	ds_write_b128 v204, v[78:81]
	s_waitcnt vmcnt(1)
	ds_write_b128 v203, v[82:85] offset:16896
	s_waitcnt vmcnt(0)
	ds_write_b128 v205, v[86:89]
	v_lshl_add_u64 v[70:71], s[58:59], 0, v[116:117]
	v_lshl_add_u64 v[72:73], s[58:59], 0, v[120:121]
	v_lshl_add_u64 v[74:75], s[58:59], 0, v[122:123]
	global_load_dwordx2 v[156:157], v[70:71], off
	global_load_dwordx2 v[152:153], v[70:71], off offset:32
	global_load_dwordx2 v[148:149], v[72:73], off
	global_load_dwordx2 v[146:147], v[74:75], off
	v_lshl_add_u64 v[70:71], s[58:59], 0, v[124:125]
	v_lshl_add_u64 v[72:73], s[58:59], 0, v[126:127]
	v_lshl_add_u64 v[74:75], s[58:59], 0, v[128:129]
	v_lshl_add_u64 v[76:77], s[58:59], 0, v[130:131]
	global_load_dwordx2 v[144:145], v[70:71], off
	global_load_dwordx2 v[142:143], v[72:73], off
	global_load_dwordx2 v[138:139], v[74:75], off
	global_load_dwordx2 v[136:137], v[76:77], off
	s_waitcnt lgkmcnt(0)
	s_barrier
	ds_read_b128 v[70:73], v206 offset:56320
	ds_read_b128 v[74:77], v180 offset:38912
	ds_read_b128 v[78:81], v206 offset:56384
	ds_read_b128 v[82:85], v180 offset:38976
	s_waitcnt lgkmcnt(2)
	v_mfma_f32_16x16x32_bf16 v[70:73], v[70:73], v[74:77], 0
	v_mov_b32_e32 v0, s49
	v_cvt_pk_bf16_f32 v166, v62, v63
	v_cvt_pk_bf16_f32 v167, v64, v65
	s_waitcnt lgkmcnt(0)
	v_mfma_f32_16x16x32_bf16 v[70:73], v[78:81], v[82:85], v[70:73]
	ds_read_b128 v[78:81], v206 offset:56448
	ds_read_b128 v[86:89], v180 offset:39040
	v_cvt_pk_bf16_f32 v168, v66, v67
	v_cvt_pk_bf16_f32 v169, v68, v69
	s_waitcnt lgkmcnt(0)
	v_mfma_f32_16x16x32_bf16 v[70:73], v[78:81], v[86:89], v[70:73]
	ds_read_b128 v[78:81], v206 offset:56512
	ds_read_b128 v[90:93], v180 offset:39104
	s_add_u32 s55, s72, s68
	s_addc_u32 s63, s73, 0
	s_waitcnt lgkmcnt(0)
	v_mfma_f32_16x16x32_bf16 v[70:73], v[78:81], v[90:93], v[70:73]
	s_add_u32 s62, s55, 0xafc1000
	s_addc_u32 s63, s63, 0
	s_waitcnt vmcnt(7)
	v_lshlrev_b32_e32 v224, 16, v156
	s_nop 3
	v_cndmask_b32_e64 v0, v70, v0, s[14:15]
	v_cndmask_b32_e64 v70, v71, 0, s[30:31]
	v_cndmask_b32_e64 v71, v72, 0, s[34:35]
	v_cndmask_b32_e64 v72, v73, 0, s[36:37]
	v_cvt_pk_bf16_f32 v70, v0, v70
	v_cvt_pk_bf16_f32 v71, v71, v72
	ds_write_b64 v207, v[70:71]
	ds_read_b128 v[70:73], v208 offset:56320
	s_waitcnt lgkmcnt(0)
	v_mfma_f32_16x16x32_bf16 v[70:73], v[70:73], v[74:77], 0
	ds_read_b128 v[74:77], v208 offset:56384
	v_mov_b32_e32 v0, s49
	v_and_b32_e32 v225, 0xffff0000, v156
	s_waitcnt lgkmcnt(0)
	v_mfma_f32_16x16x32_bf16 v[70:73], v[74:77], v[82:85], v[70:73]
	ds_read_b128 v[74:77], v208 offset:56448
	v_lshlrev_b32_e32 v156, 16, v157
	v_and_b32_e32 v157, 0xffff0000, v157
	s_waitcnt lgkmcnt(0)
	v_mfma_f32_16x16x32_bf16 v[70:73], v[74:77], v[86:89], v[70:73]
	ds_read_b128 v[74:77], v208 offset:56512
	s_waitcnt vmcnt(6)
	v_lshlrev_b32_e32 v226, 16, v152
	v_and_b32_e32 v227, 0xffff0000, v152
	s_waitcnt lgkmcnt(0)
	v_mfma_f32_16x16x32_bf16 v[70:73], v[74:77], v[90:93], v[70:73]
	v_lshlrev_b32_e32 v152, 16, v153
	v_and_b32_e32 v153, 0xffff0000, v153
	s_nop 5
	v_cndmask_b32_e64 v0, v70, v0, s[22:23]
	v_cndmask_b32_e64 v70, v71, 0, s[38:39]
	v_cndmask_b32_e64 v71, v72, 0, s[40:41]
	v_cndmask_b32_e64 v72, v73, 0, s[42:43]
	v_cvt_pk_bf16_f32 v70, v0, v70
	v_cvt_pk_bf16_f32 v71, v71, v72
	ds_write_b64 v209, v[70:71]
	s_waitcnt lgkmcnt(0)
	s_barrier
	ds_read_b64_tr_b16 v[72:73], v210 offset:2112
	ds_read_b64_tr_b16 v[70:71], v210
	ds_read_b64_tr_b16 v[74:75], v210 offset:32
	ds_read_b64_tr_b16 v[78:79], v210 offset:16896
	ds_read_b64_tr_b16 v[80:81], v210 offset:19008
	ds_read_b64_tr_b16 v[76:77], v210 offset:2144
	ds_read_b64_tr_b16 v[82:83], v210 offset:16928
	ds_read_b64_tr_b16 v[84:85], v210 offset:19040
	ds_read_b128 v[86:89], v211
	ds_read_b128 v[94:97], v211 offset:64
	ds_read_b128 v[102:105], v211 offset:2368
	s_waitcnt lgkmcnt(2)
	v_mfma_f32_16x16x32_bf16 v[90:93], v[70:73], v[86:89], 0
	ds_read_b128 v[158:161], v211 offset:4672
	v_mfma_f32_16x16x32_bf16 v[86:89], v[74:77], v[86:89], 0
	s_waitcnt lgkmcnt(2)
	v_mfma_f32_16x16x32_bf16 v[90:93], v[78:81], v[94:97], v[90:93]
	v_mfma_f32_16x16x32_bf16 v[86:89], v[82:85], v[94:97], v[86:89]
	ds_read_b128 v[94:97], v211 offset:2304
	s_waitcnt lgkmcnt(0)
	v_mfma_f32_16x16x32_bf16 v[98:101], v[70:73], v[94:97], 0
	v_mfma_f32_16x16x32_bf16 v[94:97], v[74:77], v[94:97], 0
	v_mfma_f32_16x16x32_bf16 v[98:101], v[78:81], v[102:105], v[98:101]
	v_mfma_f32_16x16x32_bf16 v[94:97], v[82:85], v[102:105], v[94:97]
	ds_read_b128 v[102:105], v211 offset:4608
	s_waitcnt lgkmcnt(0)
	v_mfma_f32_16x16x32_bf16 v[106:109], v[70:73], v[102:105], 0
	v_mfma_f32_16x16x32_bf16 v[102:105], v[74:77], v[102:105], 0
	v_mfma_f32_16x16x32_bf16 v[106:109], v[78:81], v[158:161], v[106:109]
	v_mfma_f32_16x16x32_bf16 v[102:105], v[82:85], v[158:161], v[102:105]
	ds_read_b128 v[158:161], v211 offset:6912
	s_waitcnt lgkmcnt(0)
	v_mfma_f32_16x16x32_bf16 v[70:73], v[70:73], v[158:161], 0
	v_mfma_f32_16x16x32_bf16 v[74:77], v[74:77], v[158:161], 0
	ds_read_b128 v[158:161], v211 offset:6976
	s_waitcnt lgkmcnt(0)
	v_mfma_f32_16x16x32_bf16 v[70:73], v[78:81], v[158:161], v[70:73]
	v_cvt_pk_bf16_f32 v78, v30, v31
	v_cvt_pk_bf16_f32 v79, v32, v33
	v_cvt_pk_bf16_f32 v80, v10, v11
	v_mfma_f32_16x16x32_bf16 v[74:77], v[82:85], v[158:161], v[74:77]
	v_cvt_pk_bf16_f32 v81, v12, v13
	v_cvt_pk_bf16_f32 v82, v6, v7
	v_cvt_pk_bf16_f32 v83, v8, v9
	v_cvt_pk_bf16_f32 v84, v18, v19
	v_cvt_pk_bf16_f32 v85, v20, v21
	ds_read2_b64 v[158:161], v215 offset1:4
	s_waitcnt lgkmcnt(0)
	v_mfma_f32_16x16x32_bf16 v[90:93], v[78:81], v[158:161], v[90:93]
	v_mfma_f32_16x16x32_bf16 v[86:89], v[82:85], v[158:161], v[86:89]
	ds_read2_b64 v[158:161], v216 offset0:32 offset1:36
	s_waitcnt lgkmcnt(0)
	v_mfma_f32_16x16x32_bf16 v[98:101], v[78:81], v[158:161], v[98:101]
	v_mfma_f32_16x16x32_bf16 v[94:97], v[82:85], v[158:161], v[94:97]
	ds_read2_b64 v[158:161], v217 offset0:64 offset1:68
	s_waitcnt lgkmcnt(0)
	v_mfma_f32_16x16x32_bf16 v[106:109], v[78:81], v[158:161], v[106:109]
	v_mfma_f32_16x16x32_bf16 v[102:105], v[82:85], v[158:161], v[102:105]
	ds_read2_b64 v[158:161], v218 offset0:96 offset1:100
	s_waitcnt lgkmcnt(0)
	v_mfma_f32_16x16x32_bf16 v[70:73], v[78:81], v[158:161], v[70:73]
	v_cvt_pk_bf16_f32 v78, v14, v15
	v_cvt_pk_bf16_f32 v79, v16, v17
	v_cvt_pk_bf16_f32 v80, v38, v39
	v_mfma_f32_16x16x32_bf16 v[74:77], v[82:85], v[158:161], v[74:77]
	v_cvt_pk_bf16_f32 v81, v40, v41
	v_cvt_pk_bf16_f32 v82, v26, v27
	v_cvt_pk_bf16_f32 v83, v28, v29
	v_cvt_pk_bf16_f32 v84, v50, v51
	v_cvt_pk_bf16_f32 v85, v52, v53
	ds_read2_b64 v[158:161], v215 offset0:8 offset1:12
	s_waitcnt lgkmcnt(0)
	v_mfma_f32_16x16x32_bf16 v[90:93], v[78:81], v[158:161], v[90:93]
	v_mfma_f32_16x16x32_bf16 v[86:89], v[82:85], v[158:161], v[86:89]
	ds_read2_b64 v[158:161], v216 offset0:40 offset1:44
	s_waitcnt lgkmcnt(0)
	v_mfma_f32_16x16x32_bf16 v[98:101], v[78:81], v[158:161], v[98:101]
	v_mfma_f32_16x16x32_bf16 v[94:97], v[82:85], v[158:161], v[94:97]
	ds_read2_b64 v[158:161], v217 offset0:72 offset1:76
	s_waitcnt lgkmcnt(0)
	v_mfma_f32_16x16x32_bf16 v[106:109], v[78:81], v[158:161], v[106:109]
	v_mfma_f32_16x16x32_bf16 v[102:105], v[82:85], v[158:161], v[102:105]
	ds_read2_b64 v[158:161], v218 offset0:104 offset1:108
	s_waitcnt lgkmcnt(0)
	v_mfma_f32_16x16x32_bf16 v[70:73], v[78:81], v[158:161], v[70:73]
	v_cvt_pk_bf16_f32 v78, v22, v23
	v_cvt_pk_bf16_f32 v79, v24, v25
	v_cvt_pk_bf16_f32 v80, v42, v43
	v_mfma_f32_16x16x32_bf16 v[74:77], v[82:85], v[158:161], v[74:77]
	v_cvt_pk_bf16_f32 v81, v44, v45
	v_cvt_pk_bf16_f32 v82, v34, v35
	v_cvt_pk_bf16_f32 v83, v36, v37
	v_cvt_pk_bf16_f32 v84, v54, v55
	v_cvt_pk_bf16_f32 v85, v56, v57
	ds_read2_b64 v[158:161], v215 offset0:16 offset1:20
	s_waitcnt lgkmcnt(0)
	v_mfma_f32_16x16x32_bf16 v[90:93], v[78:81], v[158:161], v[90:93]
	v_mfma_f32_16x16x32_bf16 v[86:89], v[82:85], v[158:161], v[86:89]
	ds_read2_b64 v[158:161], v216 offset0:48 offset1:52
	s_waitcnt lgkmcnt(0)
	v_mfma_f32_16x16x32_bf16 v[98:101], v[78:81], v[158:161], v[98:101]
	v_mfma_f32_16x16x32_bf16 v[94:97], v[82:85], v[158:161], v[94:97]
	ds_read2_b64 v[158:161], v217 offset0:80 offset1:84
	s_waitcnt lgkmcnt(0)
	v_mfma_f32_16x16x32_bf16 v[162:165], v[78:81], v[158:161], v[106:109]
	v_mfma_f32_16x16x32_bf16 v[158:161], v[82:85], v[158:161], v[102:105]
	s_nop 2
	ds_read2_b64 v[102:105], v218 offset0:112 offset1:116
	s_waitcnt lgkmcnt(0)
	v_mfma_f32_16x16x32_bf16 v[70:73], v[78:81], v[102:105], v[70:73]
	v_cvt_pk_bf16_f32 v78, v46, v47
	v_cvt_pk_bf16_f32 v79, v48, v49
	v_cvt_pk_bf16_f32 v80, v58, v59
	v_mfma_f32_16x16x32_bf16 v[74:77], v[82:85], v[102:105], v[74:77]
	v_cvt_pk_bf16_f32 v81, v60, v61
	ds_read2_b64 v[82:85], v215 offset0:24 offset1:28
	s_waitcnt lgkmcnt(0)
	v_mfma_f32_16x16x32_bf16 v[106:109], v[78:81], v[82:85], v[90:93]
	v_mfma_f32_16x16x32_bf16 v[102:105], v[166:169], v[82:85], v[86:89]
	ds_read2_b64 v[82:85], v216 offset0:56 offset1:60
	s_nop 5
	v_add_f32_e64 v106, v106, v224
	v_add_f32_e64 v107, v107, v225
	v_add_f32_e64 v108, v108, v156
	v_add_f32_e64 v109, v109, v157
	s_waitcnt lgkmcnt(0)
	v_mfma_f32_16x16x32_bf16 v[98:101], v[78:81], v[82:85], v[98:101]
	v_mul_f32_e64 v156, v106, v106
	v_mul_f32_e64 v157, v107, v107
	v_mul_f32_e64 v224, v108, v108
	v_mul_f32_e64 v225, v109, v109
	v_add_f32_e32 v0, v156, v157
	v_mfma_f32_16x16x32_bf16 v[94:97], v[166:169], v[82:85], v[94:97]
	ds_read2_b64 v[82:85], v217 offset0:88 offset1:92
	v_add_f32_e64 v102, v102, v226
	v_add_f32_e64 v103, v103, v227
	v_add_f32_e32 v0, v224, v0
	s_waitcnt lgkmcnt(0)
	v_mfma_f32_16x16x32_bf16 v[86:89], v[166:169], v[82:85], v[158:161]
	v_add_f32_e64 v104, v104, v152
	v_add_f32_e64 v105, v105, v153
	s_nop 0
	ds_read2_b64 v[158:161], v218 offset0:120 offset1:124
	v_mul_f32_e64 v152, v102, v102
	v_mul_f32_e64 v153, v103, v103
	v_mfma_f32_16x16x32_bf16 v[90:93], v[78:81], v[82:85], v[162:165]
	v_add_f32_e32 v0, v225, v0
	v_add_f32_e32 v0, v152, v0
	v_mul_f32_e64 v226, v104, v104
	v_mul_f32_e64 v227, v105, v105
	s_waitcnt lgkmcnt(0)
	v_mfma_f32_16x16x32_bf16 v[82:85], v[78:81], v[158:161], v[70:73]
	v_add_f32_e32 v0, v153, v0
	v_add_f32_e32 v0, v226, v0
	v_add_f32_e32 v0, v227, v0
	v_lshl_add_u64 v[70:71], s[62:63], 0, v[118:119]
	v_add_co_u32_e32 v72, vcc, s81, v70
	v_mfma_f32_16x16x32_bf16 v[78:81], v[166:169], v[158:161], v[74:77]
	s_nop 0
	v_addc_co_u32_e32 v73, vcc, 0, v71, vcc
	global_load_dwordx2 v[168:169], v[70:71], off
	global_load_dwordx2 v[166:167], v[70:71], off offset:32
	global_load_dwordx2 v[164:165], v[72:73], off
	global_load_dwordx2 v[162:163], v[72:73], off offset:32
	v_add_co_u32_e32 v72, vcc, s95, v70
	ds_bpermute_b32 v152, v190, v0
	s_nop 0
	v_addc_co_u32_e32 v73, vcc, 0, v71, vcc
	v_add_co_u32_e32 v70, vcc, s96, v70
	global_load_dwordx2 v[160:161], v[72:73], off
	global_load_dwordx2 v[158:159], v[72:73], off offset:32
	v_addc_co_u32_e32 v71, vcc, 0, v71, vcc
	global_load_dwordx2 v[150:151], v[70:71], off
	global_load_dwordx2 v[140:141], v[70:71], off offset:32
	global_load_dwordx4 v[74:77], v[134:135], off
	s_nop 0
	global_load_dwordx4 v[70:73], v[134:135], off offset:64
	s_waitcnt lgkmcnt(0)
	v_add_f32_e32 v0, v0, v152
	ds_bpermute_b32 v152, v191, v0
	s_and_saveexec_b64 s[62:63], s[4:5]
	s_cbranch_execz .LBB0_691
	s_waitcnt lgkmcnt(0)
	v_add_f32_e32 v0, v0, v152
	ds_write_b32 v185, v0
.LBB0_691:
	s_or_b64 exec, exec, s[62:63]
	s_waitcnt vmcnt(15) lgkmcnt(0)
	v_lshlrev_b32_e32 v152, 16, v148
	v_and_b32_e32 v153, 0xffff0000, v148
	v_add_f32_e64 v152, v98, v152
	v_add_f32_e64 v153, v99, v153
	v_lshlrev_b32_e32 v98, 16, v149
	v_and_b32_e32 v99, 0xffff0000, v149
	v_add_f32_e64 v100, v100, v98
	v_add_f32_e64 v101, v101, v99
	v_mul_f32_e64 v148, v152, v152
	v_mul_f32_e64 v149, v153, v153
	v_mul_f32_e64 v156, v100, v100
	v_mul_f32_e64 v157, v101, v101
	s_waitcnt vmcnt(14)
	v_lshlrev_b32_e32 v98, 16, v146
	v_and_b32_e32 v99, 0xffff0000, v146
	v_add_f32_e32 v0, v148, v149
	v_add_f32_e64 v98, v94, v98
	v_add_f32_e64 v99, v95, v99
	v_lshlrev_b32_e32 v94, 16, v147
	v_and_b32_e32 v95, 0xffff0000, v147
	v_add_f32_e32 v0, v156, v0
	v_add_f32_e64 v96, v96, v94
	v_add_f32_e64 v97, v97, v95
	v_mul_f32_e64 v94, v98, v98
	v_mul_f32_e64 v95, v99, v99
	v_add_f32_e32 v0, v157, v0
	v_add_f32_e32 v0, v94, v0
	v_mul_f32_e64 v146, v96, v96
	v_mul_f32_e64 v147, v97, v97
	v_add_f32_e32 v0, v95, v0
	v_add_f32_e32 v0, v146, v0
	v_add_f32_e32 v0, v147, v0
	ds_bpermute_b32 v94, v190, v0
	s_waitcnt lgkmcnt(0)
	v_add_f32_e32 v0, v0, v94
	ds_bpermute_b32 v94, v191, v0
	s_and_saveexec_b64 s[62:63], s[4:5]
	s_cbranch_execz .LBB0_693
	s_waitcnt lgkmcnt(0)
	v_add_f32_e32 v0, v0, v94
	ds_write_b32 v185, v0 offset:512
.LBB0_693:
	s_or_b64 exec, exec, s[62:63]
	s_waitcnt vmcnt(13) lgkmcnt(0)
	v_lshlrev_b32_e32 v94, 16, v144
	v_and_b32_e32 v95, 0xffff0000, v144
	v_add_f32_e64 v90, v90, v94
	v_add_f32_e64 v91, v91, v95
	v_lshlrev_b32_e32 v94, 16, v145
	v_and_b32_e32 v95, 0xffff0000, v145
	v_add_f32_e64 v94, v92, v94
	v_add_f32_e64 v95, v93, v95
	v_mul_f32_e64 v144, v90, v90
	v_mul_f32_e64 v145, v91, v91
	v_mul_f32_e64 v146, v94, v94
	v_mul_f32_e64 v147, v95, v95
	s_waitcnt vmcnt(12)
	v_lshlrev_b32_e32 v92, 16, v142
	v_and_b32_e32 v93, 0xffff0000, v142
	v_add_f32_e32 v0, v144, v145
	v_add_f32_e64 v92, v86, v92
	v_add_f32_e64 v93, v87, v93
	v_lshlrev_b32_e32 v86, 16, v143
	v_and_b32_e32 v87, 0xffff0000, v143
	v_add_f32_e32 v0, v146, v0
	v_add_f32_e64 v88, v88, v86
	v_add_f32_e64 v89, v89, v87
	v_mul_f32_e64 v86, v92, v92
	v_mul_f32_e64 v87, v93, v93
	v_add_f32_e32 v0, v147, v0
	v_add_f32_e32 v0, v86, v0
	v_mul_f32_e64 v142, v88, v88
	v_mul_f32_e64 v143, v89, v89
	v_add_f32_e32 v0, v87, v0
	v_add_f32_e32 v0, v142, v0
	v_add_f32_e32 v0, v143, v0
	ds_bpermute_b32 v86, v190, v0
	s_waitcnt lgkmcnt(0)
	v_add_f32_e32 v0, v0, v86
	ds_bpermute_b32 v86, v191, v0
	s_and_saveexec_b64 s[62:63], s[4:5]
	s_cbranch_execz .LBB0_695
	s_waitcnt lgkmcnt(0)
	v_add_f32_e32 v0, v0, v86
	ds_write_b32 v185, v0 offset:1024
.LBB0_695:
	s_or_b64 exec, exec, s[62:63]
	s_waitcnt vmcnt(11) lgkmcnt(0)
	v_lshlrev_b32_e32 v86, 16, v138
	v_and_b32_e32 v87, 0xffff0000, v138
	v_add_f32_e64 v86, v82, v86
	v_add_f32_e64 v87, v83, v87
	v_lshlrev_b32_e32 v82, 16, v139
	v_and_b32_e32 v83, 0xffff0000, v139
	v_add_f32_e64 v84, v84, v82
	v_add_f32_e64 v85, v85, v83
	v_mul_f32_e64 v138, v86, v86
	v_mul_f32_e64 v139, v87, v87
	v_mul_f32_e64 v142, v84, v84
	v_mul_f32_e64 v143, v85, v85
	s_waitcnt vmcnt(10)
	v_lshlrev_b32_e32 v82, 16, v136
	v_and_b32_e32 v83, 0xffff0000, v136
	v_add_f32_e32 v0, v138, v139
	v_add_f32_e64 v82, v78, v82
	v_add_f32_e64 v83, v79, v83
	v_lshlrev_b32_e32 v78, 16, v137
	v_and_b32_e32 v79, 0xffff0000, v137
	v_add_f32_e32 v0, v142, v0
	v_add_f32_e64 v78, v80, v78
	v_add_f32_e64 v79, v81, v79
	v_mul_f32_e64 v80, v82, v82
	v_mul_f32_e64 v81, v83, v83
	v_add_f32_e32 v0, v143, v0
	v_add_f32_e32 v0, v80, v0
	v_mul_f32_e64 v136, v78, v78
	v_mul_f32_e64 v137, v79, v79
	v_add_f32_e32 v0, v81, v0
	v_add_f32_e32 v0, v136, v0
	v_add_f32_e32 v0, v137, v0
	ds_bpermute_b32 v80, v190, v0
	s_waitcnt lgkmcnt(0)
	v_add_f32_e32 v0, v0, v80
	ds_bpermute_b32 v80, v191, v0
	s_and_saveexec_b64 s[62:63], s[4:5]
	s_cbranch_execz .LBB0_679
	s_waitcnt lgkmcnt(0)
	v_add_f32_e32 v0, v0, v80
	ds_write_b32 v185, v0 offset:1536
	s_branch .LBB0_679

.LBB0_1034:
	v_mov_b32_e32 v73, 0
	ds_read2_b64 v[0:3], v73 offset0:15 offset1:27
	v_readlane_b32 s0, v240, 0
	s_cmpk_gt_i32 s0, 0x107f
	s_waitcnt lgkmcnt(0)
	v_readfirstlane_b32 s77, v1
	v_readfirstlane_b32 s76, v0
	v_readfirstlane_b32 s79, v3
	v_readfirstlane_b32 s78, v2
	s_cbranch_scc1 .LBB0_1191
	v_and_b32_e32 v0, 63, v154
	v_cmp_gt_u32_e32 vcc, 16, v0
	v_lshrrev_b32_e32 v87, 3, v154
	v_lshlrev_b32_e32 v0, 3, v154
	v_lshrrev_b32_e32 v75, 6, v154
	v_and_b32_e32 v4, 15, v154
	v_bfe_u32 v1, v154, 4, 2
	v_and_b32_e32 v74, 56, v0
	v_mul_u32_u24_e32 v0, 0x48, v87
	v_lshl_or_b32 v77, v75, 4, v4
	v_lshlrev_b32_e32 v155, 1, v0
	s_movk_i32 s4, 0xf0
	v_lshlrev_b32_e32 v0, 1, v74
	v_lshlrev_b32_e32 v78, 2, v1
	v_add3_u32 v158, s4, v155, v0
	v_sub_u32_e32 v9, v78, v77
	v_bfe_u32 v0, v154, 2, 2
	v_lshlrev_b32_e32 v76, 3, v1
	v_or_b32_e32 v5, v78, v0
	v_lshlrev_b32_e32 v0, 2, v154
	v_min_i32_e32 v1, -1, v9
	v_and_b32_e32 v160, 12, v0
	v_min_i32_e32 v0, 0, v9
	v_add_u32_e32 v1, 1, v1
	v_cvt_f32_i32_e32 v0, v0
	v_cvt_f32_i32_e32 v1, v1
	v_min_i32_e32 v2, -3, v9
	v_min_i32_e32 v3, -2, v9
	v_add_u32_e32 v7, 2, v3
	v_add_u32_e32 v2, 3, v2
	v_cvt_f32_i32_e32 v3, v2
	v_cvt_f32_i32_e32 v2, v7
	s_movk_i32 s1, 0x80
	s_mov_b32 s0, 0x7149f2ca
	v_mul_f32_e64 v80, v0, s0
	v_mul_f32_e64 v81, v1, s0
	v_sub_u32_e32 v0, v77, v78
	v_writelane_b32 v240, s46, 27
	v_min_i32_e32 v0, 0, v0
	v_cmp_lt_u32_e64 s[6:7], 63, v154
	v_writelane_b32 v240, s47, 28
	v_mul_f32_e64 v82, v2, s0
	v_mul_f32_e64 v83, v3, s0
	v_cvt_f32_i32_e32 v2, v0
	v_xad_u32 v0, v78, -1, v77
	v_writelane_b32 v240, s6, 15
	v_min_i32_e32 v0, 0, v0
	v_or_b32_e32 v163, 3, v78
	v_or_b32_e32 v164, 2, v78
	v_writelane_b32 v240, s7, 16
	v_cmp_gt_u32_e64 s[6:7], s1, v154
	s_movk_i32 s1, 0xc0
	v_cvt_f32_i32_e32 v3, v0
	v_sub_u32_e32 v0, v77, v163
	v_sub_u32_e32 v1, v77, v164
	v_mul_u32_u24_e32 v161, 0x90, v4
	v_cmp_gt_u32_e64 s[10:11], s1, v154
	s_movk_i32 s1, 0x100
	v_min_i32_e32 v4, 0, v1
	v_min_i32_e32 v0, 0, v0
	v_writelane_b32 v240, s10, 17
	v_cmp_gt_u32_e64 s[14:15], s1, v154
	s_movk_i32 s1, 0x140
	v_cvt_f32_i32_e32 v1, v0
	v_cvt_f32_i32_e32 v0, v4
	v_writelane_b32 v240, s11, 18
	v_cmp_gt_u32_e64 s[10:11], s1, v154
	s_movk_i32 s1, 0x180
	v_cmp_gt_u32_e64 s[22:23], s1, v154
	v_writelane_b32 v240, s10, 19
	s_movk_i32 s1, 0x1c0
	v_mul_f32_e32 v166, 0x7149f2ca, v2
	v_writelane_b32 v240, s11, 20
	v_cmp_gt_u32_e64 s[10:11], s1, v154
	s_movk_i32 s1, 0x200
	v_mul_f32_e64 v84, v0, s0
	v_mul_f32_e64 v85, v1, s0
	v_mbcnt_lo_u32_b32 v0, -1, 0
	v_mbcnt_hi_u32_b32 v0, -1, v0
	v_and_b32_e32 v2, 64, v0
	v_xor_b32_e32 v1, 16, v0
	v_add_u32_e32 v2, 64, v2
	v_cndmask_b32_e64 v79, 0, 1.0, vcc
	v_cmp_lt_i32_e32 vcc, v1, v2
	v_mul_f32_e32 v167, 0x7149f2ca, v3
	v_min_i32_e32 v3, 0xffffffee, v9
	v_cndmask_b32_e32 v1, v0, v1, vcc
	v_lshlrev_b32_e32 v195, 2, v1
	v_xor_b32_e32 v1, 32, v0
	v_cmp_lt_i32_e32 vcc, v1, v2
	v_min_i32_e32 v2, 0xffffffed, v9
	v_cmp_gt_u32_e64 s[30:31], s1, v154
	v_cndmask_b32_e32 v0, v0, v1, vcc
	v_lshlrev_b32_e32 v196, 2, v0
	v_min_i32_e32 v0, 0xffffffef, v9
	v_min_i32_e32 v1, -16, v9
	s_movk_i32 s1, 0x7f
	v_add_u32_e32 v4, 18, v3
	v_add_u32_e32 v2, 19, v2
	v_add_u32_e32 v3, 16, v1
	v_add_u32_e32 v0, 17, v0
	v_lshlrev_b32_e32 v6, 1, v160
	v_writelane_b32 v240, s10, 21
	v_mul_u32_u24_e32 v162, 0x90, v5
	v_cmp_lt_u32_e64 s[36:37], s1, v154
	s_movk_i32 s1, 0xbf
	v_cvt_f32_i32_e32 v1, v0
	v_cvt_f32_i32_e32 v0, v3
	v_cvt_f32_i32_e32 v3, v2
	v_cvt_f32_i32_e32 v2, v4
	v_min_i32_e32 v4, 0xffffffdf, v9
	v_min_i32_e32 v5, 0xffffffe0, v9
	v_writelane_b32 v240, s11, 22
	v_add3_u32 v165, s4, v6, v162
	v_cmp_lt_u32_e64 s[4:5], s1, v154
	s_movk_i32 s1, 0xff
	v_add_u32_e32 v11, 32, v5
	v_add_u32_e32 v4, 33, v4
	v_writelane_b32 v240, s4, 23
	v_cmp_lt_u32_e64 s[40:41], s1, v154
	s_movk_i32 s1, 0x13f
	v_cvt_f32_i32_e32 v5, v4
	v_cvt_f32_i32_e32 v4, v11
	v_writelane_b32 v240, s5, 24
	v_cmp_lt_u32_e64 s[4:5], s1, v154
	s_movk_i32 s1, 0x17f
	v_cmp_lt_u32_e64 s[44:45], s1, v154
	s_movk_i32 s1, 0x1bf
	v_mul_f32_e64 v92, v2, s0
	v_mul_f32_e64 v93, v3, s0
	v_mul_f32_e64 v94, v0, s0
	v_mul_f32_e64 v95, v1, s0
	v_min_i32_e32 v0, 0xffffffcf, v9
	v_min_i32_e32 v1, 0xffffffd0, v9
	v_min_i32_e32 v2, 0xffffffcd, v9
	v_min_i32_e32 v3, 0xffffffce, v9
	v_min_i32_e32 v6, 0xffffffdd, v9
	v_min_i32_e32 v7, 0xffffffde, v9
	v_mul_f32_e64 v98, v4, s0
	v_mul_f32_e64 v99, v5, s0
	v_add_u32_e32 v4, 50, v3
	v_add_u32_e32 v2, 51, v2
	v_add_u32_e32 v3, 48, v1
	v_add_u32_e32 v0, 49, v0
	v_add_u32_e32 v10, 34, v7
	v_add_u32_e32 v6, 35, v6
	v_cvt_f32_i32_e32 v1, v0
	v_cvt_f32_i32_e32 v0, v3
	v_cvt_f32_i32_e32 v3, v2
	v_cvt_f32_i32_e32 v2, v4
	v_min_i32_e32 v4, 0xffffffbf, v9
	v_min_i32_e32 v5, 0xffffffc0, v9
	v_cvt_f32_i32_e32 v7, v6
	v_cvt_f32_i32_e32 v6, v10
	v_add_u32_e32 v11, 64, v5
	v_add_u32_e32 v4, 0x41, v4
	v_cvt_f32_i32_e32 v5, v4
	v_cvt_f32_i32_e32 v4, v11
	v_mul_f32_e64 v96, v6, s0
	v_mul_f32_e64 v97, v7, s0
	v_min_i32_e32 v6, 0xffffffbd, v9
	v_min_i32_e32 v7, 0xffffffbe, v9
	v_mul_f32_e64 v100, v2, s0
	v_mul_f32_e64 v101, v3, s0
	v_mul_f32_e64 v102, v0, s0
	v_mul_f32_e64 v103, v1, s0
	v_min_i32_e32 v0, 0xffffffaf, v9
	v_min_i32_e32 v1, 0xffffffb0, v9
	v_min_i32_e32 v2, 0xffffffad, v9
	v_min_i32_e32 v3, 0xffffffae, v9
	v_add_u32_e32 v10, 0x42, v7
	v_add_u32_e32 v6, 0x43, v6
	v_mul_f32_e64 v106, v4, s0
	v_mul_f32_e64 v107, v5, s0
	v_add_u32_e32 v4, 0x52, v3
	v_add_u32_e32 v2, 0x53, v2
	v_add_u32_e32 v3, 0x50, v1
	v_add_u32_e32 v0, 0x51, v0
	v_cvt_f32_i32_e32 v7, v6
	v_cvt_f32_i32_e32 v6, v10
	v_cvt_f32_i32_e32 v1, v0
	v_cvt_f32_i32_e32 v0, v3
	v_cvt_f32_i32_e32 v3, v2
	v_cvt_f32_i32_e32 v2, v4
	v_min_i32_e32 v4, 0xffffff9f, v9
	v_min_i32_e32 v5, 0xffffffa0, v9
	v_add_u32_e32 v11, 0x60, v5
	v_add_u32_e32 v4, 0x61, v4
	v_cvt_f32_i32_e32 v5, v4
	v_cvt_f32_i32_e32 v4, v11
	v_mul_f32_e64 v104, v6, s0
	v_mul_f32_e64 v105, v7, s0
	v_min_i32_e32 v6, 0xffffff9d, v9
	v_min_i32_e32 v7, 0xffffff9e, v9
	v_add_u32_e32 v10, 0x62, v7
	v_add_u32_e32 v6, 0x63, v6
	v_mul_f32_e64 v108, v2, s0
	v_mul_f32_e64 v109, v3, s0
	v_mul_f32_e64 v110, v0, s0
	v_mul_f32_e64 v111, v1, s0
	v_min_i32_e32 v0, 0xffffff8f, v9
	v_min_i32_e32 v1, 0xffffff90, v9
	v_min_i32_e32 v2, 0xffffff8d, v9
	v_min_i32_e32 v3, 0xffffff8e, v9
	v_or_b32_e32 v168, 17, v78
	v_or_b32_e32 v86, 16, v78
	v_cvt_f32_i32_e32 v7, v6
	v_cvt_f32_i32_e32 v6, v10
	v_mul_f32_e64 v114, v4, s0
	v_mul_f32_e64 v115, v5, s0
	v_add_u32_e32 v4, 0x72, v3
	v_add_u32_e32 v2, 0x73, v2
	v_add_u32_e32 v3, 0x70, v1
	v_add_u32_e32 v0, 0x71, v0
	v_cvt_f32_i32_e32 v1, v0
	v_cvt_f32_i32_e32 v0, v3
	v_cvt_f32_i32_e32 v3, v2
	v_cvt_f32_i32_e32 v2, v4
	v_sub_u32_e32 v4, v77, v168
	v_sub_u32_e32 v5, v77, v86
	v_min_i32_e32 v10, 0, v5
	v_min_i32_e32 v4, 0, v4
	v_or_b32_e32 v169, 19, v78
	v_or_b32_e32 v170, 18, v78
	v_cvt_f32_i32_e32 v5, v4
	v_cvt_f32_i32_e32 v4, v10
	v_mul_f32_e64 v112, v6, s0
	v_mul_f32_e64 v113, v7, s0
	v_sub_u32_e32 v6, v77, v169
	v_sub_u32_e32 v7, v77, v170
	v_or_b32_e32 v171, 33, v78
	v_or_b32_e32 v88, 32, v78
	v_or_b32_e32 v172, 35, v78
	v_or_b32_e32 v173, 34, v78
	v_min_i32_e32 v9, 0, v7
	v_min_i32_e32 v6, 0, v6
	v_cvt_f32_i32_e32 v7, v6
	v_cvt_f32_i32_e32 v6, v9
	v_mul_f32_e64 v116, v2, s0
	v_mul_f32_e64 v117, v3, s0
	v_mul_f32_e64 v118, v0, s0
	v_mul_f32_e64 v119, v1, s0
	v_sub_u32_e32 v0, v77, v171
	v_sub_u32_e32 v1, v77, v88
	v_sub_u32_e32 v2, v77, v172
	v_sub_u32_e32 v3, v77, v173
	v_or_b32_e32 v174, 49, v78
	v_or_b32_e32 v90, 48, v78
	v_mul_f32_e64 v122, v4, s0
	v_mul_f32_e64 v123, v5, s0
	v_min_i32_e32 v4, 0, v3
	v_min_i32_e32 v2, 0, v2
	v_min_i32_e32 v3, 0, v1
	v_min_i32_e32 v0, 0, v0
	v_cvt_f32_i32_e32 v1, v0
	v_cvt_f32_i32_e32 v0, v3
	v_cvt_f32_i32_e32 v3, v2
	v_cvt_f32_i32_e32 v2, v4
	v_sub_u32_e32 v4, v77, v174
	v_sub_u32_e32 v5, v77, v90
	v_or_b32_e32 v175, 51, v78
	v_or_b32_e32 v176, 50, v78
	v_min_i32_e32 v10, 0, v5
	v_min_i32_e32 v4, 0, v4
	v_mul_f32_e64 v120, v6, s0
	v_mul_f32_e64 v121, v7, s0
	v_sub_u32_e32 v6, v77, v175
	v_sub_u32_e32 v7, v77, v176
	v_cvt_f32_i32_e32 v5, v4
	v_cvt_f32_i32_e32 v4, v10
	v_min_i32_e32 v9, 0, v7
	v_min_i32_e32 v6, 0, v6
	v_or_b32_e32 v177, 0x41, v78
	v_or_b32_e32 v178, 64, v78
	v_or_b32_e32 v179, 0x43, v78
	v_or_b32_e32 v180, 0x42, v78
	v_cvt_f32_i32_e32 v7, v6
	v_cvt_f32_i32_e32 v6, v9
	v_mul_f32_e64 v124, v2, s0
	v_mul_f32_e64 v125, v3, s0
	v_mul_f32_e64 v126, v0, s0
	v_mul_f32_e64 v127, v1, s0
	v_sub_u32_e32 v0, v77, v177
	v_sub_u32_e32 v1, v77, v178
	v_sub_u32_e32 v2, v77, v179
	v_sub_u32_e32 v3, v77, v180
	v_or_b32_e32 v181, 0x51, v78
	v_or_b32_e32 v182, 0x50, v78
	v_mul_f32_e64 v130, v4, s0
	v_mul_f32_e64 v131, v5, s0
	v_min_i32_e32 v4, 0, v3
	v_min_i32_e32 v2, 0, v2
	v_min_i32_e32 v3, 0, v1
	v_min_i32_e32 v0, 0, v0
	v_or_b32_e32 v183, 0x53, v78
	v_or_b32_e32 v184, 0x52, v78
	v_cvt_f32_i32_e32 v1, v0
	v_cvt_f32_i32_e32 v0, v3
	v_cvt_f32_i32_e32 v3, v2
	v_cvt_f32_i32_e32 v2, v4
	v_sub_u32_e32 v4, v77, v181
	v_sub_u32_e32 v5, v77, v182
	v_mul_f32_e64 v128, v6, s0
	v_mul_f32_e64 v129, v7, s0
	v_sub_u32_e32 v6, v77, v183
	v_sub_u32_e32 v7, v77, v184
	v_min_i32_e32 v10, 0, v5
	v_min_i32_e32 v4, 0, v4
	v_min_i32_e32 v9, 0, v7
	v_min_i32_e32 v6, 0, v6
	v_cvt_f32_i32_e32 v5, v4
	v_cvt_f32_i32_e32 v4, v10
	v_cvt_f32_i32_e32 v7, v6
	v_cvt_f32_i32_e32 v6, v9
	v_or_b32_e32 v185, 0x61, v78
	v_or_b32_e32 v186, 0x60, v78
	v_or_b32_e32 v187, 0x63, v78
	v_or_b32_e32 v188, 0x62, v78
	v_mul_f32_e64 v132, v2, s0
	v_mul_f32_e64 v133, v3, s0
	v_mul_f32_e64 v134, v0, s0
	v_mul_f32_e64 v135, v1, s0
	v_sub_u32_e32 v0, v77, v185
	v_sub_u32_e32 v1, v77, v186
	v_sub_u32_e32 v2, v77, v187
	v_sub_u32_e32 v3, v77, v188
	v_or_b32_e32 v189, 0x71, v78
	v_or_b32_e32 v190, 0x70, v78
	v_or_b32_e32 v191, 0x73, v78
	v_or_b32_e32 v192, 0x72, v78
	v_mul_f32_e64 v138, v4, s0
	v_mul_f32_e64 v139, v5, s0
	v_min_i32_e32 v4, 0, v3
	v_min_i32_e32 v2, 0, v2
	v_min_i32_e32 v3, 0, v1
	v_min_i32_e32 v0, 0, v0
	v_mul_f32_e64 v136, v6, s0
	v_mul_f32_e64 v137, v7, s0
	v_cvt_f32_i32_e32 v1, v0
	v_cvt_f32_i32_e32 v0, v3
	v_cvt_f32_i32_e32 v3, v2
	v_cvt_f32_i32_e32 v2, v4
	v_sub_u32_e32 v4, v77, v189
	v_sub_u32_e32 v5, v77, v190
	v_sub_u32_e32 v6, v77, v191
	v_sub_u32_e32 v7, v77, v192
	v_min_i32_e32 v9, 0, v7
	v_min_i32_e32 v6, 0, v6
	v_min_i32_e32 v10, 0, v5
	v_min_i32_e32 v4, 0, v4
	v_cvt_f32_i32_e32 v5, v4
	v_cvt_f32_i32_e32 v7, v6
	v_cvt_f32_i32_e32 v6, v9
	v_cvt_f32_i32_e32 v4, v10
	s_add_u32 s82, s78, 0xad20000
	s_addc_u32 s83, s79, 0
	v_and_b32_e32 v159, 48, v154
	s_add_u32 s84, s78, 0x17320000
	v_writelane_b32 v240, s4, 25
	v_mul_f32_e64 v140, v2, s0
	v_mul_f32_e64 v141, v3, s0
	v_mul_f32_e64 v142, v0, s0
	v_mul_f32_e64 v143, v1, s0
	v_mul_f32_e64 v144, v6, s0
	v_mul_f32_e64 v145, v7, s0
	v_mul_f32_e64 v146, v4, s0
	v_mul_f32_e64 v147, v5, s0
	s_mov_b32 s0, 0x9000
	v_add_u32_e32 v8, 0xf0, v159
	s_addc_u32 s85, s79, 0
	v_writelane_b32 v240, s5, 26
	s_add_i32 s69, s0, 0xf0
	s_movk_i32 s0, 0x4800
	s_mov_b32 s81, 0
	v_or_b32_e32 v89, 0x80, v87
	v_or_b32_e32 v91, 0xffffff80, v87
	v_cmp_gt_u32_e64 s[2:3], 64, v154
	v_cmp_eq_u32_e64 s[8:9], 1, v75
	v_cmp_eq_u32_e64 s[12:13], 2, v75
	v_cmp_eq_u32_e64 s[16:17], 3, v75
	v_cmp_eq_u32_e64 s[20:21], 4, v75
	v_cmp_eq_u32_e64 s[24:25], 5, v75
	v_cmp_eq_u32_e64 s[28:29], 6, v75
	v_cmp_eq_u32_e64 s[34:35], 7, v75
	v_cmp_lt_u32_e64 s[46:47], s1, v154
	v_add_u32_e32 v193, 0xd800, v165
	v_or_b32_e32 v194, 1, v78
	s_movk_i32 s66, 0x1400
	s_mov_b32 s67, 0x50000
	s_mov_b64 s[86:87], 0xad20800
	s_mov_b32 s88, 0x3e38aa3b
	s_mov_b32 s68, 0xff800000
	s_add_i32 s72, s0, 0xf0
	v_lshlrev_b32_e32 v148, 1, v86
	v_lshlrev_b32_e32 v150, 1, v88
	v_lshlrev_b32_e32 v152, 1, v90
	v_add_u32_e32 v197, v8, v161
	v_mov_b32_e32 v198, 0xfffe7960
	v_mov_b32_e32 v199, 0x186a0
	v_readlane_b32 s73, v240, 0
	s_branch .LBB0_1037
.LBB0_1036:
	s_waitcnt vmcnt(0)
	ds_bpermute_b32 v6, v195, v149
	v_lshlrev_b64 v[0:1], 11, v[156:157]
	v_lshl_add_u64 v[0:1], s[84:85], 0, v[0:1]
	s_lshl_b32 s80, s89, 7
	v_lshlrev_b32_e32 v72, 1, v78
	s_waitcnt lgkmcnt(0)
	v_add_f32_e32 v10, v149, v6
	ds_bpermute_b32 v11, v196, v10
	v_lshl_add_u64 v[6:7], v[0:1], 0, s[80:81]
	v_lshl_add_u64 v[8:9], v[6:7], 0, v[72:73]
	s_waitcnt lgkmcnt(0)
	v_add_f32_e32 v0, v10, v11
	v_div_scale_f32 v1, s[0:1], v0, v0, 1.0
	v_div_scale_f32 v13, vcc, 1.0, v0, 1.0
	v_rcp_f32_e32 v12, v1
	s_nop 1
	v_fma_f32 v14, -v1, v12, 1.0
	v_fmac_f32_e32 v12, v14, v12
	v_mul_f32_e32 v14, v13, v12
	v_fma_f32 v15, -v1, v14, v13
	v_fmac_f32_e32 v14, v15, v12
	v_fma_f32 v1, -v1, v14, v13
	v_div_fmas_f32 v1, v1, v12, v14
	v_div_fixup_f32 v0, v1, v0, 1.0
	v_readlane_b32 s0, v240, 11
	s_add_i32 s73, s73, s0
	s_cmpk_lt_i32 s73, 0x1080
	v_readlane_b32 s1, v240, 12
	v_lshlrev_b32_e32 v12, 16, v242
	v_and_b32_e32 v13, 0xffff0000, v242
	v_lshlrev_b32_e32 v4, 16, v243
	v_and_b32_e32 v5, 0xffff0000, v243
	v_mul_f32_e32 v1, 0xbfb8aa3b, v12
	v_mul_f32_e32 v14, 0xbfb8aa3b, v13
	v_mul_f32_e32 v15, 0xbfb8aa3b, v4
	v_mul_f32_e32 v16, 0xbfb8aa3b, v5
	v_exp_f32_e32 v1, v1
	v_exp_f32_e32 v14, v14
	v_exp_f32_e32 v15, v15
	v_exp_f32_e32 v16, v16
	v_add_f32_e32 v1, 1.0, v1
	v_add_f32_e32 v17, 1.0, v14
	v_add_f32_e32 v18, 1.0, v15
	v_add_f32_e32 v19, 1.0, v16
	v_rcp_f32_e32 v14, v1
	v_rcp_f32_e32 v15, v17
	v_rcp_f32_e32 v16, v18
	v_rcp_f32_e32 v17, v19
	v_mul_f32_e64 v18, v36, v0
	v_mul_f32_e64 v19, v37, v0
	v_mul_f32_e64 v20, v38, v0
	v_mul_f32_e64 v21, v39, v0
	v_mul_f32_e64 v12, v14, v12
	v_mul_f32_e64 v13, v15, v13
	v_mul_f32_e64 v4, v16, v4
	v_mul_f32_e64 v5, v17, v5
	v_mul_f32_e64 v12, v18, v12
	v_mul_f32_e64 v13, v19, v13
	v_mul_f32_e64 v4, v20, v4
	v_mul_f32_e64 v5, v21, v5
	v_cvt_pk_bf16_f32 v12, v12, v13
	v_cvt_pk_bf16_f32 v13, v4, v5
	global_store_dwordx2 v[8:9], v[12:13], off
	v_lshlrev_b32_e32 v12, 16, v244
	v_and_b32_e32 v13, 0xffff0000, v244
	v_lshlrev_b32_e32 v4, 16, v245
	v_and_b32_e32 v5, 0xffff0000, v245
	v_mul_f32_e32 v1, 0xbfb8aa3b, v12
	v_mul_f32_e32 v14, 0xbfb8aa3b, v13
	v_mul_f32_e32 v15, 0xbfb8aa3b, v4
	v_mul_f32_e32 v16, 0xbfb8aa3b, v5
	v_exp_f32_e32 v1, v1
	v_exp_f32_e32 v14, v14
	v_exp_f32_e32 v15, v15
	v_exp_f32_e32 v16, v16
	v_add_f32_e32 v1, 1.0, v1
	v_add_f32_e32 v17, 1.0, v14
	v_add_f32_e32 v18, 1.0, v15
	v_add_f32_e32 v19, 1.0, v16
	v_rcp_f32_e32 v14, v1
	v_rcp_f32_e32 v15, v17
	v_rcp_f32_e32 v16, v18
	v_rcp_f32_e32 v17, v19
	v_mul_f32_e64 v18, v32, v0
	v_mul_f32_e64 v19, v33, v0
	v_mul_f32_e64 v20, v34, v0
	v_mul_f32_e64 v21, v35, v0
	v_mul_f32_e64 v12, v14, v12
	v_mul_f32_e64 v13, v15, v13
	v_mul_f32_e64 v4, v16, v4
	v_mul_f32_e64 v5, v17, v5
	v_mul_f32_e64 v12, v18, v12
	v_mul_f32_e64 v13, v19, v13
	v_mul_f32_e64 v4, v20, v4
	v_mul_f32_e64 v5, v21, v5
	v_cvt_pk_bf16_f32 v12, v12, v13
	v_cvt_pk_bf16_f32 v13, v4, v5
	global_store_dwordx2 v[8:9], v[12:13], off offset:32
	v_lshlrev_b32_e32 v12, 16, v246
	v_and_b32_e32 v13, 0xffff0000, v246
	v_lshlrev_b32_e32 v4, 16, v247
	v_and_b32_e32 v5, 0xffff0000, v247
	v_mul_f32_e32 v1, 0xbfb8aa3b, v12
	v_mul_f32_e32 v14, 0xbfb8aa3b, v13
	v_mul_f32_e32 v15, 0xbfb8aa3b, v4
	v_mul_f32_e32 v16, 0xbfb8aa3b, v5
	v_exp_f32_e32 v1, v1
	v_exp_f32_e32 v14, v14
	v_exp_f32_e32 v15, v15
	v_exp_f32_e32 v16, v16
	v_add_f32_e32 v1, 1.0, v1
	v_add_f32_e32 v17, 1.0, v14
	v_add_f32_e32 v18, 1.0, v15
	v_add_f32_e32 v19, 1.0, v16
	v_rcp_f32_e32 v14, v1
	v_rcp_f32_e32 v15, v17
	v_rcp_f32_e32 v16, v18
	v_rcp_f32_e32 v17, v19
	v_mul_f32_e64 v18, v28, v0
	v_mul_f32_e64 v19, v29, v0
	v_mul_f32_e64 v20, v30, v0
	v_mul_f32_e64 v21, v31, v0
	v_mul_f32_e64 v12, v14, v12
	v_mul_f32_e64 v13, v15, v13
	v_mul_f32_e64 v4, v16, v4
	v_mul_f32_e64 v5, v17, v5
	v_mul_f32_e64 v12, v18, v12
	v_mul_f32_e64 v13, v19, v13
	v_mul_f32_e64 v4, v20, v4
	v_mul_f32_e64 v5, v21, v5
	v_cvt_pk_bf16_f32 v12, v12, v13
	v_cvt_pk_bf16_f32 v13, v4, v5
	global_store_dwordx2 v[8:9], v[12:13], off offset:64
	v_lshlrev_b32_e32 v12, 16, v248
	v_and_b32_e32 v13, 0xffff0000, v248
	v_lshlrev_b32_e32 v4, 16, v249
	v_and_b32_e32 v5, 0xffff0000, v249
	v_mul_f32_e32 v1, 0xbfb8aa3b, v12
	v_mul_f32_e32 v14, 0xbfb8aa3b, v13
	v_mul_f32_e32 v15, 0xbfb8aa3b, v4
	v_mul_f32_e32 v16, 0xbfb8aa3b, v5
	v_exp_f32_e32 v1, v1
	v_exp_f32_e32 v14, v14
	v_exp_f32_e32 v15, v15
	v_exp_f32_e32 v16, v16
	v_add_f32_e32 v1, 1.0, v1
	v_add_f32_e32 v17, 1.0, v14
	v_add_f32_e32 v18, 1.0, v15
	v_add_f32_e32 v19, 1.0, v16
	v_rcp_f32_e32 v14, v1
	v_rcp_f32_e32 v15, v17
	v_rcp_f32_e32 v16, v18
	v_rcp_f32_e32 v17, v19
	v_mul_f32_e64 v18, v24, v0
	v_mul_f32_e64 v19, v25, v0
	v_mul_f32_e64 v20, v26, v0
	v_mul_f32_e64 v21, v27, v0
	v_mul_f32_e64 v12, v14, v12
	v_mul_f32_e64 v13, v15, v13
	v_mul_f32_e64 v4, v16, v4
	v_mul_f32_e64 v5, v17, v5
	v_mul_f32_e64 v12, v18, v12
	v_mul_f32_e64 v13, v19, v13
	v_mul_f32_e64 v4, v20, v4
	v_mul_f32_e64 v5, v21, v5
	v_cvt_pk_bf16_f32 v12, v12, v13
	v_cvt_pk_bf16_f32 v13, v4, v5
	global_store_dwordx2 v[8:9], v[12:13], off offset:96
	s_cbranch_scc0 .LBB0_1190

.LBB0_1041:
	s_and_b32 s89, s10, 15
	s_lshl_b32 s4, s89, 2
	s_load_dword s98, s[76:77], s4
	v_add_u32_e32 v156, s18, v77
	s_bfe_u32 s51, s10, 0x20002
	v_ashrrev_i32_e32 v157, 31, v156
	s_add_u32 s100, s78, 0xad20c00
	s_addc_u32 s101, s79, 0
	v_mov_b64_e32 v[250:251], s[100:101]
	s_lshl_b32 s80, s89, 7
	v_mad_i64_i32 v[250:251], vcc, v156, s66, v[250:251]
	v_lshlrev_b32_e32 v252, 1, v78
	v_mov_b32_e32 v253, 0
	v_lshl_add_u64 v[250:251], v[250:251], 0, s[80:81]
	v_lshl_add_u64 v[250:251], v[250:251], 0, v[252:253]
	global_load_dwordx2 v[242:243], v[250:251], off
	global_load_dwordx2 v[244:245], v[250:251], off offset:32
	global_load_dwordx2 v[246:247], v[250:251], off offset:64
	global_load_dwordx2 v[248:249], v[250:251], off offset:96
	s_andn2_b64 vcc, exec, s[0:1]
	s_mov_b64 s[48:49], -1
	s_waitcnt lgkmcnt(0)
	s_barrier
	v_mov_b32_e32 v151, s98
	v_mul_f32_e32 v151, 0x3fb8aa3b, v151
	s_cbranch_vccnz .LBB0_1112
	s_cmp_gt_i32 s50, 62
	s_cbranch_scc1 .LBB0_1112
	s_cmp_eq_u32 s50, 0
	s_cselect_b64 s[48:49], -1, 0
	s_cmp_lg_u32 s50, 0
	s_cbranch_scc0 .LBB0_1112
	s_lshl_b32 s10, s11, 13
	s_lshl_b32 s4, s50, 7
	s_or_b32 s26, s10, s4
	v_add_u32_e32 v0, s26, v89
	v_mov_b64_e32 v[32:33], s[82:83]
	v_mad_i64_i32 v[0:1], s[4:5], v0, s66, v[32:33]
	s_lshl_b32 s80, s51, 7
	v_lshl_add_u64 v[0:1], v[0:1], 0, s[80:81]
	v_lshlrev_b32_e32 v72, 1, v74
	v_lshl_add_u64 v[24:25], v[0:1], 0, v[72:73]
	v_add_u32_e32 v0, s26, v91
	v_mad_i64_i32 v[0:1], s[4:5], v0, s66, v[32:33]
	v_lshl_add_u64 v[0:1], v[0:1], 0, s[80:81]
	v_lshl_add_u64 v[8:9], v[0:1], 0, v[72:73]
	v_add_co_u32_e32 v12, vcc, s67, v8
	global_load_dwordx4 v[0:3], v[8:9], off offset:2048
	global_load_dwordx4 v[4:7], v[8:9], off offset:2560
	v_addc_co_u32_e32 v13, vcc, 0, v9, vcc
	v_add_co_u32_e32 v28, vcc, s67, v24
	global_load_dwordx4 v[8:11], v[12:13], off offset:2048
	s_nop 0
	global_load_dwordx4 v[12:15], v[12:13], off offset:2560
	s_nop 0
	global_load_dwordx4 v[16:19], v[24:25], off offset:2048
	global_load_dwordx4 v[20:23], v[24:25], off offset:2560
	v_addc_co_u32_e32 v29, vcc, 0, v25, vcc
	global_load_dwordx4 v[24:27], v[28:29], off offset:2048
	s_nop 0
	global_load_dwordx4 v[28:31], v[28:29], off offset:2560
	s_lshl_b32 s4, s89, 7
	s_mov_b32 s5, s81
	v_mad_i64_i32 v[32:33], s[18:19], v156, s66, v[32:33]
	v_lshlrev_b32_e32 v34, 1, v76
	v_mov_b32_e32 v35, v73
	v_lshl_add_u64 v[32:33], v[32:33], 0, s[4:5]
	v_lshl_add_u64 v[36:37], v[32:33], 0, v[34:35]
	global_load_dwordx4 v[32:35], v[36:37], off
	s_nop 0
	global_load_dwordx4 v[36:39], v[36:37], off offset:64
	v_mov_b64_e32 v[40:41], s[78:79]
	v_or_b32_e32 v42, s26, v87
	v_mad_i64_i32 v[40:41], s[4:5], v42, s66, v[40:41]
	v_lshl_add_u64 v[40:41], v[40:41], 0, s[80:81]
	s_mov_b32 s18, 0xad20000
	v_lshl_add_u64 v[40:41], v[40:41], 0, v[72:73]
	v_add_co_u32_e32 v44, vcc, s18, v40
	s_mov_b32 s19, 0xad70000
	s_nop 0
	v_addc_co_u32_e32 v45, vcc, 0, v41, vcc
	v_lshl_add_u64 v[42:43], v[40:41], 0, s[86:87]
	v_add_co_u32_e32 v40, vcc, s19, v40
	v_mov_b32_e32 v58, 0
	s_nop 0
	v_addc_co_u32_e32 v41, vcc, 0, v41, vcc
	v_mov_b32_e32 v68, 0
	v_mov_b32_e32 v69, 0
	v_mov_b32_e32 v70, 0
	v_mov_b32_e32 v71, 0
	s_waitcnt vmcnt(9)
	ds_write_b128 v158, v[0:3]
	s_waitcnt vmcnt(8)
	ds_write_b128 v158, v[4:7] offset:18432
	s_waitcnt vmcnt(5)
	ds_write_b128 v158, v[16:19] offset:36864
	s_waitcnt vmcnt(4)
	ds_write_b128 v158, v[20:23] offset:55296
	ds_write_b128 v158, v[8:11] offset:9216
	ds_write_b128 v158, v[12:15] offset:27648
	s_waitcnt vmcnt(3)
	ds_write_b128 v158, v[24:27] offset:46080
	s_waitcnt vmcnt(2)
	ds_write_b128 v158, v[28:31] offset:64512
	s_waitcnt lgkmcnt(0)
	s_barrier
	global_load_dwordx4 v[0:3], v[44:45], off offset:2048
	global_load_dwordx4 v[4:7], v[42:43], off offset:512
	global_load_dwordx4 v[8:11], v[40:41], off offset:2048
	global_load_dwordx4 v[12:15], v[40:41], off offset:2560
	s_waitcnt vmcnt(5)
	v_lshlrev_b32_e32 v16, 16, v32
	s_waitcnt vmcnt(4)
	v_lshlrev_b32_e32 v18, 16, v36
	v_and_b32_e32 v19, 0xffff0000, v36
	v_mul_f32_e64 v18, v18, s88
	v_mul_f32_e64 v19, v19, s88
	v_and_b32_e32 v17, 0xffff0000, v32
	v_cvt_pk_bf16_f32 v20, v18, v19
	v_lshlrev_b32_e32 v18, 16, v33
	v_and_b32_e32 v19, 0xffff0000, v33
	v_mul_f32_e64 v16, v16, s88
	v_mul_f32_e64 v17, v17, s88
	v_mul_f32_e64 v18, v18, s88
	v_mul_f32_e64 v19, v19, s88
	v_cvt_pk_bf16_f32 v16, v16, v17
	v_cvt_pk_bf16_f32 v17, v18, v19
	v_lshlrev_b32_e32 v18, 16, v37
	v_and_b32_e32 v19, 0xffff0000, v37
	v_mul_f32_e64 v18, v18, s88
	v_mul_f32_e64 v19, v19, s88
	v_lshlrev_b32_e32 v24, 16, v35
	v_cvt_pk_bf16_f32 v21, v18, v19
	v_lshlrev_b32_e32 v18, 16, v34
	v_and_b32_e32 v19, 0xffff0000, v34
	v_and_b32_e32 v25, 0xffff0000, v35
	v_mul_f32_e64 v18, v18, s88
	v_mul_f32_e64 v19, v19, s88
	v_mul_f32_e64 v24, v24, s88
	v_mul_f32_e64 v25, v25, s88
	v_cvt_pk_bf16_f32 v18, v18, v19
	v_lshlrev_b32_e32 v22, 16, v38
	v_and_b32_e32 v23, 0xffff0000, v38
	v_cvt_pk_bf16_f32 v19, v24, v25
	v_lshlrev_b32_e32 v24, 16, v39
	v_and_b32_e32 v25, 0xffff0000, v39
	v_mul_f32_e64 v22, v22, s88
	v_mul_f32_e64 v23, v23, s88
	v_mul_f32_e64 v24, v24, s88
	v_mul_f32_e64 v25, v25, s88
	v_cvt_pk_bf16_f32 v22, v22, v23
	v_cvt_pk_bf16_f32 v23, v24, v25
	v_mov_b32_e32 v24, 0xff800000
	s_and_saveexec_b64 s[4:5], s[2:3]
	s_cbranch_execz .LBB0_1046
	ds_read_b128 v[24:27], v197
	ds_read_b128 v[28:31], v197 offset:64
	s_waitcnt lgkmcnt(1)
	v_mfma_f32_16x16x32_bf16 v[24:27], v[24:27], v[16:19], 0
	s_waitcnt lgkmcnt(0)
	v_mfma_f32_16x16x32_bf16 v[24:27], v[28:31], v[20:23], v[24:27]
	s_nop 7
	v_add_f32_e64 v68, v80, v24
	v_add_f32_e64 v69, v81, v25
	v_add_f32_e64 v70, v82, v26
	v_add_f32_e64 v71, v83, v27
	v_max_f32_e32 v24, v68, v69
	v_max_f32_e32 v25, v70, v71
	v_max3_f32 v24, v24, v25, s68
.LBB0_1046:
	s_or_b64 exec, exec, s[4:5]
	v_mov_b32_e32 v67, 0
	v_mov_b32_e32 v66, 0
	v_mov_b32_e32 v65, 0
	s_and_saveexec_b64 s[4:5], s[6:7]
	s_cbranch_execz .LBB0_1048
	ds_read_b128 v[26:29], v197 offset:2304
	ds_read_b128 v[30:33], v197 offset:2368
	s_waitcnt lgkmcnt(1)
	v_mfma_f32_16x16x32_bf16 v[26:29], v[26:29], v[16:19], 0
	s_waitcnt lgkmcnt(0)
	v_mfma_f32_16x16x32_bf16 v[26:29], v[30:33], v[20:23], v[26:29]
	s_nop 7
	v_add_f32_e64 v30, v92, v28
	v_add_f32_e64 v31, v93, v29
	v_add_f32_e64 v32, v94, v26
	v_add_f32_e64 v33, v95, v27
	v_cndmask_b32_e64 v66, v28, v30, s[8:9]
	v_cndmask_b32_e64 v65, v29, v31, s[8:9]
	v_cndmask_b32_e64 v58, v26, v32, s[8:9]
	v_cndmask_b32_e64 v67, v27, v33, s[8:9]
	v_max_f32_e32 v25, v67, v67
	v_max_f32_e32 v26, v58, v58
	v_max_f32_e32 v27, v65, v65
	v_max_f32_e32 v28, v66, v66
	v_max_f32_e32 v25, v26, v25
	v_max_f32_e32 v26, v28, v27
	v_max3_f32 v24, v24, v25, v26
.LBB0_1048:
	s_or_b64 exec, exec, s[4:5]
	v_mov_b32_e32 v36, 0
	v_mov_b32_e32 v46, 0
	v_mov_b32_e32 v39, 0
	v_mov_b32_e32 v44, 0
	v_mov_b32_e32 v37, 0
	s_mov_b64 s[4:5], exec
	v_readlane_b32 s18, v240, 17
	v_readlane_b32 s19, v240, 18
	s_and_b64 s[18:19], s[4:5], s[18:19]
	s_mov_b64 exec, s[18:19]
	s_cbranch_execz .LBB0_1050
	ds_read_b128 v[26:29], v197 offset:4608
	ds_read_b128 v[30:33], v197 offset:4672
	s_waitcnt lgkmcnt(1)
	v_mfma_f32_16x16x32_bf16 v[26:29], v[26:29], v[16:19], 0
	s_waitcnt lgkmcnt(0)
	v_mfma_f32_16x16x32_bf16 v[26:29], v[30:33], v[20:23], v[26:29]
	s_nop 7
	v_add_f32_e64 v30, v96, v28
	v_add_f32_e64 v31, v97, v29
	v_add_f32_e64 v32, v98, v26
	v_add_f32_e64 v33, v99, v27
	v_cndmask_b32_e64 v44, v28, v30, s[12:13]
	v_cndmask_b32_e64 v37, v29, v31, s[12:13]
	v_cndmask_b32_e64 v46, v26, v32, s[12:13]
	v_cndmask_b32_e64 v39, v27, v33, s[12:13]
	v_max_f32_e32 v25, v39, v39
	v_max_f32_e32 v26, v46, v46
	v_max_f32_e32 v27, v37, v37
	v_max_f32_e32 v28, v44, v44
	v_max_f32_e32 v25, v26, v25
	v_max_f32_e32 v26, v28, v27
	v_max3_f32 v24, v24, v25, v26
.LBB0_1050:
	s_or_b64 exec, exec, s[4:5]
	v_mov_b32_e32 v55, 0
	v_mov_b32_e32 v60, 0
	v_mov_b32_e32 v53, 0
	s_and_saveexec_b64 s[4:5], s[14:15]
	s_cbranch_execz .LBB0_1052
	ds_read_b128 v[26:29], v197 offset:6912
	ds_read_b128 v[30:33], v197 offset:6976
	s_waitcnt lgkmcnt(1)
	v_mfma_f32_16x16x32_bf16 v[26:29], v[26:29], v[16:19], 0
	s_waitcnt lgkmcnt(0)
	v_mfma_f32_16x16x32_bf16 v[26:29], v[30:33], v[20:23], v[26:29]
	s_nop 7
	v_add_f32_e64 v30, v100, v28
	v_add_f32_e64 v31, v101, v29
	v_add_f32_e64 v32, v102, v26
	v_add_f32_e64 v33, v103, v27
	v_cndmask_b32_e64 v60, v28, v30, s[16:17]
	v_cndmask_b32_e64 v53, v29, v31, s[16:17]
	v_cndmask_b32_e64 v36, v26, v32, s[16:17]
	v_cndmask_b32_e64 v55, v27, v33, s[16:17]
	v_max_f32_e32 v25, v55, v55
	v_max_f32_e32 v26, v36, v36
	v_max_f32_e32 v27, v53, v53
	v_max_f32_e32 v28, v60, v60
	v_max_f32_e32 v25, v26, v25
	v_max_f32_e32 v26, v28, v27
	v_max3_f32 v24, v24, v25, v26
.LBB0_1052:
	s_or_b64 exec, exec, s[4:5]
	v_mov_b32_e32 v38, 0
	v_mov_b32_e32 v52, 0
	v_mov_b32_e32 v47, 0
	v_mov_b32_e32 v50, 0
	v_mov_b32_e32 v45, 0
	s_mov_b64 s[4:5], exec
	v_readlane_b32 s18, v240, 19
	v_readlane_b32 s19, v240, 20
	s_and_b64 s[18:19], s[4:5], s[18:19]
	s_mov_b64 exec, s[18:19]
	s_cbranch_execz .LBB0_1054
	ds_read_b128 v[26:29], v197 offset:9216
	ds_read_b128 v[30:33], v197 offset:9280
	s_waitcnt lgkmcnt(1)
	v_mfma_f32_16x16x32_bf16 v[26:29], v[26:29], v[16:19], 0
	s_waitcnt lgkmcnt(0)
	v_mfma_f32_16x16x32_bf16 v[26:29], v[30:33], v[20:23], v[26:29]
	s_nop 7
	v_add_f32_e64 v30, v104, v28
	v_add_f32_e64 v31, v105, v29
	v_add_f32_e64 v32, v106, v26
	v_add_f32_e64 v33, v107, v27
	v_cndmask_b32_e64 v50, v28, v30, s[20:21]
	v_cndmask_b32_e64 v45, v29, v31, s[20:21]
	v_cndmask_b32_e64 v52, v26, v32, s[20:21]
	v_cndmask_b32_e64 v47, v27, v33, s[20:21]
	v_max_f32_e32 v25, v47, v47
	v_max_f32_e32 v26, v52, v52
	v_max_f32_e32 v27, v45, v45
	v_max_f32_e32 v28, v50, v50
	v_max_f32_e32 v25, v26, v25
	v_max_f32_e32 v26, v28, v27
	v_max3_f32 v24, v24, v25, v26
.LBB0_1054:
	s_or_b64 exec, exec, s[4:5]
	v_mov_b32_e32 v59, 0
	v_mov_b32_e32 v62, 0
	v_mov_b32_e32 v57, 0
	s_and_saveexec_b64 s[4:5], s[22:23]
	s_cbranch_execz .LBB0_1056
	ds_read_b128 v[26:29], v197 offset:11520
	ds_read_b128 v[30:33], v197 offset:11584
	s_waitcnt lgkmcnt(1)
	v_mfma_f32_16x16x32_bf16 v[26:29], v[26:29], v[16:19], 0
	s_waitcnt lgkmcnt(0)
	v_mfma_f32_16x16x32_bf16 v[26:29], v[30:33], v[20:23], v[26:29]
	s_nop 7
	v_add_f32_e64 v30, v108, v28
	v_add_f32_e64 v31, v109, v29
	v_add_f32_e64 v32, v110, v26
	v_add_f32_e64 v33, v111, v27
	v_cndmask_b32_e64 v62, v28, v30, s[24:25]
	v_cndmask_b32_e64 v57, v29, v31, s[24:25]
	v_cndmask_b32_e64 v38, v26, v32, s[24:25]
	v_cndmask_b32_e64 v59, v27, v33, s[24:25]
	v_max_f32_e32 v25, v59, v59
	v_max_f32_e32 v26, v38, v38
	v_max_f32_e32 v27, v57, v57
	v_max_f32_e32 v28, v62, v62
	v_max_f32_e32 v25, v26, v25
	v_max_f32_e32 v26, v28, v27
	v_max3_f32 v24, v24, v25, v26
.LBB0_1056:
	s_or_b64 exec, exec, s[4:5]
	v_mov_b32_e32 v48, 0
	v_mov_b32_e32 v56, 0
	v_mov_b32_e32 v51, 0
	v_mov_b32_e32 v54, 0
	v_mov_b32_e32 v49, 0
	s_mov_b64 s[4:5], exec
	v_readlane_b32 s18, v240, 21
	v_readlane_b32 s19, v240, 22
	s_and_b64 s[18:19], s[4:5], s[18:19]
	s_mov_b64 exec, s[18:19]
	s_cbranch_execz .LBB0_1058
	ds_read_b128 v[26:29], v197 offset:13824
	ds_read_b128 v[30:33], v197 offset:13888
	s_waitcnt lgkmcnt(1)
	v_mfma_f32_16x16x32_bf16 v[26:29], v[26:29], v[16:19], 0
	s_waitcnt lgkmcnt(0)
	v_mfma_f32_16x16x32_bf16 v[26:29], v[30:33], v[20:23], v[26:29]
	s_nop 7
	v_add_f32_e64 v30, v112, v28
	v_add_f32_e64 v31, v113, v29
	v_add_f32_e64 v32, v114, v26
	v_add_f32_e64 v33, v115, v27
	v_cndmask_b32_e64 v54, v28, v30, s[28:29]
	v_cndmask_b32_e64 v49, v29, v31, s[28:29]
	v_cndmask_b32_e64 v56, v26, v32, s[28:29]
	v_cndmask_b32_e64 v51, v27, v33, s[28:29]
	v_max_f32_e32 v25, v51, v51
	v_max_f32_e32 v26, v56, v56
	v_max_f32_e32 v27, v49, v49
	v_max_f32_e32 v28, v54, v54
	v_max_f32_e32 v25, v26, v25
	v_max_f32_e32 v26, v28, v27
	v_max3_f32 v24, v24, v25, v26
.LBB0_1058:
	s_or_b64 exec, exec, s[4:5]
	v_mov_b32_e32 v63, 0
	v_mov_b32_e32 v64, 0
	v_mov_b32_e32 v61, 0
	s_and_saveexec_b64 s[4:5], s[30:31]
	s_cbranch_execz .LBB0_1060
	ds_read_b128 v[26:29], v197 offset:16128
	ds_read_b128 v[30:33], v197 offset:16192
	s_waitcnt lgkmcnt(1)
	v_mfma_f32_16x16x32_bf16 v[26:29], v[26:29], v[16:19], 0
	s_waitcnt lgkmcnt(0)
	v_mfma_f32_16x16x32_bf16 v[26:29], v[30:33], v[20:23], v[26:29]
	s_nop 7
	v_add_f32_e64 v30, v116, v28
	v_add_f32_e64 v31, v117, v29
	v_add_f32_e64 v32, v118, v26
	v_add_f32_e64 v33, v119, v27
	v_cndmask_b32_e64 v64, v28, v30, s[34:35]
	v_cndmask_b32_e64 v61, v29, v31, s[34:35]
	v_cndmask_b32_e64 v48, v26, v32, s[34:35]
	v_cndmask_b32_e64 v63, v27, v33, s[34:35]
	v_max_f32_e32 v25, v63, v63
	v_max_f32_e32 v26, v48, v48
	v_max_f32_e32 v27, v61, v61
	v_max_f32_e32 v28, v64, v64
	v_max_f32_e32 v25, v26, v25
	v_max_f32_e32 v26, v28, v27
	v_max3_f32 v24, v24, v25, v26

.LBB0_1081:
	s_or_b64 exec, exec, s[4:5]
	ds_read_b128 v[36:39], v197 offset:36864
	ds_read_b128 v[44:47], v197 offset:36928
	v_mov_b32_e32 v50, 0
	s_waitcnt lgkmcnt(1)
	v_mfma_f32_16x16x32_bf16 v[52:55], v[36:39], v[16:19], 0
	v_mov_b32_e32 v38, 0
	v_mov_b32_e32 v37, 0
	v_mov_b32_e32 v36, 0
	s_waitcnt lgkmcnt(0)
	v_mfma_f32_16x16x32_bf16 v[44:47], v[44:47], v[20:23], v[52:55]
	s_nop 7
	v_add_f32_e32 v39, v166, v44
	v_add_f32_e32 v51, v167, v45
	v_add_f32_e64 v48, v84, v46
	v_add_f32_e64 v49, v85, v47
	v_cndmask_b32_e64 v71, v44, v39, s[2:3]
	v_cndmask_b32_e64 v70, v46, v48, s[2:3]
	v_cndmask_b32_e64 v69, v47, v49, s[2:3]
	v_cndmask_b32_e64 v68, v45, v51, s[2:3]
	v_max_f32_e32 v39, v68, v68
	v_max_f32_e32 v44, v71, v71
	v_max_f32_e32 v45, v69, v69
	v_max_f32_e32 v46, v70, v70
	v_max_f32_e32 v39, v44, v39
	v_max_f32_e32 v44, v46, v45
	v_max3_f32 v153, v39, v44, s68
	v_mov_b32_e32 v39, 0
	s_mov_b64 s[4:5], exec
	v_readlane_b32 s18, v240, 15
	v_readlane_b32 s19, v240, 16
	s_and_b64 s[18:19], s[4:5], s[18:19]
	s_mov_b64 exec, s[18:19]
	s_cbranch_execz .LBB0_1083
	ds_read_b128 v[36:39], v197 offset:39168
	ds_read_b128 v[44:47], v197 offset:39232
	s_waitcnt lgkmcnt(1)
	v_mfma_f32_16x16x32_bf16 v[36:39], v[36:39], v[16:19], 0
	s_waitcnt lgkmcnt(0)
	v_mfma_f32_16x16x32_bf16 v[44:47], v[44:47], v[20:23], v[36:39]
	s_nop 7
	v_add_f32_e64 v36, v120, v46
	v_add_f32_e64 v37, v121, v47
	v_add_f32_e64 v48, v122, v44
	v_add_f32_e64 v49, v123, v45
	v_cndmask_b32_e64 v36, v46, v36, s[8:9]
	v_cndmask_b32_e64 v39, v47, v37, s[8:9]
	v_cndmask_b32_e64 v38, v44, v48, s[8:9]
	v_cndmask_b32_e64 v37, v45, v49, s[8:9]
	v_max_f32_e32 v44, v37, v37
	v_max_f32_e32 v45, v38, v38
	v_max_f32_e32 v46, v39, v39
	v_max_f32_e32 v47, v36, v36
	v_max_f32_e32 v44, v45, v44
	v_max_f32_e32 v45, v47, v46
	v_max3_f32 v153, v153, v44, v45
.LBB0_1083:
	s_or_b64 exec, exec, s[4:5]
	v_mov_b32_e32 v64, 0
	v_mov_b32_e32 v63, 0
	v_mov_b32_e32 v62, 0
	v_mov_b32_e32 v61, 0
	s_and_saveexec_b64 s[4:5], s[36:37]
	s_cbranch_execz .LBB0_1085
	ds_read_b128 v[44:47], v197 offset:41472
	ds_read_b128 v[52:55], v197 offset:41536
	s_waitcnt lgkmcnt(1)
	v_mfma_f32_16x16x32_bf16 v[44:47], v[44:47], v[16:19], 0
	s_waitcnt lgkmcnt(0)
	v_mfma_f32_16x16x32_bf16 v[44:47], v[52:55], v[20:23], v[44:47]
	s_nop 7
	v_add_f32_e64 v48, v124, v46
	v_add_f32_e64 v49, v125, v47
	v_add_f32_e64 v52, v126, v44
	v_add_f32_e64 v53, v127, v45
	v_cndmask_b32_e64 v62, v46, v48, s[12:13]
	v_cndmask_b32_e64 v61, v47, v49, s[12:13]
	v_cndmask_b32_e64 v64, v44, v52, s[12:13]
	v_cndmask_b32_e64 v63, v45, v53, s[12:13]
	v_max_f32_e32 v44, v63, v63
	v_max_f32_e32 v45, v64, v64
	v_max_f32_e32 v46, v61, v61
	v_max_f32_e32 v47, v62, v62
	v_max_f32_e32 v44, v45, v44
	v_max_f32_e32 v45, v47, v46
	v_max3_f32 v153, v153, v44, v45
.LBB0_1085:
	s_or_b64 exec, exec, s[4:5]
	v_mov_b32_e32 v67, 0
	v_mov_b32_e32 v66, 0
	v_mov_b32_e32 v65, 0
	s_mov_b64 s[4:5], exec
	v_readlane_b32 s18, v240, 23
	v_readlane_b32 s19, v240, 24
	s_and_b64 s[18:19], s[4:5], s[18:19]
	s_mov_b64 exec, s[18:19]
	s_cbranch_execz .LBB0_1087
	ds_read_b128 v[44:47], v197 offset:43776
	ds_read_b128 v[48:51], v197 offset:43840
	s_waitcnt lgkmcnt(1)
	v_mfma_f32_16x16x32_bf16 v[44:47], v[44:47], v[16:19], 0
	s_waitcnt lgkmcnt(0)
	v_mfma_f32_16x16x32_bf16 v[44:47], v[48:51], v[20:23], v[44:47]
	s_nop 7
	v_add_f32_e64 v48, v128, v46
	v_add_f32_e64 v49, v129, v47
	v_add_f32_e64 v50, v130, v44
	v_add_f32_e64 v51, v131, v45
	v_cndmask_b32_e64 v66, v46, v48, s[16:17]
	v_cndmask_b32_e64 v65, v47, v49, s[16:17]
	v_cndmask_b32_e64 v50, v44, v50, s[16:17]
	v_cndmask_b32_e64 v67, v45, v51, s[16:17]
	v_max_f32_e32 v44, v67, v67
	v_max_f32_e32 v45, v50, v50
	v_max_f32_e32 v46, v65, v65
	v_max_f32_e32 v47, v66, v66
	v_max_f32_e32 v44, v45, v44
	v_max_f32_e32 v45, v47, v46
	v_max3_f32 v153, v153, v44, v45
.LBB0_1087:
	s_or_b64 exec, exec, s[4:5]
	v_mov_b32_e32 v54, 0
	v_mov_b32_e32 v58, 0
	v_mov_b32_e32 v55, 0
	v_mov_b32_e32 v56, 0
	v_mov_b32_e32 v53, 0
	s_and_saveexec_b64 s[4:5], s[40:41]
	s_cbranch_execz .LBB0_1089
	ds_read_b128 v[44:47], v197 offset:46080
	ds_read_b128 v[56:59], v197 offset:46144
	s_waitcnt lgkmcnt(1)
	v_mfma_f32_16x16x32_bf16 v[44:47], v[44:47], v[16:19], 0
	s_waitcnt lgkmcnt(0)
	v_mfma_f32_16x16x32_bf16 v[44:47], v[56:59], v[20:23], v[44:47]
	s_nop 7
	v_add_f32_e64 v48, v132, v46
	v_add_f32_e64 v49, v133, v47
	v_add_f32_e64 v58, v134, v44
	v_add_f32_e64 v59, v135, v45
	v_cndmask_b32_e64 v56, v46, v48, s[20:21]
	v_cndmask_b32_e64 v53, v47, v49, s[20:21]
	v_cndmask_b32_e64 v58, v44, v58, s[20:21]
	v_cndmask_b32_e64 v55, v45, v59, s[20:21]
	v_max_f32_e32 v44, v55, v55
	v_max_f32_e32 v45, v58, v58
	v_max_f32_e32 v46, v53, v53
	v_max_f32_e32 v47, v56, v56
	v_max_f32_e32 v44, v45, v44
	v_max_f32_e32 v45, v47, v46
	v_max3_f32 v153, v153, v44, v45
.LBB0_1089:
	s_or_b64 exec, exec, s[4:5]
	v_mov_b32_e32 v59, 0
	v_mov_b32_e32 v60, 0
	v_mov_b32_e32 v57, 0
	s_mov_b64 s[4:5], exec
	v_readlane_b32 s18, v240, 25
	v_readlane_b32 s19, v240, 26
	s_and_b64 s[18:19], s[4:5], s[18:19]
	s_mov_b64 exec, s[18:19]
	s_cbranch_execz .LBB0_1091
	ds_read_b128 v[44:47], v197 offset:48384
	ds_read_b128 v[200:203], v197 offset:48448
	s_waitcnt lgkmcnt(1)
	v_mfma_f32_16x16x32_bf16 v[44:47], v[44:47], v[16:19], 0
	s_waitcnt lgkmcnt(0)
	v_mfma_f32_16x16x32_bf16 v[44:47], v[200:203], v[20:23], v[44:47]
	s_nop 7
	v_add_f32_e64 v48, v136, v46
	v_add_f32_e64 v49, v137, v47
	v_add_f32_e64 v200, v138, v44
	v_add_f32_e64 v201, v139, v45
	v_cndmask_b32_e64 v60, v46, v48, s[24:25]
	v_cndmask_b32_e64 v57, v47, v49, s[24:25]
	v_cndmask_b32_e64 v54, v44, v200, s[24:25]
	v_cndmask_b32_e64 v59, v45, v201, s[24:25]
	v_max_f32_e32 v44, v59, v59
	v_max_f32_e32 v45, v54, v54
	v_max_f32_e32 v46, v57, v57
	v_max_f32_e32 v47, v60, v60
	v_max_f32_e32 v44, v45, v44
	v_max_f32_e32 v45, v47, v46
	v_max3_f32 v153, v153, v44, v45
.LBB0_1091:
	s_or_b64 exec, exec, s[4:5]
	v_mov_b32_e32 v44, 0
	v_mov_b32_e32 v48, 0
	v_mov_b32_e32 v47, 0
	v_mov_b32_e32 v46, 0
	v_mov_b32_e32 v45, 0
	s_and_saveexec_b64 s[4:5], s[44:45]
	s_cbranch_execz .LBB0_1093
	ds_read_b128 v[46:49], v197 offset:50688
	ds_read_b128 v[200:203], v197 offset:50752
	s_waitcnt lgkmcnt(1)
	v_mfma_f32_16x16x32_bf16 v[46:49], v[46:49], v[16:19], 0
	s_waitcnt lgkmcnt(0)
	v_mfma_f32_16x16x32_bf16 v[200:203], v[200:203], v[20:23], v[46:49]
	s_nop 7
	v_add_f32_e64 v46, v140, v202
	v_add_f32_e64 v47, v141, v203
	v_add_f32_e64 v48, v142, v200
	v_add_f32_e64 v49, v143, v201
	v_cndmask_b32_e64 v46, v202, v46, s[28:29]
	v_cndmask_b32_e64 v45, v203, v47, s[28:29]
	v_cndmask_b32_e64 v48, v200, v48, s[28:29]
	v_cndmask_b32_e64 v47, v201, v49, s[28:29]
	v_max_f32_e32 v49, v47, v47
	v_max_f32_e32 v51, v48, v48
	v_max_f32_e32 v52, v45, v45
	v_max_f32_e32 v200, v46, v46
	v_max_f32_e32 v49, v51, v49
	v_max_f32_e32 v51, v200, v52
	v_max3_f32 v153, v153, v49, v51
.LBB0_1093:
	s_or_b64 exec, exec, s[4:5]
	v_mov_b32_e32 v51, 0
	v_mov_b32_e32 v52, 0
	v_mov_b32_e32 v49, 0
	s_and_saveexec_b64 s[4:5], s[46:47]
	s_cbranch_execz .LBB0_1095
	ds_read_b128 v[200:203], v197 offset:52992
	ds_read_b128 v[204:207], v197 offset:53056
	s_waitcnt lgkmcnt(1)
	v_mfma_f32_16x16x32_bf16 v[200:203], v[200:203], v[16:19], 0
	s_waitcnt lgkmcnt(0)
	v_mfma_f32_16x16x32_bf16 v[200:203], v[204:207], v[20:23], v[200:203]
	s_nop 7
	v_add_f32_e64 v204, v144, v202
	v_add_f32_e64 v205, v145, v203
	v_add_f32_e64 v206, v146, v200
	v_add_f32_e64 v207, v147, v201
	v_cndmask_b32_e64 v52, v202, v204, s[34:35]
	v_cndmask_b32_e64 v49, v203, v205, s[34:35]
	v_cndmask_b32_e64 v44, v200, v206, s[34:35]
	v_cndmask_b32_e64 v51, v201, v207, s[34:35]
	v_max_f32_e32 v200, v51, v51
	v_max_f32_e32 v201, v44, v44
	v_max_f32_e32 v202, v49, v49
	v_max_f32_e32 v203, v52, v52
	v_max_f32_e32 v200, v201, v200
	v_max_f32_e32 v201, v203, v202
	v_max3_f32 v153, v153, v200, v201

.LBB0_1107:
	s_or_b64 exec, exec, s[4:5]
	ds_read_b64_tr_b16 v[206:207], v165 offset:57600
	ds_read_b64_tr_b16 v[204:205], v165 offset:55296
	ds_read_b64_tr_b16 v[210:211], v165 offset:57632
	ds_read_b64_tr_b16 v[208:209], v165 offset:55328
	ds_read_b64_tr_b16 v[212:213], v165 offset:55360
	ds_read_b64_tr_b16 v[216:217], v165 offset:55392
	ds_read_b64_tr_b16 v[214:215], v165 offset:57664
	ds_read_b64_tr_b16 v[218:219], v165 offset:57696
	v_mul_f32_e64 v34, v34, v68
	v_mul_f32_e64 v35, v35, v68
	v_mul_f32_e64 v32, v32, v68
	v_mul_f32_e64 v33, v33, v68
	v_cvt_pk_bf16_f32 v200, v71, v72
	v_cvt_pk_bf16_f32 v201, v70, v69
	v_cvt_pk_bf16_f32 v202, v38, v37
	v_cvt_pk_bf16_f32 v203, v36, v39
	v_mul_f32_e64 v26, v26, v68
	v_mul_f32_e64 v27, v27, v68
	v_mul_f32_e64 v24, v24, v68
	v_mul_f32_e64 v25, v25, v68
	s_waitcnt lgkmcnt(6)
	v_mfma_f32_16x16x32_bf16 v[36:39], v[204:207], v[200:203], v[32:35]
	s_waitcnt lgkmcnt(4)
	v_mfma_f32_16x16x32_bf16 v[32:35], v[208:211], v[200:203], v[24:27]
	s_nop 2
	v_mul_f32_e64 v26, v30, v68
	v_mul_f32_e64 v27, v31, v68
	v_mul_f32_e64 v24, v28, v68
	v_mul_f32_e64 v25, v29, v68
	s_waitcnt lgkmcnt(1)
	s_nop 0
	v_mfma_f32_16x16x32_bf16 v[28:31], v[212:215], v[200:203], v[24:27]
	s_nop 2
	v_mul_f32_e64 v26, v42, v68
	v_mul_f32_e64 v27, v43, v68
	v_mul_f32_e64 v24, v40, v68
	v_mul_f32_e64 v25, v41, v68
	s_waitcnt lgkmcnt(0)
	s_nop 0
	v_mfma_f32_16x16x32_bf16 v[24:27], v[216:219], v[200:203], v[24:27]
	s_and_saveexec_b64 s[4:5], s[36:37]
	s_cbranch_execnz .LBB0_1188
	s_or_b64 exec, exec, s[4:5]
	s_and_saveexec_b64 s[4:5], s[40:41]
	s_cbranch_execnz .LBB0_1189

.LBB0_1117:
	s_waitcnt vmcnt(3)
	v_add_u32_e32 v2, s18, v87
	v_mov_b64_e32 v[0:1], s[82:83]
	v_mad_i64_i32 v[2:3], s[4:5], v2, s66, v[0:1]
	s_lshl_b32 s4, s51, 7
	s_mov_b32 s5, s81
	v_lshl_add_u64 v[2:3], v[2:3], 0, s[4:5]
	v_mad_i64_i32 v[0:1], s[4:5], v156, s66, v[0:1]
	v_lshlrev_b32_e32 v72, 1, v74
	s_lshl_b32 s4, s89, 7
	s_mov_b32 s5, s81
	s_waitcnt vmcnt(1)
	v_lshl_add_u64 v[8:9], v[2:3], 0, v[72:73]
	v_lshl_add_u64 v[0:1], v[0:1], 0, s[4:5]
	v_lshlrev_b32_e32 v72, 1, v76
	v_lshl_add_u64 v[0:1], v[0:1], 0, v[72:73]
	s_waitcnt vmcnt(0)
	v_add_co_u32_e32 v12, vcc, s67, v8
	global_load_dwordx4 v[16:19], v[0:1], off
	global_load_dwordx4 v[20:23], v[0:1], off offset:64
	s_nop 0
	global_load_dwordx4 v[0:3], v[8:9], off offset:2048
	global_load_dwordx4 v[4:7], v[8:9], off offset:2560
	v_addc_co_u32_e32 v13, vcc, 0, v9, vcc
	global_load_dwordx4 v[8:11], v[12:13], off offset:2048
	s_nop 0
	global_load_dwordx4 v[12:15], v[12:13], off offset:2560
	v_mov_b32_e32 v27, 0
	s_lshl_b32 s80, s51, 6
	v_mov_b32_e32 v153, v151
	v_mov_b32_e32 v26, v27
	v_mov_b32_e32 v25, v27
	v_mov_b32_e32 v24, v27
	v_mov_b32_e32 v31, v27
	v_mov_b32_e32 v30, v27
	v_mov_b32_e32 v29, v27
	v_mov_b32_e32 v28, v27
	v_mov_b32_e32 v35, v27
	v_mov_b32_e32 v34, v27
	v_mov_b32_e32 v33, v27
	v_mov_b32_e32 v32, v27
	v_mov_b32_e32 v39, v27
	v_mov_b32_e32 v38, v27
	v_mov_b32_e32 v37, v27
	v_mov_b32_e32 v36, v27
	v_mov_b32_e32 v149, v79
	s_waitcnt vmcnt(5)
	v_lshlrev_b32_e32 v40, 16, v16
	v_and_b32_e32 v41, 0xffff0000, v16
	s_waitcnt vmcnt(4)
	v_lshlrev_b32_e32 v42, 16, v20
	v_and_b32_e32 v43, 0xffff0000, v20
	v_lshlrev_b32_e32 v16, 16, v17
	v_and_b32_e32 v17, 0xffff0000, v17
	v_lshlrev_b32_e32 v20, 16, v21
	v_and_b32_e32 v21, 0xffff0000, v21
	v_lshlrev_b32_e32 v44, 16, v18
	v_and_b32_e32 v45, 0xffff0000, v18
	v_lshlrev_b32_e32 v46, 16, v22
	v_and_b32_e32 v47, 0xffff0000, v22
	v_lshlrev_b32_e32 v18, 16, v19
	v_and_b32_e32 v19, 0xffff0000, v19
	v_lshlrev_b32_e32 v22, 16, v23
	v_and_b32_e32 v23, 0xffff0000, v23
	v_mul_f32_e64 v40, v40, s88
	v_mul_f32_e64 v41, v41, s88
	v_mul_f32_e64 v42, v42, s88
	v_mul_f32_e64 v43, v43, s88
	v_mul_f32_e64 v48, v16, s88
	v_mul_f32_e64 v49, v17, s88
	v_mul_f32_e64 v50, v20, s88
	v_mul_f32_e64 v51, v21, s88
	v_mul_f32_e64 v44, v44, s88
	v_mul_f32_e64 v45, v45, s88
	v_mul_f32_e64 v46, v46, s88
	v_mul_f32_e64 v47, v47, s88
	v_mul_f32_e64 v52, v18, s88
	v_mul_f32_e64 v53, v19, s88
	v_mul_f32_e64 v54, v22, s88
	v_mul_f32_e64 v55, v23, s88
	v_cvt_pk_bf16_f32 v16, v40, v41
	v_cvt_pk_bf16_f32 v20, v42, v43
	v_cvt_pk_bf16_f32 v17, v48, v49
	v_cvt_pk_bf16_f32 v21, v50, v51
	v_cvt_pk_bf16_f32 v18, v44, v45
	v_cvt_pk_bf16_f32 v22, v46, v47
	v_cvt_pk_bf16_f32 v19, v52, v53
	v_cvt_pk_bf16_f32 v23, v54, v55

.LBB0_1166:
	s_or_b64 exec, exec, s[4:5]
	v_mul_f32_e64 v38, v38, v72
	v_mul_f32_e64 v39, v39, v72
	v_mul_f32_e64 v36, v36, v72
	v_mul_f32_e64 v37, v37, v72
	v_mul_f32_e64 v34, v34, v72
	v_mul_f32_e64 v35, v35, v72
	v_mul_f32_e64 v32, v32, v72
	v_mul_f32_e64 v33, v33, v72
	v_mul_f32_e64 v30, v30, v72
	v_mul_f32_e64 v31, v31, v72
	v_mul_f32_e64 v28, v28, v72
	v_mul_f32_e64 v29, v29, v72
	v_mul_f32_e64 v26, v26, v72
	v_mul_f32_e64 v27, v27, v72
	v_mul_f32_e64 v24, v24, v72
	v_mul_f32_e64 v25, v25, v72
	v_lshl_add_u32 v72, v160, 1, s38
	v_add_u32_e32 v72, v72, v162
	s_and_saveexec_b64 s[0:1], s[48:49]
	s_cbranch_execnz .LBB0_1178
	s_or_b64 exec, exec, s[0:1]
	s_nor_b64 s[4:5], s[52:53], vcc
	s_and_saveexec_b64 s[0:1], s[4:5]
	s_cbranch_execnz .LBB0_1179

.Lattn_fast:
	v_add_u32_e32 v241, s4, v159
	v_add_u32_e32 v201, v241, v161
	ds_read_b128 v[220:223], v201
	ds_read_b128 v[224:227], v201 offset:64
	ds_read_b128 v[228:231], v201 offset:2304
	ds_read_b128 v[232:235], v201 offset:2368
	ds_read_b128 v[236:239], v201 offset:4608
	ds_read_b128 v[252:255], v201 offset:4672
	s_waitcnt lgkmcnt(4)
	v_mfma_f32_16x16x32_bf16 v[40:43], v[220:223], v[16:19], 0
	v_mfma_f32_16x16x32_bf16 v[40:43], v[224:227], v[20:23], v[40:43]
	ds_read_b128 v[220:223], v201 offset:6912
	ds_read_b128 v[224:227], v201 offset:6976
	s_waitcnt lgkmcnt(4)
	v_mfma_f32_16x16x32_bf16 v[44:47], v[228:231], v[16:19], 0
	v_mfma_f32_16x16x32_bf16 v[44:47], v[232:235], v[20:23], v[44:47]
	ds_read_b128 v[228:231], v201 offset:9216
	ds_read_b128 v[232:235], v201 offset:9280
	s_waitcnt lgkmcnt(4)
	v_mfma_f32_16x16x32_bf16 v[48:51], v[236:239], v[16:19], 0
	v_mfma_f32_16x16x32_bf16 v[48:51], v[252:255], v[20:23], v[48:51]
	ds_read_b128 v[236:239], v201 offset:11520
	ds_read_b128 v[252:255], v201 offset:11584
	s_waitcnt lgkmcnt(4)
	v_mfma_f32_16x16x32_bf16 v[52:55], v[220:223], v[16:19], 0
	v_mfma_f32_16x16x32_bf16 v[52:55], v[224:227], v[20:23], v[52:55]
	ds_read_b128 v[220:223], v201 offset:13824
	ds_read_b128 v[224:227], v201 offset:13888
	s_waitcnt lgkmcnt(4)
	v_mfma_f32_16x16x32_bf16 v[56:59], v[228:231], v[16:19], 0
	v_mfma_f32_16x16x32_bf16 v[56:59], v[232:235], v[20:23], v[56:59]
	ds_read_b128 v[228:231], v201 offset:16128
	ds_read_b128 v[232:235], v201 offset:16192
	s_waitcnt lgkmcnt(4)
	v_mfma_f32_16x16x32_bf16 v[60:63], v[236:239], v[16:19], 0
	v_mfma_f32_16x16x32_bf16 v[60:63], v[252:255], v[20:23], v[60:63]
	s_waitcnt lgkmcnt(2)
	v_mfma_f32_16x16x32_bf16 v[64:67], v[220:223], v[16:19], 0
	v_mfma_f32_16x16x32_bf16 v[64:67], v[224:227], v[20:23], v[64:67]
	s_waitcnt lgkmcnt(0)
	v_mfma_f32_16x16x32_bf16 v[68:71], v[228:231], v[16:19], 0
	v_mfma_f32_16x16x32_bf16 v[68:71], v[232:235], v[20:23], v[68:71]
	s_nop 7
	v_max3_f32 v200, v40, v41, s68
	v_max3_f32 v202, v42, v43, s68
	v_max3_f32 v200, v200, v44, v45
	v_max3_f32 v202, v202, v46, v47
	v_max3_f32 v200, v200, v48, v49
	v_max3_f32 v202, v202, v50, v51
	v_max3_f32 v200, v200, v52, v53
	v_max3_f32 v202, v202, v54, v55
	v_max3_f32 v200, v200, v56, v57
	v_max3_f32 v202, v202, v58, v59
	v_max3_f32 v200, v200, v60, v61
	v_max3_f32 v202, v202, v62, v63
	v_max3_f32 v200, v200, v64, v65
	v_max3_f32 v202, v202, v66, v67
	v_max3_f32 v200, v200, v68, v69
	v_max3_f32 v202, v202, v70, v71
	v_max_f32_e32 v200, v200, v202
	ds_bpermute_b32 v72, v195, v200
	v_max_f32_e32 v151, v200, v200
	s_waitcnt lgkmcnt(0)
	v_max_f32_e32 v72, v72, v72
	v_max_f32_e32 v72, v151, v72
	ds_bpermute_b32 v151, v196, v72
	s_waitcnt lgkmcnt(0)
	v_max3_f32 v151, v153, v72, v151
	v_sub_f32_e32 v72, v153, v151
	v_exp_f32_e32 v72, v72
	v_sub_f32_e32 v40, v40, v151
	v_sub_f32_e32 v41, v41, v151
	v_sub_f32_e32 v42, v42, v151
	v_sub_f32_e32 v43, v43, v151
	v_sub_f32_e32 v44, v44, v151
	v_sub_f32_e32 v45, v45, v151
	v_sub_f32_e32 v46, v46, v151
	v_sub_f32_e32 v47, v47, v151
	v_sub_f32_e32 v48, v48, v151
	v_sub_f32_e32 v49, v49, v151
	v_sub_f32_e32 v50, v50, v151
	v_sub_f32_e32 v51, v51, v151
	v_sub_f32_e32 v52, v52, v151
	v_sub_f32_e32 v53, v53, v151
	v_sub_f32_e32 v54, v54, v151
	v_sub_f32_e32 v55, v55, v151
	v_sub_f32_e32 v56, v56, v151
	v_sub_f32_e32 v57, v57, v151
	v_sub_f32_e32 v58, v58, v151
	v_sub_f32_e32 v59, v59, v151
	v_sub_f32_e32 v60, v60, v151
	v_sub_f32_e32 v61, v61, v151
	v_sub_f32_e32 v62, v62, v151
	v_sub_f32_e32 v63, v63, v151
	v_sub_f32_e32 v64, v64, v151
	v_sub_f32_e32 v65, v65, v151
	v_sub_f32_e32 v66, v66, v151
	v_sub_f32_e32 v67, v67, v151
	v_sub_f32_e32 v68, v68, v151
	v_sub_f32_e32 v69, v69, v151
	v_sub_f32_e32 v70, v70, v151
	v_sub_f32_e32 v71, v71, v151
	v_mul_f32_e32 v149, v149, v72
	v_exp_f32_e32 v40, v40
	v_exp_f32_e32 v41, v41
	v_exp_f32_e32 v42, v42
	v_exp_f32_e32 v43, v43
	v_exp_f32_e32 v44, v44
	v_exp_f32_e32 v45, v45
	v_exp_f32_e32 v46, v46
	v_exp_f32_e32 v47, v47
	v_exp_f32_e32 v48, v48
	v_exp_f32_e32 v49, v49
	v_exp_f32_e32 v50, v50
	v_exp_f32_e32 v51, v51
	v_exp_f32_e32 v52, v52
	v_exp_f32_e32 v53, v53
	v_exp_f32_e32 v54, v54
	v_exp_f32_e32 v55, v55
	v_exp_f32_e32 v56, v56
	v_exp_f32_e32 v57, v57
	v_exp_f32_e32 v58, v58
	v_exp_f32_e32 v59, v59
	v_exp_f32_e32 v60, v60
	v_exp_f32_e32 v61, v61
	v_exp_f32_e32 v62, v62
	v_exp_f32_e32 v63, v63
	v_exp_f32_e32 v64, v64
	v_exp_f32_e32 v65, v65
	v_exp_f32_e32 v66, v66
	v_exp_f32_e32 v67, v67
	v_exp_f32_e32 v68, v68
	v_exp_f32_e32 v69, v69
	v_exp_f32_e32 v70, v70
	v_exp_f32_e32 v71, v71
	v_mul_f32_e64 v38, v38, v72
	v_mul_f32_e64 v39, v39, v72
	v_mul_f32_e64 v36, v36, v72
	v_mul_f32_e64 v37, v37, v72
	v_mul_f32_e64 v34, v34, v72
	v_mul_f32_e64 v35, v35, v72
	v_mul_f32_e64 v32, v32, v72
	v_mul_f32_e64 v33, v33, v72
	v_mul_f32_e64 v30, v30, v72
	v_mul_f32_e64 v31, v31, v72
	v_mul_f32_e64 v28, v28, v72
	v_mul_f32_e64 v29, v29, v72
	v_mul_f32_e64 v26, v26, v72
	v_mul_f32_e64 v27, v27, v72
	v_mul_f32_e64 v24, v24, v72
	v_mul_f32_e64 v25, v25, v72
	v_lshl_add_u32 v241, v160, 1, s38
	v_add_u32_e32 v241, v241, v162
	ds_read_b64_tr_b16 v[220:221], v241
	ds_read_b64_tr_b16 v[222:223], v241 offset:2304
	ds_read_b64_tr_b16 v[224:225], v241 offset:32
	ds_read_b64_tr_b16 v[226:227], v241 offset:2336
	ds_read_b64_tr_b16 v[228:229], v241 offset:64
	ds_read_b64_tr_b16 v[230:231], v241 offset:2368
	ds_read_b64_tr_b16 v[232:233], v241 offset:96
	ds_read_b64_tr_b16 v[234:235], v241 offset:2400
	ds_read_b64_tr_b16 v[236:237], v241 offset:4608
	ds_read_b64_tr_b16 v[238:239], v241 offset:6912
	ds_read_b64_tr_b16 v[252:253], v241 offset:4640
	ds_read_b64_tr_b16 v[254:255], v241 offset:6944
	v_add_f32_e32 v149, v40, v149
	v_add_f32_e32 v149, v41, v149
	v_add_f32_e32 v149, v42, v149
	v_add_f32_e32 v149, v43, v149
	v_add_f32_e32 v149, v44, v149
	v_add_f32_e32 v149, v45, v149
	v_add_f32_e32 v149, v46, v149
	v_add_f32_e32 v149, v47, v149
	v_add_f32_e32 v149, v48, v149
	v_add_f32_e32 v149, v49, v149
	v_add_f32_e32 v149, v50, v149
	v_add_f32_e32 v149, v51, v149
	v_add_f32_e32 v149, v52, v149
	v_add_f32_e32 v149, v53, v149
	v_add_f32_e32 v149, v54, v149
	v_add_f32_e32 v149, v55, v149
	v_add_f32_e32 v149, v56, v149
	v_add_f32_e32 v149, v57, v149
	v_add_f32_e32 v149, v58, v149
	v_add_f32_e32 v149, v59, v149
	v_add_f32_e32 v149, v60, v149
	v_add_f32_e32 v149, v61, v149
	v_add_f32_e32 v149, v62, v149
	v_add_f32_e32 v149, v63, v149
	v_add_f32_e32 v149, v64, v149
	v_add_f32_e32 v149, v65, v149
	v_add_f32_e32 v149, v66, v149
	v_add_f32_e32 v149, v67, v149
	v_add_f32_e32 v149, v68, v149
	v_add_f32_e32 v149, v69, v149
	v_add_f32_e32 v149, v70, v149
	v_add_f32_e32 v149, v71, v149
	v_cvt_pk_bf16_f32 v40, v40, v41
	v_cvt_pk_bf16_f32 v41, v42, v43
	v_cvt_pk_bf16_f32 v42, v44, v45
	v_cvt_pk_bf16_f32 v43, v46, v47
	v_cvt_pk_bf16_f32 v48, v48, v49
	v_cvt_pk_bf16_f32 v49, v50, v51
	v_cvt_pk_bf16_f32 v50, v52, v53
	v_cvt_pk_bf16_f32 v51, v54, v55
	v_cvt_pk_bf16_f32 v56, v56, v57
	v_cvt_pk_bf16_f32 v57, v58, v59
	v_cvt_pk_bf16_f32 v58, v60, v61
	v_cvt_pk_bf16_f32 v59, v62, v63
	v_cvt_pk_bf16_f32 v64, v64, v65
	v_cvt_pk_bf16_f32 v65, v66, v67
	v_cvt_pk_bf16_f32 v66, v68, v69
	v_cvt_pk_bf16_f32 v67, v70, v71
	s_nop 1
	s_waitcnt lgkmcnt(10)
	v_mfma_f32_16x16x32_bf16 v[36:39], v[220:223], v[40:43], v[36:39]
	ds_read_b64_tr_b16 v[220:221], v241 offset:4672
	ds_read_b64_tr_b16 v[222:223], v241 offset:6976
	s_waitcnt lgkmcnt(10)
	v_mfma_f32_16x16x32_bf16 v[32:35], v[224:227], v[40:43], v[32:35]
	ds_read_b64_tr_b16 v[224:225], v241 offset:4704
	ds_read_b64_tr_b16 v[226:227], v241 offset:7008
	s_waitcnt lgkmcnt(10)
	v_mfma_f32_16x16x32_bf16 v[28:31], v[228:231], v[40:43], v[28:31]
	ds_read_b64_tr_b16 v[228:229], v241 offset:9216
	ds_read_b64_tr_b16 v[230:231], v241 offset:11520
	s_waitcnt lgkmcnt(10)
	v_mfma_f32_16x16x32_bf16 v[24:27], v[232:235], v[40:43], v[24:27]
	ds_read_b64_tr_b16 v[232:233], v241 offset:9248
	ds_read_b64_tr_b16 v[234:235], v241 offset:11552
	s_waitcnt lgkmcnt(10)
	v_mfma_f32_16x16x32_bf16 v[36:39], v[236:239], v[48:51], v[36:39]
	ds_read_b64_tr_b16 v[236:237], v241 offset:9280
	ds_read_b64_tr_b16 v[238:239], v241 offset:11584
	s_waitcnt lgkmcnt(10)
	v_mfma_f32_16x16x32_bf16 v[32:35], v[252:255], v[48:51], v[32:35]
	ds_read_b64_tr_b16 v[252:253], v241 offset:9312
	ds_read_b64_tr_b16 v[254:255], v241 offset:11616
	s_waitcnt lgkmcnt(10)
	v_mfma_f32_16x16x32_bf16 v[28:31], v[220:223], v[48:51], v[28:31]
	ds_read_b64_tr_b16 v[220:221], v241 offset:13824
	ds_read_b64_tr_b16 v[222:223], v241 offset:16128
	s_waitcnt lgkmcnt(10)
	v_mfma_f32_16x16x32_bf16 v[24:27], v[224:227], v[48:51], v[24:27]
	ds_read_b64_tr_b16 v[224:225], v241 offset:13856
	ds_read_b64_tr_b16 v[226:227], v241 offset:16160
	s_waitcnt lgkmcnt(10)
	v_mfma_f32_16x16x32_bf16 v[36:39], v[228:231], v[56:59], v[36:39]
	ds_read_b64_tr_b16 v[228:229], v241 offset:13888
	ds_read_b64_tr_b16 v[230:231], v241 offset:16192
	s_waitcnt lgkmcnt(10)
	v_mfma_f32_16x16x32_bf16 v[32:35], v[232:235], v[56:59], v[32:35]
	ds_read_b64_tr_b16 v[232:233], v241 offset:13920
	ds_read_b64_tr_b16 v[234:235], v241 offset:16224
	s_waitcnt lgkmcnt(10)
	v_mfma_f32_16x16x32_bf16 v[28:31], v[236:239], v[56:59], v[28:31]
	s_waitcnt lgkmcnt(8)
	v_mfma_f32_16x16x32_bf16 v[24:27], v[252:255], v[56:59], v[24:27]
	s_waitcnt lgkmcnt(6)
	v_mfma_f32_16x16x32_bf16 v[36:39], v[220:223], v[64:67], v[36:39]
	s_waitcnt lgkmcnt(4)
	v_mfma_f32_16x16x32_bf16 v[32:35], v[224:227], v[64:67], v[32:35]
	s_waitcnt lgkmcnt(2)
	v_mfma_f32_16x16x32_bf16 v[28:31], v[228:231], v[64:67], v[28:31]
	s_waitcnt lgkmcnt(0)
	v_mfma_f32_16x16x32_bf16 v[24:27], v[232:235], v[64:67], v[24:27]
	s_nop 7
	s_branch .LBB0_1170

.LBB0_1517:
	s_or_b64 exec, exec, s[58:59]
	v_max_f32_e64 v68, -v76, -v76
	v_max_f32_e32 v69, 0, v68
	v_add_f32_e32 v68, -1.0, v78
	v_sub_f32_e32 v70, v68, v78
	v_add_f32_e32 v70, 1.0, v70
	v_sub_f32_e32 v68, v74, v68
	s_waitcnt vmcnt(2)
	v_mul_f32_e64 v128, v64, s16
	v_mul_f32_e64 v129, v65, s16
	v_max_f32_e64 v64, -v77, -v77
	v_add_f32_e32 v72, v68, v70
	v_max_f32_e32 v68, 0, v64
	v_add_f32_e32 v64, -1.0, v79
	v_sub_f32_e32 v65, v64, v79
	v_add_f32_e32 v65, 1.0, v65
	v_sub_f32_e32 v64, v75, v64
	v_cvt_f64_f32_e32 v[70:71], v78
	v_mul_f32_e64 v126, v66, s16
	v_mul_f32_e64 v127, v67, s16
	v_add_f32_e32 v66, v64, v65
	v_cvt_f64_f32_e32 v[64:65], v79
	v_frexp_exp_i32_f64_e32 v70, v[70:71]
	v_frexp_exp_i32_f64_e32 v64, v[64:65]
	v_subbrev_co_u32_e64 v88, s[12:13], 0, v64, s[12:13]
	v_subbrev_co_u32_e64 v89, s[0:1], 0, v70, s[0:1]
	v_sub_u32_e32 v64, 0, v89
	v_sub_u32_e32 v70, 0, v88
	v_ldexp_f32 v65, v78, v64
	v_ldexp_f32 v67, v72, v64
	v_ldexp_f32 v64, v79, v70
	v_ldexp_f32 v66, v66, v70
	v_add_f32_e64 v70, v64, 1.0
	v_add_f32_e64 v71, v65, 1.0
	v_add_f32_e64 v80, v64, -1.0
	v_add_f32_e64 v81, v65, -1.0
	v_add_f32_e64 v72, v70, -1.0
	v_add_f32_e64 v73, v71, -1.0
	v_add_f32_e64 v82, v80, 1.0
	v_add_f32_e64 v83, v81, 1.0
	v_add_f32_e64 v72, v64, -v72
	v_add_f32_e64 v73, v65, -v73
	v_add_f32_e64 v64, v64, -v82
	v_add_f32_e64 v65, v65, -v83
	v_add_f32_e64 v72, v66, v72
	v_add_f32_e64 v73, v67, v73
	v_add_f32_e64 v64, v66, v64
	v_add_f32_e64 v65, v67, v65
	v_add_f32_e64 v76, v70, v72
	v_add_f32_e64 v77, v71, v73
	v_add_f32_e64 v66, v80, v64
	v_add_f32_e64 v67, v81, v65
	v_rcp_f32_e32 v79, v77
	v_rcp_f32_e32 v78, v76
	v_add_f32_e64 v70, v70, -v76
	v_add_f32_e64 v71, v71, -v77
	v_add_f32_e64 v80, v80, -v66
	v_add_f32_e64 v81, v81, -v67
	v_add_f32_e64 v70, v72, v70
	v_add_f32_e64 v71, v73, v71
	v_mul_f32_e64 v72, v66, v78
	v_mul_f32_e64 v73, v67, v79
	v_add_f32_e64 v64, v64, v80
	v_add_f32_e64 v65, v65, v81
	v_mul_f32_e64 v80, v76, v72
	v_mul_f32_e64 v81, v77, v73
	s_nop 0
	v_fma_f32 v82, v72, v76, -v80
	v_fma_f32 v83, v73, v77, -v81
	s_nop 0
	v_fma_f32 v82, v72, v70, v82
	v_fma_f32 v83, v73, v71, v83
	s_nop 0
	v_add_f32_e64 v84, v80, v82
	v_add_f32_e64 v85, v81, v83
	s_nop 0
	v_add_f32_e64 v86, v66, -v84
	v_add_f32_e64 v87, v67, -v85
	v_add_f32_e64 v80, v84, -v80
	v_add_f32_e64 v81, v85, -v81
	v_add_f32_e64 v66, v66, -v86
	v_add_f32_e64 v67, v67, -v87
	s_nop 0
	v_add_f32_e64 v66, v66, -v84
	v_add_f32_e64 v67, v67, -v85
	s_nop 0
	v_add_f32_e64 v64, v64, v66
	v_add_f32_e64 v65, v65, v67
	v_add_f32_e64 v66, v80, -v82
	v_add_f32_e64 v67, v81, -v83
	s_nop 0
	v_add_f32_e64 v64, v66, v64
	v_add_f32_e64 v65, v67, v65
	s_nop 0
	v_add_f32_e64 v66, v86, v64
	v_add_f32_e64 v67, v87, v65
	s_nop 0
	v_mul_f32_e64 v80, v78, v66
	v_mul_f32_e64 v81, v79, v67
	s_nop 0
	v_mul_f32_e64 v82, v76, v80
	v_mul_f32_e64 v83, v77, v81
	s_nop 0
	v_fma_f32 v76, v80, v76, -v82
	v_fma_f32 v77, v81, v77, -v83
	s_nop 0
	v_fma_f32 v70, v80, v70, v76
	v_fma_f32 v71, v81, v71, v77
	v_add_f32_e64 v76, v86, -v66
	v_add_f32_e64 v77, v87, -v67
	s_nop 0
	v_add_f32_e64 v64, v64, v76
	v_add_f32_e64 v65, v65, v77
	v_add_f32_e64 v76, v82, v70
	v_add_f32_e64 v77, v83, v71
	s_nop 0
	v_add_f32_e64 v84, v66, -v76
	v_add_f32_e64 v85, v67, -v77
	v_add_f32_e64 v82, v76, -v82
	v_add_f32_e64 v83, v77, -v83
	v_add_f32_e64 v66, v66, -v84
	v_add_f32_e64 v67, v67, -v85
	s_nop 0
	v_add_f32_e64 v66, v66, -v76
	v_add_f32_e64 v67, v67, -v77
	v_cvt_f32_i32_e32 v76, v88
	v_add_f32_e64 v64, v64, v66
	v_add_f32_e64 v65, v65, v67
	v_add_f32_e64 v66, v82, -v70
	v_add_f32_e64 v67, v83, -v71
	v_cvt_f32_i32_e32 v77, v89
	v_add_f32_e64 v64, v66, v64
	v_add_f32_e64 v65, v67, v65
	v_add_f32_e64 v66, v72, v80
	v_add_f32_e64 v67, v73, v81
	v_add_f32_e64 v64, v84, v64
	v_add_f32_e64 v65, v85, v65
	v_add_f32_e64 v70, v66, -v72
	v_add_f32_e64 v71, v67, -v73
	v_mul_f32_e64 v64, v78, v64
	v_mul_f32_e64 v65, v79, v65
	v_add_f32_e64 v70, v80, -v70
	v_add_f32_e64 v71, v81, -v71
	v_mul_f32_e64 v82, v76, s50
	v_mul_f32_e64 v83, v77, s50
	v_add_f32_e64 v64, v70, v64
	v_add_f32_e64 v65, v71, v65
	v_fma_f32 v84, v76, s50, -v82
	v_fma_f32 v85, v77, s50, -v83
	v_add_f32_e64 v70, v66, v64
	v_add_f32_e64 v71, v67, v65
	v_fma_f32 v76, v76, s52, v84
	v_fma_f32 v77, v77, s52, v85
	v_mul_f32_e64 v78, v70, v70
	v_mul_f32_e64 v79, v71, v71
	v_add_f32_e64 v66, v70, -v66
	v_add_f32_e64 v67, v71, -v67
	v_fma_f32 v80, v78, s46, v122
	v_fma_f32 v81, v79, s46, v122
	v_add_f32_e64 v64, v64, -v66
	v_add_f32_e64 v65, v65, -v67
	v_ldexp_f32 v67, v71, 1
	v_fma_f32 v80, v78, v80, s48
	v_fma_f32 v81, v79, v81, s48
	v_ldexp_f32 v66, v70, 1
	v_mul_f32_e64 v70, v70, v78
	v_mul_f32_e64 v71, v71, v79
	v_ldexp_f32 v73, v65, 1
	v_mul_f32_e64 v70, v70, v80
	v_mul_f32_e64 v71, v71, v81
	v_mov_b32_e32 v72, v76
	v_add_f32_e64 v78, v66, v70
	v_add_f32_e64 v79, v67, v71
	v_add_f32_e64 v84, v82, v76
	v_add_f32_e64 v85, v83, v77
	v_add_f32_e64 v66, v78, -v66
	v_add_f32_e64 v67, v79, -v67
	v_mov_b32_e32 v90, v84
	v_add_f32_e64 v66, v70, -v66
	v_add_f32_e64 v67, v71, -v67
	v_mov_b32_e32 v70, v82
	v_mov_b32_e32 v71, v67
	v_add_f32_e64 v70, v70, v72
	v_add_f32_e64 v71, v71, v73
	v_ldexp_f32 v72, v64, 1
	v_add_f32_e64 v64, v72, v66
	v_add_f32_e64 v65, v73, v67
	v_mov_b32_e32 v67, v79
	v_mov_b32_e32 v73, v65
	v_add_f32_e64 v66, v72, v66
	v_add_f32_e64 v67, v73, v67
	v_add_f32_e64 v72, v78, v64
	v_add_f32_e64 v73, v79, v65
	v_mov_b32_e32 v91, v79
	v_mov_b32_e32 v92, v72
	v_mov_b32_e32 v93, v65
	v_mov_b32_e32 v80, v84
	v_mov_b32_e32 v81, v83
	v_mov_b32_e32 v86, v72
	v_mov_b32_e32 v87, v77
	v_add_f32_e64 v90, v90, v92
	v_add_f32_e64 v91, v91, v93
	v_add_f32_e64 v92, v84, v72
	v_add_f32_e64 v93, v85, v73
	v_add_f32_e64 v88, v80, v86
	v_add_f32_e64 v89, v81, v87
	v_mov_b32_e32 v94, v72
	v_mov_b32_e32 v95, v93
	v_mov_b32_e32 v96, v78
	v_mov_b32_e32 v97, v85
	v_add_f32_e64 v94, v94, -v96
	v_add_f32_e64 v95, v95, -v97
	v_add_f32_e64 v80, v88, -v80
	v_add_f32_e64 v81, v89, -v81
	v_mov_b32_e32 v96, v84
	v_mov_b32_e32 v97, v93
	v_mov_b32_e32 v83, v95
	v_add_f32_e64 v72, v72, -v78
	v_add_f32_e64 v73, v73, -v79
	v_mov_b32_e32 v78, v80
	v_add_f32_e64 v82, v96, -v82
	v_add_f32_e64 v83, v97, -v83
	v_mov_b32_e32 v84, v76
	v_add_f32_e64 v78, v90, -v78
	v_add_f32_e64 v79, v91, -v79
	v_add_f32_e64 v84, v84, -v82
	v_add_f32_e64 v85, v85, -v83
	v_mov_b32_e32 v83, v81
	v_add_f32_e64 v66, v66, -v94
	v_add_f32_e64 v67, v67, -v95
	v_add_f32_e64 v70, v70, -v78
	v_add_f32_e64 v71, v71, -v79
	v_add_f32_e64 v76, v76, -v82
	v_add_f32_e64 v77, v77, -v83
	v_add_f32_e64 v64, v64, -v72
	v_add_f32_e64 v65, v65, -v73
	v_add_f32_e64 v72, v86, -v80
	v_add_f32_e64 v73, v87, -v81
	v_add_f32_e64 v80, v66, v84
	v_add_f32_e64 v81, v67, v85
	v_mov_b32_e32 v67, v71
	v_add_f32_e64 v78, v72, v70
	v_add_f32_e64 v79, v73, v71
	v_add_f32_e64 v66, v76, v66
	v_add_f32_e64 v67, v77, v67
	v_mov_b32_e32 v85, v73
	v_add_f32_e64 v66, v66, -v84
	v_add_f32_e64 v67, v67, -v85
	v_mov_b32_e32 v70, v80
	v_mov_b32_e32 v71, v79
	v_add_f32_e64 v70, v70, -v66
	v_add_f32_e64 v71, v71, -v67
	v_add_f32_e64 v64, v64, -v66
	v_add_f32_e64 v65, v65, -v67
	v_add_f32_e64 v70, v84, -v70
	v_add_f32_e64 v71, v85, -v71
	v_add_f32_e64 v66, v78, v80
	v_add_f32_e64 v67, v79, v81
	v_add_f32_e64 v64, v64, v70
	v_add_f32_e64 v65, v65, v71
	v_add_f32_e64 v70, v92, v66
	v_add_f32_e64 v71, v93, v67
	s_nop 0
	v_add_f32_e64 v72, v70, -v92
	v_add_f32_e64 v73, v71, -v93
	s_nop 0
	v_add_f32_e64 v66, v66, -v72
	v_add_f32_e64 v67, v67, -v73
	s_nop 0
	v_add_f32_e64 v64, v64, v66
	v_add_f32_e64 v65, v65, v67
	s_nop 0
	v_add_f32_e64 v64, v70, v64
	v_add_f32_e64 v65, v71, v65
	s_nop 0
	v_cndmask_b32_e64 v64, v161, v64, s[8:9]
	v_cndmask_b32_e32 v65, v161, v65, vcc
	v_cndmask_b32_e64 v65, v65, v74, s[10:11]
	v_cndmask_b32_e64 v64, v64, v75, s[6:7]
	v_add_f32_e64 v64, v68, v64
	v_add_f32_e64 v65, v69, v65
	s_mov_b32 s8, s56
	v_mul_f32_e64 v130, v64, s54
	v_mul_f32_e64 v131, v65, s54

.LBB0_1671:
	s_or_b64 exec, exec, s[78:79]
	v_add_f32_e32 v71, -1.0, v80
	v_sub_f32_e32 v72, v71, v80
	v_add_f32_e32 v72, 1.0, v72
	v_sub_f32_e32 v71, v76, v71
	s_waitcnt vmcnt(2)
	v_mul_f32_e64 v174, v66, s52
	v_mul_f32_e64 v175, v67, s52
	v_max_f32_e64 v66, -v79, -v79
	v_add_f32_e32 v74, v71, v72
	v_max_f32_e32 v71, 0, v66
	v_add_f32_e32 v66, -1.0, v81
	v_sub_f32_e32 v67, v66, v81
	v_add_f32_e32 v67, 1.0, v67
	v_sub_f32_e32 v66, v77, v66
	v_cvt_f64_f32_e32 v[72:73], v80
	v_mul_f32_e64 v172, v68, s52
	v_mul_f32_e64 v173, v69, s52
	v_add_f32_e32 v69, v66, v67
	v_cvt_f64_f32_e32 v[66:67], v81
	v_frexp_exp_i32_f64_e32 v72, v[72:73]
	v_frexp_exp_i32_f64_e32 v66, v[66:67]
	v_subbrev_co_u32_e64 v90, s[18:19], 0, v66, s[18:19]
	v_subbrev_co_u32_e64 v91, s[0:1], 0, v72, s[0:1]
	v_sub_u32_e32 v67, 0, v91
	v_sub_u32_e32 v72, 0, v90
	v_ldexp_f32 v66, v80, v67
	v_ldexp_f32 v68, v74, v67
	v_ldexp_f32 v67, v81, v72
	v_ldexp_f32 v69, v69, v72
	v_add_f32_e64 v72, v66, 1.0
	v_add_f32_e64 v73, v67, 1.0
	v_max_f32_e64 v70, -v78, -v78
	v_add_f32_e64 v74, v72, -1.0
	v_add_f32_e64 v75, v73, -1.0
	v_add_f32_e64 v82, v66, -1.0
	v_add_f32_e64 v83, v67, -1.0
	v_add_f32_e64 v74, v66, -v74
	v_add_f32_e64 v75, v67, -v75
	v_add_f32_e64 v84, v82, 1.0
	v_add_f32_e64 v85, v83, 1.0
	v_add_f32_e64 v74, v68, v74
	v_add_f32_e64 v75, v69, v75
	v_add_f32_e64 v66, v66, -v84
	v_add_f32_e64 v67, v67, -v85
	v_add_f32_e64 v78, v72, v74
	v_add_f32_e64 v79, v73, v75
	v_add_f32_e64 v66, v68, v66
	v_add_f32_e64 v67, v69, v67
	v_rcp_f32_e32 v80, v78
	v_rcp_f32_e32 v81, v79
	v_add_f32_e64 v68, v82, v66
	v_add_f32_e64 v69, v83, v67
	v_add_f32_e64 v72, v72, -v78
	v_add_f32_e64 v73, v73, -v79
	v_add_f32_e64 v82, v82, -v68
	v_add_f32_e64 v83, v83, -v69
	v_add_f32_e64 v72, v74, v72
	v_add_f32_e64 v73, v75, v73
	v_mul_f32_e64 v74, v68, v80
	v_mul_f32_e64 v75, v69, v81
	v_add_f32_e64 v66, v66, v82
	v_add_f32_e64 v67, v67, v83
	v_mul_f32_e64 v82, v78, v74
	v_mul_f32_e64 v83, v79, v75
	v_max_f32_e32 v70, 0, v70
	v_fma_f32 v84, v74, v78, -v82
	v_fma_f32 v85, v75, v79, -v83
	s_nop 0
	v_fma_f32 v84, v74, v72, v84
	v_fma_f32 v85, v75, v73, v85
	s_nop 0
	v_add_f32_e64 v86, v82, v84
	v_add_f32_e64 v87, v83, v85
	s_nop 0
	v_add_f32_e64 v88, v68, -v86
	v_add_f32_e64 v89, v69, -v87
	v_add_f32_e64 v82, v86, -v82
	v_add_f32_e64 v83, v87, -v83
	v_add_f32_e64 v68, v68, -v88
	v_add_f32_e64 v69, v69, -v89
	s_nop 0
	v_add_f32_e64 v68, v68, -v86
	v_add_f32_e64 v69, v69, -v87
	s_nop 0
	v_add_f32_e64 v66, v66, v68
	v_add_f32_e64 v67, v67, v69
	v_add_f32_e64 v68, v82, -v84
	v_add_f32_e64 v69, v83, -v85
	s_nop 0
	v_add_f32_e64 v66, v68, v66
	v_add_f32_e64 v67, v69, v67
	s_nop 0
	v_add_f32_e64 v68, v88, v66
	v_add_f32_e64 v69, v89, v67
	s_nop 0
	v_mul_f32_e64 v82, v80, v68
	v_mul_f32_e64 v83, v81, v69
	s_nop 0
	v_mul_f32_e64 v84, v78, v82
	v_mul_f32_e64 v85, v79, v83
	s_nop 0
	v_fma_f32 v78, v82, v78, -v84
	v_fma_f32 v79, v83, v79, -v85
	s_nop 0
	v_fma_f32 v72, v82, v72, v78
	v_fma_f32 v73, v83, v73, v79
	v_add_f32_e64 v78, v88, -v68
	v_add_f32_e64 v79, v89, -v69
	s_nop 0
	v_add_f32_e64 v66, v66, v78
	v_add_f32_e64 v67, v67, v79
	v_add_f32_e64 v78, v84, v72
	v_add_f32_e64 v79, v85, v73
	s_nop 0
	v_add_f32_e64 v86, v68, -v78
	v_add_f32_e64 v87, v69, -v79
	v_add_f32_e64 v84, v78, -v84
	v_add_f32_e64 v85, v79, -v85
	v_add_f32_e64 v68, v68, -v86
	v_add_f32_e64 v69, v69, -v87
	s_nop 0
	v_add_f32_e64 v68, v68, -v78
	v_add_f32_e64 v69, v69, -v79
	s_nop 0
	v_add_f32_e64 v66, v66, v68
	v_add_f32_e64 v67, v67, v69
	v_add_f32_e64 v68, v84, -v72
	v_add_f32_e64 v69, v85, -v73
	s_nop 0
	v_add_f32_e64 v66, v68, v66
	v_add_f32_e64 v67, v69, v67
	v_add_f32_e64 v68, v74, v82
	v_add_f32_e64 v69, v75, v83
	v_add_f32_e64 v66, v86, v66
	v_add_f32_e64 v67, v87, v67
	v_add_f32_e64 v72, v68, -v74
	v_add_f32_e64 v73, v69, -v75
	v_mul_f32_e64 v66, v80, v66
	v_mul_f32_e64 v67, v81, v67
	v_add_f32_e64 v72, v82, -v72
	v_add_f32_e64 v73, v83, -v73
	v_cvt_f32_i32_e32 v75, v90
	v_add_f32_e64 v66, v72, v66
	v_add_f32_e64 v67, v73, v67
	v_cvt_f32_i32_e32 v74, v91
	v_add_f32_e64 v72, v68, v66
	v_add_f32_e64 v73, v69, v67
	v_mul_f32_e64 v82, v74, s58
	v_mul_f32_e64 v83, v75, s58
	v_mul_f32_e64 v78, v72, v72
	v_mul_f32_e64 v79, v73, v73
	v_add_f32_e64 v68, v72, -v68
	v_add_f32_e64 v69, v73, -v69
	v_fma_f32 v80, v78, s54, v170
	v_fma_f32 v81, v79, s54, v170
	v_add_f32_e64 v66, v66, -v68
	v_add_f32_e64 v67, v67, -v69
	v_ldexp_f32 v68, v72, 1
	v_fma_f32 v80, v78, v80, s56
	v_fma_f32 v81, v79, v81, s56
	v_ldexp_f32 v69, v73, 1
	v_mul_f32_e64 v72, v72, v78
	v_mul_f32_e64 v73, v73, v79
	v_ldexp_f32 v87, v67, 1
	v_mul_f32_e64 v72, v72, v80
	v_mul_f32_e64 v73, v73, v81
	v_ldexp_f32 v66, v66, 1
	v_add_f32_e64 v78, v68, v72
	v_add_f32_e64 v79, v69, v73
	v_mov_b32_e32 v67, v87
	v_add_f32_e64 v68, v78, -v68
	v_add_f32_e64 v69, v79, -v69
	v_fma_f32 v84, v74, s58, -v82
	v_fma_f32 v85, v75, s58, -v83
	v_add_f32_e64 v68, v72, -v68
	v_add_f32_e64 v69, v73, -v69
	v_fma_f32 v74, v74, s60, v84
	v_fma_f32 v75, v75, s60, v85
	v_add_f32_e64 v80, v66, v68
	v_add_f32_e64 v81, v67, v69
	v_mov_b32_e32 v73, v69
	v_mov_b32_e32 v67, v81
	v_mov_b32_e32 v69, v79
	v_add_f32_e64 v84, v82, v74
	v_add_f32_e64 v85, v83, v75
	v_mov_b32_e32 v72, v82
	v_mov_b32_e32 v86, v74
	v_add_f32_e64 v66, v66, v68
	v_add_f32_e64 v67, v67, v69
	v_add_f32_e64 v68, v78, v80
	v_add_f32_e64 v69, v79, v81
	v_add_f32_e64 v72, v72, v86
	v_add_f32_e64 v73, v73, v87
	v_mov_b32_e32 v86, v84
	v_mov_b32_e32 v87, v83
	v_mov_b32_e32 v88, v68
	v_mov_b32_e32 v89, v75
	v_mov_b32_e32 v92, v84
	v_mov_b32_e32 v93, v79
	v_mov_b32_e32 v94, v68
	v_mov_b32_e32 v95, v81
	v_add_f32_e64 v90, v86, v88
	v_add_f32_e64 v91, v87, v89
	v_add_f32_e64 v92, v92, v94
	v_add_f32_e64 v93, v93, v95
	v_add_f32_e64 v94, v84, v68
	v_add_f32_e64 v95, v85, v69
	v_add_f32_e64 v86, v90, -v86
	v_add_f32_e64 v87, v91, -v87
	v_mov_b32_e32 v90, v68
	v_mov_b32_e32 v91, v95
	v_mov_b32_e32 v96, v78
	v_mov_b32_e32 v97, v85
	v_add_f32_e64 v90, v90, -v96
	v_add_f32_e64 v91, v91, -v97
	v_mov_b32_e32 v96, v84
	v_mov_b32_e32 v97, v95
	v_mov_b32_e32 v83, v91
	v_add_f32_e64 v82, v96, -v82
	v_add_f32_e64 v83, v97, -v83
	v_add_f32_e64 v88, v88, -v86
	v_add_f32_e64 v89, v89, -v87
	v_mov_b32_e32 v96, v82
	v_mov_b32_e32 v97, v87
	v_mov_b32_e32 v87, v79
	v_add_f32_e64 v96, v74, -v96
	v_add_f32_e64 v97, v75, -v97
	v_add_f32_e64 v86, v92, -v86
	v_add_f32_e64 v87, v93, -v87
	v_mov_b32_e32 v75, v85
	v_add_f32_e64 v72, v72, -v86
	v_add_f32_e64 v73, v73, -v87
	v_add_f32_e64 v74, v74, -v82
	v_add_f32_e64 v75, v75, -v83
	v_add_f32_e64 v66, v66, -v90
	v_add_f32_e64 v67, v67, -v91
	v_add_f32_e64 v68, v68, -v78
	v_add_f32_e64 v69, v69, -v79
	v_add_f32_e64 v78, v66, v74
	v_add_f32_e64 v79, v67, v75
	v_mov_b32_e32 v67, v73
	v_add_f32_e64 v68, v80, -v68
	v_add_f32_e64 v69, v81, -v69
	v_add_f32_e64 v80, v88, v72
	v_add_f32_e64 v81, v89, v73
	v_add_f32_e64 v66, v96, v66
	v_add_f32_e64 v67, v97, v67
	v_mov_b32_e32 v75, v89
	v_add_f32_e64 v66, v66, -v74
	v_add_f32_e64 v67, v67, -v75
	v_mov_b32_e32 v72, v78
	v_mov_b32_e32 v73, v81
	v_add_f32_e64 v72, v72, -v66
	v_add_f32_e64 v73, v73, -v67
	v_add_f32_e64 v66, v68, -v66
	v_add_f32_e64 v67, v69, -v67
	v_add_f32_e64 v72, v74, -v72
	v_add_f32_e64 v73, v75, -v73
	v_add_f32_e64 v68, v80, v78
	v_add_f32_e64 v69, v81, v79
	v_add_f32_e64 v66, v66, v72
	v_add_f32_e64 v67, v67, v73
	v_add_f32_e64 v72, v94, v68
	v_add_f32_e64 v73, v95, v69
	s_nop 0
	v_add_f32_e64 v74, v72, -v94
	v_add_f32_e64 v75, v73, -v95
	s_nop 0
	v_add_f32_e64 v68, v68, -v74
	v_add_f32_e64 v69, v69, -v75
	s_nop 0
	v_add_f32_e64 v66, v66, v68
	v_add_f32_e64 v67, v67, v69
	s_nop 0
	v_add_f32_e64 v66, v72, v66
	v_add_f32_e64 v67, v73, v67
	s_nop 0
	v_cndmask_b32_e32 v66, v195, v66, vcc
	v_cndmask_b32_e64 v67, v195, v67, s[12:13]
	v_cndmask_b32_e64 v67, v67, v77, s[14:15]
	v_cndmask_b32_e64 v66, v66, v76, s[16:17]
	v_add_f32_e64 v66, v70, v66
	v_add_f32_e64 v67, v71, v67
	s_mov_b32 s14, s62
	v_mul_f32_e64 v176, v66, s64
	v_mul_f32_e64 v177, v67, s64

.LBB0_2085:
	ds_read_b128 v[136:139], v119 offset:6144
	ds_read_b128 v[140:143], v119 offset:6160
	s_waitcnt vmcnt(5)
	v_lshlrev_b32_e32 v144, 16, v54
	v_and_b32_e32 v145, 0xffff0000, v54
	s_add_i32 s24, s25, s24
	s_waitcnt lgkmcnt(1)
	v_mul_f32_e32 v136, 0xbfb8aa3b, v136
	v_mul_f32_e32 v137, 0xbfb8aa3b, v137
	v_exp_f32_e32 v136, v136
	v_exp_f32_e32 v137, v137
	v_mul_f32_e32 v54, 0xbfb8aa3b, v138
	v_exp_f32_e32 v138, v54
	v_mul_f32_e32 v54, 0xbfb8aa3b, v139
	v_exp_f32_e32 v139, v54
	v_mul_f32_e64 v136, v136, v144
	v_mul_f32_e64 v137, v137, v145
	s_add_i32 s57, s57, 1
	v_cvt_pk_bf16_f32 v54, v136, v137
	v_lshlrev_b32_e32 v136, 16, v55
	v_and_b32_e32 v137, 0xffff0000, v55
	s_waitcnt lgkmcnt(0)
	v_mul_f32_e32 v55, 0xbfb8aa3b, v140
	v_mul_f32_e64 v136, v138, v136
	v_mul_f32_e64 v137, v139, v137
	v_exp_f32_e32 v138, v55
	v_mul_f32_e32 v55, 0xbfb8aa3b, v141
	v_exp_f32_e32 v139, v55
	v_cvt_pk_bf16_f32 v55, v136, v137
	v_lshlrev_b32_e32 v136, 16, v56
	v_and_b32_e32 v137, 0xffff0000, v56
	v_mul_f32_e32 v56, 0xbfb8aa3b, v142
	v_mul_f32_e64 v136, v138, v136
	v_mul_f32_e64 v137, v139, v137
	v_exp_f32_e32 v138, v56
	v_mul_f32_e32 v56, 0xbfb8aa3b, v143
	v_exp_f32_e32 v139, v56
	v_cvt_pk_bf16_f32 v56, v136, v137
	v_lshlrev_b32_e32 v136, 16, v57
	v_and_b32_e32 v137, 0xffff0000, v57
	v_mul_f32_e64 v136, v138, v136
	v_mul_f32_e64 v137, v139, v137
	s_waitcnt vmcnt(4)
	v_lshlrev_b32_e32 v140, 16, v6
	v_cvt_pk_bf16_f32 v57, v136, v137
	ds_write_b128 v120, v[54:57] offset:56320
	ds_read_b128 v[54:57], v121 offset:6144
	ds_read_b128 v[136:139], v121 offset:6160
	v_and_b32_e32 v141, 0xffff0000, v6
	s_mul_i32 s31, s24, 0x1800
	s_mul_hi_i32 s30, s24, 0x1800
	s_waitcnt lgkmcnt(1)
	v_mul_f32_e32 v54, 0xbfb8aa3b, v54
	v_mul_f32_e32 v55, 0xbfb8aa3b, v55
	v_exp_f32_e32 v54, v54
	v_exp_f32_e32 v55, v55
	v_mul_f32_e32 v6, 0xbfb8aa3b, v56
	v_exp_f32_e32 v56, v6
	v_mul_f32_e32 v6, 0xbfb8aa3b, v57
	v_exp_f32_e32 v57, v6
	v_mul_f32_e64 v54, v54, v140
	v_mul_f32_e64 v55, v55, v141
	s_add_u32 s28, s61, s31
	v_cvt_pk_bf16_f32 v6, v54, v55
	v_lshlrev_b32_e32 v54, 16, v7
	v_and_b32_e32 v55, 0xffff0000, v7
	s_waitcnt lgkmcnt(0)
	v_mul_f32_e32 v7, 0xbfb8aa3b, v136
	v_mul_f32_e64 v54, v56, v54
	v_mul_f32_e64 v55, v57, v55
	v_exp_f32_e32 v56, v7
	v_mul_f32_e32 v7, 0xbfb8aa3b, v137
	v_exp_f32_e32 v57, v7
	v_cvt_pk_bf16_f32 v7, v54, v55
	v_lshlrev_b32_e32 v54, 16, v8
	v_and_b32_e32 v55, 0xffff0000, v8
	v_mul_f32_e32 v8, 0xbfb8aa3b, v138
	v_mul_f32_e64 v54, v56, v54
	v_mul_f32_e64 v55, v57, v55
	v_exp_f32_e32 v56, v8
	v_mul_f32_e32 v8, 0xbfb8aa3b, v139
	v_exp_f32_e32 v57, v8
	v_cvt_pk_bf16_f32 v8, v54, v55
	v_lshlrev_b32_e32 v54, 16, v9
	v_and_b32_e32 v55, 0xffff0000, v9
	v_mul_f32_e64 v54, v56, v54
	v_mul_f32_e64 v55, v57, v55
	s_addc_u32 s29, s62, s30
	v_cvt_pk_bf16_f32 v9, v54, v55
	ds_write_b128 v122, v[6:9] offset:56320
	s_waitcnt vmcnt(3)
	ds_write_b128 v123, v[2:5]
	s_waitcnt vmcnt(2)
	ds_write_b128 v124, v[10:13]
	s_waitcnt vmcnt(1)
	ds_write_b128 v123, v[14:17] offset:16896
	s_waitcnt vmcnt(0)
	ds_write_b128 v125, v[18:21]
	v_lshl_add_u64 v[2:3], s[28:29], 0, v[96:97]
	s_add_u32 s28, s20, s31
	s_addc_u32 s29, s21, s30
	s_add_u32 s28, s28, s56
	s_addc_u32 s29, s29, 0
	s_add_u32 s28, s28, 0xad20800
	v_add_co_u32_e32 v4, vcc, s42, v2
	s_addc_u32 s29, s29, 0
	s_nop 0
	v_addc_co_u32_e32 v5, vcc, 0, v3, vcc
	v_lshl_add_u64 v[14:15], s[28:29], 0, v[98:99]
	v_add_co_u32_e32 v10, vcc, s43, v14
	global_load_dwordx4 v[54:57], v[2:3], off offset:1024
	global_load_dwordx4 v[6:9], v[4:5], off offset:1024
	v_addc_co_u32_e32 v11, vcc, 0, v15, vcc
	v_add_co_u32_e32 v16, vcc, s42, v14
	global_load_dwordx4 v[2:5], v[14:15], off
	s_nop 0
	global_load_dwordx4 v[10:13], v[10:11], off
	v_addc_co_u32_e32 v17, vcc, 0, v15, vcc
	v_add_co_u32_e32 v18, vcc, s44, v14
	s_cmp_eq_u32 s23, s57
	s_nop 0
	v_addc_co_u32_e32 v19, vcc, 0, v15, vcc
	global_load_dwordx4 v[14:17], v[16:17], off
	s_nop 0
	global_load_dwordx4 v[18:21], v[18:19], off
	s_waitcnt lgkmcnt(0)
	s_barrier
	ds_read_b64_tr_b16 v[138:139], v127 offset:57408
	ds_read_b64_tr_b16 v[136:137], v127 offset:56320
	ds_read_b64_tr_b16 v[142:143], v126 offset:2112
	ds_read_b64_tr_b16 v[140:141], v126
	ds_read_b64_tr_b16 v[146:147], v126 offset:2144
	ds_read_b64_tr_b16 v[144:145], v126 offset:32
	ds_read_b64_tr_b16 v[148:149], v127 offset:56352
	ds_read_b64_tr_b16 v[156:157], v127 offset:56384
	ds_read_b64_tr_b16 v[160:161], v127 offset:56416
	ds_read_b64_tr_b16 v[150:151], v127 offset:57440
	ds_read_b64_tr_b16 v[158:159], v127 offset:57472
	ds_read_b64_tr_b16 v[162:163], v127 offset:57504
	ds_read_b64_tr_b16 v[164:165], v127 offset:65024
	ds_read_b64_tr_b16 v[166:167], v128 offset:57408
	ds_read_b64_tr_b16 v[168:169], v126 offset:16896
	ds_read_b64_tr_b16 v[170:171], v126 offset:19008
	ds_read_b64_tr_b16 v[174:175], v126 offset:19040
	ds_read_b64_tr_b16 v[172:173], v126 offset:16928
	s_waitcnt lgkmcnt(8)
	v_mfma_f32_16x16x32_bf16 v[58:61], v[148:151], v[140:143], v[58:61]
	v_mfma_f32_16x16x32_bf16 v[78:81], v[148:151], v[144:147], v[78:81]
	v_mfma_f32_16x16x32_bf16 v[66:69], v[136:139], v[140:143], v[66:69]
	v_mfma_f32_16x16x32_bf16 v[62:65], v[136:139], v[144:147], v[62:65]
	ds_read_b64_tr_b16 v[136:137], v127 offset:65056
	ds_read_b64_tr_b16 v[176:177], v127 offset:65088
	ds_read_b64_tr_b16 v[180:181], v127 offset:65120
	ds_read_b64_tr_b16 v[138:139], v128 offset:57440
	ds_read_b64_tr_b16 v[178:179], v128 offset:57472
	ds_read_b64_tr_b16 v[182:183], v128 offset:57504
	s_waitcnt lgkmcnt(2)
	v_mfma_f32_16x16x32_bf16 v[58:61], v[136:139], v[168:171], v[58:61]
	v_mfma_f32_16x16x32_bf16 v[78:81], v[136:139], v[172:175], v[78:81]
	ds_read_b64_tr_b16 v[136:137], v127 offset:56448
	ds_read_b64_tr_b16 v[138:139], v127 offset:57536
	v_mfma_f32_16x16x32_bf16 v[74:77], v[156:159], v[140:143], v[74:77]
	v_mfma_f32_16x16x32_bf16 v[70:73], v[156:159], v[144:147], v[70:73]
	v_mfma_f32_16x16x32_bf16 v[82:85], v[160:163], v[140:143], v[82:85]
	v_mfma_f32_16x16x32_bf16 v[86:89], v[160:163], v[144:147], v[86:89]
	ds_read_b64_tr_b16 v[148:149], v127 offset:56480
	ds_read_b64_tr_b16 v[156:157], v127 offset:56512
	ds_read_b64_tr_b16 v[160:161], v127 offset:56544
	ds_read_b64_tr_b16 v[150:151], v127 offset:57568
	ds_read_b64_tr_b16 v[158:159], v127 offset:57600
	ds_read_b64_tr_b16 v[162:163], v127 offset:57632
	s_waitcnt lgkmcnt(2)
	v_mfma_f32_16x16x32_bf16 v[22:25], v[148:151], v[140:143], v[22:25]
	v_mfma_f32_16x16x32_bf16 v[50:53], v[148:151], v[144:147], v[50:53]
	v_lshl_add_u32 v150, s63, 9, v111
	v_mfma_f32_16x16x32_bf16 v[66:69], v[164:167], v[168:171], v[66:69]
	v_mfma_f32_16x16x32_bf16 v[62:65], v[164:167], v[172:175], v[62:65]
	ds_read_b64_tr_b16 v[164:165], v127 offset:65152
	ds_read_b64_tr_b16 v[166:167], v128 offset:57536
	v_mfma_f32_16x16x32_bf16 v[74:77], v[176:179], v[168:171], v[74:77]
	v_mfma_f32_16x16x32_bf16 v[70:73], v[176:179], v[172:175], v[70:73]
	v_mfma_f32_16x16x32_bf16 v[82:85], v[180:183], v[168:171], v[82:85]
	v_mfma_f32_16x16x32_bf16 v[86:89], v[180:183], v[172:175], v[86:89]
	v_mfma_f32_16x16x32_bf16 v[30:33], v[136:139], v[140:143], v[30:33]
	v_mfma_f32_16x16x32_bf16 v[26:29], v[136:139], v[144:147], v[26:29]
	ds_read_b64_tr_b16 v[136:137], v127 offset:65184
	ds_read_b64_tr_b16 v[176:177], v127 offset:65216
	ds_read_b64_tr_b16 v[180:181], v127 offset:65248
	ds_read_b64_tr_b16 v[138:139], v128 offset:57568
	ds_read_b64_tr_b16 v[178:179], v128 offset:57600
	ds_read_b64_tr_b16 v[182:183], v128 offset:57632
	s_waitcnt lgkmcnt(2)
	v_mfma_f32_16x16x32_bf16 v[22:25], v[136:139], v[168:171], v[22:25]
	v_mfma_f32_16x16x32_bf16 v[50:53], v[136:139], v[172:175], v[50:53]
	ds_read_b128 v[136:139], v150 offset:4096
	v_mfma_f32_16x16x32_bf16 v[34:37], v[156:159], v[140:143], v[34:37]
	v_mfma_f32_16x16x32_bf16 v[38:41], v[160:163], v[140:143], v[38:41]
	ds_read_b128 v[140:143], v150 offset:4160
	s_waitcnt lgkmcnt(1)
	v_mul_f32_e32 v136, 0x3fb8aa3b, v136
	v_mfma_f32_16x16x32_bf16 v[46:49], v[156:159], v[144:147], v[46:49]
	v_mfma_f32_16x16x32_bf16 v[42:45], v[160:163], v[144:147], v[42:45]
	v_exp_f32_e32 v144, v136
	v_mul_f32_e32 v145, 0x3fb8aa3b, v137
	v_mul_f32_e32 v136, 0x3fb8aa3b, v138
	v_mul_f32_e32 v137, 0x3fb8aa3b, v139
	v_exp_f32_e32 v136, v136
	v_exp_f32_e32 v137, v137
	v_exp_f32_e32 v145, v145
	v_mfma_f32_16x16x32_bf16 v[30:33], v[164:167], v[168:171], v[30:33]
	v_mul_f32_e64 v68, v68, v136
	v_mul_f32_e64 v69, v69, v137
	v_mul_f32_e64 v64, v64, v136
	v_mul_f32_e64 v65, v65, v137
	s_waitcnt lgkmcnt(0)
	v_mul_f32_e32 v136, 0x3fb8aa3b, v140
	v_mul_f32_e32 v137, 0x3fb8aa3b, v142
	v_exp_f32_e32 v146, v136
	v_mul_f32_e32 v136, 0x3fb8aa3b, v141
	v_exp_f32_e32 v148, v137
	v_mul_f32_e32 v137, 0x3fb8aa3b, v143
	v_exp_f32_e32 v149, v137
	v_exp_f32_e32 v147, v136
	ds_read_b128 v[136:139], v150 offset:4224
	ds_read_b128 v[140:143], v150 offset:4288
	v_mul_f32_e64 v66, v66, v144
	v_mul_f32_e64 v67, v67, v145
	v_mul_f32_e64 v62, v62, v144
	v_mul_f32_e64 v63, v63, v145
	v_mul_f32_e64 v60, v60, v148
	v_mul_f32_e64 v61, v61, v149
	s_waitcnt lgkmcnt(1)
	v_mul_f32_e32 v136, 0x3fb8aa3b, v136
	v_exp_f32_e32 v144, v136
	v_mul_f32_e32 v145, 0x3fb8aa3b, v137
	v_mul_f32_e32 v136, 0x3fb8aa3b, v138
	v_mul_f32_e32 v137, 0x3fb8aa3b, v139
	v_exp_f32_e32 v136, v136
	v_exp_f32_e32 v137, v137
	v_mul_f32_e64 v58, v58, v146
	v_mul_f32_e64 v59, v59, v147
	v_mul_f32_e64 v80, v80, v148
	v_mul_f32_e64 v81, v81, v149
	v_mul_f32_e64 v78, v78, v146
	v_mul_f32_e64 v79, v79, v147
	v_mul_f32_e64 v76, v76, v136
	v_mul_f32_e64 v77, v77, v137
	v_mul_f32_e64 v72, v72, v136
	v_mul_f32_e64 v73, v73, v137
	s_waitcnt lgkmcnt(0)
	v_mul_f32_e32 v136, 0x3fb8aa3b, v140
	v_mul_f32_e32 v137, 0x3fb8aa3b, v142
	v_exp_f32_e32 v146, v136
	v_mul_f32_e32 v136, 0x3fb8aa3b, v141
	v_exp_f32_e32 v148, v137
	v_mul_f32_e32 v137, 0x3fb8aa3b, v143
	v_exp_f32_e32 v149, v137
	v_exp_f32_e32 v147, v136
	ds_read_b128 v[136:139], v150 offset:4352
	ds_read_b128 v[140:143], v150 offset:4416
	v_exp_f32_e32 v145, v145
	v_mfma_f32_16x16x32_bf16 v[26:29], v[164:167], v[172:175], v[26:29]
	v_mul_f32_e64 v84, v84, v148
	v_mul_f32_e64 v85, v85, v149
	s_waitcnt lgkmcnt(1)
	v_mul_f32_e32 v136, 0x3fb8aa3b, v136
	v_mul_f32_e64 v74, v74, v144
	v_mul_f32_e64 v75, v75, v145
	v_mul_f32_e64 v70, v70, v144
	v_mul_f32_e64 v71, v71, v145
	v_exp_f32_e32 v144, v136
	v_mul_f32_e32 v145, 0x3fb8aa3b, v137
	v_mul_f32_e32 v136, 0x3fb8aa3b, v138
	v_mul_f32_e32 v137, 0x3fb8aa3b, v139
	v_exp_f32_e32 v136, v136
	v_exp_f32_e32 v137, v137
	v_mul_f32_e64 v82, v82, v146
	v_mul_f32_e64 v83, v83, v147
	v_mul_f32_e64 v88, v88, v148
	v_mul_f32_e64 v89, v89, v149
	v_mul_f32_e64 v86, v86, v146
	v_mul_f32_e64 v87, v87, v147
	v_mul_f32_e64 v32, v32, v136
	v_mul_f32_e64 v33, v33, v137
	v_mul_f32_e64 v28, v28, v136
	v_mul_f32_e64 v29, v29, v137
	s_waitcnt lgkmcnt(0)
	v_mul_f32_e32 v136, 0x3fb8aa3b, v140
	v_mul_f32_e32 v137, 0x3fb8aa3b, v142
	v_exp_f32_e32 v146, v136
	v_mul_f32_e32 v136, 0x3fb8aa3b, v141
	v_exp_f32_e32 v148, v137
	v_mul_f32_e32 v137, 0x3fb8aa3b, v143
	v_exp_f32_e32 v149, v137
	v_exp_f32_e32 v147, v136
	ds_read_b128 v[136:139], v150 offset:4480
	ds_read_b128 v[140:143], v150 offset:4544
	v_mfma_f32_16x16x32_bf16 v[34:37], v[176:179], v[168:171], v[34:37]
	v_exp_f32_e32 v145, v145
	v_mul_f32_e64 v24, v24, v148
	v_mul_f32_e64 v25, v25, v149
	s_waitcnt lgkmcnt(1)
	v_mul_f32_e32 v136, 0x3fb8aa3b, v136
	v_mul_f32_e32 v137, 0x3fb8aa3b, v137
	v_mul_f32_e32 v138, 0x3fb8aa3b, v138
	v_mul_f32_e32 v139, 0x3fb8aa3b, v139
	s_waitcnt lgkmcnt(0)
	v_mul_f32_e32 v140, 0x3fb8aa3b, v140
	v_mul_f32_e32 v141, 0x3fb8aa3b, v141
	v_mul_f32_e32 v142, 0x3fb8aa3b, v142
	v_mul_f32_e32 v143, 0x3fb8aa3b, v143
	v_mfma_f32_16x16x32_bf16 v[46:49], v[176:179], v[172:175], v[46:49]
	v_exp_f32_e32 v136, v136
	v_exp_f32_e32 v138, v138
	v_exp_f32_e32 v139, v139
	v_mfma_f32_16x16x32_bf16 v[38:41], v[180:183], v[168:171], v[38:41]
	v_exp_f32_e32 v137, v137
	v_exp_f32_e32 v140, v140
	v_exp_f32_e32 v142, v142
	v_mfma_f32_16x16x32_bf16 v[42:45], v[180:183], v[172:175], v[42:45]
	v_exp_f32_e32 v143, v143
	v_exp_f32_e32 v141, v141
	v_mul_f32_e64 v30, v30, v144
	v_mul_f32_e64 v31, v31, v145
	v_mul_f32_e64 v26, v26, v144
	v_mul_f32_e64 v27, v27, v145
	v_mul_f32_e64 v22, v22, v146
	v_mul_f32_e64 v23, v23, v147
	v_mul_f32_e64 v52, v52, v148
	v_mul_f32_e64 v53, v53, v149
	v_mul_f32_e64 v50, v50, v146
	v_mul_f32_e64 v51, v51, v147
	v_mul_f32_e64 v36, v36, v138
	v_mul_f32_e64 v37, v37, v139
	v_mul_f32_e64 v34, v34, v136
	v_mul_f32_e64 v35, v35, v137
	v_mul_f32_e64 v48, v48, v138
	v_mul_f32_e64 v49, v49, v139
	v_mul_f32_e64 v46, v46, v136
	v_mul_f32_e64 v47, v47, v137
	v_mul_f32_e64 v40, v40, v142
	v_mul_f32_e64 v41, v41, v143
	v_mul_f32_e64 v38, v38, v140
	v_mul_f32_e64 v39, v39, v141
	v_mul_f32_e64 v44, v44, v142
	v_mul_f32_e64 v45, v45, v143
	v_mul_f32_e64 v42, v42, v140
	v_mul_f32_e64 v43, v43, v141
	s_cbranch_scc1 .LBB0_2101

.LBB0_2111:
	s_or_b64 exec, exec, s[14:15]
	ds_read_b128 v[90:93], v119 offset:6144
	ds_read_b128 v[130:133], v119 offset:6160
	s_waitcnt vmcnt(5)
	v_lshlrev_b32_e32 v134, 16, v54
	v_and_b32_e32 v135, 0xffff0000, v54
	s_waitcnt lgkmcnt(1)
	v_mul_f32_e32 v90, 0xbfb8aa3b, v90
	v_mul_f32_e32 v91, 0xbfb8aa3b, v91
	v_exp_f32_e32 v90, v90
	v_exp_f32_e32 v91, v91
	v_mul_f32_e32 v54, 0xbfb8aa3b, v92
	v_exp_f32_e32 v92, v54
	v_mul_f32_e32 v54, 0xbfb8aa3b, v93
	v_exp_f32_e32 v93, v54
	v_mul_f32_e64 v90, v90, v134
	v_mul_f32_e64 v91, v91, v135
	s_nop 0
	v_cvt_pk_bf16_f32 v54, v90, v91
	v_lshlrev_b32_e32 v90, 16, v55
	v_and_b32_e32 v91, 0xffff0000, v55
	s_waitcnt lgkmcnt(0)
	v_mul_f32_e32 v55, 0xbfb8aa3b, v130
	v_mul_f32_e64 v90, v92, v90
	v_mul_f32_e64 v91, v93, v91
	v_exp_f32_e32 v92, v55
	v_mul_f32_e32 v55, 0xbfb8aa3b, v131
	v_exp_f32_e32 v93, v55
	v_cvt_pk_bf16_f32 v55, v90, v91
	v_lshlrev_b32_e32 v90, 16, v56
	v_and_b32_e32 v91, 0xffff0000, v56
	v_mul_f32_e32 v56, 0xbfb8aa3b, v132
	v_mul_f32_e64 v90, v92, v90
	v_mul_f32_e64 v91, v93, v91
	v_exp_f32_e32 v92, v56
	v_mul_f32_e32 v56, 0xbfb8aa3b, v133
	v_exp_f32_e32 v93, v56
	v_cvt_pk_bf16_f32 v56, v90, v91
	v_lshlrev_b32_e32 v90, 16, v57
	v_and_b32_e32 v91, 0xffff0000, v57
	v_mul_f32_e64 v90, v92, v90
	v_mul_f32_e64 v91, v93, v91
	s_waitcnt vmcnt(4)
	v_lshlrev_b32_e32 v130, 16, v6
	v_cvt_pk_bf16_f32 v57, v90, v91
	ds_write_b128 v120, v[54:57] offset:56320
	ds_read_b128 v[54:57], v121 offset:6144
	ds_read_b128 v[90:93], v121 offset:6160
	v_and_b32_e32 v131, 0xffff0000, v6
	s_waitcnt lgkmcnt(1)
	v_mul_f32_e32 v54, 0xbfb8aa3b, v54
	v_mul_f32_e32 v55, 0xbfb8aa3b, v55
	v_exp_f32_e32 v54, v54
	v_exp_f32_e32 v55, v55
	v_mul_f32_e32 v6, 0xbfb8aa3b, v56
	v_exp_f32_e32 v56, v6
	v_mul_f32_e32 v6, 0xbfb8aa3b, v57
	v_exp_f32_e32 v57, v6
	v_mul_f32_e64 v54, v54, v130
	v_mul_f32_e64 v55, v55, v131
	s_nop 0
	v_cvt_pk_bf16_f32 v6, v54, v55
	v_lshlrev_b32_e32 v54, 16, v7
	v_and_b32_e32 v55, 0xffff0000, v7
	s_waitcnt lgkmcnt(0)
	v_mul_f32_e32 v7, 0xbfb8aa3b, v90
	v_mul_f32_e64 v54, v56, v54
	v_mul_f32_e64 v55, v57, v55
	v_exp_f32_e32 v56, v7
	v_mul_f32_e32 v7, 0xbfb8aa3b, v91
	v_exp_f32_e32 v57, v7
	v_cvt_pk_bf16_f32 v7, v54, v55
	v_lshlrev_b32_e32 v54, 16, v8
	v_and_b32_e32 v55, 0xffff0000, v8
	v_mul_f32_e32 v8, 0xbfb8aa3b, v92
	v_mul_f32_e64 v54, v56, v54
	v_mul_f32_e64 v55, v57, v55
	v_exp_f32_e32 v56, v8
	v_mul_f32_e32 v8, 0xbfb8aa3b, v93
	v_exp_f32_e32 v57, v8
	v_cvt_pk_bf16_f32 v8, v54, v55
	v_lshlrev_b32_e32 v54, 16, v9
	v_and_b32_e32 v55, 0xffff0000, v9
	v_mul_f32_e64 v54, v56, v54
	v_mul_f32_e64 v55, v57, v55
	s_nop 0
	v_cvt_pk_bf16_f32 v9, v54, v55
	ds_write_b128 v122, v[6:9] offset:56320
	s_waitcnt vmcnt(3)
	ds_write_b128 v123, v[2:5]
	s_waitcnt vmcnt(2)
	ds_write_b128 v124, v[10:13]
	s_waitcnt vmcnt(1)
	ds_write_b128 v123, v[14:17] offset:16896
	s_waitcnt vmcnt(0)
	ds_write_b128 v125, v[18:21]
	s_waitcnt lgkmcnt(0)
	s_barrier
	ds_read_b64_tr_b16 v[4:5], v127 offset:57408
	ds_read_b64_tr_b16 v[2:3], v127 offset:56320
	ds_read_b64_tr_b16 v[8:9], v126 offset:2112
	ds_read_b64_tr_b16 v[6:7], v126
	ds_read_b64_tr_b16 v[12:13], v126 offset:2144
	ds_read_b64_tr_b16 v[10:11], v126 offset:32
	ds_read_b64_tr_b16 v[14:15], v127 offset:56352
	ds_read_b64_tr_b16 v[18:19], v127 offset:56384
	ds_read_b64_tr_b16 v[54:55], v127 offset:56416
	ds_read_b64_tr_b16 v[16:17], v127 offset:57440
	ds_read_b64_tr_b16 v[20:21], v127 offset:57472
	ds_read_b64_tr_b16 v[56:57], v127 offset:57504
	ds_read_b64_tr_b16 v[90:91], v127 offset:65024
	ds_read_b64_tr_b16 v[92:93], v128 offset:57408
	ds_read_b64_tr_b16 v[130:131], v126 offset:16896
	ds_read_b64_tr_b16 v[132:133], v126 offset:19008
	ds_read_b64_tr_b16 v[136:137], v126 offset:19040
	ds_read_b64_tr_b16 v[134:135], v126 offset:16928
	s_waitcnt lgkmcnt(8)
	v_mfma_f32_16x16x32_bf16 v[58:61], v[14:17], v[6:9], v[58:61]
	v_mfma_f32_16x16x32_bf16 v[14:17], v[14:17], v[10:13], v[78:81]
	v_mfma_f32_16x16x32_bf16 v[66:69], v[2:5], v[6:9], v[66:69]
	v_mfma_f32_16x16x32_bf16 v[2:5], v[2:5], v[10:13], v[62:65]
	s_nop 2
	ds_read_b64_tr_b16 v[62:63], v127 offset:65056
	ds_read_b64_tr_b16 v[138:139], v127 offset:65088
	ds_read_b64_tr_b16 v[142:143], v127 offset:65120
	ds_read_b64_tr_b16 v[64:65], v128 offset:57440
	ds_read_b64_tr_b16 v[140:141], v128 offset:57472
	ds_read_b64_tr_b16 v[144:145], v128 offset:57504
	s_waitcnt lgkmcnt(2)
	v_mfma_f32_16x16x32_bf16 v[58:61], v[62:65], v[130:133], v[58:61]
	v_mfma_f32_16x16x32_bf16 v[14:17], v[62:65], v[134:137], v[14:17]
	v_mfma_f32_16x16x32_bf16 v[62:65], v[18:21], v[6:9], v[74:77]
	s_nop 2
	ds_read_b64_tr_b16 v[74:75], v127 offset:56448
	ds_read_b64_tr_b16 v[76:77], v127 offset:57536
	v_mfma_f32_16x16x32_bf16 v[18:21], v[18:21], v[10:13], v[70:73]
	v_mfma_f32_16x16x32_bf16 v[70:73], v[54:57], v[6:9], v[82:85]
	v_mfma_f32_16x16x32_bf16 v[54:57], v[54:57], v[10:13], v[86:89]
	ds_read_b64_tr_b16 v[78:79], v127 offset:56480
	s_nop 0
	ds_read_b64_tr_b16 v[82:83], v127 offset:56512
	ds_read_b64_tr_b16 v[86:87], v127 offset:56544
	ds_read_b64_tr_b16 v[80:81], v127 offset:57568
	ds_read_b64_tr_b16 v[84:85], v127 offset:57600
	ds_read_b64_tr_b16 v[88:89], v127 offset:57632
	s_waitcnt lgkmcnt(1)
	v_mfma_f32_16x16x32_bf16 v[34:37], v[82:85], v[6:9], v[34:37]
	v_mfma_f32_16x16x32_bf16 v[46:49], v[82:85], v[10:13], v[46:49]
	v_add_u32_e32 v82, s23, v111
	s_ashr_i32 s23, s22, 31
	s_lshl_b64 s[14:15], s[22:23], 17
	v_mfma_f32_16x16x32_bf16 v[66:69], v[90:93], v[130:133], v[66:69]
	v_mfma_f32_16x16x32_bf16 v[2:5], v[90:93], v[134:137], v[2:5]
	ds_read_b64_tr_b16 v[90:91], v127 offset:65152
	ds_read_b64_tr_b16 v[92:93], v128 offset:57536
	v_mfma_f32_16x16x32_bf16 v[62:65], v[138:141], v[130:133], v[62:65]
	v_mfma_f32_16x16x32_bf16 v[18:21], v[138:141], v[134:137], v[18:21]
	v_mfma_f32_16x16x32_bf16 v[70:73], v[142:145], v[130:133], v[70:73]
	v_mfma_f32_16x16x32_bf16 v[54:57], v[142:145], v[134:137], v[54:57]
	v_mfma_f32_16x16x32_bf16 v[30:33], v[74:77], v[6:9], v[30:33]
	v_mfma_f32_16x16x32_bf16 v[26:29], v[74:77], v[10:13], v[26:29]
	ds_read_b64_tr_b16 v[74:75], v127 offset:65184
	ds_read_b64_tr_b16 v[138:139], v127 offset:65216
	ds_read_b64_tr_b16 v[142:143], v127 offset:65248
	ds_read_b64_tr_b16 v[76:77], v128 offset:57568
	ds_read_b64_tr_b16 v[140:141], v128 offset:57600
	ds_read_b64_tr_b16 v[144:145], v128 offset:57632
	v_mfma_f32_16x16x32_bf16 v[22:25], v[78:81], v[6:9], v[22:25]
	s_waitcnt lgkmcnt(8)
	v_mfma_f32_16x16x32_bf16 v[6:9], v[86:89], v[6:9], v[38:41]
	s_nop 2
	ds_read_b128 v[38:41], v82 offset:4096
	v_mfma_f32_16x16x32_bf16 v[50:53], v[78:81], v[10:13], v[50:53]
	v_mfma_f32_16x16x32_bf16 v[10:13], v[86:89], v[10:13], v[42:45]
	s_nop 2
	ds_read_b128 v[42:45], v82 offset:4160
	s_waitcnt lgkmcnt(1)
	v_mul_f32_e32 v38, 0x3fb8aa3b, v38
	v_mfma_f32_16x16x32_bf16 v[22:25], v[74:77], v[130:133], v[22:25]
	s_waitcnt lgkmcnt(0)
	v_mul_f32_e32 v42, 0x3fb8aa3b, v42
	v_mfma_f32_16x16x32_bf16 v[50:53], v[74:77], v[134:137], v[50:53]
	v_exp_f32_e32 v74, v38
	v_mul_f32_e32 v38, 0x3fb8aa3b, v39
	v_mul_f32_e32 v39, 0x3fb8aa3b, v40
	v_exp_f32_e32 v76, v39
	v_mul_f32_e32 v39, 0x3fb8aa3b, v41
	v_exp_f32_e32 v77, v39
	v_exp_f32_e32 v75, v38
	v_mfma_f32_16x16x32_bf16 v[30:33], v[90:93], v[130:133], v[30:33]
	v_mul_f32_e64 v40, v68, v76
	v_mul_f32_e64 v41, v69, v77
	v_mul_f32_e64 v4, v4, v76
	v_mul_f32_e64 v5, v5, v77
	v_exp_f32_e32 v76, v42
	v_mul_f32_e32 v42, 0x3fb8aa3b, v43
	v_mul_f32_e32 v43, 0x3fb8aa3b, v44
	v_exp_f32_e32 v78, v43
	v_mul_f32_e32 v43, 0x3fb8aa3b, v45
	v_exp_f32_e32 v79, v43
	v_exp_f32_e32 v77, v42
	ds_read_b128 v[42:45], v82 offset:4224
	v_mul_f32_e64 v38, v66, v74
	v_mul_f32_e64 v39, v67, v75
	ds_read_b128 v[66:69], v82 offset:4288
	v_mul_f32_e64 v2, v2, v74
	v_mul_f32_e64 v3, v3, v75
	v_mul_f32_e64 v60, v60, v78
	v_mul_f32_e64 v61, v61, v79
	s_waitcnt lgkmcnt(1)
	v_mul_f32_e32 v42, 0x3fb8aa3b, v42
	v_exp_f32_e32 v74, v42
	v_mul_f32_e32 v42, 0x3fb8aa3b, v43
	v_mul_f32_e32 v43, 0x3fb8aa3b, v44
	v_exp_f32_e32 v75, v42
	v_exp_f32_e32 v80, v43
	v_mul_f32_e32 v43, 0x3fb8aa3b, v45
	v_exp_f32_e32 v81, v43
	v_mul_f32_e64 v42, v62, v74
	v_mul_f32_e64 v43, v63, v75
	s_waitcnt lgkmcnt(0)
	v_mul_f32_e32 v62, 0x3fb8aa3b, v66
	v_mul_f32_e32 v63, 0x3fb8aa3b, v68
	v_mul_f32_e64 v58, v58, v76
	v_mul_f32_e64 v59, v59, v77
	v_mul_f32_e64 v16, v16, v78
	v_mul_f32_e64 v17, v17, v79
	v_mul_f32_e64 v14, v14, v76
	v_mul_f32_e64 v15, v15, v77
	v_exp_f32_e32 v76, v62
	v_mul_f32_e32 v62, 0x3fb8aa3b, v67
	v_exp_f32_e32 v78, v63
	v_mul_f32_e32 v63, 0x3fb8aa3b, v69
	v_mul_f32_e64 v44, v64, v80
	v_mul_f32_e64 v45, v65, v81
	v_exp_f32_e32 v79, v63
	v_exp_f32_e32 v77, v62
	ds_read_b128 v[62:65], v82 offset:4352
	v_mul_f32_e64 v18, v18, v74
	v_mul_f32_e64 v19, v19, v75
	v_mul_f32_e64 v68, v72, v78
	v_mul_f32_e64 v69, v73, v79
	v_mul_f32_e64 v66, v70, v76
	v_mul_f32_e64 v67, v71, v77
	ds_read_b128 v[70:73], v82 offset:4416
	s_waitcnt lgkmcnt(1)
	v_mul_f32_e32 v62, 0x3fb8aa3b, v62
	v_exp_f32_e32 v74, v62
	v_mul_f32_e32 v75, 0x3fb8aa3b, v63
	v_mul_f32_e32 v62, 0x3fb8aa3b, v64
	v_mul_f32_e32 v63, 0x3fb8aa3b, v65
	v_mfma_f32_16x16x32_bf16 v[26:29], v[90:93], v[134:137], v[26:29]
	v_exp_f32_e32 v62, v62
	v_exp_f32_e32 v63, v63
	v_mul_f32_e64 v56, v56, v78
	v_mul_f32_e64 v57, v57, v79
	v_mul_f32_e64 v54, v54, v76
	v_mul_f32_e64 v55, v55, v77
	v_mfma_f32_16x16x32_bf16 v[34:37], v[138:141], v[130:133], v[34:37]
	v_mul_f32_e64 v32, v32, v62
	v_mul_f32_e64 v33, v33, v63
	s_nop 0
	v_mul_f32_e64 v28, v28, v62
	v_mul_f32_e64 v29, v29, v63
	s_waitcnt lgkmcnt(0)
	v_mul_f32_e32 v62, 0x3fb8aa3b, v70
	v_mul_f32_e32 v63, 0x3fb8aa3b, v72
	v_exp_f32_e32 v76, v62
	v_mul_f32_e32 v62, 0x3fb8aa3b, v71
	v_exp_f32_e32 v78, v63
	v_mul_f32_e32 v63, 0x3fb8aa3b, v73
	v_exp_f32_e32 v79, v63
	v_exp_f32_e32 v77, v62
	ds_read_b128 v[62:65], v82 offset:4480
	ds_read_b128 v[70:73], v82 offset:4544
	v_mfma_f32_16x16x32_bf16 v[46:49], v[138:141], v[134:137], v[46:49]
	v_mul_f32_e64 v20, v20, v80
	v_mul_f32_e64 v21, v21, v81
	v_exp_f32_e32 v75, v75
	s_waitcnt lgkmcnt(1)
	v_mul_f32_e32 v62, 0x3fb8aa3b, v62
	v_mul_f32_e32 v63, 0x3fb8aa3b, v63
	v_exp_f32_e32 v62, v62
	v_exp_f32_e32 v63, v63
	v_mul_f32_e64 v30, v30, v74
	v_mul_f32_e64 v31, v31, v75
	v_mul_f32_e64 v26, v26, v74
	v_mul_f32_e64 v27, v27, v75
	v_mul_f32_e32 v64, 0x3fb8aa3b, v64
	v_mul_f32_e64 v34, v34, v62
	v_mul_f32_e64 v35, v35, v63
	v_mul_f32_e64 v46, v46, v62
	v_mul_f32_e64 v47, v47, v63
	v_lshl_add_u64 v[62:63], v[102:103], 0, s[14:15]
	global_store_dwordx4 v[62:63], v[38:41], off
	v_mul_f32_e32 v65, 0x3fb8aa3b, v65
	v_mul_f32_e64 v24, v24, v78
	v_mul_f32_e64 v25, v25, v79
	v_add_co_u32_e32 v38, vcc, s40, v62
	v_mul_f32_e64 v22, v22, v76
	v_mul_f32_e64 v23, v23, v77
	s_nop 0
	v_addc_co_u32_e32 v39, vcc, 0, v63, vcc
	global_store_dwordx4 v[38:39], v[2:5], off
	v_exp_f32_e32 v64, v64
	v_exp_f32_e32 v65, v65
	v_add_co_u32_e32 v2, vcc, s34, v62
	v_mul_f32_e64 v52, v52, v78
	v_mul_f32_e64 v53, v53, v79
	s_nop 0
	v_addc_co_u32_e32 v3, vcc, 0, v63, vcc
	global_store_dwordx4 v[2:3], v[58:61], off
	v_add_co_u32_e32 v2, vcc, s41, v62
	v_mul_f32_e64 v50, v50, v76
	v_mul_f32_e64 v51, v51, v77
	s_nop 0
	v_addc_co_u32_e32 v3, vcc, 0, v63, vcc
	global_store_dwordx4 v[2:3], v[14:17], off
	v_add_co_u32_e32 v2, vcc, s39, v62
	s_waitcnt lgkmcnt(0)
	v_mul_f32_e32 v70, 0x3fb8aa3b, v70
	v_addc_co_u32_e32 v3, vcc, 0, v63, vcc
	global_store_dwordx4 v[2:3], v[42:45], off
	v_add_co_u32_e32 v2, vcc, s48, v62
	v_mul_f32_e32 v71, 0x3fb8aa3b, v71
	s_nop 0
	v_addc_co_u32_e32 v3, vcc, 0, v63, vcc
	global_store_dwordx4 v[2:3], v[18:21], off
	v_add_co_u32_e32 v2, vcc, s49, v62
	v_mul_f32_e32 v72, 0x3fb8aa3b, v72
	s_nop 0
	v_addc_co_u32_e32 v3, vcc, 0, v63, vcc
	global_store_dwordx4 v[2:3], v[66:69], off
	v_add_co_u32_e32 v2, vcc, s50, v62
	v_mul_f32_e32 v73, 0x3fb8aa3b, v73
	s_nop 0
	v_addc_co_u32_e32 v3, vcc, 0, v63, vcc
	global_store_dwordx4 v[2:3], v[54:57], off
	v_add_co_u32_e32 v2, vcc, s51, v62
	v_mfma_f32_16x16x32_bf16 v[6:9], v[142:145], v[130:133], v[6:9]
	s_nop 0
	v_addc_co_u32_e32 v3, vcc, 0, v63, vcc
	global_store_dwordx4 v[2:3], v[30:33], off
	v_add_co_u32_e32 v2, vcc, s45, v62
	v_mul_f32_e64 v36, v36, v64
	v_mul_f32_e64 v37, v37, v65
	s_nop 0
	v_addc_co_u32_e32 v3, vcc, 0, v63, vcc
	global_store_dwordx4 v[2:3], v[26:29], off
	v_add_co_u32_e32 v2, vcc, s52, v62
	v_exp_f32_e32 v70, v70
	s_nop 0
	v_addc_co_u32_e32 v3, vcc, 0, v63, vcc
	global_store_dwordx4 v[2:3], v[22:25], off
	v_add_co_u32_e32 v2, vcc, s53, v62
	v_exp_f32_e32 v72, v72
	s_nop 0
	v_addc_co_u32_e32 v3, vcc, 0, v63, vcc
	global_store_dwordx4 v[2:3], v[50:53], off
	v_add_co_u32_e32 v2, vcc, s43, v62
	v_exp_f32_e32 v73, v73
	v_exp_f32_e32 v71, v71
	v_addc_co_u32_e32 v3, vcc, 0, v63, vcc
	global_store_dwordx4 v[2:3], v[34:37], off
	v_add_co_u32_e32 v2, vcc, s54, v62
	v_mfma_f32_16x16x32_bf16 v[10:13], v[142:145], v[134:137], v[10:13]
	v_mul_f32_e64 v48, v48, v64
	v_mul_f32_e64 v49, v49, v65
	v_addc_co_u32_e32 v3, vcc, 0, v63, vcc
	global_store_dwordx4 v[2:3], v[46:49], off
	v_add_co_u32_e32 v2, vcc, 0x1c000, v62
	v_mul_f32_e64 v8, v8, v72
	v_mul_f32_e64 v9, v9, v73
	v_mul_f32_e64 v6, v6, v70
	v_mul_f32_e64 v7, v7, v71
	v_addc_co_u32_e32 v3, vcc, 0, v63, vcc
	global_store_dwordx4 v[2:3], v[6:9], off
	v_add_co_u32_e32 v2, vcc, 0x1e000, v62
	v_mul_f32_e64 v12, v12, v72
	v_mul_f32_e64 v13, v13, v73
	v_mul_f32_e64 v10, v10, v70
	v_mul_f32_e64 v11, v11, v71
	v_addc_co_u32_e32 v3, vcc, 0, v63, vcc
	global_store_dwordx4 v[2:3], v[10:13], off
	s_and_saveexec_b64 s[14:15], s[4:5]
	s_cbranch_execz .LBB0_2073
	v_mul_f32_e32 v1, 0x3fb8aa3b, v1
	v_exp_f32_e32 v1, v1
	s_lshl_b64 s[24:25], s[22:23], 9
	v_lshl_add_u64 v[2:3], v[100:101], 0, s[24:25]
	global_store_dword v[2:3], v1, off
	s_branch .LBB0_2073

.LBB0_2182:
	s_or_b64 exec, exec, s[0:1]
	s_waitcnt lgkmcnt(0)
	s_barrier
	ds_read_b128 v[132:135], v180
	ds_read_b128 v[138:141], v180 offset:16
	s_add_i32 s56, s56, 1
	s_add_u32 s46, s46, 0xffffe000
	s_addc_u32 s47, s47, -1
	s_waitcnt lgkmcnt(1)
	v_mov_b32_e32 v78, v133
	v_mov_b32_e32 v79, v134
	v_mov_b32_e32 v133, v135
	s_waitcnt vmcnt(9)
	v_lshlrev_b32_e32 v134, 16, v162
	v_and_b32_e32 v135, 0xffff0000, v162
	v_add_f32_e64 v78, v78, v132
	v_add_f32_e64 v79, v79, v133
	s_waitcnt lgkmcnt(0)
	v_mov_b32_e32 v132, v140
	v_mov_b32_e32 v133, v138
	v_mov_b32_e32 v138, v141
	v_mul_f32_e32 v140, 0xbfb8aa3b, v134
	v_mul_f32_e32 v141, 0xbfb8aa3b, v135
	v_exp_f32_e32 v140, v140
	v_exp_f32_e32 v141, v141
	v_add_f32_e64 v144, v132, v138
	v_add_f32_e64 v145, v133, v139
	v_lshlrev_b32_e32 v138, 16, v163
	v_and_b32_e32 v139, 0xffff0000, v163
	v_add_f32_e32 v132, 1.0, v140
	v_add_f32_e32 v133, 1.0, v141
	v_mul_f32_e32 v140, 0xbfb8aa3b, v138
	v_mul_f32_e32 v141, 0xbfb8aa3b, v139
	v_rcp_f32_e32 v132, v132
	v_rcp_f32_e32 v133, v133
	v_exp_f32_e32 v140, v140
	v_exp_f32_e32 v141, v141
	s_waitcnt vmcnt(8)
	v_lshlrev_b32_e32 v162, 16, v152
	v_mul_f32_e64 v146, v132, v134
	v_mul_f32_e64 v147, v133, v135
	v_add_f32_e32 v132, 1.0, v140
	v_add_f32_e32 v133, 1.0, v141
	v_and_b32_e32 v163, 0xffff0000, v152
	v_mul_f32_e32 v134, 0xbfb8aa3b, v162
	v_rcp_f32_e32 v132, v132
	v_rcp_f32_e32 v133, v133
	v_exp_f32_e32 v134, v134
	v_mul_f32_e32 v135, 0xbfb8aa3b, v163
	v_exp_f32_e32 v135, v135
	v_mul_f32_e64 v200, v132, v138
	v_mul_f32_e64 v201, v133, v139
	v_add_f32_e32 v132, 1.0, v134
	v_rcp_f32_e32 v202, v132
	v_add_f32_e32 v132, 1.0, v135
	v_lshlrev_b32_e32 v152, 16, v153
	v_and_b32_e32 v153, 0xffff0000, v153
	v_rcp_f32_e32 v203, v132
	v_mul_f32_e32 v132, 0xbfb8aa3b, v152
	v_mul_f32_e32 v133, 0xbfb8aa3b, v153
	v_exp_f32_e32 v132, v132
	v_exp_f32_e32 v138, v133
	s_add_u32 s34, s34, 0xfffa0000
	s_addc_u32 s35, s35, -1
	v_add_f32_e32 v139, 1.0, v132
	ds_read_b128 v[132:135], v180 offset:512
	v_add_f32_e32 v138, 1.0, v138
	v_rcp_f32_e32 v204, v139
	v_rcp_f32_e32 v205, v138
	ds_read_b128 v[138:141], v180 offset:528
	s_waitcnt lgkmcnt(1)
	v_mov_b32_e32 v206, v133
	v_mov_b32_e32 v207, v134
	v_mov_b32_e32 v133, v135
	v_add_f32_e64 v132, v206, v132
	v_add_f32_e64 v133, v207, v133
	s_waitcnt lgkmcnt(0)
	v_mov_b32_e32 v134, v140
	v_mov_b32_e32 v135, v138
	v_mov_b32_e32 v138, v141
	v_add_f32_e64 v134, v134, v138
	v_add_f32_e64 v135, v135, v139
	v_mov_b32_e32 v138, v132
	v_mov_b32_e32 v139, v78
	v_mov_b32_e32 v78, v133
	v_add_f32_e64 v78, v138, v78
	v_add_f32_e64 v79, v139, v79
	v_mov_b32_e32 v132, v135
	v_mov_b32_e32 v133, v145
	v_add_f32_e64 v78, v78, v132
	v_add_f32_e64 v79, v79, v133
	v_mov_b32_e32 v135, v144
	v_add_f32_e64 v132, v134, v78
	v_add_f32_e64 v133, v135, v79
	v_mov_b64_e32 v[78:79], s[40:41]
	v_fma_f32 v132, v132, s38, v78
	v_fma_f32 v133, v133, s38, v78
	v_mul_f32_e64 v138, v202, v162
	v_mul_f32_e64 v139, v203, v163
	v_mul_f32_e32 v134, 0x4b800000, v133
	v_cmp_gt_f32_e64 s[0:1], s55, v133
	v_mul_f32_e64 v140, v204, v152
	v_mul_f32_e64 v141, v205, v153
	v_lshl_add_u64 v[152:153], s[28:29], 0, v[116:117]
	v_cndmask_b32_e64 v133, v133, v134, s[0:1]
	v_rsq_f32_e32 v133, v133
	v_lshl_add_u64 v[134:135], s[28:29], 0, v[106:107]
	v_mul_f32_e32 v144, 0x45800000, v133
	v_cndmask_b32_e64 v144, v133, v144, s[0:1]
	v_mul_f32_e64 v148, v148, v144
	v_mul_f32_e64 v149, v149, v144
	v_mul_f32_e32 v133, 0x4b800000, v132
	s_waitcnt vmcnt(1)
	v_mul_f32_e64 v148, v72, v148
	v_mul_f32_e64 v149, v73, v149
	v_cmp_gt_f32_e64 s[0:1], s55, v132
	v_mul_f32_e64 v146, v146, v148
	v_mul_f32_e64 v147, v147, v149
	v_mul_f32_e64 v148, v150, v144
	v_mul_f32_e64 v149, v151, v144
	v_cvt_pk_bf16_f32 v146, v146, v147
	v_mul_f32_e64 v148, v74, v148
	v_mul_f32_e64 v149, v75, v149
	v_cndmask_b32_e64 v132, v132, v133, s[0:1]
	v_mul_f32_e64 v148, v200, v148
	v_mul_f32_e64 v149, v201, v149
	v_rsq_f32_e32 v133, v132
	v_cvt_pk_bf16_f32 v147, v148, v149
	global_store_dwordx2 v[134:135], v[146:147], off
	v_mul_f32_e64 v146, v156, v144
	v_mul_f32_e64 v147, v157, v144
	v_mul_f32_e64 v145, v159, v144
	v_mul_f32_e64 v144, v158, v144
	s_waitcnt vmcnt(1)
	v_mul_f32_e64 v146, v68, v146
	v_mul_f32_e64 v147, v69, v147
	v_mul_f32_e64 v144, v70, v144
	v_mul_f32_e64 v145, v71, v145
	v_mul_f32_e64 v138, v138, v146
	v_mul_f32_e64 v139, v139, v147
	v_mul_f32_e64 v140, v140, v144
	v_mul_f32_e64 v141, v141, v145
	v_cvt_pk_bf16_f32 v138, v138, v139
	v_cvt_pk_bf16_f32 v139, v140, v141
	v_lshlrev_b32_e32 v132, 16, v142
	global_store_dwordx2 v[134:135], v[138:139], off offset:32
	v_mul_f32_e32 v134, 0xbfb8aa3b, v132
	v_exp_f32_e32 v135, v134
	v_mul_f32_e32 v134, 0x45800000, v133
	v_cndmask_b32_e64 v134, v133, v134, s[0:1]
	v_and_b32_e32 v133, 0xffff0000, v142
	v_mul_f32_e32 v138, 0xbfb8aa3b, v133
	v_exp_f32_e32 v139, v138
	v_add_f32_e32 v135, 1.0, v135
	v_rcp_f32_e32 v138, v135
	v_mul_f32_e64 v140, v160, v134
	v_mul_f32_e64 v141, v161, v134
	v_add_f32_e32 v135, 1.0, v139
	v_lshlrev_b32_e32 v142, 16, v143
	v_rcp_f32_e32 v139, v135
	v_and_b32_e32 v143, 0xffff0000, v143
	v_mul_f32_e32 v135, 0xbfb8aa3b, v142
	v_exp_f32_e32 v135, v135
	v_mul_f32_e32 v144, 0xbfb8aa3b, v143
	v_exp_f32_e32 v144, v144
	v_mul_f32_e64 v132, v138, v132
	v_mul_f32_e64 v133, v139, v133
	v_add_f32_e32 v135, 1.0, v135
	v_rcp_f32_e32 v138, v135
	v_add_f32_e32 v135, 1.0, v144
	v_rcp_f32_e32 v139, v135
	v_mul_f32_e64 v98, v98, v134
	v_mul_f32_e64 v99, v99, v134
	v_mul_f32_e64 v140, v72, v140
	v_mul_f32_e64 v141, v73, v141
	v_mul_f32_e64 v98, v74, v98
	v_mul_f32_e64 v99, v75, v99
	v_mul_f32_e64 v138, v138, v142
	v_mul_f32_e64 v139, v139, v143
	v_mul_f32_e64 v132, v132, v140
	v_mul_f32_e64 v133, v133, v141
	v_mul_f32_e64 v98, v138, v98
	v_mul_f32_e64 v99, v139, v99
	v_cvt_pk_bf16_f32 v132, v132, v133
	v_cvt_pk_bf16_f32 v133, v98, v99
	v_lshlrev_b32_e32 v98, 16, v136
	v_mul_f32_e32 v99, 0xbfb8aa3b, v98
	v_exp_f32_e32 v135, v99
	v_lshl_add_u64 v[138:139], s[28:29], 0, v[110:111]
	v_and_b32_e32 v99, 0xffff0000, v136
	global_store_dwordx2 v[138:139], v[132:133], off
	v_mul_f32_e32 v133, 0xbfb8aa3b, v99
	v_exp_f32_e32 v133, v133
	v_lshlrev_b32_e32 v136, 16, v137
	v_and_b32_e32 v137, 0xffff0000, v137
	v_add_f32_e32 v132, 1.0, v135
	v_mul_f32_e64 v96, v96, v134
	v_mul_f32_e64 v97, v97, v134
	v_add_f32_e32 v133, 1.0, v133
	v_mul_f32_e32 v135, 0xbfb8aa3b, v136
	v_mul_f32_e32 v138, 0xbfb8aa3b, v137
	v_rcp_f32_e32 v132, v132
	v_rcp_f32_e32 v133, v133
	v_exp_f32_e32 v135, v135
	v_exp_f32_e32 v138, v138
	v_mul_f32_e64 v96, v68, v96
	v_mul_f32_e64 v97, v69, v97
	v_mul_f32_e64 v98, v132, v98
	v_mul_f32_e64 v99, v133, v99
	v_add_f32_e32 v132, 1.0, v135
	v_add_f32_e32 v133, 1.0, v138
	v_rcp_f32_e32 v132, v132
	v_rcp_f32_e32 v133, v133
	v_mul_f32_e64 v94, v94, v134
	v_mul_f32_e64 v95, v95, v134
	v_mul_f32_e64 v96, v98, v96
	v_mul_f32_e64 v97, v99, v97
	v_mul_f32_e64 v94, v70, v94
	v_mul_f32_e64 v95, v71, v95
	v_mul_f32_e64 v98, v132, v136
	v_mul_f32_e64 v99, v133, v137
	v_cvt_pk_bf16_f32 v132, v96, v97
	v_mul_f32_e64 v98, v98, v94
	v_mul_f32_e64 v99, v99, v95
	ds_read_b128 v[94:97], v180 offset:1024
	v_cvt_pk_bf16_f32 v133, v98, v99
	v_lshl_add_u64 v[98:99], s[28:29], 0, v[112:113]
	global_store_dwordx2 v[98:99], v[132:133], off
	ds_read_b128 v[132:135], v180 offset:1040
	s_waitcnt lgkmcnt(1)
	v_mov_b32_e32 v98, v95
	v_mov_b32_e32 v99, v96
	v_mov_b32_e32 v95, v97
	v_lshlrev_b32_e32 v96, 16, v130
	v_add_f32_e64 v98, v98, v94
	v_add_f32_e64 v99, v99, v95
	v_and_b32_e32 v97, 0xffff0000, v130
	v_mul_f32_e32 v95, 0xbfb8aa3b, v96
	v_exp_f32_e32 v130, v95
	v_mul_f32_e32 v95, 0xbfb8aa3b, v97
	s_waitcnt lgkmcnt(0)
	v_mov_b32_e32 v94, v134
	v_exp_f32_e32 v134, v95
	v_lshlrev_b32_e32 v136, 16, v131
	v_and_b32_e32 v137, 0xffff0000, v131
	v_mul_f32_e32 v131, 0xbfb8aa3b, v136
	v_mov_b32_e32 v95, v132
	v_add_f32_e32 v132, 1.0, v134
	v_exp_f32_e32 v134, v131
	v_mul_f32_e32 v131, 0xbfb8aa3b, v137
	v_exp_f32_e32 v139, v131
	v_rcp_f32_e32 v131, v132
	v_add_f32_e32 v132, 1.0, v134
	v_rcp_f32_e32 v138, v132
	v_add_f32_e32 v132, 1.0, v139
	v_rcp_f32_e32 v139, v132
	v_mov_b32_e32 v132, v135
	v_add_f32_e64 v132, v94, v132
	v_add_f32_e64 v133, v95, v133
	v_lshlrev_b32_e32 v144, 16, v129
	v_mul_f32_e64 v136, v138, v136
	v_mul_f32_e64 v137, v139, v137
	v_lshlrev_b32_e32 v138, 16, v128
	v_and_b32_e32 v139, 0xffff0000, v128
	v_mul_f32_e32 v94, 0xbfb8aa3b, v138
	v_exp_f32_e32 v94, v94
	v_mul_f32_e32 v95, 0xbfb8aa3b, v139
	v_exp_f32_e32 v95, v95
	v_and_b32_e32 v145, 0xffff0000, v129
	v_add_f32_e32 v94, 1.0, v94
	v_rcp_f32_e32 v142, v94
	v_add_f32_e32 v94, 1.0, v95
	v_add_f32_e32 v130, 1.0, v130
	v_rcp_f32_e32 v143, v94
	v_mul_f32_e32 v94, 0xbfb8aa3b, v144
	v_mul_f32_e32 v95, 0xbfb8aa3b, v145
	v_rcp_f32_e32 v130, v130
	v_exp_f32_e32 v94, v94
	v_exp_f32_e32 v128, v95
	v_lshl_add_u64 v[140:141], s[28:29], 0, v[114:115]
	v_mul_f32_e64 v134, v130, v96
	v_mul_f32_e64 v135, v131, v97
	v_add_f32_e32 v129, 1.0, v94
	ds_read_b128 v[94:97], v180 offset:1536
	v_add_f32_e32 v128, 1.0, v128
	v_rcp_f32_e32 v146, v129
	v_rcp_f32_e32 v147, v128
	ds_read_b128 v[128:131], v180 offset:1552
	s_waitcnt lgkmcnt(1)
	v_mov_b32_e32 v148, v95
	v_mov_b32_e32 v149, v96
	v_mov_b32_e32 v95, v97
	v_add_f32_e64 v94, v148, v94
	v_add_f32_e64 v95, v149, v95
	s_waitcnt lgkmcnt(0)
	v_mov_b32_e32 v96, v130
	v_mov_b32_e32 v97, v128
	v_mov_b32_e32 v128, v131
	v_add_f32_e64 v96, v96, v128
	v_add_f32_e64 v97, v97, v129
	v_mov_b32_e32 v128, v94
	v_mov_b32_e32 v129, v98
	v_mov_b32_e32 v98, v95
	v_add_f32_e64 v94, v128, v98
	v_add_f32_e64 v95, v129, v99
	v_mov_b32_e32 v98, v97
	v_mov_b32_e32 v99, v133
	v_add_f32_e64 v94, v94, v98
	v_add_f32_e64 v95, v95, v99
	v_mov_b32_e32 v97, v132
	v_add_f32_e64 v94, v96, v94
	v_add_f32_e64 v95, v97, v95
	v_mul_f32_e64 v98, v146, v144
	v_mul_f32_e64 v99, v147, v145
	v_fma_f32 v79, v95, s38, v78
	v_fma_f32 v78, v94, s38, v78
	s_nop 0
	v_mul_f32_e32 v94, 0x4b800000, v79
	v_cmp_gt_f32_e64 s[0:1], s55, v79
	s_nop 1
	v_cndmask_b32_e64 v79, v79, v94, s[0:1]
	v_rsq_f32_e32 v79, v79
	v_mul_f32_e64 v94, v142, v138
	v_mul_f32_e64 v95, v143, v139
	v_mul_f32_e32 v96, 0x45800000, v79
	v_cndmask_b32_e64 v96, v79, v96, s[0:1]
	v_mul_f32_e64 v88, v88, v96
	v_mul_f32_e64 v89, v89, v96
	v_mul_f32_e64 v92, v92, v96
	v_mul_f32_e64 v93, v93, v96
	v_mul_f32_e64 v88, v72, v88
	v_mul_f32_e64 v89, v73, v89
	v_mul_f32_e64 v92, v74, v92
	v_mul_f32_e64 v93, v75, v93
	v_mul_f32_e64 v88, v134, v88
	v_mul_f32_e64 v89, v135, v89
	v_mul_f32_e64 v92, v136, v92
	v_mul_f32_e64 v93, v137, v93
	v_cvt_pk_bf16_f32 v88, v88, v89
	v_cvt_pk_bf16_f32 v89, v92, v93
	global_store_dwordx2 v[140:141], v[88:89], off
	v_mul_f32_e64 v88, v90, v96
	v_mul_f32_e64 v89, v91, v96
	v_mul_f32_e32 v79, 0x4b800000, v78
	v_cmp_gt_f32_e64 s[0:1], s55, v78
	v_mul_f32_e64 v88, v68, v88
	v_mul_f32_e64 v89, v69, v89
	v_mul_f32_e64 v86, v86, v96
	v_mul_f32_e64 v87, v87, v96
	v_cndmask_b32_e64 v78, v78, v79, s[0:1]
	v_mul_f32_e64 v200, v94, v88
	v_mul_f32_e64 v201, v95, v89
	v_mul_f32_e64 v202, v70, v86
	v_mul_f32_e64 v203, v71, v87
	ds_read_b64_tr_b16 v[88:89], v196 offset:57408
	ds_read_b64_tr_b16 v[86:87], v196 offset:56320
	ds_read_b64_tr_b16 v[92:93], v198 offset:2112
	ds_read_b64_tr_b16 v[90:91], v198
	ds_read_b64_tr_b16 v[96:97], v198 offset:2144
	ds_read_b64_tr_b16 v[94:95], v198 offset:32
	ds_read_b64_tr_b16 v[128:129], v196 offset:56352
	ds_read_b64_tr_b16 v[132:133], v196 offset:56384
	ds_read_b64_tr_b16 v[136:137], v196 offset:56416
	ds_read_b64_tr_b16 v[130:131], v196 offset:57440
	ds_read_b64_tr_b16 v[134:135], v196 offset:57472
	ds_read_b64_tr_b16 v[138:139], v196 offset:57504
	v_rsq_f32_e32 v78, v78
	ds_read_b64_tr_b16 v[140:141], v196 offset:65024
	ds_read_b64_tr_b16 v[142:143], v197 offset:57408
	ds_read_b64_tr_b16 v[144:145], v198 offset:16896
	ds_read_b64_tr_b16 v[146:147], v198 offset:19008
	ds_read_b64_tr_b16 v[150:151], v198 offset:19040
	ds_read_b64_tr_b16 v[148:149], v198 offset:16928
	v_mul_f32_e64 v98, v98, v202
	v_mul_f32_e64 v99, v99, v203
	s_waitcnt lgkmcnt(8)
	v_mfma_f32_16x16x32_bf16 v[12:15], v[128:131], v[90:93], v[12:15]
	v_cvt_pk_bf16_f32 v200, v200, v201
	v_cvt_pk_bf16_f32 v201, v98, v99
	v_mul_f32_e32 v79, 0x45800000, v78
	v_mfma_f32_16x16x32_bf16 v[36:39], v[128:131], v[94:97], v[36:39]
	v_lshlrev_b32_e32 v98, 16, v126
	v_cndmask_b32_e64 v78, v78, v79, s[0:1]
	v_and_b32_e32 v99, 0xffff0000, v126
	v_mfma_f32_16x16x32_bf16 v[8:11], v[86:89], v[90:93], v[8:11]
	v_mul_f32_e32 v79, 0xbfb8aa3b, v98
	v_exp_f32_e32 v79, v79
	v_mul_f32_e32 v126, 0xbfb8aa3b, v99
	v_mfma_f32_16x16x32_bf16 v[4:7], v[86:89], v[94:97], v[4:7]
	ds_read_b64_tr_b16 v[86:87], v196 offset:65056
	ds_read_b64_tr_b16 v[156:157], v196 offset:65088
	ds_read_b64_tr_b16 v[160:161], v196 offset:65120
	ds_read_b64_tr_b16 v[88:89], v197 offset:57440
	ds_read_b64_tr_b16 v[158:159], v197 offset:57472
	ds_read_b64_tr_b16 v[162:163], v197 offset:57504
	v_add_f32_e32 v79, 1.0, v79
	global_store_dwordx2 v[152:153], v[200:201], off
	s_waitcnt lgkmcnt(2)
	v_mfma_f32_16x16x32_bf16 v[12:15], v[86:89], v[144:147], v[12:15]
	v_mfma_f32_16x16x32_bf16 v[36:39], v[86:89], v[148:151], v[36:39]
	v_exp_f32_e32 v87, v126
	v_rcp_f32_e32 v86, v79
	v_add_f32_e32 v79, 1.0, v87
	v_rcp_f32_e32 v87, v79
	v_mul_f32_e64 v84, v84, v78
	v_mul_f32_e64 v85, v85, v78
	v_mfma_f32_16x16x32_bf16 v[24:27], v[132:135], v[90:93], v[24:27]
	v_mul_f32_e64 v72, v72, v84
	v_mul_f32_e64 v73, v73, v85
	v_mul_f32_e64 v84, v86, v98
	v_mul_f32_e64 v85, v87, v99
	v_lshlrev_b32_e32 v86, 16, v127
	v_mul_f32_e32 v79, 0xbfb8aa3b, v86
	v_exp_f32_e32 v79, v79
	v_mul_f32_e64 v98, v84, v72
	v_mul_f32_e64 v99, v85, v73
	v_and_b32_e32 v87, 0xffff0000, v127
	v_mfma_f32_16x16x32_bf16 v[32:35], v[132:135], v[94:97], v[32:35]
	v_add_f32_e32 v72, 1.0, v79
	v_rcp_f32_e32 v84, v72
	v_mul_f32_e32 v72, 0xbfb8aa3b, v87
	v_exp_f32_e32 v79, v72
	v_mfma_f32_16x16x32_bf16 v[40:43], v[136:139], v[90:93], v[40:43]
	v_cvt_pk_bf16_f32 v98, v98, v99
	v_mul_f32_e64 v72, v82, v78
	v_mul_f32_e64 v73, v83, v78
	s_nop 0
	v_mul_f32_e64 v134, v74, v72
	v_mul_f32_e64 v135, v75, v73
	v_add_f32_e32 v72, 1.0, v79
	v_rcp_f32_e32 v85, v72
	ds_read_b64_tr_b16 v[72:73], v196 offset:56448
	ds_read_b64_tr_b16 v[74:75], v196 offset:57536
	v_mfma_f32_16x16x32_bf16 v[64:67], v[136:139], v[94:97], v[64:67]
	v_mul_f32_e64 v136, v84, v86
	v_mul_f32_e64 v137, v85, v87
	ds_read_b64_tr_b16 v[82:83], v196 offset:56480
	ds_read_b64_tr_b16 v[86:87], v196 offset:56512
	ds_read_b64_tr_b16 v[126:127], v196 offset:56544
	ds_read_b64_tr_b16 v[84:85], v196 offset:57568
	ds_read_b64_tr_b16 v[88:89], v196 offset:57600
	ds_read_b64_tr_b16 v[128:129], v196 offset:57632
	v_mfma_f32_16x16x32_bf16 v[8:11], v[140:143], v[144:147], v[8:11]
	ds_read_b64_tr_b16 v[130:131], v196 offset:65152
	ds_read_b64_tr_b16 v[132:133], v197 offset:57536
	v_mfma_f32_16x16x32_bf16 v[4:7], v[140:143], v[148:151], v[4:7]
	v_mul_f32_e64 v142, v136, v134
	v_mul_f32_e64 v143, v137, v135
	v_cvt_pk_bf16_f32 v99, v142, v143
	v_lshl_add_u64 v[142:143], s[28:29], 0, v[118:119]
	s_waitcnt lgkmcnt(8)
	v_mfma_f32_16x16x32_bf16 v[16:19], v[72:75], v[90:93], v[16:19]
	v_mfma_f32_16x16x32_bf16 v[20:23], v[72:75], v[94:97], v[20:23]
	ds_read_b64_tr_b16 v[72:73], v196 offset:65184
	ds_read_b64_tr_b16 v[134:135], v196 offset:65216
	ds_read_b64_tr_b16 v[138:139], v196 offset:65248
	ds_read_b64_tr_b16 v[74:75], v197 offset:57568
	ds_read_b64_tr_b16 v[136:137], v197 offset:57600
	ds_read_b64_tr_b16 v[140:141], v197 offset:57632
	global_store_dwordx2 v[142:143], v[98:99], off
	v_lshlrev_b32_e32 v98, 16, v124
	v_and_b32_e32 v99, 0xffff0000, v124
	v_mul_f32_e32 v79, 0xbfb8aa3b, v98
	v_exp_f32_e32 v79, v79
	v_mul_f32_e32 v124, 0xbfb8aa3b, v99
	s_waitcnt lgkmcnt(10)
	v_mfma_f32_16x16x32_bf16 v[28:31], v[82:85], v[90:93], v[28:31]
	v_add_f32_e32 v79, 1.0, v79
	v_mfma_f32_16x16x32_bf16 v[48:51], v[82:85], v[94:97], v[48:51]
	v_exp_f32_e32 v83, v124
	v_rcp_f32_e32 v82, v79
	v_add_f32_e32 v79, 1.0, v83
	v_rcp_f32_e32 v83, v79
	v_mul_f32_e64 v80, v80, v78
	v_mul_f32_e64 v81, v81, v78
	s_waitcnt lgkmcnt(2)
	v_mfma_f32_16x16x32_bf16 v[28:31], v[72:75], v[144:147], v[28:31]
	v_mul_f32_e64 v68, v68, v80
	v_mul_f32_e64 v69, v69, v81
	v_mul_f32_e64 v76, v76, v78
	v_mul_f32_e64 v77, v77, v78
	v_lshl_add_u64 v[78:79], s[28:29], 0, v[120:121]
	v_mfma_f32_16x16x32_bf16 v[48:51], v[72:75], v[148:151], v[48:51]
	v_mul_f32_e64 v72, v82, v98
	v_mul_f32_e64 v73, v83, v99
	v_mul_f32_e64 v70, v70, v76
	v_mul_f32_e64 v71, v71, v77
	v_mul_f32_e64 v68, v72, v68
	v_mul_f32_e64 v69, v73, v69
	v_lshlrev_b32_e32 v72, 16, v125
	v_and_b32_e32 v73, 0xffff0000, v125
	v_mul_f32_e32 v74, 0xbfb8aa3b, v72
	v_mul_f32_e32 v75, 0xbfb8aa3b, v73
	v_exp_f32_e32 v74, v74
	v_exp_f32_e32 v75, v75
	v_lshl_add_u32 v82, s57, 9, v176
	v_cvt_pk_bf16_f32 v76, v68, v69
	v_add_f32_e32 v74, 1.0, v74
	v_add_f32_e32 v75, 1.0, v75
	v_rcp_f32_e32 v74, v74
	v_rcp_f32_e32 v75, v75
	v_mfma_f32_16x16x32_bf16 v[24:27], v[156:159], v[144:147], v[24:27]
	s_add_u32 s28, s28, 0xfffe0000
	s_addc_u32 s29, s29, -1
	v_mul_f32_e64 v72, v74, v72
	v_mul_f32_e64 v73, v75, v73
	v_mfma_f32_16x16x32_bf16 v[32:35], v[156:159], v[148:151], v[32:35]
	v_mul_f32_e64 v72, v72, v70
	v_mul_f32_e64 v73, v73, v71
	ds_read_b128 v[68:71], v82 offset:4096
	v_cvt_pk_bf16_f32 v77, v72, v73
	ds_read_b128 v[72:75], v82 offset:4160
	global_store_dwordx2 v[78:79], v[76:77], off
	v_mfma_f32_16x16x32_bf16 v[16:19], v[130:133], v[144:147], v[16:19]
	s_waitcnt lgkmcnt(1)
	v_mul_f32_e32 v68, 0x3fb8aa3b, v68
	v_exp_f32_e32 v80, v68
	v_mul_f32_e32 v81, 0x3fb8aa3b, v69
	v_mul_f32_e32 v68, 0x3fb8aa3b, v70
	v_mul_f32_e32 v69, 0x3fb8aa3b, v71
	v_exp_f32_e32 v68, v68
	v_exp_f32_e32 v69, v69
	v_exp_f32_e32 v81, v81
	v_mfma_f32_16x16x32_bf16 v[20:23], v[130:133], v[148:151], v[20:23]
	s_add_u32 s30, s30, 0xfffe0000
	v_mul_f32_e64 v10, v10, v68
	v_mul_f32_e64 v11, v11, v69
	v_mul_f32_e64 v6, v6, v68
	v_mul_f32_e64 v7, v7, v69
	s_waitcnt lgkmcnt(0)
	v_mul_f32_e32 v68, 0x3fb8aa3b, v72
	v_mul_f32_e32 v69, 0x3fb8aa3b, v74
	v_exp_f32_e32 v76, v68
	v_mul_f32_e32 v68, 0x3fb8aa3b, v73
	v_exp_f32_e32 v78, v69
	v_mul_f32_e32 v69, 0x3fb8aa3b, v75
	v_exp_f32_e32 v79, v69
	v_exp_f32_e32 v77, v68
	ds_read_b128 v[68:71], v82 offset:4224
	ds_read_b128 v[72:75], v82 offset:4288
	v_mul_f32_e64 v8, v8, v80
	v_mul_f32_e64 v9, v9, v81
	v_mul_f32_e64 v4, v4, v80
	v_mul_f32_e64 v5, v5, v81
	v_mul_f32_e64 v14, v14, v78
	v_mul_f32_e64 v15, v15, v79
	s_waitcnt lgkmcnt(1)
	v_mul_f32_e32 v68, 0x3fb8aa3b, v68
	v_exp_f32_e32 v80, v68
	v_mul_f32_e32 v81, 0x3fb8aa3b, v69
	v_mul_f32_e32 v68, 0x3fb8aa3b, v70
	v_mul_f32_e32 v69, 0x3fb8aa3b, v71
	v_exp_f32_e32 v68, v68
	v_exp_f32_e32 v69, v69
	v_mul_f32_e64 v12, v12, v76
	v_mul_f32_e64 v13, v13, v77
	v_mul_f32_e64 v38, v38, v78
	v_mul_f32_e64 v39, v39, v79
	v_mul_f32_e64 v36, v36, v76
	v_mul_f32_e64 v37, v37, v77
	v_mul_f32_e64 v26, v26, v68
	v_mul_f32_e64 v27, v27, v69
	v_mul_f32_e64 v34, v34, v68
	v_mul_f32_e64 v35, v35, v69
	s_waitcnt lgkmcnt(0)
	v_mul_f32_e32 v68, 0x3fb8aa3b, v72
	v_mul_f32_e32 v69, 0x3fb8aa3b, v74
	v_exp_f32_e32 v76, v68
	v_mul_f32_e32 v68, 0x3fb8aa3b, v73
	v_exp_f32_e32 v78, v69
	v_mul_f32_e32 v69, 0x3fb8aa3b, v75
	v_exp_f32_e32 v79, v69
	v_exp_f32_e32 v77, v68
	ds_read_b128 v[68:71], v82 offset:4352
	ds_read_b128 v[72:75], v82 offset:4416
	v_exp_f32_e32 v81, v81
	v_mfma_f32_16x16x32_bf16 v[40:43], v[160:163], v[144:147], v[40:43]
	s_addc_u32 s31, s31, -1
	s_waitcnt lgkmcnt(1)
	v_mul_f32_e32 v68, 0x3fb8aa3b, v68
	v_mul_f32_e64 v24, v24, v80
	v_mul_f32_e64 v25, v25, v81
	v_mul_f32_e64 v32, v32, v80
	v_mul_f32_e64 v33, v33, v81
	v_exp_f32_e32 v80, v68
	v_mul_f32_e32 v81, 0x3fb8aa3b, v69
	v_mul_f32_e32 v68, 0x3fb8aa3b, v70
	v_mul_f32_e32 v69, 0x3fb8aa3b, v71
	v_exp_f32_e32 v68, v68
	v_exp_f32_e32 v69, v69
	v_mfma_f32_16x16x32_bf16 v[64:67], v[160:163], v[148:151], v[64:67]
	v_mul_f32_e64 v42, v42, v78
	v_mul_f32_e64 v43, v43, v79
	v_mul_f32_e64 v40, v40, v76
	v_mul_f32_e64 v41, v41, v77
	v_mul_f32_e64 v18, v18, v68
	v_mul_f32_e64 v19, v19, v69
	v_mul_f32_e64 v22, v22, v68
	v_mul_f32_e64 v23, v23, v69
	s_waitcnt lgkmcnt(0)
	v_mul_f32_e32 v68, 0x3fb8aa3b, v72
	v_mul_f32_e32 v69, 0x3fb8aa3b, v74
	v_mul_f32_e64 v66, v66, v78
	v_mul_f32_e64 v67, v67, v79
	v_mul_f32_e64 v64, v64, v76
	v_mul_f32_e64 v65, v65, v77
	v_exp_f32_e32 v76, v68
	v_mul_f32_e32 v68, 0x3fb8aa3b, v73
	v_exp_f32_e32 v78, v69
	v_mul_f32_e32 v69, 0x3fb8aa3b, v75
	v_exp_f32_e32 v79, v69
	v_exp_f32_e32 v77, v68
	ds_read_b128 v[68:71], v82 offset:4480
	ds_read_b128 v[72:75], v82 offset:4544
	v_mfma_f32_16x16x32_bf16 v[44:47], v[86:89], v[90:93], v[44:47]
	v_exp_f32_e32 v81, v81
	v_mul_f32_e64 v30, v30, v78
	v_mul_f32_e64 v31, v31, v79
	s_waitcnt lgkmcnt(1)
	v_mul_f32_e32 v68, 0x3fb8aa3b, v68
	v_mfma_f32_16x16x32_bf16 v[56:59], v[86:89], v[94:97], v[56:59]
	v_mul_f32_e32 v69, 0x3fb8aa3b, v69
	v_mul_f32_e32 v70, 0x3fb8aa3b, v70
	v_mul_f32_e32 v71, 0x3fb8aa3b, v71
	v_mfma_f32_16x16x32_bf16 v[52:55], v[126:129], v[90:93], v[52:55]
	s_waitcnt lgkmcnt(0)
	v_mul_f32_e32 v72, 0x3fb8aa3b, v72
	v_mul_f32_e32 v73, 0x3fb8aa3b, v73
	v_mul_f32_e32 v74, 0x3fb8aa3b, v74
	v_mfma_f32_16x16x32_bf16 v[60:63], v[126:129], v[94:97], v[60:63]
	v_mul_f32_e32 v75, 0x3fb8aa3b, v75
	v_exp_f32_e32 v68, v68
	v_exp_f32_e32 v70, v70
	v_mfma_f32_16x16x32_bf16 v[44:47], v[134:137], v[144:147], v[44:47]
	v_exp_f32_e32 v71, v71
	v_exp_f32_e32 v69, v69
	v_exp_f32_e32 v72, v72
	v_mfma_f32_16x16x32_bf16 v[56:59], v[134:137], v[148:151], v[56:59]
	v_exp_f32_e32 v74, v74
	v_exp_f32_e32 v75, v75
	v_exp_f32_e32 v73, v73
	v_mfma_f32_16x16x32_bf16 v[52:55], v[138:141], v[144:147], v[52:55]
	v_mul_f32_e64 v16, v16, v80
	v_mul_f32_e64 v17, v17, v81
	v_mul_f32_e64 v20, v20, v80
	v_mul_f32_e64 v21, v21, v81
	v_mul_f32_e64 v28, v28, v76
	v_mul_f32_e64 v29, v29, v77
	v_mfma_f32_16x16x32_bf16 v[60:63], v[138:141], v[148:151], v[60:63]
	v_mul_f32_e64 v50, v50, v78
	v_mul_f32_e64 v51, v51, v79
	v_mul_f32_e64 v48, v48, v76
	v_mul_f32_e64 v49, v49, v77
	v_mul_f32_e64 v46, v46, v70
	v_mul_f32_e64 v47, v47, v71
	v_mul_f32_e64 v44, v44, v68
	v_mul_f32_e64 v45, v45, v69
	v_mul_f32_e64 v58, v58, v70
	v_mul_f32_e64 v59, v59, v71
	v_mul_f32_e64 v56, v56, v68
	v_mul_f32_e64 v57, v57, v69
	v_mul_f32_e64 v54, v54, v74
	v_mul_f32_e64 v55, v55, v75
	v_mul_f32_e64 v52, v52, v72
	v_mul_f32_e64 v53, v53, v73
	v_mul_f32_e64 v62, v62, v74
	v_mul_f32_e64 v63, v63, v75
	s_cmp_eq_u32 s56, 4
	v_mul_f32_e64 v60, v60, v72
	v_mul_f32_e64 v61, v61, v73
	s_cbranch_scc1 .LBB0_2200

.LBB0_2192:
	ds_read_b128 v[124:127], v185 offset:6144
	ds_read_b128 v[128:131], v185 offset:6160
	s_waitcnt vmcnt(6)
	v_lshlrev_b32_e32 v132, 16, v96
	s_waitcnt lgkmcnt(1)
	v_mul_f32_e32 v133, 0xbfb8aa3b, v124
	v_mul_f32_e32 v135, 0xbfb8aa3b, v125
	v_exp_f32_e32 v134, v133
	v_exp_f32_e32 v135, v135
	v_and_b32_e32 v133, 0xffff0000, v96
	v_mul_f32_e32 v96, 0xbfb8aa3b, v126
	v_exp_f32_e32 v136, v96
	v_mul_f32_e64 v132, v134, v132
	v_mul_f32_e64 v133, v135, v133
	v_mul_f32_e32 v96, 0xbfb8aa3b, v127
	v_exp_f32_e32 v137, v96
	v_cvt_pk_bf16_f32 v96, v132, v133
	v_lshlrev_b32_e32 v132, 16, v97
	v_and_b32_e32 v133, 0xffff0000, v97
	s_waitcnt lgkmcnt(0)
	v_mul_f32_e32 v97, 0xbfb8aa3b, v128
	v_exp_f32_e32 v134, v97
	v_mul_f32_e32 v97, 0xbfb8aa3b, v129
	v_exp_f32_e32 v135, v97
	v_mul_f32_e64 v132, v136, v132
	v_mul_f32_e64 v133, v137, v133
	v_mul_f32_e32 v124, 0x3fb8aa3b, v124
	v_cvt_pk_bf16_f32 v97, v132, v133
	v_lshlrev_b32_e32 v132, 16, v98
	v_and_b32_e32 v133, 0xffff0000, v98
	v_mul_f32_e32 v98, 0xbfb8aa3b, v130
	v_mul_f32_e64 v132, v134, v132
	v_mul_f32_e64 v133, v135, v133
	v_exp_f32_e32 v134, v98
	v_mul_f32_e32 v98, 0xbfb8aa3b, v131
	v_exp_f32_e32 v135, v98
	v_mul_f32_e32 v125, 0x3fb8aa3b, v125
	v_exp_f32_e32 v124, v124
	v_exp_f32_e32 v125, v125
	v_cvt_pk_bf16_f32 v98, v132, v133
	v_lshlrev_b32_e32 v132, 16, v99
	v_and_b32_e32 v133, 0xffff0000, v99
	v_mul_f32_e64 v132, v134, v132
	v_mul_f32_e64 v133, v135, v133
	s_nop 0
	v_cvt_pk_bf16_f32 v99, v132, v133
	ds_write_b128 v182, v[96:99] offset:56320
	v_lshlrev_b32_e32 v96, 16, v92
	v_and_b32_e32 v97, 0xffff0000, v92
	v_mul_f32_e64 v98, v124, s36
	v_mul_f32_e64 v99, v125, s36
	v_mul_f32_e32 v92, 0x3fb8aa3b, v126
	v_mul_f32_e64 v96, v98, v96
	v_mul_f32_e64 v97, v99, v97
	v_exp_f32_e32 v98, v92
	v_mul_f32_e32 v92, 0x3fb8aa3b, v127
	v_exp_f32_e32 v99, v92
	v_cvt_pk_bf16_f32 v92, v96, v97
	v_lshlrev_b32_e32 v96, 16, v93
	v_and_b32_e32 v97, 0xffff0000, v93
	v_mul_f32_e64 v98, v98, s36
	v_mul_f32_e64 v99, v99, s36
	v_mul_f32_e32 v93, 0x3fb8aa3b, v128
	v_mul_f32_e64 v96, v98, v96
	v_mul_f32_e64 v97, v99, v97
	v_exp_f32_e32 v98, v93
	v_mul_f32_e32 v93, 0x3fb8aa3b, v129
	v_exp_f32_e32 v99, v93
	v_cvt_pk_bf16_f32 v93, v96, v97
	v_lshlrev_b32_e32 v96, 16, v94
	v_and_b32_e32 v97, 0xffff0000, v94
	v_mul_f32_e64 v98, v98, s36
	v_mul_f32_e64 v99, v99, s36
	v_mul_f32_e32 v94, 0x3fb8aa3b, v130
	v_mul_f32_e64 v96, v98, v96
	v_mul_f32_e64 v97, v99, v97
	v_exp_f32_e32 v98, v94
	v_mul_f32_e32 v94, 0x3fb8aa3b, v131
	v_exp_f32_e32 v99, v94
	v_cvt_pk_bf16_f32 v94, v96, v97
	v_lshlrev_b32_e32 v96, 16, v95
	v_and_b32_e32 v97, 0xffff0000, v95
	v_mul_f32_e64 v98, v98, s36
	v_mul_f32_e64 v99, v99, s36
	s_waitcnt vmcnt(4)
	v_lshlrev_b32_e32 v126, 16, v88
	v_mul_f32_e64 v96, v98, v96
	v_mul_f32_e64 v97, v99, v97
	v_and_b32_e32 v127, 0xffff0000, v88
	v_cvt_pk_bf16_f32 v95, v96, v97
	ds_write_b128 v182, v[92:95] offset:38912
	ds_read_b128 v[92:95], v186 offset:6144
	ds_read_b128 v[96:99], v186 offset:6160
	s_waitcnt lgkmcnt(1)
	v_mul_f32_e32 v124, 0xbfb8aa3b, v92
	v_mul_f32_e32 v125, 0xbfb8aa3b, v93
	v_exp_f32_e32 v124, v124
	v_exp_f32_e32 v125, v125
	v_mul_f32_e32 v88, 0xbfb8aa3b, v94
	v_mul_f32_e32 v92, 0x3fb8aa3b, v92
	v_mul_f32_e32 v93, 0x3fb8aa3b, v93
	v_mul_f32_e64 v124, v124, v126
	v_mul_f32_e64 v125, v125, v127
	v_exp_f32_e32 v126, v88
	v_mul_f32_e32 v88, 0xbfb8aa3b, v95
	v_exp_f32_e32 v127, v88
	v_cvt_pk_bf16_f32 v88, v124, v125
	v_lshlrev_b32_e32 v124, 16, v89
	v_and_b32_e32 v125, 0xffff0000, v89
	s_waitcnt lgkmcnt(0)
	v_mul_f32_e32 v89, 0xbfb8aa3b, v96
	v_mul_f32_e64 v124, v126, v124
	v_mul_f32_e64 v125, v127, v125
	v_exp_f32_e32 v126, v89
	v_mul_f32_e32 v89, 0xbfb8aa3b, v97
	v_exp_f32_e32 v127, v89
	v_cvt_pk_bf16_f32 v89, v124, v125
	v_lshlrev_b32_e32 v124, 16, v90
	v_and_b32_e32 v125, 0xffff0000, v90
	v_mul_f32_e32 v90, 0xbfb8aa3b, v98
	v_mul_f32_e64 v124, v126, v124
	v_mul_f32_e64 v125, v127, v125
	v_exp_f32_e32 v126, v90
	v_mul_f32_e32 v90, 0xbfb8aa3b, v99
	v_exp_f32_e32 v127, v90
	v_exp_f32_e32 v92, v92
	v_exp_f32_e32 v93, v93
	v_cvt_pk_bf16_f32 v90, v124, v125
	v_lshlrev_b32_e32 v124, 16, v91
	v_and_b32_e32 v125, 0xffff0000, v91
	v_mul_f32_e64 v124, v126, v124
	v_mul_f32_e64 v125, v127, v125
	s_nop 0
	v_cvt_pk_bf16_f32 v91, v124, v125
	ds_write_b128 v183, v[88:91] offset:56320
	v_lshlrev_b32_e32 v88, 16, v84
	v_and_b32_e32 v89, 0xffff0000, v84
	v_mul_f32_e64 v90, v92, s36
	v_mul_f32_e64 v91, v93, s36
	v_mul_f32_e32 v84, 0x3fb8aa3b, v94
	v_mul_f32_e64 v88, v90, v88
	v_mul_f32_e64 v89, v91, v89
	v_exp_f32_e32 v90, v84
	v_mul_f32_e32 v84, 0x3fb8aa3b, v95
	v_exp_f32_e32 v91, v84
	v_cvt_pk_bf16_f32 v84, v88, v89
	v_lshlrev_b32_e32 v88, 16, v85
	v_and_b32_e32 v89, 0xffff0000, v85
	v_mul_f32_e64 v90, v90, s36
	v_mul_f32_e64 v91, v91, s36
	v_mul_f32_e32 v85, 0x3fb8aa3b, v96
	v_mul_f32_e64 v88, v90, v88
	v_mul_f32_e64 v89, v91, v89
	v_exp_f32_e32 v90, v85
	v_mul_f32_e32 v85, 0x3fb8aa3b, v97
	v_exp_f32_e32 v91, v85
	v_cvt_pk_bf16_f32 v85, v88, v89
	v_lshlrev_b32_e32 v88, 16, v86
	v_and_b32_e32 v89, 0xffff0000, v86
	v_mul_f32_e64 v90, v90, s36
	v_mul_f32_e64 v91, v91, s36
	v_mul_f32_e32 v86, 0x3fb8aa3b, v98
	v_mul_f32_e64 v88, v90, v88
	v_mul_f32_e64 v89, v91, v89
	v_exp_f32_e32 v90, v86
	v_mul_f32_e32 v86, 0x3fb8aa3b, v99
	v_exp_f32_e32 v91, v86
	v_cvt_pk_bf16_f32 v86, v88, v89
	v_lshlrev_b32_e32 v88, 16, v87
	v_and_b32_e32 v89, 0xffff0000, v87
	v_mul_f32_e64 v90, v90, s36
	v_mul_f32_e64 v91, v91, s36
	s_nop 0
	v_mul_f32_e64 v88, v90, v88
	v_mul_f32_e64 v89, v91, v89
	s_nop 0
	v_cvt_pk_bf16_f32 v87, v88, v89
	ds_write_b128 v183, v[84:87] offset:38912
	s_waitcnt vmcnt(3)
	ds_write_b128 v187, v[68:71]
	s_waitcnt vmcnt(2)
	ds_write_b128 v188, v[72:75]
	s_waitcnt vmcnt(1)
	ds_write_b128 v187, v[76:79] offset:16896
	s_waitcnt vmcnt(0)
	ds_write_b128 v189, v[80:83]
	v_lshl_add_u64 v[68:69], s[30:31], 0, v[106:107]
	v_lshl_add_u64 v[70:71], s[30:31], 0, v[110:111]
	v_lshl_add_u64 v[72:73], s[30:31], 0, v[112:113]
	global_load_dwordx2 v[78:79], v[68:69], off
	global_load_dwordx2 v[76:77], v[68:69], off offset:32
	global_load_dwordx2 v[146:147], v[70:71], off
	global_load_dwordx2 v[144:145], v[72:73], off
	v_lshl_add_u64 v[68:69], s[30:31], 0, v[114:115]
	v_lshl_add_u64 v[70:71], s[30:31], 0, v[116:117]
	v_lshl_add_u64 v[72:73], s[30:31], 0, v[118:119]
	v_lshl_add_u64 v[74:75], s[30:31], 0, v[120:121]
	global_load_dwordx2 v[140:141], v[68:69], off
	global_load_dwordx2 v[138:139], v[70:71], off
	global_load_dwordx2 v[134:135], v[72:73], off
	global_load_dwordx2 v[132:133], v[74:75], off
	s_waitcnt lgkmcnt(0)
	s_barrier
	ds_read_b128 v[68:71], v190 offset:56320
	ds_read_b128 v[72:75], v190 offset:56384
	ds_read_b128 v[80:83], v177 offset:38912
	ds_read_b128 v[84:87], v177 offset:38976
	s_waitcnt lgkmcnt(1)
	v_mfma_f32_16x16x32_bf16 v[68:71], v[68:71], v[80:83], 0
	ds_read_b128 v[88:91], v190 offset:56448
	ds_read_b128 v[92:95], v190 offset:56512
	v_add_u32_e32 v199, 0x9800, v195
	v_add_u32_e32 v232, 0xa800, v195
	s_waitcnt lgkmcnt(2)
	v_mfma_f32_16x16x32_bf16 v[68:71], v[72:75], v[84:87], v[68:71]
	ds_read_b128 v[72:75], v177 offset:39040
	ds_read_b128 v[96:99], v177 offset:39104
	v_add_u32_e32 v236, 0xb800, v195
	v_add_u32_e32 v237, 0xc800, v195
	s_waitcnt lgkmcnt(1)
	v_mfma_f32_16x16x32_bf16 v[68:71], v[88:91], v[72:75], v[68:71]
	v_mov_b32_e32 v88, s41
	v_cvt_pk_bf16_f32 v204, v32, v33
	v_cvt_pk_bf16_f32 v205, v34, v35
	s_waitcnt lgkmcnt(0)
	v_mfma_f32_16x16x32_bf16 v[68:71], v[92:95], v[96:99], v[68:71]
	v_cvt_pk_bf16_f32 v206, v64, v65
	v_cvt_pk_bf16_f32 v207, v66, v67
	s_add_u32 s0, s58, s44
	s_addc_u32 s1, s59, 0
	s_add_u32 s0, s0, 0x16e41000
	s_nop 2
	v_cndmask_b32_e64 v68, v68, v88, s[10:11]
	v_cndmask_b32_e64 v69, v69, 0, s[12:13]
	v_cndmask_b32_e64 v70, v70, 0, s[14:15]
	v_cndmask_b32_e64 v71, v71, 0, s[16:17]
	v_cvt_pk_bf16_f32 v68, v68, v69
	v_cvt_pk_bf16_f32 v69, v70, v71
	ds_write_b64 v191, v[68:69]
	ds_read_b128 v[68:71], v192 offset:56320
	ds_read_b128 v[88:91], v192 offset:56384
	s_waitcnt lgkmcnt(1)
	v_mfma_f32_16x16x32_bf16 v[68:71], v[68:71], v[80:83], 0
	ds_read_b128 v[80:83], v192 offset:56448
	s_addc_u32 s1, s1, 0
	v_cvt_pk_bf16_f32 v208, v16, v17
	s_waitcnt lgkmcnt(1)
	v_mfma_f32_16x16x32_bf16 v[68:71], v[88:91], v[84:87], v[68:71]
	ds_read_b128 v[84:87], v192 offset:56512
	v_cvt_pk_bf16_f32 v209, v18, v19
	v_cvt_pk_bf16_f32 v210, v28, v29
	s_waitcnt lgkmcnt(1)
	v_mfma_f32_16x16x32_bf16 v[68:71], v[80:83], v[72:75], v[68:71]
	v_mov_b32_e32 v72, s41
	v_cvt_pk_bf16_f32 v211, v30, v31
	v_cvt_pk_bf16_f32 v224, v44, v45
	s_waitcnt lgkmcnt(0)
	v_mfma_f32_16x16x32_bf16 v[68:71], v[84:87], v[96:99], v[68:71]
	v_cvt_pk_bf16_f32 v225, v46, v47
	v_cvt_pk_bf16_f32 v226, v52, v53
	v_cvt_pk_bf16_f32 v227, v54, v55
	v_cvt_pk_bf16_f32 v228, v56, v57
	v_cvt_pk_bf16_f32 v229, v58, v59
	s_nop 2
	v_cndmask_b32_e64 v68, v68, v72, s[18:19]
	v_cndmask_b32_e64 v69, v69, 0, s[20:21]
	v_cndmask_b32_e64 v70, v70, 0, s[22:23]
	v_cndmask_b32_e64 v71, v71, 0, s[24:25]
	v_cvt_pk_bf16_f32 v68, v68, v69
	v_cvt_pk_bf16_f32 v69, v70, v71
	ds_write_b64 v193, v[68:69]
	s_waitcnt lgkmcnt(0)
	s_barrier
	ds_read_b64_tr_b16 v[70:71], v198 offset:2112
	ds_read_b64_tr_b16 v[68:69], v198
	ds_read_b64_tr_b16 v[74:75], v198 offset:2144
	ds_read_b64_tr_b16 v[72:73], v198 offset:32
	ds_read_b128 v[80:83], v194
	ds_read_b128 v[84:87], v194 offset:64
	ds_read_b128 v[92:95], v194 offset:2304
	ds_read_b128 v[96:99], v194 offset:2368
	ds_read_b128 v[128:131], v194 offset:4608
	ds_read_b64_tr_b16 v[148:149], v198 offset:16896
	ds_read_b64_tr_b16 v[150:151], v198 offset:19008
	ds_read_b128 v[156:159], v194 offset:4672
	ds_read_b64_tr_b16 v[202:203], v198 offset:19040
	ds_read_b64_tr_b16 v[200:201], v198 offset:16928
	s_waitcnt lgkmcnt(9)
	v_mfma_f32_16x16x32_bf16 v[88:91], v[68:71], v[80:83], 0
	v_cvt_pk_bf16_f32 v230, v60, v61
	v_cvt_pk_bf16_f32 v231, v62, v63
	v_mfma_f32_16x16x32_bf16 v[80:83], v[72:75], v[80:83], 0
	s_waitcnt lgkmcnt(7)
	v_mfma_f32_16x16x32_bf16 v[124:127], v[68:71], v[92:95], 0
	v_mfma_f32_16x16x32_bf16 v[92:95], v[72:75], v[92:95], 0
	s_waitcnt lgkmcnt(5)
	v_mfma_f32_16x16x32_bf16 v[160:163], v[68:71], v[128:131], 0
	s_waitcnt lgkmcnt(3)
	v_mfma_f32_16x16x32_bf16 v[88:91], v[148:151], v[84:87], v[88:91]
	s_waitcnt lgkmcnt(0)
	v_mfma_f32_16x16x32_bf16 v[80:83], v[200:203], v[84:87], v[80:83]
	v_mfma_f32_16x16x32_bf16 v[84:87], v[148:151], v[96:99], v[124:127]
	v_mfma_f32_16x16x32_bf16 v[92:95], v[200:203], v[96:99], v[92:95]
	v_mfma_f32_16x16x32_bf16 v[96:99], v[72:75], v[128:131], 0
	v_mfma_f32_16x16x32_bf16 v[124:127], v[148:151], v[156:159], v[160:163]
	v_mfma_f32_16x16x32_bf16 v[96:99], v[200:203], v[156:159], v[96:99]
	ds_read_b128 v[128:131], v194 offset:6912
	ds_read_b128 v[156:159], v194 offset:6976
	ds_read2_b64 v[160:163], v236 offset0:64 offset1:68
	s_waitcnt lgkmcnt(2)
	v_mfma_f32_16x16x32_bf16 v[68:71], v[68:71], v[128:131], 0
	v_mfma_f32_16x16x32_bf16 v[72:75], v[72:75], v[128:131], 0
	v_cvt_pk_bf16_f32 v128, v8, v9
	v_cvt_pk_bf16_f32 v129, v10, v11
	v_cvt_pk_bf16_f32 v130, v12, v13
	s_waitcnt lgkmcnt(1)
	v_mfma_f32_16x16x32_bf16 v[68:71], v[148:151], v[156:159], v[68:71]
	v_cvt_pk_bf16_f32 v131, v14, v15
	ds_read2_b64 v[148:151], v199 offset1:4
	v_mfma_f32_16x16x32_bf16 v[72:75], v[200:203], v[156:159], v[72:75]
	v_cvt_pk_bf16_f32 v156, v4, v5
	v_cvt_pk_bf16_f32 v157, v6, v7
	v_cvt_pk_bf16_f32 v158, v36, v37
	v_cvt_pk_bf16_f32 v159, v38, v39
	s_waitcnt lgkmcnt(0)
	v_mfma_f32_16x16x32_bf16 v[88:91], v[128:131], v[148:151], v[88:91]
	v_cvt_pk_bf16_f32 v200, v24, v25
	v_cvt_pk_bf16_f32 v201, v26, v27
	v_cvt_pk_bf16_f32 v202, v40, v41
	v_mfma_f32_16x16x32_bf16 v[80:83], v[156:159], v[148:151], v[80:83]
	ds_read2_b64 v[148:151], v232 offset0:32 offset1:36
	v_cvt_pk_bf16_f32 v203, v42, v43
	s_waitcnt lgkmcnt(0)
	v_mfma_f32_16x16x32_bf16 v[84:87], v[128:131], v[148:151], v[84:87]
	v_mfma_f32_16x16x32_bf16 v[92:95], v[156:159], v[148:151], v[92:95]
	ds_read2_b64 v[148:151], v237 offset0:96 offset1:100
	v_mfma_f32_16x16x32_bf16 v[124:127], v[128:131], v[160:163], v[124:127]
	v_mfma_f32_16x16x32_bf16 v[96:99], v[156:159], v[160:163], v[96:99]
	s_waitcnt lgkmcnt(0)
	v_mfma_f32_16x16x32_bf16 v[68:71], v[128:131], v[148:151], v[68:71]
	ds_read2_b64 v[128:131], v199 offset0:8 offset1:12
	ds_read2_b64 v[160:163], v232 offset0:40 offset1:44
	v_mfma_f32_16x16x32_bf16 v[148:151], v[156:159], v[148:151], v[72:75]
	s_nop 2
	ds_read2_b64 v[72:75], v236 offset0:72 offset1:76
	ds_read2_b64 v[156:159], v237 offset0:104 offset1:108
	ds_read2_b64 v[212:215], v199 offset0:16 offset1:20
	s_waitcnt lgkmcnt(4)
	v_mfma_f32_16x16x32_bf16 v[88:91], v[200:203], v[128:131], v[88:91]
	v_mfma_f32_16x16x32_bf16 v[80:83], v[204:207], v[128:131], v[80:83]
	v_lshl_add_u64 v[128:129], s[0:1], 0, v[108:109]
	v_add_co_u32_e64 v130, s[0:1], s45, v128
	s_waitcnt lgkmcnt(2)
	v_mfma_f32_16x16x32_bf16 v[216:219], v[200:203], v[72:75], v[124:127]
	v_addc_co_u32_e64 v131, s[0:1], 0, v129, s[0:1]
	v_mfma_f32_16x16x32_bf16 v[96:99], v[204:207], v[72:75], v[96:99]
	v_add_co_u32_e64 v72, s[0:1], s50, v128
	s_nop 1
	v_addc_co_u32_e64 v73, s[0:1], 0, v129, s[0:1]
	v_mfma_f32_16x16x32_bf16 v[84:87], v[200:203], v[160:163], v[84:87]
	s_waitcnt lgkmcnt(1)
	v_mfma_f32_16x16x32_bf16 v[200:203], v[200:203], v[156:159], v[68:71]
	s_nop 2
	v_add_co_u32_e64 v68, s[0:1], s51, v128
	v_mfma_f32_16x16x32_bf16 v[92:95], v[204:207], v[160:163], v[92:95]
	s_nop 0
	v_addc_co_u32_e64 v69, s[0:1], 0, v129, s[0:1]
	global_load_dwordx2 v[162:163], v[128:129], off
	global_load_dwordx2 v[152:153], v[128:129], off offset:32
	global_load_dwordx2 v[142:143], v[130:131], off
	global_load_dwordx2 v[136:137], v[130:131], off offset:32
	s_nop 0
	global_load_dwordx2 v[130:131], v[72:73], off
	global_load_dwordx2 v[128:129], v[72:73], off offset:32
	global_load_dwordx2 v[126:127], v[68:69], off
	global_load_dwordx2 v[124:125], v[68:69], off offset:32
	s_nop 0
	global_load_dwordx4 v[72:75], v[122:123], off
	global_load_dwordx4 v[68:71], v[122:123], off offset:64
	v_mfma_f32_16x16x32_bf16 v[156:159], v[204:207], v[156:159], v[148:151]
	v_cvt_pk_bf16_f32 v204, v20, v21
	v_cvt_pk_bf16_f32 v205, v22, v23
	v_cvt_pk_bf16_f32 v206, v48, v49
	v_cvt_pk_bf16_f32 v207, v50, v51
	s_waitcnt lgkmcnt(0)
	v_mfma_f32_16x16x32_bf16 v[88:91], v[208:211], v[212:215], v[88:91]
	ds_read2_b64 v[148:151], v232 offset0:48 offset1:52
	v_mfma_f32_16x16x32_bf16 v[80:83], v[204:207], v[212:215], v[80:83]
	ds_read2_b64 v[212:215], v236 offset0:80 offset1:84
	ds_read2_b64 v[220:223], v237 offset0:112 offset1:116
	s_waitcnt lgkmcnt(1)
	v_mfma_f32_16x16x32_bf16 v[216:219], v[208:211], v[212:215], v[216:219]
	v_mfma_f32_16x16x32_bf16 v[212:215], v[204:207], v[212:215], v[96:99]
	s_nop 2
	ds_read2_b64 v[96:99], v199 offset0:24 offset1:28
	ds_read2_b64 v[232:235], v232 offset0:56 offset1:60
	s_waitcnt lgkmcnt(1)
	v_mfma_f32_16x16x32_bf16 v[88:91], v[224:227], v[96:99], v[88:91]
	v_mfma_f32_16x16x32_bf16 v[84:87], v[208:211], v[148:151], v[84:87]
	v_mfma_f32_16x16x32_bf16 v[92:95], v[204:207], v[148:151], v[92:95]
	s_waitcnt vmcnt(17)
	v_lshlrev_b32_e32 v148, 16, v78
	v_and_b32_e32 v149, 0xffff0000, v78
	v_lshlrev_b32_e32 v78, 16, v79
	v_and_b32_e32 v79, 0xffff0000, v79
	s_nop 0
	v_add_f32_e64 v150, v90, v78
	v_add_f32_e64 v151, v91, v79
	v_mfma_f32_16x16x32_bf16 v[78:81], v[228:231], v[96:99], v[80:83]
	v_add_f32_e64 v148, v88, v148
	v_add_f32_e64 v149, v89, v149
	s_waitcnt vmcnt(16)
	v_lshlrev_b32_e32 v88, 16, v76
	v_mul_f32_e64 v160, v148, v148
	v_mul_f32_e64 v161, v149, v149
	v_and_b32_e32 v89, 0xffff0000, v76
	v_lshlrev_b32_e32 v76, 16, v77
	v_and_b32_e32 v77, 0xffff0000, v77
	v_mfma_f32_16x16x32_bf16 v[204:207], v[204:207], v[220:223], v[156:159]
	v_mul_f32_e64 v82, v150, v150
	v_mul_f32_e64 v83, v151, v151
	s_nop 0
	v_add_f32_e64 v158, v80, v76
	v_add_f32_e64 v159, v81, v77
	v_add_f32_e32 v80, v160, v161
	v_add_f32_e64 v156, v78, v88
	v_add_f32_e64 v157, v79, v89
	v_add_f32_e32 v80, v82, v80
	v_mul_f32_e64 v76, v156, v156
	v_mul_f32_e64 v77, v157, v157
	v_add_f32_e32 v80, v83, v80
	v_add_f32_e32 v76, v76, v80
	v_mul_f32_e64 v78, v158, v158
	v_mul_f32_e64 v79, v159, v159
	v_add_f32_e32 v76, v77, v76
	v_add_f32_e32 v76, v78, v76
	v_add_f32_e32 v76, v79, v76
	ds_bpermute_b32 v77, v178, v76
	v_mfma_f32_16x16x32_bf16 v[200:203], v[208:211], v[220:223], v[200:203]
	ds_read2_b64 v[208:211], v236 offset0:88 offset1:92
	ds_read2_b64 v[236:239], v237 offset0:120 offset1:124
	s_waitcnt lgkmcnt(2)
	v_add_f32_e32 v160, v76, v77
	ds_bpermute_b32 v161, v179, v160
	v_mfma_f32_16x16x32_bf16 v[96:99], v[224:227], v[232:235], v[84:87]
	v_mfma_f32_16x16x32_bf16 v[92:95], v[228:231], v[232:235], v[92:95]
	s_waitcnt lgkmcnt(2)
	v_mfma_f32_16x16x32_bf16 v[88:91], v[224:227], v[208:211], v[216:219]
	v_mfma_f32_16x16x32_bf16 v[84:87], v[228:231], v[208:211], v[212:215]
	s_waitcnt lgkmcnt(1)
	v_mfma_f32_16x16x32_bf16 v[80:83], v[224:227], v[236:239], v[200:203]
	v_mfma_f32_16x16x32_bf16 v[76:79], v[228:231], v[236:239], v[204:207]
	s_and_saveexec_b64 s[0:1], s[6:7]
	s_cbranch_execz .LBB0_2194
	s_waitcnt lgkmcnt(0)
	v_add_f32_e32 v160, v160, v161
	ds_write_b32 v181, v160

.LBB0_2266:
	ds_read_b128 v[138:141], v205 offset:6144
	ds_read_b128 v[142:145], v205 offset:6160
	s_waitcnt vmcnt(6)
	v_lshlrev_b32_e32 v146, 16, v98
	v_and_b32_e32 v147, 0xffff0000, v98
	v_add_u32_e32 v219, 0x9800, v216
	s_waitcnt lgkmcnt(1)
	v_mul_f32_e32 v107, 0xbfb8aa3b, v138
	v_exp_f32_e32 v108, v107
	v_mul_f32_e32 v107, 0xbfb8aa3b, v139
	v_exp_f32_e32 v109, v107
	v_mul_f32_e32 v107, 0xbfb8aa3b, v140
	v_cvt_pk_bf16_f32 v160, v10, v11
	v_cvt_pk_bf16_f32 v161, v12, v13
	v_mul_f32_e64 v108, v108, v146
	v_mul_f32_e64 v109, v109, v147
	v_lshlrev_b32_e32 v146, 16, v99
	v_cvt_pk_bf16_f32 v98, v108, v109
	v_exp_f32_e32 v108, v107
	v_mul_f32_e32 v107, 0xbfb8aa3b, v141
	v_exp_f32_e32 v109, v107
	v_and_b32_e32 v147, 0xffff0000, v99
	s_waitcnt lgkmcnt(0)
	v_mul_f32_e32 v107, 0xbfb8aa3b, v142
	v_cvt_pk_bf16_f32 v162, v26, v27
	v_mul_f32_e64 v108, v108, v146
	v_mul_f32_e64 v109, v109, v147
	v_lshlrev_b32_e32 v146, 16, v100
	v_cvt_pk_bf16_f32 v99, v108, v109
	v_exp_f32_e32 v108, v107
	v_mul_f32_e32 v107, 0xbfb8aa3b, v143
	v_exp_f32_e32 v109, v107
	v_and_b32_e32 v147, 0xffff0000, v100
	v_mul_f32_e32 v107, 0xbfb8aa3b, v144
	v_cvt_pk_bf16_f32 v163, v28, v29
	v_mul_f32_e64 v108, v108, v146
	v_mul_f32_e64 v109, v109, v147
	v_lshlrev_b32_e32 v146, 16, v101
	v_cvt_pk_bf16_f32 v100, v108, v109
	v_exp_f32_e32 v108, v107
	v_mul_f32_e32 v107, 0xbfb8aa3b, v145
	v_exp_f32_e32 v109, v107
	v_and_b32_e32 v147, 0xffff0000, v101
	v_add_u32_e32 v220, 0xa800, v216
	v_add_u32_e32 v221, 0xb800, v216
	v_mul_f32_e64 v108, v108, v146
	v_mul_f32_e64 v109, v109, v147
	v_add_u32_e32 v222, 0xc800, v216
	v_cvt_pk_bf16_f32 v101, v108, v109
	ds_write_b128 v184, v[98:101] offset:56320
	v_mul_f32_e32 v98, 0x3fb8aa3b, v138
	v_mul_f32_e32 v99, 0x3fb8aa3b, v139
	v_exp_f32_e32 v98, v98
	v_exp_f32_e32 v99, v99
	v_lshlrev_b32_e32 v100, 16, v94
	v_and_b32_e32 v101, 0xffff0000, v94
	s_waitcnt vmcnt(4)
	v_lshlrev_b32_e32 v138, 16, v90
	v_mul_f32_e64 v98, v98, s48
	v_mul_f32_e64 v99, v99, s48
	v_and_b32_e32 v139, 0xffff0000, v90
	v_mul_f32_e64 v98, v98, v100
	v_mul_f32_e64 v99, v99, v101
	v_lshlrev_b32_e32 v100, 16, v95
	v_cvt_pk_bf16_f32 v94, v98, v99
	v_mul_f32_e32 v98, 0x3fb8aa3b, v140
	v_mul_f32_e32 v99, 0x3fb8aa3b, v141
	v_exp_f32_e32 v98, v98
	v_exp_f32_e32 v99, v99
	v_and_b32_e32 v101, 0xffff0000, v95
	s_mov_b32 s61, 0x8000
	s_add_u32 s74, s74, 0x60000
	v_mul_f32_e64 v98, v98, s48
	v_mul_f32_e64 v99, v99, s48
	s_addc_u32 s75, s75, 0
	v_mul_f32_e64 v98, v98, v100
	v_mul_f32_e64 v99, v99, v101
	v_lshlrev_b32_e32 v100, 16, v96
	v_cvt_pk_bf16_f32 v95, v98, v99
	v_mul_f32_e32 v98, 0x3fb8aa3b, v142
	v_mul_f32_e32 v99, 0x3fb8aa3b, v143
	v_exp_f32_e32 v98, v98
	v_exp_f32_e32 v99, v99
	v_and_b32_e32 v101, 0xffff0000, v96
	s_add_i32 s60, s60, 64
	v_mul_f32_e64 v98, v98, s48
	v_mul_f32_e64 v99, v99, s48
	s_nop 0
	v_mul_f32_e64 v98, v98, v100
	v_mul_f32_e64 v99, v99, v101
	v_lshlrev_b32_e32 v100, 16, v97
	v_cvt_pk_bf16_f32 v96, v98, v99
	v_mul_f32_e32 v98, 0x3fb8aa3b, v144
	v_mul_f32_e32 v99, 0x3fb8aa3b, v145
	v_exp_f32_e32 v98, v98
	v_exp_f32_e32 v99, v99
	v_and_b32_e32 v101, 0xffff0000, v97
	v_mul_f32_e64 v98, v98, s48
	v_mul_f32_e64 v99, v99, s48
	s_nop 0
	v_mul_f32_e64 v98, v98, v100
	v_mul_f32_e64 v99, v99, v101
	s_nop 0
	v_cvt_pk_bf16_f32 v97, v98, v99
	ds_write_b128 v184, v[94:97] offset:38912
	ds_read_b128 v[94:97], v206 offset:6144
	ds_read_b128 v[98:101], v206 offset:6160
	s_waitcnt lgkmcnt(1)
	v_mul_f32_e32 v107, 0xbfb8aa3b, v94
	v_exp_f32_e32 v108, v107
	v_mul_f32_e32 v107, 0xbfb8aa3b, v95
	v_exp_f32_e32 v109, v107
	v_mul_f32_e32 v107, 0xbfb8aa3b, v96
	v_mul_f32_e64 v108, v108, v138
	v_mul_f32_e64 v109, v109, v139
	s_nop 0
	v_cvt_pk_bf16_f32 v90, v108, v109
	v_exp_f32_e32 v108, v107
	v_mul_f32_e32 v107, 0xbfb8aa3b, v97
	v_exp_f32_e32 v109, v107
	v_lshlrev_b32_e32 v138, 16, v91
	v_and_b32_e32 v139, 0xffff0000, v91
	s_waitcnt lgkmcnt(0)
	v_mul_f32_e32 v107, 0xbfb8aa3b, v98
	v_mul_f32_e64 v108, v108, v138
	v_mul_f32_e64 v109, v109, v139
	v_lshlrev_b32_e32 v138, 16, v92
	v_cvt_pk_bf16_f32 v91, v108, v109
	v_exp_f32_e32 v108, v107
	v_mul_f32_e32 v107, 0xbfb8aa3b, v99
	v_exp_f32_e32 v109, v107
	v_and_b32_e32 v139, 0xffff0000, v92
	v_mul_f32_e32 v107, 0xbfb8aa3b, v100
	v_mul_f32_e64 v108, v108, v138
	v_mul_f32_e64 v109, v109, v139
	s_nop 0
	v_cvt_pk_bf16_f32 v92, v108, v109
	v_exp_f32_e32 v108, v107
	v_mul_f32_e32 v107, 0xbfb8aa3b, v101
	v_exp_f32_e32 v109, v107
	v_lshlrev_b32_e32 v138, 16, v93
	v_and_b32_e32 v139, 0xffff0000, v93
	v_mul_f32_e64 v108, v108, v138
	v_mul_f32_e64 v109, v109, v139
	s_nop 0
	v_cvt_pk_bf16_f32 v93, v108, v109
	ds_write_b128 v185, v[90:93] offset:56320
	v_mul_f32_e32 v90, 0x3fb8aa3b, v94
	v_mul_f32_e32 v91, 0x3fb8aa3b, v95
	v_exp_f32_e32 v90, v90
	v_exp_f32_e32 v91, v91
	v_lshlrev_b32_e32 v92, 16, v70
	v_and_b32_e32 v93, 0xffff0000, v70
	v_mul_f32_e64 v90, v90, s48
	v_mul_f32_e64 v91, v91, s48
	s_nop 0
	v_mul_f32_e64 v90, v90, v92
	v_mul_f32_e64 v91, v91, v93
	v_lshlrev_b32_e32 v92, 16, v71
	v_cvt_pk_bf16_f32 v70, v90, v91
	v_mul_f32_e32 v90, 0x3fb8aa3b, v96
	v_mul_f32_e32 v91, 0x3fb8aa3b, v97
	v_exp_f32_e32 v90, v90
	v_exp_f32_e32 v91, v91
	v_and_b32_e32 v93, 0xffff0000, v71
	v_mul_f32_e64 v90, v90, s48
	v_mul_f32_e64 v91, v91, s48
	s_nop 0
	v_mul_f32_e64 v90, v90, v92
	v_mul_f32_e64 v91, v91, v93
	v_lshlrev_b32_e32 v92, 16, v72
	v_cvt_pk_bf16_f32 v71, v90, v91
	v_mul_f32_e32 v90, 0x3fb8aa3b, v98
	v_mul_f32_e32 v91, 0x3fb8aa3b, v99
	v_exp_f32_e32 v90, v90
	v_exp_f32_e32 v91, v91
	v_and_b32_e32 v93, 0xffff0000, v72
	v_mul_f32_e64 v90, v90, s48
	v_mul_f32_e64 v91, v91, s48
	s_nop 0
	v_mul_f32_e64 v90, v90, v92
	v_mul_f32_e64 v91, v91, v93
	v_lshlrev_b32_e32 v92, 16, v73
	v_cvt_pk_bf16_f32 v72, v90, v91
	v_mul_f32_e32 v90, 0x3fb8aa3b, v100
	v_mul_f32_e32 v91, 0x3fb8aa3b, v101
	v_exp_f32_e32 v90, v90
	v_exp_f32_e32 v91, v91
	v_and_b32_e32 v93, 0xffff0000, v73
	v_mul_f32_e64 v90, v90, s48
	v_mul_f32_e64 v91, v91, s48
	s_nop 0
	v_mul_f32_e64 v90, v90, v92
	v_mul_f32_e64 v91, v91, v93
	s_nop 0
	v_cvt_pk_bf16_f32 v73, v90, v91
	ds_write_b128 v185, v[70:73] offset:38912
	s_waitcnt vmcnt(3)
	ds_write_b128 v207, v[74:77]
	s_waitcnt vmcnt(2)
	ds_write_b128 v208, v[78:81]
	s_waitcnt vmcnt(1)
	ds_write_b128 v207, v[82:85] offset:16896
	s_waitcnt vmcnt(0)
	ds_write_b128 v209, v[86:89]
	s_waitcnt lgkmcnt(0)
	s_barrier
	ds_read_b128 v[70:73], v210 offset:56320
	ds_read_b128 v[74:77], v183 offset:38912
	ds_read_b128 v[78:81], v210 offset:56384
	ds_read_b128 v[82:85], v183 offset:38976
	s_waitcnt lgkmcnt(2)
	v_mfma_f32_16x16x32_bf16 v[70:73], v[70:73], v[74:77], 0
	s_waitcnt lgkmcnt(0)
	v_mfma_f32_16x16x32_bf16 v[70:73], v[78:81], v[82:85], v[70:73]
	ds_read_b128 v[78:81], v210 offset:56448
	ds_read_b128 v[86:89], v183 offset:39040
	s_waitcnt lgkmcnt(0)
	v_mfma_f32_16x16x32_bf16 v[70:73], v[78:81], v[86:89], v[70:73]
	ds_read_b128 v[78:81], v210 offset:56512
	ds_read_b128 v[90:93], v183 offset:39104
	s_waitcnt lgkmcnt(0)
	v_mfma_f32_16x16x32_bf16 v[70:73], v[78:81], v[90:93], v[70:73]
	v_mov_b32_e32 v78, s93
	s_nop 6
	v_cndmask_b32_e64 v78, v70, v78, s[12:13]
	v_cndmask_b32_e64 v70, v78, v70, s[14:15]
	v_cndmask_b32_e64 v71, 0, v71, s[14:15]
	v_cndmask_b32_e64 v72, v72, 0, s[16:17]
	v_cndmask_b32_e64 v73, v73, 0, s[18:19]
	v_cvt_pk_bf16_f32 v70, v70, v71
	v_cvt_pk_bf16_f32 v71, v72, v73
	ds_write_b64 v211, v[70:71]
	ds_read_b128 v[70:73], v212 offset:56320
	s_waitcnt lgkmcnt(0)
	v_mfma_f32_16x16x32_bf16 v[70:73], v[70:73], v[74:77], 0
	ds_read_b128 v[74:77], v212 offset:56384
	s_waitcnt lgkmcnt(0)
	v_mfma_f32_16x16x32_bf16 v[70:73], v[74:77], v[82:85], v[70:73]
	ds_read_b128 v[74:77], v212 offset:56448
	s_waitcnt lgkmcnt(0)
	v_mfma_f32_16x16x32_bf16 v[70:73], v[74:77], v[86:89], v[70:73]
	ds_read_b128 v[74:77], v212 offset:56512
	s_waitcnt lgkmcnt(0)
	v_mfma_f32_16x16x32_bf16 v[70:73], v[74:77], v[90:93], v[70:73]
	v_mov_b32_e32 v74, s93
	s_nop 6
	v_cndmask_b32_e64 v74, v70, v74, s[20:21]
	v_cndmask_b32_e64 v70, v74, v70, s[22:23]
	v_cndmask_b32_e64 v71, 0, v71, s[22:23]
	v_cndmask_b32_e64 v72, v72, 0, s[24:25]
	v_cndmask_b32_e64 v73, v73, 0, s[26:27]
	v_cvt_pk_bf16_f32 v70, v70, v71
	v_cvt_pk_bf16_f32 v71, v72, v73
	ds_write_b64 v213, v[70:71]
	s_waitcnt lgkmcnt(0)
	s_barrier
	ds_read_b64_tr_b16 v[80:81], v214 offset:2112
	ds_read_b64_tr_b16 v[78:79], v214
	ds_read_b64_tr_b16 v[82:83], v214 offset:32
	ds_read_b64_tr_b16 v[70:71], v214 offset:16896
	ds_read_b64_tr_b16 v[72:73], v214 offset:19008
	ds_read_b64_tr_b16 v[84:85], v214 offset:2144
	ds_read_b64_tr_b16 v[74:75], v214 offset:16928
	ds_read_b64_tr_b16 v[76:77], v214 offset:19040
	ds_read_b128 v[86:89], v215
	ds_read_b128 v[94:97], v215 offset:64
	ds_read_b128 v[138:141], v215 offset:2368
	s_waitcnt lgkmcnt(2)
	v_mfma_f32_16x16x32_bf16 v[90:93], v[78:81], v[86:89], 0
	ds_read_b128 v[146:149], v215 offset:4672
	ds_read_b128 v[156:159], v215 offset:6976
	ds_read2_b64 v[164:167], v219 offset1:4
	v_mfma_f32_16x16x32_bf16 v[86:89], v[82:85], v[86:89], 0
	s_waitcnt lgkmcnt(4)
	v_mfma_f32_16x16x32_bf16 v[90:93], v[70:73], v[94:97], v[90:93]
	v_mfma_f32_16x16x32_bf16 v[86:89], v[74:77], v[94:97], v[86:89]
	ds_read_b128 v[94:97], v215 offset:2304
	s_waitcnt lgkmcnt(0)
	v_mfma_f32_16x16x32_bf16 v[98:101], v[78:81], v[94:97], 0
	v_mfma_f32_16x16x32_bf16 v[94:97], v[82:85], v[94:97], 0
	v_mfma_f32_16x16x32_bf16 v[98:101], v[70:73], v[138:141], v[98:101]
	v_mfma_f32_16x16x32_bf16 v[94:97], v[74:77], v[138:141], v[94:97]
	ds_read_b128 v[138:141], v215 offset:4608
	s_waitcnt lgkmcnt(0)
	v_mfma_f32_16x16x32_bf16 v[142:145], v[78:81], v[138:141], 0
	v_mfma_f32_16x16x32_bf16 v[138:141], v[82:85], v[138:141], 0
	v_mfma_f32_16x16x32_bf16 v[142:145], v[70:73], v[146:149], v[142:145]
	v_mfma_f32_16x16x32_bf16 v[138:141], v[74:77], v[146:149], v[138:141]
	ds_read_b128 v[146:149], v215 offset:6912
	s_waitcnt lgkmcnt(0)
	v_mfma_f32_16x16x32_bf16 v[150:153], v[78:81], v[146:149], 0
	v_mfma_f32_16x16x32_bf16 v[146:149], v[82:85], v[146:149], 0
	v_mfma_f32_16x16x32_bf16 v[150:153], v[70:73], v[156:159], v[150:153]
	v_mfma_f32_16x16x32_bf16 v[146:149], v[74:77], v[156:159], v[146:149]
	v_cvt_pk_bf16_f32 v156, v6, v7
	v_cvt_pk_bf16_f32 v157, v8, v9
	v_cvt_pk_bf16_f32 v158, v22, v23
	v_cvt_pk_bf16_f32 v159, v24, v25
	v_mfma_f32_16x16x32_bf16 v[86:89], v[160:163], v[164:167], v[86:89]
	s_nop 0
	v_mfma_f32_16x16x32_bf16 v[90:93], v[156:159], v[164:167], v[90:93]
	ds_read2_b64 v[164:167], v220 offset0:32 offset1:36
	s_waitcnt lgkmcnt(0)
	v_mfma_f32_16x16x32_bf16 v[98:101], v[156:159], v[164:167], v[98:101]
	v_mfma_f32_16x16x32_bf16 v[94:97], v[160:163], v[164:167], v[94:97]
	ds_read2_b64 v[164:167], v221 offset0:64 offset1:68
	s_waitcnt lgkmcnt(0)
	v_mfma_f32_16x16x32_bf16 v[142:145], v[156:159], v[164:167], v[142:145]
	v_mfma_f32_16x16x32_bf16 v[138:141], v[160:163], v[164:167], v[138:141]
	ds_read2_b64 v[164:167], v222 offset0:96 offset1:100
	s_waitcnt lgkmcnt(0)
	v_mfma_f32_16x16x32_bf16 v[150:153], v[156:159], v[164:167], v[150:153]
	v_cvt_pk_bf16_f32 v156, v14, v15
	v_cvt_pk_bf16_f32 v157, v16, v17
	v_cvt_pk_bf16_f32 v158, v38, v39
	v_mfma_f32_16x16x32_bf16 v[146:149], v[160:163], v[164:167], v[146:149]
	v_cvt_pk_bf16_f32 v159, v40, v41
	v_cvt_pk_bf16_f32 v160, v18, v19
	v_cvt_pk_bf16_f32 v161, v20, v21
	v_cvt_pk_bf16_f32 v162, v42, v43
	v_cvt_pk_bf16_f32 v163, v44, v45
	ds_read2_b64 v[164:167], v219 offset0:8 offset1:12
	s_waitcnt lgkmcnt(0)
	v_mfma_f32_16x16x32_bf16 v[90:93], v[156:159], v[164:167], v[90:93]
	v_mfma_f32_16x16x32_bf16 v[86:89], v[160:163], v[164:167], v[86:89]
	ds_read2_b64 v[164:167], v220 offset0:40 offset1:44
	s_waitcnt lgkmcnt(0)
	v_mfma_f32_16x16x32_bf16 v[98:101], v[156:159], v[164:167], v[98:101]
	v_mfma_f32_16x16x32_bf16 v[94:97], v[160:163], v[164:167], v[94:97]
	ds_read2_b64 v[164:167], v221 offset0:72 offset1:76
	s_waitcnt lgkmcnt(0)
	v_mfma_f32_16x16x32_bf16 v[142:145], v[156:159], v[164:167], v[142:145]
	v_mfma_f32_16x16x32_bf16 v[138:141], v[160:163], v[164:167], v[138:141]
	ds_read2_b64 v[164:167], v222 offset0:104 offset1:108
	s_waitcnt lgkmcnt(0)
	v_mfma_f32_16x16x32_bf16 v[150:153], v[156:159], v[164:167], v[150:153]
	v_cvt_pk_bf16_f32 v156, v30, v31
	v_cvt_pk_bf16_f32 v157, v32, v33
	v_cvt_pk_bf16_f32 v158, v46, v47
	v_mfma_f32_16x16x32_bf16 v[146:149], v[160:163], v[164:167], v[146:149]
	v_cvt_pk_bf16_f32 v159, v48, v49
	v_cvt_pk_bf16_f32 v160, v34, v35
	v_cvt_pk_bf16_f32 v161, v36, v37
	v_cvt_pk_bf16_f32 v162, v54, v55
	v_cvt_pk_bf16_f32 v163, v56, v57
	ds_read2_b64 v[164:167], v219 offset0:16 offset1:20
	s_waitcnt lgkmcnt(0)
	v_mfma_f32_16x16x32_bf16 v[90:93], v[156:159], v[164:167], v[90:93]
	v_mfma_f32_16x16x32_bf16 v[86:89], v[160:163], v[164:167], v[86:89]
	ds_read2_b64 v[164:167], v220 offset0:48 offset1:52
	s_waitcnt lgkmcnt(0)
	v_mfma_f32_16x16x32_bf16 v[98:101], v[156:159], v[164:167], v[98:101]
	v_mfma_f32_16x16x32_bf16 v[94:97], v[160:163], v[164:167], v[94:97]
	ds_read2_b64 v[164:167], v221 offset0:80 offset1:84
	s_waitcnt lgkmcnt(0)
	v_mfma_f32_16x16x32_bf16 v[142:145], v[156:159], v[164:167], v[142:145]
	v_mfma_f32_16x16x32_bf16 v[138:141], v[160:163], v[164:167], v[138:141]
	ds_read2_b64 v[164:167], v222 offset0:112 offset1:116
	s_waitcnt lgkmcnt(0)
	v_mfma_f32_16x16x32_bf16 v[150:153], v[156:159], v[164:167], v[150:153]
	v_cvt_pk_bf16_f32 v156, v50, v51
	v_cvt_pk_bf16_f32 v157, v52, v53
	v_cvt_pk_bf16_f32 v158, v62, v63
	v_mfma_f32_16x16x32_bf16 v[146:149], v[160:163], v[164:167], v[146:149]
	v_cvt_pk_bf16_f32 v159, v64, v65
	v_cvt_pk_bf16_f32 v160, v58, v59
	v_cvt_pk_bf16_f32 v161, v60, v61
	v_cvt_pk_bf16_f32 v162, v66, v67
	v_cvt_pk_bf16_f32 v163, v68, v69
	ds_read2_b64 v[164:167], v219 offset0:24 offset1:28
	s_waitcnt lgkmcnt(0)
	v_mfma_f32_16x16x32_bf16 v[90:93], v[156:159], v[164:167], v[90:93]
	v_mfma_f32_16x16x32_bf16 v[86:89], v[160:163], v[164:167], v[86:89]
	ds_read2_b64 v[164:167], v220 offset0:56 offset1:60
	s_nop 5
	v_cvt_pk_bf16_f32 v90, v90, v91
	v_cvt_pk_bf16_f32 v91, v92, v93
	s_waitcnt lgkmcnt(0)
	v_mfma_f32_16x16x32_bf16 v[98:101], v[156:159], v[164:167], v[98:101]
	v_lshl_add_u64 v[92:93], s[64:65], 0, v[118:119]
	v_cvt_pk_bf16_f32 v86, v86, v87
	v_cvt_pk_bf16_f32 v87, v88, v89
	v_mfma_f32_16x16x32_bf16 v[94:97], v[160:163], v[164:167], v[94:97]
	ds_read2_b64 v[164:167], v221 offset0:88 offset1:92
	v_add_co_u32_e32 v88, vcc, s61, v92
	s_waitcnt lgkmcnt(0)
	v_mfma_f32_16x16x32_bf16 v[142:145], v[156:159], v[164:167], v[142:145]
	global_store_dwordx2 v[92:93], v[86:87], off offset:32
	v_cvt_pk_bf16_f32 v86, v98, v99
	v_cvt_pk_bf16_f32 v87, v100, v101
	v_mfma_f32_16x16x32_bf16 v[138:141], v[160:163], v[164:167], v[138:141]
	ds_read2_b64 v[164:167], v222 offset0:120 offset1:124
	v_addc_co_u32_e32 v89, vcc, 0, v93, vcc
	global_store_dwordx2 v[88:89], v[86:87], off
	v_cvt_pk_bf16_f32 v86, v94, v95
	v_cvt_pk_bf16_f32 v87, v96, v97
	s_mov_b32 s61, 0x10000
	s_waitcnt lgkmcnt(0)
	v_mfma_f32_16x16x32_bf16 v[150:153], v[156:159], v[164:167], v[150:153]
	global_store_dwordx2 v[88:89], v[86:87], off offset:32
	v_add_co_u32_e32 v88, vcc, s61, v92
	v_mfma_f32_16x16x32_bf16 v[146:149], v[160:163], v[164:167], v[146:149]
	v_cvt_pk_bf16_f32 v86, v142, v143
	v_cvt_pk_bf16_f32 v87, v144, v145
	v_addc_co_u32_e32 v89, vcc, 0, v93, vcc
	global_store_dwordx2 v[88:89], v[86:87], off
	v_cvt_pk_bf16_f32 v86, v138, v139
	v_cvt_pk_bf16_f32 v87, v140, v141
	global_store_dwordx2 v[88:89], v[86:87], off offset:32
	v_add_co_u32_e32 v88, vcc, s81, v92
	v_cvt_pk_bf16_f32 v86, v150, v151
	v_cvt_pk_bf16_f32 v87, v152, v153
	v_addc_co_u32_e32 v89, vcc, 0, v93, vcc
	global_store_dwordx2 v[88:89], v[86:87], off
	v_cvt_pk_bf16_f32 v86, v146, v147
	v_cvt_pk_bf16_f32 v87, v148, v149
	global_store_dwordx2 v[92:93], v[90:91], off
	global_store_dwordx2 v[88:89], v[86:87], off offset:32
	ds_read_b64_tr_b16 v[88:89], v217 offset:57408
	ds_read_b64_tr_b16 v[86:87], v217 offset:56320
	ds_read_b64_tr_b16 v[90:91], v217 offset:56352
	s_waitcnt lgkmcnt(1)
	v_mfma_f32_16x16x32_bf16 v[6:9], v[86:89], v[78:81], v[6:9]
	s_add_u32 s64, s64, 0x20000
	s_addc_u32 s65, s65, 0
	s_add_i32 s95, s95, 1
	v_mfma_f32_16x16x32_bf16 v[10:13], v[86:89], v[82:85], v[10:13]
	ds_read_b64_tr_b16 v[86:87], v217 offset:65024
	ds_read_b64_tr_b16 v[88:89], v218 offset:57408
	ds_read_b64_tr_b16 v[94:95], v218 offset:57440
	ds_read_b64_tr_b16 v[92:93], v217 offset:57440
	s_cmp_lg_u32 s74, 0x300000
	s_waitcnt lgkmcnt(2)
	v_mfma_f32_16x16x32_bf16 v[6:9], v[86:89], v[70:73], v[6:9]
	v_mfma_f32_16x16x32_bf16 v[10:13], v[86:89], v[74:77], v[10:13]
	s_waitcnt lgkmcnt(0)
	v_mfma_f32_16x16x32_bf16 v[22:25], v[90:93], v[78:81], v[22:25]
	v_mfma_f32_16x16x32_bf16 v[26:29], v[90:93], v[82:85], v[26:29]
	ds_read_b64_tr_b16 v[92:93], v217 offset:65056
	ds_read_b64_tr_b16 v[86:87], v217 offset:56384
	ds_read_b64_tr_b16 v[88:89], v217 offset:57472
	s_waitcnt lgkmcnt(0)
	v_mfma_f32_16x16x32_bf16 v[14:17], v[86:89], v[78:81], v[14:17]
	v_mfma_f32_16x16x32_bf16 v[18:21], v[86:89], v[82:85], v[18:21]
	ds_read_b64_tr_b16 v[86:87], v217 offset:65088
	ds_read_b64_tr_b16 v[88:89], v218 offset:57472
	s_waitcnt lgkmcnt(0)
	v_mfma_f32_16x16x32_bf16 v[14:17], v[86:89], v[70:73], v[14:17]
	v_mfma_f32_16x16x32_bf16 v[18:21], v[86:89], v[74:77], v[18:21]
	ds_read_b64_tr_b16 v[86:87], v217 offset:56416
	ds_read_b64_tr_b16 v[88:89], v217 offset:57504
	s_waitcnt lgkmcnt(0)
	v_mfma_f32_16x16x32_bf16 v[38:41], v[86:89], v[78:81], v[38:41]
	v_mfma_f32_16x16x32_bf16 v[42:45], v[86:89], v[82:85], v[42:45]
	ds_read_b64_tr_b16 v[86:87], v217 offset:65120
	ds_read_b64_tr_b16 v[88:89], v218 offset:57504
	s_waitcnt lgkmcnt(0)
	v_mfma_f32_16x16x32_bf16 v[38:41], v[86:89], v[70:73], v[38:41]
	v_mfma_f32_16x16x32_bf16 v[42:45], v[86:89], v[74:77], v[42:45]
	ds_read_b64_tr_b16 v[86:87], v217 offset:56448
	ds_read_b64_tr_b16 v[88:89], v217 offset:57536
	s_waitcnt lgkmcnt(0)
	v_mfma_f32_16x16x32_bf16 v[30:33], v[86:89], v[78:81], v[30:33]
	v_mfma_f32_16x16x32_bf16 v[34:37], v[86:89], v[82:85], v[34:37]
	ds_read_b64_tr_b16 v[86:87], v217 offset:65152
	ds_read_b64_tr_b16 v[88:89], v218 offset:57536
	s_waitcnt lgkmcnt(0)
	v_mfma_f32_16x16x32_bf16 v[30:33], v[86:89], v[70:73], v[30:33]
	v_mfma_f32_16x16x32_bf16 v[34:37], v[86:89], v[74:77], v[34:37]
	ds_read_b64_tr_b16 v[86:87], v217 offset:56480
	ds_read_b64_tr_b16 v[88:89], v217 offset:57568
	s_waitcnt lgkmcnt(0)
	v_mfma_f32_16x16x32_bf16 v[46:49], v[86:89], v[78:81], v[46:49]
	v_mfma_f32_16x16x32_bf16 v[54:57], v[86:89], v[82:85], v[54:57]
	ds_read_b64_tr_b16 v[86:87], v217 offset:65184
	ds_read_b64_tr_b16 v[88:89], v218 offset:57568
	s_waitcnt lgkmcnt(0)
	v_mfma_f32_16x16x32_bf16 v[46:49], v[86:89], v[70:73], v[46:49]
	v_mfma_f32_16x16x32_bf16 v[54:57], v[86:89], v[74:77], v[54:57]
	ds_read_b64_tr_b16 v[86:87], v217 offset:56512
	ds_read_b64_tr_b16 v[88:89], v217 offset:57600
	s_waitcnt lgkmcnt(0)
	v_mfma_f32_16x16x32_bf16 v[50:53], v[86:89], v[78:81], v[50:53]
	v_mfma_f32_16x16x32_bf16 v[58:61], v[86:89], v[82:85], v[58:61]
	ds_read_b64_tr_b16 v[86:87], v217 offset:65216
	ds_read_b64_tr_b16 v[88:89], v218 offset:57600
	s_waitcnt lgkmcnt(0)
	v_mfma_f32_16x16x32_bf16 v[50:53], v[86:89], v[70:73], v[50:53]
	v_mfma_f32_16x16x32_bf16 v[58:61], v[86:89], v[74:77], v[58:61]
	ds_read_b64_tr_b16 v[86:87], v217 offset:56544
	ds_read_b64_tr_b16 v[88:89], v217 offset:57632
	s_waitcnt lgkmcnt(0)
	v_mfma_f32_16x16x32_bf16 v[62:65], v[86:89], v[78:81], v[62:65]
	ds_read_b64_tr_b16 v[78:79], v217 offset:65248
	ds_read_b64_tr_b16 v[80:81], v218 offset:57632
	v_mfma_f32_16x16x32_bf16 v[66:69], v[86:89], v[82:85], v[66:69]
	v_mfma_f32_16x16x32_bf16 v[22:25], v[92:95], v[70:73], v[22:25]
	s_waitcnt lgkmcnt(0)
	v_mfma_f32_16x16x32_bf16 v[62:65], v[78:81], v[70:73], v[62:65]
	v_lshl_add_u32 v70, s49, 9, v182
	v_mfma_f32_16x16x32_bf16 v[26:29], v[92:95], v[74:77], v[26:29]
	v_mfma_f32_16x16x32_bf16 v[66:69], v[78:81], v[74:77], v[66:69]
	ds_read_b128 v[72:75], v70 offset:4096
	s_waitcnt lgkmcnt(0)
	v_mul_f32_e32 v71, 0x3fb8aa3b, v72
	v_exp_f32_e32 v72, v71
	v_mul_f32_e32 v71, 0x3fb8aa3b, v73
	v_exp_f32_e32 v73, v71
	v_mul_f32_e32 v71, 0x3fb8aa3b, v74
	v_exp_f32_e32 v74, v71
	v_mul_f32_e32 v71, 0x3fb8aa3b, v75
	v_exp_f32_e32 v75, v71
	v_mul_f32_e64 v6, v6, v72
	v_mul_f32_e64 v7, v7, v73
	v_mul_f32_e64 v10, v10, v72
	v_mul_f32_e64 v11, v11, v73
	v_mul_f32_e64 v8, v8, v74
	v_mul_f32_e64 v9, v9, v75
	v_mul_f32_e64 v12, v12, v74
	v_mul_f32_e64 v13, v13, v75
	ds_read_b128 v[72:75], v70 offset:4160
	s_waitcnt lgkmcnt(0)
	v_mul_f32_e32 v71, 0x3fb8aa3b, v72
	v_exp_f32_e32 v72, v71
	v_mul_f32_e32 v71, 0x3fb8aa3b, v73
	v_exp_f32_e32 v73, v71
	v_mul_f32_e32 v71, 0x3fb8aa3b, v74
	v_exp_f32_e32 v74, v71
	v_mul_f32_e32 v71, 0x3fb8aa3b, v75
	v_exp_f32_e32 v75, v71
	v_mul_f32_e64 v22, v22, v72
	v_mul_f32_e64 v23, v23, v73
	v_mul_f32_e64 v26, v26, v72
	v_mul_f32_e64 v27, v27, v73
	v_mul_f32_e64 v24, v24, v74
	v_mul_f32_e64 v25, v25, v75
	v_mul_f32_e64 v28, v28, v74
	v_mul_f32_e64 v29, v29, v75
	ds_read_b128 v[72:75], v70 offset:4224
	s_waitcnt lgkmcnt(0)
	v_mul_f32_e32 v71, 0x3fb8aa3b, v72
	v_exp_f32_e32 v72, v71
	v_mul_f32_e32 v71, 0x3fb8aa3b, v73
	v_exp_f32_e32 v73, v71
	v_mul_f32_e32 v71, 0x3fb8aa3b, v74
	v_exp_f32_e32 v74, v71
	v_mul_f32_e32 v71, 0x3fb8aa3b, v75
	v_exp_f32_e32 v75, v71
	v_mul_f32_e64 v14, v14, v72
	v_mul_f32_e64 v15, v15, v73
	v_mul_f32_e64 v18, v18, v72
	v_mul_f32_e64 v19, v19, v73
	v_mul_f32_e64 v16, v16, v74
	v_mul_f32_e64 v17, v17, v75
	v_mul_f32_e64 v20, v20, v74
	v_mul_f32_e64 v21, v21, v75
	ds_read_b128 v[72:75], v70 offset:4288
	s_waitcnt lgkmcnt(0)
	v_mul_f32_e32 v71, 0x3fb8aa3b, v72
	v_exp_f32_e32 v72, v71
	v_mul_f32_e32 v71, 0x3fb8aa3b, v73
	v_exp_f32_e32 v73, v71
	v_mul_f32_e32 v71, 0x3fb8aa3b, v74
	v_exp_f32_e32 v74, v71
	v_mul_f32_e32 v71, 0x3fb8aa3b, v75
	v_exp_f32_e32 v75, v71
	v_mul_f32_e64 v38, v38, v72
	v_mul_f32_e64 v39, v39, v73
	v_mul_f32_e64 v42, v42, v72
	v_mul_f32_e64 v43, v43, v73
	v_mul_f32_e64 v40, v40, v74
	v_mul_f32_e64 v41, v41, v75
	v_mul_f32_e64 v44, v44, v74
	v_mul_f32_e64 v45, v45, v75
	ds_read_b128 v[72:75], v70 offset:4352
	s_waitcnt lgkmcnt(0)
	v_mul_f32_e32 v71, 0x3fb8aa3b, v72
	v_exp_f32_e32 v72, v71
	v_mul_f32_e32 v71, 0x3fb8aa3b, v73
	v_exp_f32_e32 v73, v71
	v_mul_f32_e32 v71, 0x3fb8aa3b, v74
	v_exp_f32_e32 v74, v71
	v_mul_f32_e32 v71, 0x3fb8aa3b, v75
	v_exp_f32_e32 v75, v71
	v_mul_f32_e64 v30, v30, v72
	v_mul_f32_e64 v31, v31, v73
	v_mul_f32_e64 v34, v34, v72
	v_mul_f32_e64 v35, v35, v73
	v_mul_f32_e64 v32, v32, v74
	v_mul_f32_e64 v33, v33, v75
	v_mul_f32_e64 v36, v36, v74
	v_mul_f32_e64 v37, v37, v75
	ds_read_b128 v[72:75], v70 offset:4416
	s_waitcnt lgkmcnt(0)
	v_mul_f32_e32 v71, 0x3fb8aa3b, v72
	v_exp_f32_e32 v72, v71
	v_mul_f32_e32 v71, 0x3fb8aa3b, v73
	v_exp_f32_e32 v73, v71
	v_mul_f32_e32 v71, 0x3fb8aa3b, v74
	v_exp_f32_e32 v74, v71
	v_mul_f32_e32 v71, 0x3fb8aa3b, v75
	v_exp_f32_e32 v75, v71
	v_mul_f32_e64 v46, v46, v72
	v_mul_f32_e64 v47, v47, v73
	v_mul_f32_e64 v54, v54, v72
	v_mul_f32_e64 v55, v55, v73
	v_mul_f32_e64 v48, v48, v74
	v_mul_f32_e64 v49, v49, v75
	v_mul_f32_e64 v56, v56, v74
	v_mul_f32_e64 v57, v57, v75
	ds_read_b128 v[72:75], v70 offset:4480
	s_waitcnt lgkmcnt(0)
	v_mul_f32_e32 v71, 0x3fb8aa3b, v72
	v_exp_f32_e32 v72, v71
	v_mul_f32_e32 v71, 0x3fb8aa3b, v73
	v_exp_f32_e32 v73, v71
	v_mul_f32_e32 v71, 0x3fb8aa3b, v74
	v_exp_f32_e32 v74, v71
	v_mul_f32_e32 v71, 0x3fb8aa3b, v75
	v_exp_f32_e32 v75, v71
	v_mul_f32_e64 v50, v50, v72
	v_mul_f32_e64 v51, v51, v73
	v_mul_f32_e64 v58, v58, v72
	v_mul_f32_e64 v59, v59, v73
	ds_read_b128 v[70:73], v70 offset:4544
	v_mul_f32_e64 v52, v52, v74
	v_mul_f32_e64 v53, v53, v75
	v_mul_f32_e64 v60, v60, v74
	v_mul_f32_e64 v61, v61, v75
	s_waitcnt lgkmcnt(0)
	v_mul_f32_e32 v70, 0x3fb8aa3b, v70
	v_mul_f32_e32 v71, 0x3fb8aa3b, v71
	v_mul_f32_e32 v72, 0x3fb8aa3b, v72
	v_mul_f32_e32 v73, 0x3fb8aa3b, v73
	v_exp_f32_e32 v70, v70
	v_exp_f32_e32 v71, v71
	v_exp_f32_e32 v72, v72
	v_exp_f32_e32 v73, v73
	v_mul_f32_e64 v62, v62, v70
	v_mul_f32_e64 v63, v63, v71
	v_mul_f32_e64 v66, v66, v70
	v_mul_f32_e64 v67, v67, v71
	v_mul_f32_e64 v64, v64, v72
	v_mul_f32_e64 v65, v65, v73
	v_mul_f32_e64 v68, v68, v72
	v_mul_f32_e64 v69, v69, v73
	s_cbranch_scc0 .LBB0_2275

.LBB0_2282:
	s_or_b64 exec, exec, s[60:61]
	s_waitcnt lgkmcnt(0)
	s_barrier
	ds_read_b128 v[140:143], v188
	ds_read_b128 v[146:149], v188 offset:16
	s_waitcnt vmcnt(8)
	v_lshlrev_b32_e32 v160, 16, v170
	v_and_b32_e32 v161, 0xffff0000, v170
	v_lshlrev_b32_e32 v170, 16, v171
	s_waitcnt lgkmcnt(1)
	v_mov_b32_e32 v81, v142
	v_lshlrev_b32_e32 v142, 16, v172
	v_mov_b32_e32 v80, v141
	v_mov_b32_e32 v141, v143
	v_and_b32_e32 v143, 0xffff0000, v172
	v_mul_f32_e32 v0, 0xbfb8aa3b, v142
	v_exp_f32_e32 v0, v0
	v_mul_f32_e32 v135, 0xbfb8aa3b, v143
	v_exp_f32_e32 v135, v135
	v_add_f32_e64 v80, v80, v140
	v_add_f32_e64 v81, v81, v141
	s_waitcnt lgkmcnt(0)
	v_mov_b32_e32 v140, v148
	v_mov_b32_e32 v141, v146
	v_mov_b32_e32 v146, v149
	v_add_f32_e32 v0, 1.0, v0
	v_add_f32_e64 v150, v140, v146
	v_add_f32_e64 v151, v141, v147
	v_rcp_f32_e32 v140, v0
	v_add_f32_e32 v0, 1.0, v135
	v_lshlrev_b32_e32 v146, 16, v173
	v_rcp_f32_e32 v141, v0
	v_and_b32_e32 v147, 0xffff0000, v173
	v_mul_f32_e32 v0, 0xbfb8aa3b, v146
	v_exp_f32_e32 v0, v0
	v_mul_f32_e32 v135, 0xbfb8aa3b, v147
	v_exp_f32_e32 v135, v135
	v_mul_f32_e64 v152, v140, v142
	v_mul_f32_e64 v153, v141, v143
	v_add_f32_e32 v0, 1.0, v0
	v_rcp_f32_e32 v140, v0
	v_add_f32_e32 v0, 1.0, v135
	v_rcp_f32_e32 v141, v0
	v_mul_f32_e32 v0, 0xbfb8aa3b, v160
	v_exp_f32_e32 v0, v0
	v_mul_f32_e32 v135, 0xbfb8aa3b, v161
	v_exp_f32_e32 v135, v135
	v_mul_f32_e64 v172, v140, v146
	v_mul_f32_e64 v173, v141, v147
	ds_read_b128 v[140:143], v188 offset:512
	ds_read_b128 v[146:149], v188 offset:528
	v_add_f32_e32 v0, 1.0, v0
	v_rcp_f32_e32 v228, v0
	v_add_f32_e32 v0, 1.0, v135
	v_rcp_f32_e32 v229, v0
	v_mul_f32_e32 v0, 0xbfb8aa3b, v170
	v_and_b32_e32 v171, 0xffff0000, v171
	s_waitcnt lgkmcnt(1)
	v_mov_b32_e32 v232, v141
	v_mov_b32_e32 v233, v142
	v_mov_b32_e32 v141, v143
	v_exp_f32_e32 v0, v0
	v_mul_f32_e32 v135, 0xbfb8aa3b, v171
	v_add_f32_e64 v140, v232, v140
	v_add_f32_e64 v141, v233, v141
	s_waitcnt lgkmcnt(0)
	v_mov_b32_e32 v142, v148
	v_mov_b32_e32 v143, v146
	v_mov_b32_e32 v146, v149
	v_exp_f32_e32 v135, v135
	v_add_f32_e64 v142, v142, v146
	v_add_f32_e64 v143, v143, v147
	v_mov_b32_e32 v146, v140
	v_mov_b32_e32 v147, v80
	v_mov_b32_e32 v80, v141
	v_add_f32_e64 v80, v146, v80
	v_add_f32_e64 v81, v147, v81
	v_mov_b32_e32 v140, v143
	v_mov_b32_e32 v141, v151
	v_add_f32_e64 v80, v80, v140
	v_add_f32_e64 v81, v81, v141
	v_mov_b32_e32 v143, v150
	s_mov_b32 s60, 0x358637bd
	v_add_f32_e32 v0, 1.0, v0
	v_add_f32_e64 v140, v142, v80
	v_add_f32_e64 v141, v143, v81
	v_mov_b64_e32 v[80:81], s[60:61]
	v_rcp_f32_e32 v230, v0
	v_add_f32_e32 v0, 1.0, v135
	v_fma_f32 v140, v140, s50, v80
	v_fma_f32 v141, v141, s50, v80
	v_rcp_f32_e32 v231, v0
	v_mul_f32_e32 v0, 0x4b800000, v141
	v_cmp_gt_f32_e32 vcc, s80, v141
	v_mul_f32_e64 v146, v228, v160
	v_mul_f32_e64 v147, v229, v161
	v_mul_f32_e64 v148, v230, v170
	v_mul_f32_e64 v149, v231, v171
	v_cndmask_b32_e32 v0, v141, v0, vcc
	v_rsq_f32_e32 v0, v0
	v_lshl_add_u64 v[142:143], s[54:55], 0, v[118:119]
	s_waitcnt vmcnt(4)
	v_lshlrev_b32_e32 v150, 16, v163
	v_and_b32_e32 v151, 0xffff0000, v163
	v_mul_f32_e32 v135, 0x45800000, v0
	v_cndmask_b32_e32 v0, v0, v135, vcc
	v_mul_f32_e64 v106, v106, v0
	v_mul_f32_e64 v107, v107, v0
	v_mul_f32_e64 v108, v108, v0
	v_mul_f32_e64 v109, v109, v0
	v_mul_f32_e64 v102, v102, v0
	v_mul_f32_e64 v103, v103, v0
	v_mul_f32_e64 v104, v104, v0
	v_mul_f32_e64 v105, v105, v0
	v_mul_f32_e32 v0, 0x4b800000, v140
	v_cmp_gt_f32_e32 vcc, s80, v140
	s_waitcnt vmcnt(0)
	v_mul_f32_e64 v102, v70, v102
	v_mul_f32_e64 v103, v71, v103
	v_mul_f32_e64 v104, v72, v104
	v_mul_f32_e64 v105, v73, v105
	v_cndmask_b32_e32 v0, v140, v0, vcc
	v_mul_f32_e64 v102, v146, v102
	v_mul_f32_e64 v103, v147, v103
	v_mul_f32_e64 v104, v148, v104
	v_mul_f32_e64 v105, v149, v105
	v_rsq_f32_e32 v0, v0
	v_cvt_pk_bf16_f32 v102, v102, v103
	v_cvt_pk_bf16_f32 v103, v104, v105
	global_store_dwordx2 v[142:143], v[102:103], off offset:32
	v_lshlrev_b32_e32 v102, 16, v168
	v_mul_f32_e32 v103, 0xbfb8aa3b, v102
	v_exp_f32_e32 v104, v103
	v_mul_f32_e32 v103, 0x45800000, v0
	v_cndmask_b32_e32 v0, v0, v103, vcc
	v_and_b32_e32 v103, 0xffff0000, v168
	v_mul_f32_e32 v105, 0xbfb8aa3b, v103
	v_exp_f32_e32 v105, v105
	v_mul_f32_e64 v106, v74, v106
	v_mul_f32_e64 v107, v75, v107
	v_mul_f32_e64 v108, v76, v108
	v_mul_f32_e64 v109, v77, v109
	v_mul_f32_e64 v106, v152, v106
	v_mul_f32_e64 v107, v153, v107
	v_mul_f32_e64 v108, v172, v108
	v_mul_f32_e64 v109, v173, v109
	v_cvt_pk_bf16_f32 v106, v106, v107
	v_cvt_pk_bf16_f32 v107, v108, v109
	v_lshlrev_b32_e32 v108, 16, v169
	v_and_b32_e32 v109, 0xffff0000, v169
	v_add_f32_e32 v104, 1.0, v104
	v_add_f32_e32 v105, 1.0, v105
	v_mul_f32_e32 v135, 0xbfb8aa3b, v108
	v_mul_f32_e32 v137, 0xbfb8aa3b, v109
	v_rcp_f32_e32 v104, v104
	v_rcp_f32_e32 v105, v105
	v_exp_f32_e32 v135, v135
	v_exp_f32_e32 v137, v137
	global_store_dwordx2 v[142:143], v[106:107], off
	v_mul_f32_e64 v102, v104, v102
	v_mul_f32_e64 v103, v105, v103
	v_add_f32_e32 v104, 1.0, v135
	v_add_f32_e32 v105, 1.0, v137
	v_rcp_f32_e32 v104, v104
	v_rcp_f32_e32 v105, v105
	v_mul_f32_e64 v106, v158, v0
	v_mul_f32_e64 v107, v159, v0
	v_mul_f32_e64 v100, v100, v0
	v_mul_f32_e64 v101, v101, v0
	v_mul_f32_e64 v106, v74, v106
	v_mul_f32_e64 v107, v75, v107
	v_mul_f32_e64 v100, v76, v100
	v_mul_f32_e64 v101, v77, v101
	v_mul_f32_e64 v104, v104, v108
	v_mul_f32_e64 v105, v105, v109
	v_mul_f32_e64 v102, v102, v106
	v_mul_f32_e64 v103, v103, v107
	v_mul_f32_e64 v100, v104, v100
	v_mul_f32_e64 v101, v105, v101
	v_cvt_pk_bf16_f32 v102, v102, v103
	v_cvt_pk_bf16_f32 v103, v100, v101
	v_lshlrev_b32_e32 v100, 16, v166
	v_mul_f32_e32 v101, 0xbfb8aa3b, v100
	v_exp_f32_e32 v106, v101
	v_lshl_add_u64 v[104:105], s[54:55], 0, v[122:123]
	v_and_b32_e32 v101, 0xffff0000, v166
	global_store_dwordx2 v[104:105], v[102:103], off
	v_mul_f32_e32 v103, 0xbfb8aa3b, v101
	v_exp_f32_e32 v103, v103
	v_lshlrev_b32_e32 v104, 16, v167
	v_and_b32_e32 v105, 0xffff0000, v167
	v_add_f32_e32 v102, 1.0, v106
	v_add_f32_e32 v103, 1.0, v103
	v_mul_f32_e32 v106, 0xbfb8aa3b, v104
	v_mul_f32_e32 v107, 0xbfb8aa3b, v105
	v_rcp_f32_e32 v102, v102
	v_rcp_f32_e32 v103, v103
	v_exp_f32_e32 v106, v106
	v_exp_f32_e32 v107, v107
	v_mul_f32_e64 v98, v98, v0
	v_mul_f32_e64 v99, v99, v0
	v_mul_f32_e64 v100, v102, v100
	v_mul_f32_e64 v101, v103, v101
	v_add_f32_e32 v102, 1.0, v106
	v_add_f32_e32 v103, 1.0, v107
	v_rcp_f32_e32 v102, v102
	v_rcp_f32_e32 v103, v103
	v_mul_f32_e64 v98, v70, v98
	v_mul_f32_e64 v99, v71, v99
	v_mul_f32_e64 v96, v96, v0
	v_mul_f32_e64 v97, v97, v0
	v_mul_f32_e64 v98, v100, v98
	v_mul_f32_e64 v99, v101, v99
	v_mul_f32_e64 v96, v72, v96
	v_mul_f32_e64 v97, v73, v97
	v_mul_f32_e64 v100, v102, v104
	v_mul_f32_e64 v101, v103, v105
	v_cvt_pk_bf16_f32 v102, v98, v99
	v_mul_f32_e64 v100, v100, v96
	v_mul_f32_e64 v101, v101, v97
	ds_read_b128 v[96:99], v188 offset:1024
	v_cvt_pk_bf16_f32 v103, v100, v101
	v_lshl_add_u64 v[100:101], s[54:55], 0, v[124:125]
	global_store_dwordx2 v[100:101], v[102:103], off
	ds_read_b128 v[100:103], v188 offset:1040
	s_waitcnt lgkmcnt(1)
	v_mov_b32_e32 v105, v98
	v_lshlrev_b32_e32 v98, 16, v164
	v_mov_b32_e32 v104, v97
	v_mov_b32_e32 v97, v99
	v_and_b32_e32 v99, 0xffff0000, v164
	v_mul_f32_e32 v0, 0xbfb8aa3b, v98
	v_add_f32_e64 v104, v104, v96
	v_add_f32_e64 v105, v105, v97
	v_exp_f32_e32 v0, v0
	v_mul_f32_e32 v97, 0xbfb8aa3b, v99
	s_waitcnt lgkmcnt(0)
	v_mov_b32_e32 v96, v102
	v_exp_f32_e32 v102, v97
	v_lshlrev_b32_e32 v108, 16, v165
	v_mov_b32_e32 v97, v100
	v_add_f32_e32 v0, 1.0, v0
	v_and_b32_e32 v109, 0xffff0000, v165
	v_mul_f32_e32 v100, 0xbfb8aa3b, v108
	v_rcp_f32_e32 v106, v0
	v_add_f32_e32 v0, 1.0, v102
	v_exp_f32_e32 v100, v100
	v_mul_f32_e32 v102, 0xbfb8aa3b, v109
	v_exp_f32_e32 v102, v102
	v_rcp_f32_e32 v107, v0
	v_add_f32_e32 v0, 1.0, v100
	v_rcp_f32_e32 v140, v0
	v_add_f32_e32 v0, 1.0, v102
	v_rcp_f32_e32 v141, v0
	v_mov_b32_e32 v100, v103
	v_add_f32_e64 v142, v96, v100
	v_add_f32_e64 v143, v97, v101
	v_mul_f32_e64 v106, v106, v98
	v_mul_f32_e64 v107, v107, v99
	v_mul_f32_e64 v108, v140, v108
	v_mul_f32_e64 v109, v141, v109
	v_lshlrev_b32_e32 v140, 16, v162
	v_and_b32_e32 v141, 0xffff0000, v162
	v_mul_f32_e32 v0, 0xbfb8aa3b, v140
	v_exp_f32_e32 v0, v0
	v_mul_f32_e32 v96, 0xbfb8aa3b, v141
	v_exp_f32_e32 v96, v96
	v_lshl_add_u64 v[146:147], s[54:55], 0, v[126:127]
	v_add_f32_e32 v0, 1.0, v0
	v_rcp_f32_e32 v148, v0
	v_add_f32_e32 v0, 1.0, v96
	v_rcp_f32_e32 v149, v0
	v_mul_f32_e32 v0, 0xbfb8aa3b, v150
	v_exp_f32_e32 v0, v0
	v_mul_f32_e32 v96, 0xbfb8aa3b, v151
	v_exp_f32_e32 v100, v96
	ds_read_b128 v[96:99], v188 offset:1536
	v_add_f32_e32 v0, 1.0, v0
	v_rcp_f32_e32 v152, v0
	v_add_f32_e32 v0, 1.0, v100
	ds_read_b128 v[100:103], v188 offset:1552
	s_waitcnt lgkmcnt(1)
	v_mov_b32_e32 v158, v97
	v_mov_b32_e32 v159, v98
	v_mov_b32_e32 v97, v99
	v_add_f32_e64 v96, v158, v96
	v_add_f32_e64 v97, v159, v97
	s_waitcnt lgkmcnt(0)
	v_mov_b32_e32 v98, v102
	v_mov_b32_e32 v99, v100
	v_mov_b32_e32 v100, v103
	v_add_f32_e64 v98, v98, v100
	v_add_f32_e64 v99, v99, v101
	v_mov_b32_e32 v100, v96
	v_mov_b32_e32 v101, v104
	v_mov_b32_e32 v104, v97
	v_add_f32_e64 v96, v100, v104
	v_add_f32_e64 v97, v101, v105
	v_mov_b32_e32 v100, v99
	v_mov_b32_e32 v101, v143
	v_add_f32_e64 v96, v96, v100
	v_add_f32_e64 v97, v97, v101
	v_mov_b32_e32 v99, v142
	v_add_f32_e64 v96, v98, v96
	v_add_f32_e64 v97, v99, v97
	v_rcp_f32_e32 v153, v0
	v_fma_f32 v81, v97, s50, v80
	v_fma_f32 v80, v96, s50, v80
	v_mul_f32_e64 v96, v148, v140
	v_mul_f32_e64 v97, v149, v141
	v_mul_f32_e32 v0, 0x4b800000, v81
	v_cmp_gt_f32_e32 vcc, s80, v81
	v_mul_f32_e64 v170, v152, v150
	v_mul_f32_e64 v171, v153, v151
	v_lshl_add_u64 v[172:173], s[54:55], 0, v[128:129]
	v_cndmask_b32_e32 v0, v81, v0, vcc
	v_rsq_f32_e32 v0, v0
	s_add_i32 s74, s74, 1
	s_add_u32 s58, s58, 0xfffa0000
	s_addc_u32 s59, s59, -1
	v_mul_f32_e32 v81, 0x45800000, v0
	v_cndmask_b32_e32 v0, v0, v81, vcc
	v_mul_f32_e64 v90, v90, v0
	v_mul_f32_e64 v91, v91, v0
	v_mul_f32_e64 v94, v94, v0
	v_mul_f32_e64 v95, v95, v0
	v_mul_f32_e64 v90, v74, v90
	v_mul_f32_e64 v91, v75, v91
	v_mul_f32_e64 v94, v76, v94
	v_mul_f32_e64 v95, v77, v95
	v_mul_f32_e64 v90, v106, v90
	v_mul_f32_e64 v91, v107, v91
	v_mul_f32_e64 v94, v108, v94
	v_mul_f32_e64 v95, v109, v95
	v_cvt_pk_bf16_f32 v90, v90, v91
	v_cvt_pk_bf16_f32 v91, v94, v95
	global_store_dwordx2 v[146:147], v[90:91], off
	v_mul_f32_e64 v90, v92, v0
	v_mul_f32_e64 v91, v93, v0
	v_mul_f32_e64 v88, v88, v0
	v_mul_f32_e64 v89, v89, v0
	v_mul_f32_e32 v0, 0x4b800000, v80
	v_cmp_gt_f32_e32 vcc, s80, v80
	v_mul_f32_e64 v90, v70, v90
	v_mul_f32_e64 v91, v71, v91
	v_mul_f32_e64 v228, v72, v88
	v_mul_f32_e64 v229, v73, v89
	v_cndmask_b32_e32 v0, v80, v0, vcc
	v_mul_f32_e64 v108, v96, v90
	v_mul_f32_e64 v109, v97, v91
	ds_read_b64_tr_b16 v[90:91], v217 offset:57408
	ds_read_b64_tr_b16 v[88:89], v217 offset:56320
	ds_read_b64_tr_b16 v[94:95], v214 offset:2112
	ds_read_b64_tr_b16 v[92:93], v214
	ds_read_b64_tr_b16 v[98:99], v214 offset:2144
	ds_read_b64_tr_b16 v[96:97], v214 offset:32
	ds_read_b64_tr_b16 v[100:101], v217 offset:56352
	ds_read_b64_tr_b16 v[104:105], v217 offset:56384
	ds_read_b64_tr_b16 v[140:141], v217 offset:56416
	ds_read_b64_tr_b16 v[102:103], v217 offset:57440
	ds_read_b64_tr_b16 v[106:107], v217 offset:57472
	ds_read_b64_tr_b16 v[142:143], v217 offset:57504
	v_rsq_f32_e32 v0, v0
	ds_read_b64_tr_b16 v[146:147], v217 offset:65024
	ds_read_b64_tr_b16 v[148:149], v218 offset:57408
	ds_read_b64_tr_b16 v[150:151], v214 offset:16896
	ds_read_b64_tr_b16 v[152:153], v214 offset:19008
	ds_read_b64_tr_b16 v[160:161], v214 offset:19040
	ds_read_b64_tr_b16 v[158:159], v214 offset:16928
	s_waitcnt lgkmcnt(8)
	v_mfma_f32_16x16x32_bf16 v[10:13], v[100:103], v[92:95], v[10:13]
	v_and_b32_e32 v81, 0xffff0000, v156
	v_mul_f32_e32 v80, 0x45800000, v0
	v_cndmask_b32_e32 v0, v0, v80, vcc
	v_mfma_f32_16x16x32_bf16 v[18:21], v[100:103], v[96:99], v[18:21]
	v_lshlrev_b32_e32 v80, 16, v156
	v_mul_f32_e32 v100, 0xbfb8aa3b, v80
	v_mul_f32_e32 v101, 0xbfb8aa3b, v81
	v_mfma_f32_16x16x32_bf16 v[30:33], v[88:91], v[92:95], v[30:33]
	v_exp_f32_e32 v100, v100
	v_mul_f32_e64 v86, v86, v0
	v_mul_f32_e64 v87, v87, v0
	v_mul_f32_e64 v170, v170, v228
	v_mul_f32_e64 v171, v171, v229
	v_mfma_f32_16x16x32_bf16 v[6:9], v[88:91], v[96:99], v[6:9]
	ds_read_b64_tr_b16 v[88:89], v217 offset:65056
	ds_read_b64_tr_b16 v[162:163], v217 offset:65088
	ds_read_b64_tr_b16 v[166:167], v217 offset:65120
	ds_read_b64_tr_b16 v[90:91], v218 offset:57440
	ds_read_b64_tr_b16 v[164:165], v218 offset:57472
	ds_read_b64_tr_b16 v[168:169], v218 offset:57504
	v_mul_f32_e64 v74, v74, v86
	v_mul_f32_e64 v75, v75, v87
	v_lshlrev_b32_e32 v86, 16, v157
	s_waitcnt lgkmcnt(2)
	v_mfma_f32_16x16x32_bf16 v[10:13], v[88:91], v[150:153], v[10:13]
	v_mul_f32_e32 v87, 0xbfb8aa3b, v86
	v_cvt_pk_bf16_f32 v108, v108, v109
	v_cvt_pk_bf16_f32 v109, v170, v171
	v_mfma_f32_16x16x32_bf16 v[18:21], v[88:91], v[158:161], v[18:21]
	v_exp_f32_e32 v89, v101
	v_add_f32_e32 v88, 1.0, v100
	v_rcp_f32_e32 v88, v88
	global_store_dwordx2 v[172:173], v[108:109], off
	v_add_f32_e32 v89, 1.0, v89
	v_rcp_f32_e32 v89, v89
	v_mfma_f32_16x16x32_bf16 v[14:17], v[104:107], v[92:95], v[14:17]
	v_mul_f32_e64 v82, v82, v0
	v_mul_f32_e64 v83, v83, v0
	v_mul_f32_e64 v78, v78, v0
	v_mul_f32_e64 v79, v79, v0
	v_mul_f32_e64 v80, v88, v80
	v_mul_f32_e64 v81, v89, v81
	v_exp_f32_e32 v88, v87
	v_mul_f32_e64 v80, v80, v74
	v_mul_f32_e64 v81, v81, v75
	v_and_b32_e32 v87, 0xffff0000, v157
	v_mfma_f32_16x16x32_bf16 v[26:29], v[104:107], v[96:99], v[26:29]
	v_add_f32_e32 v74, 1.0, v88
	v_rcp_f32_e32 v88, v74
	v_mul_f32_e32 v74, 0xbfb8aa3b, v87
	v_exp_f32_e32 v89, v74
	v_mul_f32_e64 v74, v84, v0
	v_mul_f32_e64 v75, v85, v0
	v_mfma_f32_16x16x32_bf16 v[38:41], v[140:143], v[92:95], v[38:41]
	v_mul_f32_e64 v108, v76, v74
	v_mul_f32_e64 v109, v77, v75
	v_add_f32_e32 v74, 1.0, v89
	v_rcp_f32_e32 v89, v74
	ds_read_b64_tr_b16 v[74:75], v217 offset:56448
	ds_read_b64_tr_b16 v[76:77], v217 offset:57536
	v_mfma_f32_16x16x32_bf16 v[50:53], v[140:143], v[96:99], v[50:53]
	v_cvt_pk_bf16_f32 v80, v80, v81
	v_mul_f32_e64 v140, v88, v86
	v_mul_f32_e64 v141, v89, v87
	ds_read_b64_tr_b16 v[84:85], v217 offset:56480
	ds_read_b64_tr_b16 v[88:89], v217 offset:56512
	ds_read_b64_tr_b16 v[100:101], v217 offset:56544
	ds_read_b64_tr_b16 v[86:87], v217 offset:57568
	ds_read_b64_tr_b16 v[90:91], v217 offset:57600
	ds_read_b64_tr_b16 v[102:103], v217 offset:57632
	ds_read_b64_tr_b16 v[104:105], v217 offset:65152
	ds_read_b64_tr_b16 v[106:107], v218 offset:57536
	s_waitcnt lgkmcnt(8)
	v_mfma_f32_16x16x32_bf16 v[22:25], v[74:77], v[92:95], v[22:25]
	v_mul_f32_e64 v108, v140, v108
	v_mul_f32_e64 v109, v141, v109
	v_mul_f32_e64 v70, v70, v82
	v_mul_f32_e64 v71, v71, v83
	v_cvt_pk_bf16_f32 v81, v108, v109
	v_mfma_f32_16x16x32_bf16 v[34:37], v[74:77], v[96:99], v[34:37]
	v_lshl_add_u64 v[108:109], s[54:55], 0, v[130:131]
	v_mul_f32_e64 v72, v72, v78
	v_mul_f32_e64 v73, v73, v79
	v_lshl_add_u32 v0, s68, 9, v182
	v_mfma_f32_16x16x32_bf16 v[30:33], v[146:149], v[150:153], v[30:33]
	s_sub_i32 s52, s52, 64
	v_mfma_f32_16x16x32_bf16 v[6:9], v[146:149], v[158:161], v[6:9]
	ds_read_b64_tr_b16 v[74:75], v217 offset:65184
	ds_read_b64_tr_b16 v[140:141], v217 offset:65216
	ds_read_b64_tr_b16 v[146:147], v217 offset:65248
	ds_read_b64_tr_b16 v[76:77], v218 offset:57568
	ds_read_b64_tr_b16 v[142:143], v218 offset:57600
	ds_read_b64_tr_b16 v[148:149], v218 offset:57632
	global_store_dwordx2 v[108:109], v[80:81], off
	v_lshlrev_b32_e32 v80, 16, v144
	v_and_b32_e32 v81, 0xffff0000, v144
	s_waitcnt lgkmcnt(6)
	v_mfma_f32_16x16x32_bf16 v[22:25], v[104:107], v[150:153], v[22:25]
	v_mfma_f32_16x16x32_bf16 v[34:37], v[104:107], v[158:161], v[34:37]
	v_mul_f32_e32 v104, 0xbfb8aa3b, v80
	v_mul_f32_e32 v105, 0xbfb8aa3b, v81
	v_exp_f32_e32 v104, v104
	v_mfma_f32_16x16x32_bf16 v[42:45], v[84:87], v[92:95], v[42:45]
	v_mfma_f32_16x16x32_bf16 v[54:57], v[84:87], v[96:99], v[54:57]
	v_exp_f32_e32 v85, v105
	v_add_f32_e32 v84, 1.0, v104
	v_rcp_f32_e32 v84, v84
	s_waitcnt lgkmcnt(2)
	v_mfma_f32_16x16x32_bf16 v[42:45], v[74:77], v[150:153], v[42:45]
	v_add_f32_e32 v85, 1.0, v85
	v_rcp_f32_e32 v85, v85
	v_mfma_f32_16x16x32_bf16 v[54:57], v[74:77], v[158:161], v[54:57]
	v_mul_f32_e64 v74, v84, v80
	v_mul_f32_e64 v75, v85, v81
	v_mul_f32_e64 v70, v74, v70
	v_mul_f32_e64 v71, v75, v71
	v_lshlrev_b32_e32 v74, 16, v145
	v_and_b32_e32 v75, 0xffff0000, v145
	v_mul_f32_e32 v76, 0xbfb8aa3b, v74
	v_mul_f32_e32 v77, 0xbfb8aa3b, v75
	v_exp_f32_e32 v76, v76
	v_exp_f32_e32 v77, v77
	v_cvt_pk_bf16_f32 v78, v70, v71
	v_lshl_add_u64 v[80:81], s[54:55], 0, v[132:133]
	v_add_f32_e32 v76, 1.0, v76
	v_add_f32_e32 v77, 1.0, v77
	v_rcp_f32_e32 v76, v76
	v_rcp_f32_e32 v77, v77
	v_mfma_f32_16x16x32_bf16 v[14:17], v[162:165], v[150:153], v[14:17]
	s_add_u32 s54, s54, 0xfffe0000
	s_addc_u32 s55, s55, -1
	v_mul_f32_e64 v74, v76, v74
	v_mul_f32_e64 v75, v77, v75
	v_mfma_f32_16x16x32_bf16 v[26:29], v[162:165], v[158:161], v[26:29]
	v_mul_f32_e64 v74, v74, v72
	v_mul_f32_e64 v75, v75, v73
	ds_read_b128 v[70:73], v0 offset:4096
	v_cvt_pk_bf16_f32 v79, v74, v75
	ds_read_b128 v[74:77], v0 offset:4160
	global_store_dwordx2 v[80:81], v[78:79], off
	v_mfma_f32_16x16x32_bf16 v[38:41], v[166:169], v[150:153], v[38:41]
	s_waitcnt lgkmcnt(1)
	v_mul_f32_e32 v70, 0x3fb8aa3b, v70
	v_exp_f32_e32 v82, v70
	v_mul_f32_e32 v83, 0x3fb8aa3b, v71
	v_mul_f32_e32 v70, 0x3fb8aa3b, v72
	v_mul_f32_e32 v71, 0x3fb8aa3b, v73
	v_exp_f32_e32 v70, v70
	v_exp_f32_e32 v71, v71
	v_exp_f32_e32 v83, v83
	v_mfma_f32_16x16x32_bf16 v[50:53], v[166:169], v[158:161], v[50:53]
	s_add_u32 s56, s56, 0xfffe0000
	v_mul_f32_e64 v32, v32, v70
	v_mul_f32_e64 v33, v33, v71
	v_mul_f32_e64 v8, v8, v70
	v_mul_f32_e64 v9, v9, v71
	s_waitcnt lgkmcnt(0)
	v_mul_f32_e32 v70, 0x3fb8aa3b, v74
	v_mul_f32_e32 v71, 0x3fb8aa3b, v76
	v_exp_f32_e32 v78, v70
	v_mul_f32_e32 v70, 0x3fb8aa3b, v75
	v_exp_f32_e32 v80, v71
	v_mul_f32_e32 v71, 0x3fb8aa3b, v77
	v_exp_f32_e32 v81, v71
	v_exp_f32_e32 v79, v70
	ds_read_b128 v[70:73], v0 offset:4224
	ds_read_b128 v[74:77], v0 offset:4288
	v_mul_f32_e64 v30, v30, v82
	v_mul_f32_e64 v31, v31, v83
	v_mul_f32_e64 v6, v6, v82
	v_mul_f32_e64 v7, v7, v83
	v_mul_f32_e64 v12, v12, v80
	v_mul_f32_e64 v13, v13, v81
	s_waitcnt lgkmcnt(1)
	v_mul_f32_e32 v70, 0x3fb8aa3b, v70
	v_exp_f32_e32 v82, v70
	v_mul_f32_e32 v83, 0x3fb8aa3b, v71
	v_mul_f32_e32 v70, 0x3fb8aa3b, v72
	v_mul_f32_e32 v71, 0x3fb8aa3b, v73
	v_exp_f32_e32 v70, v70
	v_exp_f32_e32 v71, v71
	v_mul_f32_e64 v10, v10, v78
	v_mul_f32_e64 v11, v11, v79
	v_mul_f32_e64 v20, v20, v80
	v_mul_f32_e64 v21, v21, v81
	v_mul_f32_e64 v18, v18, v78
	v_mul_f32_e64 v19, v19, v79
	v_mul_f32_e64 v16, v16, v70
	v_mul_f32_e64 v17, v17, v71
	v_mul_f32_e64 v28, v28, v70
	v_mul_f32_e64 v29, v29, v71
	s_waitcnt lgkmcnt(0)
	v_mul_f32_e32 v70, 0x3fb8aa3b, v74
	v_mul_f32_e32 v71, 0x3fb8aa3b, v76
	v_exp_f32_e32 v78, v70
	v_mul_f32_e32 v70, 0x3fb8aa3b, v75
	v_exp_f32_e32 v80, v71
	v_mul_f32_e32 v71, 0x3fb8aa3b, v77
	v_exp_f32_e32 v81, v71
	v_exp_f32_e32 v79, v70
	ds_read_b128 v[70:73], v0 offset:4352
	ds_read_b128 v[74:77], v0 offset:4416
	v_exp_f32_e32 v83, v83
	v_mul_f32_e64 v40, v40, v80
	v_mul_f32_e64 v41, v41, v81
	v_mul_f32_e64 v38, v38, v78
	v_mul_f32_e64 v39, v39, v79
	s_waitcnt lgkmcnt(1)
	v_mul_f32_e32 v70, 0x3fb8aa3b, v70
	v_mul_f32_e64 v14, v14, v82
	v_mul_f32_e64 v15, v15, v83
	v_mul_f32_e64 v26, v26, v82
	v_mul_f32_e64 v27, v27, v83
	v_exp_f32_e32 v82, v70
	v_mul_f32_e32 v83, 0x3fb8aa3b, v71
	v_mul_f32_e32 v70, 0x3fb8aa3b, v72
	v_mul_f32_e32 v71, 0x3fb8aa3b, v73
	v_exp_f32_e32 v70, v70
	v_exp_f32_e32 v71, v71
	v_mul_f32_e64 v52, v52, v80
	v_mul_f32_e64 v53, v53, v81
	v_mul_f32_e64 v50, v50, v78
	v_mul_f32_e64 v51, v51, v79
	v_mfma_f32_16x16x32_bf16 v[46:49], v[88:91], v[92:95], v[46:49]
	v_mul_f32_e64 v24, v24, v70
	v_mul_f32_e64 v25, v25, v71
	v_mul_f32_e64 v36, v36, v70
	v_mul_f32_e64 v37, v37, v71
	s_waitcnt lgkmcnt(0)
	v_mul_f32_e32 v70, 0x3fb8aa3b, v74
	v_mul_f32_e32 v71, 0x3fb8aa3b, v76
	v_exp_f32_e32 v78, v70
	v_mul_f32_e32 v70, 0x3fb8aa3b, v75
	v_exp_f32_e32 v80, v71
	v_mul_f32_e32 v71, 0x3fb8aa3b, v77
	v_exp_f32_e32 v81, v71
	v_exp_f32_e32 v79, v70
	ds_read_b128 v[70:73], v0 offset:4480
	ds_read_b128 v[74:77], v0 offset:4544
	v_mfma_f32_16x16x32_bf16 v[62:65], v[88:91], v[96:99], v[62:65]
	v_exp_f32_e32 v83, v83
	s_addc_u32 s57, s57, -1
	s_waitcnt lgkmcnt(1)
	v_mul_f32_e32 v0, 0x3fb8aa3b, v70
	v_exp_f32_e32 v70, v0
	v_mul_f32_e32 v0, 0x3fb8aa3b, v71
	v_mul_f32_e32 v71, 0x3fb8aa3b, v72
	v_mfma_f32_16x16x32_bf16 v[58:61], v[100:103], v[92:95], v[58:61]
	v_exp_f32_e32 v72, v71
	v_mul_f32_e32 v71, 0x3fb8aa3b, v73
	v_exp_f32_e32 v73, v71
	v_mfma_f32_16x16x32_bf16 v[66:69], v[100:103], v[96:99], v[66:69]
	v_exp_f32_e32 v71, v0
	s_waitcnt lgkmcnt(0)
	v_mul_f32_e32 v0, 0x3fb8aa3b, v74
	v_exp_f32_e32 v74, v0
	v_mul_f32_e32 v0, 0x3fb8aa3b, v75
	v_mul_f32_e32 v75, 0x3fb8aa3b, v76
	v_exp_f32_e32 v76, v75
	v_mul_f32_e32 v75, 0x3fb8aa3b, v77
	v_mfma_f32_16x16x32_bf16 v[46:49], v[140:143], v[150:153], v[46:49]
	v_exp_f32_e32 v77, v75
	v_exp_f32_e32 v75, v0
	v_mul_f32_e64 v22, v22, v82
	v_mul_f32_e64 v23, v23, v83
	v_mfma_f32_16x16x32_bf16 v[62:65], v[140:143], v[158:161], v[62:65]
	v_mul_f32_e64 v34, v34, v82
	v_mul_f32_e64 v35, v35, v83
	v_mul_f32_e64 v44, v44, v80
	v_mul_f32_e64 v45, v45, v81
	v_mul_f32_e64 v42, v42, v78
	v_mul_f32_e64 v43, v43, v79
	v_mfma_f32_16x16x32_bf16 v[58:61], v[146:149], v[150:153], v[58:61]
	v_mul_f32_e64 v56, v56, v80
	v_mul_f32_e64 v57, v57, v81
	v_mul_f32_e64 v54, v54, v78
	v_mul_f32_e64 v55, v55, v79
	v_mul_f32_e64 v48, v48, v72
	v_mul_f32_e64 v49, v49, v73
	v_mfma_f32_16x16x32_bf16 v[66:69], v[146:149], v[158:161], v[66:69]
	v_mul_f32_e64 v46, v46, v70
	v_mul_f32_e64 v47, v47, v71
	v_mul_f32_e64 v64, v64, v72
	v_mul_f32_e64 v65, v65, v73
	v_mul_f32_e64 v62, v62, v70
	v_mul_f32_e64 v63, v63, v71
	v_mul_f32_e64 v60, v60, v76
	v_mul_f32_e64 v61, v61, v77
	v_mul_f32_e64 v58, v58, v74
	v_mul_f32_e64 v59, v59, v75
	s_nop 1
	v_mul_f32_e64 v68, v68, v76
	v_mul_f32_e64 v69, v69, v77
	s_cmp_lg_u32 s74, 8
	v_mul_f32_e64 v66, v66, v74
	v_mul_f32_e64 v67, v67, v75
	s_cbranch_scc0 .LBB0_2257

.LBB0_2292:
	ds_read_b128 v[102:105], v205 offset:6144
	ds_read_b128 v[106:109], v205 offset:6160
	s_waitcnt vmcnt(6)
	v_lshlrev_b32_e32 v142, 16, v98
	v_and_b32_e32 v143, 0xffff0000, v98
	s_waitcnt lgkmcnt(1)
	v_mul_f32_e32 v0, 0xbfb8aa3b, v102
	v_exp_f32_e32 v140, v0
	v_mul_f32_e32 v0, 0xbfb8aa3b, v103
	v_exp_f32_e32 v141, v0
	v_mul_f32_e32 v0, 0xbfb8aa3b, v104
	v_mul_f32_e64 v140, v140, v142
	v_mul_f32_e64 v141, v141, v143
	s_nop 0
	v_cvt_pk_bf16_f32 v98, v140, v141
	v_exp_f32_e32 v140, v0
	v_mul_f32_e32 v0, 0xbfb8aa3b, v105
	v_exp_f32_e32 v141, v0
	v_lshlrev_b32_e32 v142, 16, v99
	v_and_b32_e32 v143, 0xffff0000, v99
	s_waitcnt lgkmcnt(0)
	v_mul_f32_e32 v0, 0xbfb8aa3b, v106
	v_mul_f32_e64 v140, v140, v142
	v_mul_f32_e64 v141, v141, v143
	v_lshlrev_b32_e32 v142, 16, v100
	v_cvt_pk_bf16_f32 v99, v140, v141
	v_exp_f32_e32 v140, v0
	v_mul_f32_e32 v0, 0xbfb8aa3b, v107
	v_exp_f32_e32 v141, v0
	v_and_b32_e32 v143, 0xffff0000, v100
	v_mul_f32_e32 v0, 0xbfb8aa3b, v108
	v_mul_f32_e64 v140, v140, v142
	v_mul_f32_e64 v141, v141, v143
	s_nop 0
	v_cvt_pk_bf16_f32 v100, v140, v141
	v_exp_f32_e32 v140, v0
	v_mul_f32_e32 v0, 0xbfb8aa3b, v109
	v_exp_f32_e32 v141, v0
	v_lshlrev_b32_e32 v142, 16, v101
	v_and_b32_e32 v143, 0xffff0000, v101
	v_mul_f32_e32 v0, 0x3fb8aa3b, v102
	v_mul_f32_e64 v140, v140, v142
	v_mul_f32_e64 v141, v141, v143
	s_nop 0
	v_cvt_pk_bf16_f32 v101, v140, v141
	ds_write_b128 v184, v[98:101] offset:56320
	v_exp_f32_e32 v98, v0
	v_mul_f32_e32 v0, 0x3fb8aa3b, v103
	v_exp_f32_e32 v99, v0
	v_lshlrev_b32_e32 v100, 16, v94
	v_and_b32_e32 v101, 0xffff0000, v94
	v_mul_f32_e32 v0, 0x3fb8aa3b, v104
	v_mul_f32_e64 v98, v98, s48
	v_mul_f32_e64 v99, v99, s48
	s_waitcnt vmcnt(4)
	v_lshlrev_b32_e32 v104, 16, v90
	v_mul_f32_e64 v98, v98, v100
	v_mul_f32_e64 v99, v99, v101
	v_lshlrev_b32_e32 v100, 16, v95
	v_cvt_pk_bf16_f32 v94, v98, v99
	v_exp_f32_e32 v98, v0
	v_mul_f32_e32 v0, 0x3fb8aa3b, v105
	v_exp_f32_e32 v99, v0
	v_and_b32_e32 v101, 0xffff0000, v95
	v_mul_f32_e32 v0, 0x3fb8aa3b, v106
	v_and_b32_e32 v105, 0xffff0000, v90
	v_mul_f32_e64 v98, v98, s48
	v_mul_f32_e64 v99, v99, s48
	s_nop 0
	v_mul_f32_e64 v98, v98, v100
	v_mul_f32_e64 v99, v99, v101
	v_lshlrev_b32_e32 v100, 16, v96
	v_cvt_pk_bf16_f32 v95, v98, v99
	v_exp_f32_e32 v98, v0
	v_mul_f32_e32 v0, 0x3fb8aa3b, v107
	v_exp_f32_e32 v99, v0
	v_and_b32_e32 v101, 0xffff0000, v96
	v_mul_f32_e32 v0, 0x3fb8aa3b, v108
	v_mul_f32_e64 v98, v98, s48
	v_mul_f32_e64 v99, v99, s48
	s_nop 0
	v_mul_f32_e64 v98, v98, v100
	v_mul_f32_e64 v99, v99, v101
	v_lshlrev_b32_e32 v100, 16, v97
	v_cvt_pk_bf16_f32 v96, v98, v99
	v_exp_f32_e32 v98, v0
	v_mul_f32_e32 v0, 0x3fb8aa3b, v109
	v_exp_f32_e32 v99, v0
	v_and_b32_e32 v101, 0xffff0000, v97
	v_mul_f32_e64 v98, v98, s48
	v_mul_f32_e64 v99, v99, s48
	s_nop 0
	v_mul_f32_e64 v98, v98, v100
	v_mul_f32_e64 v99, v99, v101
	s_nop 0
	v_cvt_pk_bf16_f32 v97, v98, v99
	ds_write_b128 v184, v[94:97] offset:38912
	ds_read_b128 v[94:97], v206 offset:6144
	ds_read_b128 v[98:101], v206 offset:6160
	s_waitcnt lgkmcnt(1)
	v_mul_f32_e32 v0, 0xbfb8aa3b, v94
	v_exp_f32_e32 v102, v0
	v_mul_f32_e32 v0, 0xbfb8aa3b, v95
	v_exp_f32_e32 v103, v0
	v_mul_f32_e32 v0, 0xbfb8aa3b, v96
	v_mul_f32_e64 v102, v102, v104
	v_mul_f32_e64 v103, v103, v105
	s_nop 0
	v_cvt_pk_bf16_f32 v90, v102, v103
	v_exp_f32_e32 v102, v0
	v_mul_f32_e32 v0, 0xbfb8aa3b, v97
	v_exp_f32_e32 v103, v0
	v_lshlrev_b32_e32 v104, 16, v91
	v_and_b32_e32 v105, 0xffff0000, v91
	s_waitcnt lgkmcnt(0)
	v_mul_f32_e32 v0, 0xbfb8aa3b, v98
	v_mul_f32_e64 v102, v102, v104
	v_mul_f32_e64 v103, v103, v105
	v_lshlrev_b32_e32 v104, 16, v92
	v_cvt_pk_bf16_f32 v91, v102, v103
	v_exp_f32_e32 v102, v0
	v_mul_f32_e32 v0, 0xbfb8aa3b, v99
	v_exp_f32_e32 v103, v0
	v_and_b32_e32 v105, 0xffff0000, v92
	v_mul_f32_e32 v0, 0xbfb8aa3b, v100
	v_mul_f32_e64 v102, v102, v104
	v_mul_f32_e64 v103, v103, v105
	s_nop 0
	v_cvt_pk_bf16_f32 v92, v102, v103
	v_exp_f32_e32 v102, v0
	v_mul_f32_e32 v0, 0xbfb8aa3b, v101
	v_exp_f32_e32 v103, v0
	v_lshlrev_b32_e32 v104, 16, v93
	v_and_b32_e32 v105, 0xffff0000, v93
	v_mul_f32_e32 v0, 0x3fb8aa3b, v94
	v_mul_f32_e64 v102, v102, v104
	v_mul_f32_e64 v103, v103, v105
	s_nop 0
	v_cvt_pk_bf16_f32 v93, v102, v103
	ds_write_b128 v185, v[90:93] offset:56320
	v_exp_f32_e32 v90, v0
	v_mul_f32_e32 v0, 0x3fb8aa3b, v95
	v_exp_f32_e32 v91, v0
	v_lshlrev_b32_e32 v92, 16, v70
	v_and_b32_e32 v93, 0xffff0000, v70
	v_mul_f32_e32 v0, 0x3fb8aa3b, v96
	v_mul_f32_e64 v90, v90, s48
	v_mul_f32_e64 v91, v91, s48
	s_nop 0
	v_mul_f32_e64 v90, v90, v92
	v_mul_f32_e64 v91, v91, v93
	v_lshlrev_b32_e32 v92, 16, v71
	v_cvt_pk_bf16_f32 v70, v90, v91
	v_exp_f32_e32 v90, v0
	v_mul_f32_e32 v0, 0x3fb8aa3b, v97
	v_exp_f32_e32 v91, v0
	v_and_b32_e32 v93, 0xffff0000, v71
	v_mul_f32_e32 v0, 0x3fb8aa3b, v98
	v_mul_f32_e64 v90, v90, s48
	v_mul_f32_e64 v91, v91, s48
	s_nop 0
	v_mul_f32_e64 v90, v90, v92
	v_mul_f32_e64 v91, v91, v93
	v_lshlrev_b32_e32 v92, 16, v72
	v_cvt_pk_bf16_f32 v71, v90, v91
	v_exp_f32_e32 v90, v0
	v_mul_f32_e32 v0, 0x3fb8aa3b, v99
	v_exp_f32_e32 v91, v0
	v_and_b32_e32 v93, 0xffff0000, v72
	v_mul_f32_e32 v0, 0x3fb8aa3b, v100
	v_mul_f32_e64 v90, v90, s48
	v_mul_f32_e64 v91, v91, s48
	s_nop 0
	v_mul_f32_e64 v90, v90, v92
	v_mul_f32_e64 v91, v91, v93
	v_lshlrev_b32_e32 v92, 16, v73
	v_cvt_pk_bf16_f32 v72, v90, v91
	v_exp_f32_e32 v90, v0
	v_mul_f32_e32 v0, 0x3fb8aa3b, v101
	v_exp_f32_e32 v91, v0
	v_and_b32_e32 v93, 0xffff0000, v73
	v_mul_f32_e64 v90, v90, s48
	v_mul_f32_e64 v91, v91, s48
	s_nop 0
	v_mul_f32_e64 v90, v90, v92
	v_mul_f32_e64 v91, v91, v93
	s_nop 0
	v_cvt_pk_bf16_f32 v73, v90, v91
	ds_write_b128 v185, v[70:73] offset:38912
	s_waitcnt vmcnt(3)
	ds_write_b128 v207, v[74:77]
	s_waitcnt vmcnt(2)
	ds_write_b128 v208, v[78:81]
	s_waitcnt vmcnt(1)
	ds_write_b128 v207, v[82:85] offset:16896
	s_waitcnt vmcnt(0)
	ds_write_b128 v209, v[86:89]
	v_lshl_add_u64 v[70:71], s[56:57], 0, v[118:119]
	v_lshl_add_u64 v[72:73], s[56:57], 0, v[122:123]
	v_lshl_add_u64 v[74:75], s[56:57], 0, v[124:125]
	global_load_dwordx2 v[160:161], v[70:71], off
	global_load_dwordx2 v[158:159], v[70:71], off offset:32
	global_load_dwordx2 v[152:153], v[72:73], off
	global_load_dwordx2 v[150:151], v[74:75], off
	v_lshl_add_u64 v[70:71], s[56:57], 0, v[126:127]
	v_lshl_add_u64 v[72:73], s[56:57], 0, v[128:129]
	v_lshl_add_u64 v[74:75], s[56:57], 0, v[130:131]
	v_lshl_add_u64 v[76:77], s[56:57], 0, v[132:133]
	global_load_dwordx2 v[148:149], v[70:71], off
	global_load_dwordx2 v[146:147], v[72:73], off
	global_load_dwordx2 v[142:143], v[74:75], off
	global_load_dwordx2 v[140:141], v[76:77], off
	s_waitcnt lgkmcnt(0)
	s_barrier
	ds_read_b128 v[70:73], v210 offset:56320
	ds_read_b128 v[74:77], v183 offset:38912
	ds_read_b128 v[78:81], v210 offset:56384
	ds_read_b128 v[82:85], v183 offset:38976
	s_waitcnt lgkmcnt(2)
	v_mfma_f32_16x16x32_bf16 v[70:73], v[70:73], v[74:77], 0
	v_mov_b32_e32 v0, s93
	v_cvt_pk_bf16_f32 v170, v62, v63
	v_cvt_pk_bf16_f32 v171, v64, v65
	s_waitcnt lgkmcnt(0)
	v_mfma_f32_16x16x32_bf16 v[70:73], v[78:81], v[82:85], v[70:73]
	ds_read_b128 v[78:81], v210 offset:56448
	ds_read_b128 v[86:89], v183 offset:39040
	v_cvt_pk_bf16_f32 v172, v66, v67
	v_cvt_pk_bf16_f32 v173, v68, v69
	s_waitcnt lgkmcnt(0)
	v_mfma_f32_16x16x32_bf16 v[70:73], v[78:81], v[86:89], v[70:73]
	ds_read_b128 v[78:81], v210 offset:56512
	ds_read_b128 v[90:93], v183 offset:39104
	s_add_u32 s49, s49, s0
	s_addc_u32 s53, s69, 0
	s_waitcnt lgkmcnt(0)
	v_mfma_f32_16x16x32_bf16 v[70:73], v[78:81], v[90:93], v[70:73]
	s_add_u32 s60, s49, 0xafc1000
	s_addc_u32 s61, s53, 0
	s_waitcnt vmcnt(7)
	v_lshlrev_b32_e32 v228, 16, v160
	s_nop 3
	v_cndmask_b32_e64 v0, v70, v0, s[14:15]
	v_cndmask_b32_e64 v70, v71, 0, s[30:31]
	v_cndmask_b32_e64 v71, v72, 0, s[34:35]
	v_cndmask_b32_e64 v72, v73, 0, s[36:37]
	v_cvt_pk_bf16_f32 v70, v0, v70
	v_cvt_pk_bf16_f32 v71, v71, v72
	ds_write_b64 v211, v[70:71]
	ds_read_b128 v[70:73], v212 offset:56320
	s_waitcnt lgkmcnt(0)
	v_mfma_f32_16x16x32_bf16 v[70:73], v[70:73], v[74:77], 0
	ds_read_b128 v[74:77], v212 offset:56384
	v_mov_b32_e32 v0, s93
	v_and_b32_e32 v229, 0xffff0000, v160
	s_waitcnt lgkmcnt(0)
	v_mfma_f32_16x16x32_bf16 v[70:73], v[74:77], v[82:85], v[70:73]
	ds_read_b128 v[74:77], v212 offset:56448
	v_lshlrev_b32_e32 v160, 16, v161
	v_and_b32_e32 v161, 0xffff0000, v161
	s_waitcnt lgkmcnt(0)
	v_mfma_f32_16x16x32_bf16 v[70:73], v[74:77], v[86:89], v[70:73]
	ds_read_b128 v[74:77], v212 offset:56512
	s_waitcnt vmcnt(6)
	v_lshlrev_b32_e32 v230, 16, v158
	v_and_b32_e32 v231, 0xffff0000, v158
	s_waitcnt lgkmcnt(0)
	v_mfma_f32_16x16x32_bf16 v[70:73], v[74:77], v[90:93], v[70:73]
	v_lshlrev_b32_e32 v158, 16, v159
	v_and_b32_e32 v159, 0xffff0000, v159
	s_nop 5
	v_cndmask_b32_e64 v0, v70, v0, s[22:23]
	v_cndmask_b32_e64 v70, v71, 0, s[38:39]
	v_cndmask_b32_e64 v71, v72, 0, s[40:41]
	v_cndmask_b32_e64 v72, v73, 0, s[42:43]
	v_cvt_pk_bf16_f32 v70, v0, v70
	v_cvt_pk_bf16_f32 v71, v71, v72
	ds_write_b64 v213, v[70:71]
	s_waitcnt lgkmcnt(0)
	s_barrier
	ds_read_b64_tr_b16 v[72:73], v214 offset:2112
	ds_read_b64_tr_b16 v[70:71], v214
	ds_read_b64_tr_b16 v[74:75], v214 offset:32
	ds_read_b64_tr_b16 v[78:79], v214 offset:16896
	ds_read_b64_tr_b16 v[80:81], v214 offset:19008
	ds_read_b64_tr_b16 v[76:77], v214 offset:2144
	ds_read_b64_tr_b16 v[82:83], v214 offset:16928
	ds_read_b64_tr_b16 v[84:85], v214 offset:19040
	ds_read_b128 v[86:89], v215
	ds_read_b128 v[94:97], v215 offset:64
	ds_read_b128 v[102:105], v215 offset:2368
	s_waitcnt lgkmcnt(2)
	v_mfma_f32_16x16x32_bf16 v[90:93], v[70:73], v[86:89], 0
	ds_read_b128 v[162:165], v215 offset:4672
	v_mfma_f32_16x16x32_bf16 v[86:89], v[74:77], v[86:89], 0
	s_waitcnt lgkmcnt(2)
	v_mfma_f32_16x16x32_bf16 v[90:93], v[78:81], v[94:97], v[90:93]
	v_mfma_f32_16x16x32_bf16 v[86:89], v[82:85], v[94:97], v[86:89]
	ds_read_b128 v[94:97], v215 offset:2304
	s_waitcnt lgkmcnt(0)
	v_mfma_f32_16x16x32_bf16 v[98:101], v[70:73], v[94:97], 0
	v_mfma_f32_16x16x32_bf16 v[94:97], v[74:77], v[94:97], 0
	v_mfma_f32_16x16x32_bf16 v[98:101], v[78:81], v[102:105], v[98:101]
	v_mfma_f32_16x16x32_bf16 v[94:97], v[82:85], v[102:105], v[94:97]
	ds_read_b128 v[102:105], v215 offset:4608
	s_waitcnt lgkmcnt(0)
	v_mfma_f32_16x16x32_bf16 v[106:109], v[70:73], v[102:105], 0
	v_mfma_f32_16x16x32_bf16 v[102:105], v[74:77], v[102:105], 0
	v_mfma_f32_16x16x32_bf16 v[106:109], v[78:81], v[162:165], v[106:109]
	v_mfma_f32_16x16x32_bf16 v[102:105], v[82:85], v[162:165], v[102:105]
	ds_read_b128 v[162:165], v215 offset:6912
	s_waitcnt lgkmcnt(0)
	v_mfma_f32_16x16x32_bf16 v[70:73], v[70:73], v[162:165], 0
	v_mfma_f32_16x16x32_bf16 v[74:77], v[74:77], v[162:165], 0
	ds_read_b128 v[162:165], v215 offset:6976
	s_waitcnt lgkmcnt(0)
	v_mfma_f32_16x16x32_bf16 v[70:73], v[78:81], v[162:165], v[70:73]
	v_cvt_pk_bf16_f32 v78, v30, v31
	v_cvt_pk_bf16_f32 v79, v32, v33
	v_cvt_pk_bf16_f32 v80, v10, v11
	v_mfma_f32_16x16x32_bf16 v[74:77], v[82:85], v[162:165], v[74:77]
	v_cvt_pk_bf16_f32 v81, v12, v13
	v_cvt_pk_bf16_f32 v82, v6, v7
	v_cvt_pk_bf16_f32 v83, v8, v9
	v_cvt_pk_bf16_f32 v84, v18, v19
	v_cvt_pk_bf16_f32 v85, v20, v21
	ds_read2_b64 v[162:165], v219 offset1:4
	s_waitcnt lgkmcnt(0)
	v_mfma_f32_16x16x32_bf16 v[90:93], v[78:81], v[162:165], v[90:93]
	v_mfma_f32_16x16x32_bf16 v[86:89], v[82:85], v[162:165], v[86:89]
	ds_read2_b64 v[162:165], v220 offset0:32 offset1:36
	s_waitcnt lgkmcnt(0)
	v_mfma_f32_16x16x32_bf16 v[98:101], v[78:81], v[162:165], v[98:101]
	v_mfma_f32_16x16x32_bf16 v[94:97], v[82:85], v[162:165], v[94:97]
	ds_read2_b64 v[162:165], v221 offset0:64 offset1:68
	s_waitcnt lgkmcnt(0)
	v_mfma_f32_16x16x32_bf16 v[106:109], v[78:81], v[162:165], v[106:109]
	v_mfma_f32_16x16x32_bf16 v[102:105], v[82:85], v[162:165], v[102:105]
	ds_read2_b64 v[162:165], v222 offset0:96 offset1:100
	s_waitcnt lgkmcnt(0)
	v_mfma_f32_16x16x32_bf16 v[70:73], v[78:81], v[162:165], v[70:73]
	v_cvt_pk_bf16_f32 v78, v14, v15
	v_cvt_pk_bf16_f32 v79, v16, v17
	v_cvt_pk_bf16_f32 v80, v38, v39
	v_mfma_f32_16x16x32_bf16 v[74:77], v[82:85], v[162:165], v[74:77]
	v_cvt_pk_bf16_f32 v81, v40, v41
	v_cvt_pk_bf16_f32 v82, v26, v27
	v_cvt_pk_bf16_f32 v83, v28, v29
	v_cvt_pk_bf16_f32 v84, v50, v51
	v_cvt_pk_bf16_f32 v85, v52, v53
	ds_read2_b64 v[162:165], v219 offset0:8 offset1:12
	s_waitcnt lgkmcnt(0)
	v_mfma_f32_16x16x32_bf16 v[90:93], v[78:81], v[162:165], v[90:93]
	v_mfma_f32_16x16x32_bf16 v[86:89], v[82:85], v[162:165], v[86:89]
	ds_read2_b64 v[162:165], v220 offset0:40 offset1:44
	s_waitcnt lgkmcnt(0)
	v_mfma_f32_16x16x32_bf16 v[98:101], v[78:81], v[162:165], v[98:101]
	v_mfma_f32_16x16x32_bf16 v[94:97], v[82:85], v[162:165], v[94:97]
	ds_read2_b64 v[162:165], v221 offset0:72 offset1:76
	s_waitcnt lgkmcnt(0)
	v_mfma_f32_16x16x32_bf16 v[106:109], v[78:81], v[162:165], v[106:109]
	v_mfma_f32_16x16x32_bf16 v[102:105], v[82:85], v[162:165], v[102:105]
	ds_read2_b64 v[162:165], v222 offset0:104 offset1:108
	s_waitcnt lgkmcnt(0)
	v_mfma_f32_16x16x32_bf16 v[70:73], v[78:81], v[162:165], v[70:73]
	v_cvt_pk_bf16_f32 v78, v22, v23
	v_cvt_pk_bf16_f32 v79, v24, v25
	v_cvt_pk_bf16_f32 v80, v42, v43
	v_mfma_f32_16x16x32_bf16 v[74:77], v[82:85], v[162:165], v[74:77]
	v_cvt_pk_bf16_f32 v81, v44, v45
	v_cvt_pk_bf16_f32 v82, v34, v35
	v_cvt_pk_bf16_f32 v83, v36, v37
	v_cvt_pk_bf16_f32 v84, v54, v55
	v_cvt_pk_bf16_f32 v85, v56, v57
	ds_read2_b64 v[162:165], v219 offset0:16 offset1:20
	s_waitcnt lgkmcnt(0)
	v_mfma_f32_16x16x32_bf16 v[90:93], v[78:81], v[162:165], v[90:93]
	v_mfma_f32_16x16x32_bf16 v[86:89], v[82:85], v[162:165], v[86:89]
	ds_read2_b64 v[162:165], v220 offset0:48 offset1:52
	s_waitcnt lgkmcnt(0)
	v_mfma_f32_16x16x32_bf16 v[98:101], v[78:81], v[162:165], v[98:101]
	v_mfma_f32_16x16x32_bf16 v[94:97], v[82:85], v[162:165], v[94:97]
	ds_read2_b64 v[162:165], v221 offset0:80 offset1:84
	s_waitcnt lgkmcnt(0)
	v_mfma_f32_16x16x32_bf16 v[166:169], v[78:81], v[162:165], v[106:109]
	v_mfma_f32_16x16x32_bf16 v[162:165], v[82:85], v[162:165], v[102:105]
	s_nop 2
	ds_read2_b64 v[102:105], v222 offset0:112 offset1:116
	s_waitcnt lgkmcnt(0)
	v_mfma_f32_16x16x32_bf16 v[70:73], v[78:81], v[102:105], v[70:73]
	v_cvt_pk_bf16_f32 v78, v46, v47
	v_cvt_pk_bf16_f32 v79, v48, v49
	v_cvt_pk_bf16_f32 v80, v58, v59
	v_mfma_f32_16x16x32_bf16 v[74:77], v[82:85], v[102:105], v[74:77]
	v_cvt_pk_bf16_f32 v81, v60, v61
	ds_read2_b64 v[82:85], v219 offset0:24 offset1:28
	s_waitcnt lgkmcnt(0)
	v_mfma_f32_16x16x32_bf16 v[106:109], v[78:81], v[82:85], v[90:93]
	v_mfma_f32_16x16x32_bf16 v[102:105], v[170:173], v[82:85], v[86:89]
	ds_read2_b64 v[82:85], v220 offset0:56 offset1:60
	s_nop 5
	v_add_f32_e64 v106, v106, v228
	v_add_f32_e64 v107, v107, v229
	v_add_f32_e64 v108, v108, v160
	v_add_f32_e64 v109, v109, v161
	s_waitcnt lgkmcnt(0)
	v_mfma_f32_16x16x32_bf16 v[98:101], v[78:81], v[82:85], v[98:101]
	v_mul_f32_e64 v160, v106, v106
	v_mul_f32_e64 v161, v107, v107
	v_mul_f32_e64 v228, v108, v108
	v_mul_f32_e64 v229, v109, v109
	v_add_f32_e32 v0, v160, v161
	v_mfma_f32_16x16x32_bf16 v[94:97], v[170:173], v[82:85], v[94:97]
	ds_read2_b64 v[82:85], v221 offset0:88 offset1:92
	v_add_f32_e64 v102, v102, v230
	v_add_f32_e64 v103, v103, v231
	v_add_f32_e32 v0, v228, v0
	s_waitcnt lgkmcnt(0)
	v_mfma_f32_16x16x32_bf16 v[86:89], v[170:173], v[82:85], v[162:165]
	v_add_f32_e64 v104, v104, v158
	v_add_f32_e64 v105, v105, v159
	s_nop 0
	ds_read2_b64 v[162:165], v222 offset0:120 offset1:124
	v_mul_f32_e64 v158, v102, v102
	v_mul_f32_e64 v159, v103, v103
	v_mfma_f32_16x16x32_bf16 v[90:93], v[78:81], v[82:85], v[166:169]
	v_add_f32_e32 v0, v229, v0
	v_add_f32_e32 v0, v158, v0
	v_mul_f32_e64 v230, v104, v104
	v_mul_f32_e64 v231, v105, v105
	s_waitcnt lgkmcnt(0)
	v_mfma_f32_16x16x32_bf16 v[82:85], v[78:81], v[162:165], v[70:73]
	v_add_f32_e32 v0, v159, v0
	v_add_f32_e32 v0, v230, v0
	v_add_f32_e32 v0, v231, v0
	v_lshl_add_u64 v[70:71], s[60:61], 0, v[120:121]
	v_add_co_u32_e32 v72, vcc, s81, v70
	v_mfma_f32_16x16x32_bf16 v[78:81], v[170:173], v[162:165], v[74:77]
	s_nop 0
	v_addc_co_u32_e32 v73, vcc, 0, v71, vcc
	global_load_dwordx2 v[172:173], v[70:71], off
	global_load_dwordx2 v[170:171], v[70:71], off offset:32
	global_load_dwordx2 v[168:169], v[72:73], off
	global_load_dwordx2 v[166:167], v[72:73], off offset:32
	v_add_co_u32_e32 v72, vcc, s72, v70
	ds_bpermute_b32 v135, v194, v0
	s_nop 0
	v_addc_co_u32_e32 v73, vcc, 0, v71, vcc
	v_add_co_u32_e32 v70, vcc, s73, v70
	global_load_dwordx2 v[164:165], v[72:73], off
	global_load_dwordx2 v[162:163], v[72:73], off offset:32
	v_addc_co_u32_e32 v71, vcc, 0, v71, vcc
	global_load_dwordx2 v[156:157], v[70:71], off
	global_load_dwordx2 v[144:145], v[70:71], off offset:32
	global_load_dwordx4 v[74:77], v[138:139], off
	s_nop 0
	global_load_dwordx4 v[70:73], v[138:139], off offset:64
	s_waitcnt lgkmcnt(0)
	v_add_f32_e32 v0, v0, v135
	ds_bpermute_b32 v135, v195, v0
	s_and_saveexec_b64 s[60:61], s[4:5]
	s_cbranch_execz .LBB0_2294
	s_waitcnt lgkmcnt(0)
	v_add_f32_e32 v0, v0, v135
	ds_write_b32 v189, v0
.LBB0_2294:
	s_or_b64 exec, exec, s[60:61]
	s_waitcnt vmcnt(15)
	v_lshlrev_b32_e32 v158, 16, v152
	v_and_b32_e32 v159, 0xffff0000, v152
	v_add_f32_e64 v158, v98, v158
	v_add_f32_e64 v159, v99, v159
	v_lshlrev_b32_e32 v98, 16, v153
	v_and_b32_e32 v99, 0xffff0000, v153
	v_add_f32_e64 v100, v100, v98
	v_add_f32_e64 v101, v101, v99
	v_mul_f32_e64 v152, v158, v158
	v_mul_f32_e64 v153, v159, v159
	v_mul_f32_e64 v160, v100, v100
	v_mul_f32_e64 v161, v101, v101
	s_waitcnt vmcnt(14)
	v_lshlrev_b32_e32 v98, 16, v150
	v_and_b32_e32 v99, 0xffff0000, v150
	v_add_f32_e32 v0, v152, v153
	v_add_f32_e64 v98, v94, v98
	v_add_f32_e64 v99, v95, v99
	v_lshlrev_b32_e32 v94, 16, v151
	v_and_b32_e32 v95, 0xffff0000, v151
	v_add_f32_e32 v0, v160, v0
	v_add_f32_e64 v96, v96, v94
	v_add_f32_e64 v97, v97, v95
	v_mul_f32_e64 v94, v98, v98
	v_mul_f32_e64 v95, v99, v99
	v_add_f32_e32 v0, v161, v0
	v_add_f32_e32 v0, v94, v0
	v_mul_f32_e64 v150, v96, v96
	v_mul_f32_e64 v151, v97, v97
	v_add_f32_e32 v0, v95, v0
	v_add_f32_e32 v0, v150, v0
	v_add_f32_e32 v0, v151, v0
	ds_bpermute_b32 v94, v194, v0
	s_waitcnt lgkmcnt(0)
	v_add_f32_e32 v0, v0, v94
	ds_bpermute_b32 v94, v195, v0
	s_and_saveexec_b64 s[60:61], s[4:5]
	s_cbranch_execz .LBB0_2296
	s_waitcnt lgkmcnt(0)
	v_add_f32_e32 v0, v0, v94
	ds_write_b32 v189, v0 offset:512
.LBB0_2296:
	s_or_b64 exec, exec, s[60:61]
	s_waitcnt vmcnt(13) lgkmcnt(0)
	v_lshlrev_b32_e32 v94, 16, v148
	v_and_b32_e32 v95, 0xffff0000, v148
	v_add_f32_e64 v90, v90, v94
	v_add_f32_e64 v91, v91, v95
	v_lshlrev_b32_e32 v94, 16, v149
	v_and_b32_e32 v95, 0xffff0000, v149
	v_add_f32_e64 v94, v92, v94
	v_add_f32_e64 v95, v93, v95
	v_mul_f32_e64 v148, v90, v90
	v_mul_f32_e64 v149, v91, v91
	v_mul_f32_e64 v150, v94, v94
	v_mul_f32_e64 v151, v95, v95
	s_waitcnt vmcnt(12)
	v_lshlrev_b32_e32 v92, 16, v146
	v_and_b32_e32 v93, 0xffff0000, v146
	v_add_f32_e32 v0, v148, v149
	v_add_f32_e64 v92, v86, v92
	v_add_f32_e64 v93, v87, v93
	v_lshlrev_b32_e32 v86, 16, v147
	v_and_b32_e32 v87, 0xffff0000, v147
	v_add_f32_e32 v0, v150, v0
	v_add_f32_e64 v88, v88, v86
	v_add_f32_e64 v89, v89, v87
	v_mul_f32_e64 v86, v92, v92
	v_mul_f32_e64 v87, v93, v93
	v_add_f32_e32 v0, v151, v0
	v_add_f32_e32 v0, v86, v0
	v_mul_f32_e64 v146, v88, v88
	v_mul_f32_e64 v147, v89, v89
	v_add_f32_e32 v0, v87, v0
	v_add_f32_e32 v0, v146, v0
	v_add_f32_e32 v0, v147, v0
	ds_bpermute_b32 v86, v194, v0
	s_waitcnt lgkmcnt(0)
	v_add_f32_e32 v0, v0, v86
	ds_bpermute_b32 v86, v195, v0
	s_and_saveexec_b64 s[60:61], s[4:5]
	s_cbranch_execz .LBB0_2298
	s_waitcnt lgkmcnt(0)
	v_add_f32_e32 v0, v0, v86
	ds_write_b32 v189, v0 offset:1024
.LBB0_2298:
	s_or_b64 exec, exec, s[60:61]
	s_waitcnt vmcnt(11) lgkmcnt(0)
	v_lshlrev_b32_e32 v86, 16, v142
	v_and_b32_e32 v87, 0xffff0000, v142
	v_add_f32_e64 v86, v82, v86
	v_add_f32_e64 v87, v83, v87
	v_lshlrev_b32_e32 v82, 16, v143
	v_and_b32_e32 v83, 0xffff0000, v143
	v_add_f32_e64 v84, v84, v82
	v_add_f32_e64 v85, v85, v83
	v_mul_f32_e64 v142, v86, v86
	v_mul_f32_e64 v143, v87, v87
	v_mul_f32_e64 v146, v84, v84
	v_mul_f32_e64 v147, v85, v85
	s_waitcnt vmcnt(10)
	v_lshlrev_b32_e32 v82, 16, v140
	v_and_b32_e32 v83, 0xffff0000, v140
	v_add_f32_e32 v0, v142, v143
	v_add_f32_e64 v82, v78, v82
	v_add_f32_e64 v83, v79, v83
	v_lshlrev_b32_e32 v78, 16, v141
	v_and_b32_e32 v79, 0xffff0000, v141
	v_add_f32_e32 v0, v146, v0
	v_add_f32_e64 v78, v80, v78
	v_add_f32_e64 v79, v81, v79
	v_mul_f32_e64 v80, v82, v82
	v_mul_f32_e64 v81, v83, v83
	v_add_f32_e32 v0, v147, v0
	v_add_f32_e32 v0, v80, v0
	v_mul_f32_e64 v140, v78, v78
	v_mul_f32_e64 v141, v79, v79
	v_add_f32_e32 v0, v81, v0
	v_add_f32_e32 v0, v140, v0
	v_add_f32_e32 v0, v141, v0
	ds_bpermute_b32 v80, v194, v0
	s_waitcnt lgkmcnt(0)
	v_add_f32_e32 v0, v0, v80
	ds_bpermute_b32 v80, v195, v0
	s_and_saveexec_b64 s[60:61], s[4:5]
	s_cbranch_execz .LBB0_2282
	s_waitcnt lgkmcnt(0)
	v_add_f32_e32 v0, v0, v80
	ds_write_b32 v189, v0 offset:1536
	s_branch .LBB0_2282
